# experiment: all global stores inside the layer loop marked sc1 (write-through) so the barrier's L2 write-back has little left to flush
# baseline (speedup 1.0000x reference)
; DI void phase_modulate(const float* xin, const float* norm_w, const float* modp, const float* adab,
;                        bf16* H, LAS unsigned char* lds, int tid, int G, float* MODF, const float* MODP_all, const float* adab_all) {
;     ...
;     if (MODF) for (int idx = blockIdx.x * 512 + tid; idx < 2 * 8 * 3072; idx += G * 512) { const int l2 = idx / 24576, rem = idx - l2 * 24576, b2 = rem / 3072, c2 = rem - b2 * 3072;
;         float v = adab_all[l2 * 3072 + c2];
; #pragma unroll
;         for (int ks = 0; ks < 8; ++ks) v += MODP_all[((size_t)(l2 * 8 + ks) * 8 + b2) * 3072 + c2];
;         MODF[idx] = v; }
.LBB0_97:
	v_mul_hi_i32 v5, v4, s89
	v_lshrrev_b32_e32 v8, 31, v5
	v_ashrrev_i32_e32 v5, 12, v5
	v_add_u32_e32 v5, v5, v8
	v_mad_i32_i24 v9, v5, s16, v4
	v_mul_hi_i32 v11, v9, s89
	v_lshrrev_b32_e32 v26, 31, v11
	v_ashrrev_i32_e32 v27, 9, v11
	v_add_u32_e32 v26, v27, v26
	v_mul_i32_i24_e32 v28, 0xfffff400, v26
	v_mul_i32_i24_e32 v21, 0xc00, v5
	v_lshlrev_b32_e32 v8, 3, v5
	v_mad_i32_i24 v5, v5, s16, v28
	v_add3_u32 v28, v5, v21, v4
	v_or_b32_e32 v10, 1, v8
	v_or_b32_e32 v12, 2, v8
	v_or_b32_e32 v14, 3, v8
	v_or_b32_e32 v16, 4, v8
	v_or_b32_e32 v18, 5, v8
	v_or_b32_e32 v22, 6, v8
	v_or_b32_e32 v24, 7, v8
	v_ashrrev_i32_e32 v29, 31, v28
	v_ashrrev_i32_e32 v9, 31, v8
	v_ashrrev_i32_e32 v11, 31, v10
	v_ashrrev_i32_e32 v13, 31, v12
	v_ashrrev_i32_e32 v15, 31, v14
	v_ashrrev_i32_e32 v17, 31, v16
	v_ashrrev_i32_e32 v19, 31, v18
	v_ashrrev_i32_e32 v23, 31, v22
	v_ashrrev_i32_e32 v25, 31, v24
	v_ashrrev_i32_e32 v27, 31, v26
	v_lshl_add_u64 v[28:29], v[28:29], 2, s[44:45]
	v_lshl_add_u64 v[8:9], v[8:9], 3, v[26:27]
	v_lshl_add_u64 v[10:11], v[10:11], 3, v[26:27]
	v_lshl_add_u64 v[12:13], v[12:13], 3, v[26:27]
	v_lshl_add_u64 v[14:15], v[14:15], 3, v[26:27]
	v_lshl_add_u64 v[16:17], v[16:17], 3, v[26:27]
	v_lshl_add_u64 v[18:19], v[18:19], 3, v[26:27]
	v_lshl_add_u64 v[22:23], v[22:23], 3, v[26:27]
	v_lshl_add_u64 v[24:25], v[24:25], 3, v[26:27]
	v_add_u32_e32 v26, v4, v5
	global_load_dword v5, v[28:29], off
	v_ashrrev_i32_e32 v27, 31, v26
	v_lshl_add_u64 v[26:27], v[26:27], 2, s[58:59]
	v_mad_u64_u32 v[28:29], s[4:5], v8, s3, v[26:27]
	v_mad_u64_u32 v[30:31], s[4:5], v10, s3, v[26:27]
	v_mad_u64_u32 v[32:33], s[4:5], v12, s3, v[26:27]
	v_mad_u64_u32 v[34:35], s[4:5], v14, s3, v[26:27]
	v_mad_u64_u32 v[36:37], s[4:5], v16, s3, v[26:27]
	v_mad_u64_u32 v[38:39], s[4:5], v18, s3, v[26:27]
	v_mad_u64_u32 v[40:41], s[4:5], v22, s3, v[26:27]
	v_mad_u64_u32 v[26:27], s[4:5], v24, s3, v[26:27]
	v_mad_i32_i24 v29, v9, s3, v29
	v_mad_i32_i24 v31, v11, s3, v31
	v_mad_i32_i24 v33, v13, s3, v33
	v_mad_i32_i24 v35, v15, s3, v35
	v_mad_i32_i24 v37, v17, s3, v37
	v_mad_i32_i24 v39, v19, s3, v39
	v_mad_i32_i24 v41, v23, s3, v41
	v_mad_i32_i24 v27, v25, s3, v27
	global_load_dword v8, v[28:29], off
	global_load_dword v9, v[30:31], off
	global_load_dword v10, v[32:33], off
	global_load_dword v11, v[34:35], off
	global_load_dword v12, v[36:37], off
	global_load_dword v13, v[38:39], off
	global_load_dword v14, v[40:41], off
	global_load_dword v15, v[26:27], off
	v_add_u32_e32 v4, s56, v4
	s_mov_b32 s2, 0xbfff
	v_cmp_lt_i32_e32 vcc, s2, v4
	s_or_b64 s[26:27], vcc, s[26:27]
	s_waitcnt vmcnt(0)
	v_add_f32_e32 v5, v5, v8
	v_add_f32_e32 v5, v5, v9
	v_add_f32_e32 v5, v5, v10
	v_add_f32_e32 v5, v5, v11
	v_add_f32_e32 v5, v5, v12
	v_add_f32_e32 v5, v5, v13
	v_add_f32_e32 v5, v5, v14
	v_add_f32_e32 v5, v5, v15
	global_store_dword v[6:7], v5, off sc1
	v_lshl_add_u64 v[6:7], v[6:7], 0, s[90:91]
	s_andn2_b64 exec, exec, s[26:27]
	s_cbranch_execnz .LBB0_97

; #define LAS __attribute__((address_space(3)))
; DI unsigned pk2(float lo, float hi) { f32x2_t v = {lo, hi}; bf16x2_t b = __builtin_convertvector(v, bf16x2_t); return __builtin_bit_cast(unsigned, b); }
; DI void phase_modulate(const float* xin, const float* norm_w, const float* modp, const float* adab,
;                        bf16* H, LAS unsigned char* lds, int tid, int G, float* MODF, const float* MODP_all, const float* adab_all) {
;     ...
; #pragma unroll
;         for (int pre = 0; pre < 2; ++pre) { const f32x4* xr = (const f32x4*)(xin + (size_t)(rb * 64 + wave + 8 * pre) * 1024) + lane;
; #pragma unroll
;             for (int j = 0; j < 4; ++j) vbuf[pre][j] = __builtin_nontemporal_load(xr + 64 * j); }
; #pragma unroll
;         for (int it = 0; it < 8; ++it) {
;             const int row = rb * 64 + wave + 8 * it;
;             if (it + 2 < 8) { const f32x4* xr = (const f32x4*)(xin + (size_t)(row + 16) * 1024) + lane;
; #pragma unroll
;                 for (int j = 0; j < 4; ++j) vbuf[(it + 2) % 3][j] = __builtin_nontemporal_load(xr + 64 * j); }
;             f32x4 v[4]; float ss = 0.f;
; #pragma unroll
;             for (int j = 0; j < 4; ++j) { v[j] = vbuf[it % 3][j]; ss += (v[j][0] * v[j][0] + v[j][1] * v[j][1]) + (v[j][2] * v[j][2] + v[j][3] * v[j][3]); }
;             const float rstd = rsqrtf(wave_sum(ss) * (1.f / 1024.f) + EPS);
; #pragma unroll
;             for (int j = 0; j < 4; ++j) { const int col = 4 * lane + 256 * j;
;                 const f32x4 shv = *(const LAS f32x4*)(sh + col), scv = *(const LAS f32x4*)(sc + col);
;                 const f32x4 hv = v[j] * rstd * nw[j] * scv + shv;
;                 u32x2 o; o.x = pk2(hv[0], hv[1]); o.y = pk2(hv[2], hv[3]);
;                 *(u32x2*)(H + (size_t)row * 1024 + col) = o; asm volatile("" ::: "memory"); }
.LBB0_101:
	v_lshl_add_u32 v82, s5, 6, v90
	v_ashrrev_i32_e32 v83, 31, v82
	v_lshlrev_b64 v[20:21], 12, v[82:83]
	v_lshl_add_u64 v[20:21], v[78:79], 0, v[20:21]
	v_add_u32_e32 v60, 8, v82
	global_load_dwordx4 v[52:55], v[20:21], off nt
	global_load_dwordx4 v[44:47], v[20:21], off offset:1024 nt
	global_load_dwordx4 v[24:27], v[20:21], off offset:3072 nt
	global_load_dwordx4 v[36:39], v[20:21], off offset:2048 nt
	v_ashrrev_i32_e32 v61, 31, v60
	v_lshlrev_b64 v[20:21], 12, v[60:61]
	v_lshl_add_u64 v[28:29], v[78:79], 0, v[20:21]
	global_load_dwordx4 v[48:51], v[28:29], off nt
	global_load_dwordx4 v[40:43], v[28:29], off offset:1024 nt
	global_load_dwordx4 v[20:23], v[28:29], off offset:3072 nt
	s_nop 0
	global_load_dwordx4 v[28:31], v[28:29], off offset:2048 nt
	v_add_u32_e32 v84, 24, v82
	v_add_u32_e32 v86, 16, v82
	ds_read_b128 v[56:59], v97
	ds_read_b128 v[102:105], v97 offset:4096
	s_add_i32 s5, s5, s88
	s_cmpk_lt_i32 s5, 0x100
	s_waitcnt vmcnt(0)
	v_pk_mul_f32 v[32:33], v[54:55], v[54:55]
	v_pk_mul_f32 v[34:35], v[52:53], v[52:53]
	v_pk_mul_f32 v[62:63], v[46:47], v[46:47]
	v_pk_mul_f32 v[64:65], v[44:45], v[44:45]
	v_mul_f32_e32 v66, v37, v37
	v_mul_f32_e32 v68, v39, v39
	v_mul_f32_e32 v101, v26, v26
	v_mul_f32_e32 v107, v27, v27
	v_pk_mov_b32 v[70:71], v[34:35], v[32:33] op_sel:[1,0]
	v_mov_b32_e32 v35, v33
	v_pk_mov_b32 v[32:33], v[64:65], v[62:63] op_sel:[1,0]
	v_mov_b32_e32 v65, v63
	v_pk_fma_f32 v[62:63], v[36:37], v[36:37], v[66:67] op_sel_hi:[1,1,0]
	v_pk_fma_f32 v[66:67], v[38:39], v[38:39], v[68:69] op_sel_hi:[1,1,0]
	v_pk_mul_f32 v[68:69], v[50:51], v[50:51]
	v_pk_mul_f32 v[72:73], v[48:49], v[48:49]
	v_pk_mul_f32 v[74:75], v[42:43], v[42:43]
	v_pk_mul_f32 v[88:89], v[40:41], v[40:41]
	v_pk_add_f32 v[34:35], v[70:71], v[34:35]
	v_pk_add_f32 v[32:33], v[32:33], v[64:65]
	v_mov_b32_e32 v63, v101
	v_mov_b32_e32 v67, v107
	v_pk_mov_b32 v[64:65], v[72:73], v[68:69] op_sel:[1,0]
	v_mov_b32_e32 v73, v69
	v_pk_mov_b32 v[68:69], v[88:89], v[74:75] op_sel:[1,0]
	v_mov_b32_e32 v89, v75
	v_mul_f32_e32 v85, v24, v24
	v_mul_f32_e32 v87, v25, v25
	v_mul_f32_e32 v109, v20, v20
	v_mul_f32_e32 v106, v29, v29
	v_mul_f32_e32 v108, v31, v31
	v_pk_add_f32 v[34:35], v[34:35], v[34:35] op_sel:[0,1] op_sel_hi:[1,0]
	v_pk_add_f32 v[32:33], v[32:33], v[32:33] op_sel:[0,1] op_sel_hi:[1,0]
	v_pk_add_f32 v[62:63], v[62:63], v[66:67]
	v_pk_add_f32 v[64:65], v[64:65], v[72:73]
	v_pk_add_f32 v[66:67], v[68:69], v[88:89]
	v_mul_f32_e32 v110, v21, v21
	v_mul_f32_e32 v111, v22, v22
	v_mul_f32_e32 v112, v23, v23
	v_pk_fma_f32 v[70:71], v[28:29], v[28:29], v[106:107] op_sel_hi:[1,1,0]
	v_pk_fma_f32 v[74:75], v[30:31], v[30:31], v[108:109] op_sel_hi:[1,1,0]
	v_mov_b32_e32 v35, v85
	v_mov_b32_e32 v33, v87
	v_pk_add_f32 v[64:65], v[64:65], v[64:65] op_sel:[0,1] op_sel_hi:[1,0]
	v_pk_add_f32 v[66:67], v[66:67], v[66:67] op_sel:[0,1] op_sel_hi:[1,0]
	v_mov_b32_e32 v71, v111
	v_mov_b32_e32 v75, v112
	v_pk_add_f32 v[32:33], v[34:35], v[32:33]
	v_mov_b32_e32 v65, v109
	v_mov_b32_e32 v67, v110
	v_pk_add_f32 v[68:69], v[70:71], v[74:75]
	v_pk_add_f32 v[32:33], v[32:33], v[62:63]
	v_pk_add_f32 v[34:35], v[64:65], v[66:67]
	v_add_f32_e32 v62, v32, v33
	v_pk_add_f32 v[32:33], v[34:35], v[68:69]
	ds_bpermute_b32 v34, v91, v62
	v_add_f32_e32 v35, v32, v33
	ds_bpermute_b32 v63, v91, v35
	v_lshlrev_b64 v[32:33], 11, v[82:83]
	v_ashrrev_i32_e32 v85, 31, v84
	s_waitcnt lgkmcnt(1)
	v_add_f32_e32 v62, v62, v34
	ds_bpermute_b32 v64, v92, v62
	s_waitcnt lgkmcnt(1)
	v_add_f32_e32 v63, v35, v63
	ds_bpermute_b32 v65, v92, v63
	v_ashrrev_i32_e32 v87, 31, v86
	v_lshlrev_b64 v[34:35], 12, v[86:87]
	s_waitcnt lgkmcnt(1)
	v_add_f32_e32 v64, v62, v64
	ds_bpermute_b32 v66, v93, v64
	s_waitcnt lgkmcnt(1)
	v_add_f32_e32 v65, v63, v65
	ds_bpermute_b32 v67, v93, v65
	v_lshl_add_u64 v[62:63], v[80:81], 0, v[32:33]
	v_lshlrev_b64 v[32:33], 12, v[84:85]
	s_waitcnt lgkmcnt(1)
	v_add_f32_e32 v64, v64, v66
	ds_bpermute_b32 v66, v94, v64
	s_waitcnt lgkmcnt(1)
	v_add_f32_e32 v65, v65, v67
	ds_bpermute_b32 v67, v94, v65
	v_lshl_add_u64 v[88:89], v[78:79], 0, v[32:33]
	v_lshl_add_u64 v[34:35], v[78:79], 0, v[34:35]
	s_waitcnt lgkmcnt(1)
	v_add_f32_e32 v32, v64, v66
	ds_bpermute_b32 v33, v95, v32
	s_waitcnt lgkmcnt(1)
	v_add_f32_e32 v64, v65, v67
	ds_bpermute_b32 v65, v95, v64
	global_load_dwordx4 v[72:75], v[34:35], off nt
	global_load_dwordx4 v[68:71], v[34:35], off offset:1024 nt
	v_lshlrev_b64 v[86:87], 11, v[86:87]
	s_waitcnt lgkmcnt(1)
	v_add_f32_e32 v83, v32, v33
	ds_bpermute_b32 v101, v96, v83
	s_waitcnt lgkmcnt(1)
	v_add_f32_e32 v106, v64, v65
	global_load_dwordx4 v[64:67], v[34:35], off offset:2048 nt
	s_nop 0
	global_load_dwordx4 v[32:35], v[34:35], off offset:3072 nt
	ds_bpermute_b32 v107, v96, v106
	s_waitcnt lgkmcnt(1)
	v_add_f32_e32 v83, v83, v101
	v_fmamk_f32 v83, v83, 0x3a800000, v190
	v_cmp_gt_f32_e32 vcc, s15, v83
	s_waitcnt lgkmcnt(0)
	v_add_f32_e32 v101, v106, v107
	v_mul_f32_e32 v106, 0x4b800000, v83
	v_cndmask_b32_e32 v83, v83, v106, vcc
	v_rsq_f32_e32 v83, v83
	v_fmamk_f32 v101, v101, 0x3a800000, v190
	v_mul_f32_e32 v106, 0x4b800000, v101
	v_cmp_gt_f32_e64 s[0:1], s15, v101
	s_nop 1
	v_cndmask_b32_e64 v101, v101, v106, s[0:1]
	v_mul_f32_e32 v106, 0x45800000, v83
	v_cndmask_b32_e32 v106, v83, v106, vcc
	v_pk_mul_f32 v[54:55], v[54:55], v[106:107] op_sel_hi:[1,0]
	v_pk_mul_f32 v[52:53], v[52:53], v[106:107] op_sel_hi:[1,0]
	v_pk_mul_f32 v[54:55], v[6:7], v[54:55]
	v_pk_mul_f32 v[52:53], v[4:5], v[52:53]
	v_pk_fma_f32 v[54:55], v[104:105], v[54:55], v[58:59]
	v_pk_fma_f32 v[52:53], v[102:103], v[52:53], v[56:57]
	v_pk_mul_f32 v[46:47], v[46:47], v[106:107] op_sel_hi:[1,0]
	v_cvt_pk_bf16_f32 v52, v52, v53
	v_cvt_pk_bf16_f32 v53, v54, v55
	global_store_dwordx2 v[62:63], v[52:53], off sc1
	ds_read_b128 v[52:55], v97 offset:1024
	ds_read_b128 v[56:59], v97 offset:5120
	v_pk_mul_f32 v[44:45], v[44:45], v[106:107] op_sel_hi:[1,0]
	v_pk_mul_f32 v[46:47], v[10:11], v[46:47]
	v_pk_mul_f32 v[44:45], v[8:9], v[44:45]
	v_pk_mul_f32 v[38:39], v[38:39], v[106:107] op_sel_hi:[1,0]
	s_waitcnt lgkmcnt(0)
; #define LAS __attribute__((address_space(3)))
; DI unsigned pk2(float lo, float hi) { f32x2_t v = {lo, hi}; bf16x2_t b = __builtin_convertvector(v, bf16x2_t); return __builtin_bit_cast(unsigned, b); }
; DI void phase_modulate(const float* xin, const float* norm_w, const float* modp, const float* adab,
;                        bf16* H, LAS unsigned char* lds, int tid, int G, float* MODF, const float* MODP_all, const float* adab_all) {
;     ...
; #pragma unroll
;         for (int pre = 0; pre < 2; ++pre) { const f32x4* xr = (const f32x4*)(xin + (size_t)(rb * 64 + wave + 8 * pre) * 1024) + lane;
; #pragma unroll
;             for (int j = 0; j < 4; ++j) vbuf[pre][j] = __builtin_nontemporal_load(xr + 64 * j); }
; #pragma unroll
;         for (int it = 0; it < 8; ++it) {
;             const int row = rb * 64 + wave + 8 * it;
;             if (it + 2 < 8) { const f32x4* xr = (const f32x4*)(xin + (size_t)(row + 16) * 1024) + lane;
; #pragma unroll
;                 for (int j = 0; j < 4; ++j) vbuf[(it + 2) % 3][j] = __builtin_nontemporal_load(xr + 64 * j); }
;             f32x4 v[4]; float ss = 0.f;
; #pragma unroll
;             for (int j = 0; j < 4; ++j) { v[j] = vbuf[it % 3][j]; ss += (v[j][0] * v[j][0] + v[j][1] * v[j][1]) + (v[j][2] * v[j][2] + v[j][3] * v[j][3]); }
;             const float rstd = rsqrtf(wave_sum(ss) * (1.f / 1024.f) + EPS);
; #pragma unroll
;             for (int j = 0; j < 4; ++j) { const int col = 4 * lane + 256 * j;
;                 const f32x4 shv = *(const LAS f32x4*)(sh + col), scv = *(const LAS f32x4*)(sc + col);
;                 const f32x4 hv = v[j] * rstd * nw[j] * scv + shv;
;                 u32x2 o; o.x = pk2(hv[0], hv[1]); o.y = pk2(hv[2], hv[3]);
;                 *(u32x2*)(H + (size_t)row * 1024 + col) = o; asm volatile("" ::: "memory"); }
	v_pk_fma_f32 v[46:47], v[58:59], v[46:47], v[54:55]
	v_pk_fma_f32 v[44:45], v[56:57], v[44:45], v[52:53]
	v_pk_mul_f32 v[36:37], v[36:37], v[106:107] op_sel_hi:[1,0]
	v_cvt_pk_bf16_f32 v44, v44, v45
	v_cvt_pk_bf16_f32 v45, v46, v47
	global_store_dwordx2 v[62:63], v[44:45], off offset:512 sc1
	ds_read_b128 v[44:47], v97 offset:2048
	ds_read_b128 v[52:55], v97 offset:6144
	v_pk_mul_f32 v[36:37], v[12:13], v[36:37]
	v_pk_mul_f32 v[38:39], v[14:15], v[38:39]
	v_pk_mul_f32 v[26:27], v[26:27], v[106:107] op_sel_hi:[1,0]
	v_pk_mul_f32 v[24:25], v[24:25], v[106:107] op_sel_hi:[1,0]
	s_waitcnt lgkmcnt(0)
	v_pk_fma_f32 v[38:39], v[54:55], v[38:39], v[46:47]
	v_pk_fma_f32 v[36:37], v[52:53], v[36:37], v[44:45]
	v_rsq_f32_e32 v101, v101
	v_cvt_pk_bf16_f32 v36, v36, v37
	v_cvt_pk_bf16_f32 v37, v38, v39
	global_store_dwordx2 v[62:63], v[36:37], off offset:1024 sc1
	ds_read_b128 v[36:39], v97 offset:3072
	ds_read_b128 v[44:47], v97 offset:7168
	v_pk_mul_f32 v[24:25], v[16:17], v[24:25]
	v_pk_mul_f32 v[26:27], v[18:19], v[26:27]
	v_mul_f32_e32 v52, 0x45800000, v101
	v_lshlrev_b64 v[102:103], 11, v[60:61]
	s_waitcnt lgkmcnt(0)
	v_pk_fma_f32 v[26:27], v[26:27], v[46:47], v[38:39]
	v_pk_fma_f32 v[24:25], v[24:25], v[44:45], v[36:37]
	s_waitcnt vmcnt(3)
	v_mul_f32_e32 v83, v34, v34
	v_cvt_pk_bf16_f32 v24, v24, v25
	v_cvt_pk_bf16_f32 v25, v26, v27
	global_store_dwordx2 v[62:63], v[24:25], off offset:1536 sc1
	global_load_dwordx4 v[56:59], v[88:89], off nt
	global_load_dwordx4 v[44:47], v[88:89], off offset:1024 nt
	global_load_dwordx4 v[36:39], v[88:89], off offset:2048 nt
	global_load_dwordx4 v[24:27], v[88:89], off offset:3072 nt
	v_cndmask_b32_e64 v88, v101, v52, s[0:1]
	ds_read_b128 v[52:55], v97
	ds_read_b128 v[60:63], v97 offset:4096
	v_pk_mul_f32 v[50:51], v[50:51], v[88:89] op_sel_hi:[1,0]
	v_pk_mul_f32 v[48:49], v[48:49], v[88:89] op_sel_hi:[1,0]
	v_pk_mul_f32 v[50:51], v[6:7], v[50:51]
	v_pk_mul_f32 v[48:49], v[4:5], v[48:49]
	s_waitcnt lgkmcnt(0)
	v_pk_fma_f32 v[50:51], v[62:63], v[50:51], v[54:55]
	v_pk_fma_f32 v[48:49], v[60:61], v[48:49], v[52:53]
	v_lshl_add_u64 v[60:61], v[80:81], 0, v[102:103]
	v_cvt_pk_bf16_f32 v48, v48, v49
	v_cvt_pk_bf16_f32 v49, v50, v51
	global_store_dwordx2 v[60:61], v[48:49], off sc1
	ds_read_b128 v[48:51], v97 offset:1024
	ds_read_b128 v[52:55], v97 offset:5120
	v_pk_mul_f32 v[42:43], v[42:43], v[88:89] op_sel_hi:[1,0]
	v_pk_mul_f32 v[40:41], v[40:41], v[88:89] op_sel_hi:[1,0]
	v_pk_mul_f32 v[42:43], v[10:11], v[42:43]
	v_pk_mul_f32 v[40:41], v[8:9], v[40:41]
	s_waitcnt lgkmcnt(0)
	v_pk_fma_f32 v[42:43], v[54:55], v[42:43], v[50:51]
	v_pk_fma_f32 v[40:41], v[52:53], v[40:41], v[48:49]
	v_pk_mul_f32 v[52:53], v[74:75], v[74:75]
	v_pk_mul_f32 v[54:55], v[72:73], v[72:73]
	v_pk_mul_f32 v[30:31], v[30:31], v[88:89] op_sel_hi:[1,0]
	v_pk_mov_b32 v[62:63], v[54:55], v[52:53] op_sel:[1,0]
	v_mov_b32_e32 v55, v53
	v_pk_add_f32 v[52:53], v[62:63], v[54:55]
	v_pk_mul_f32 v[54:55], v[70:71], v[70:71]
	v_pk_mul_f32 v[62:63], v[68:69], v[68:69]
	v_pk_add_f32 v[52:53], v[52:53], v[52:53] op_sel:[0,1] op_sel_hi:[1,0]
	v_pk_mov_b32 v[102:103], v[62:63], v[54:55] op_sel:[1,0]
	v_mov_b32_e32 v63, v55
	v_pk_add_f32 v[54:55], v[102:103], v[62:63]
	v_mul_f32_e32 v62, v32, v32
	v_mul_f32_e32 v63, v33, v33
	v_pk_add_f32 v[54:55], v[54:55], v[54:55] op_sel:[0,1] op_sel_hi:[1,0]
	v_mov_b32_e32 v53, v62
	v_mov_b32_e32 v55, v63
	v_pk_add_f32 v[52:53], v[52:53], v[54:55]
	v_mul_f32_e32 v54, v65, v65
	v_mul_f32_e32 v62, v67, v67
	v_pk_mul_f32 v[28:29], v[28:29], v[88:89] op_sel_hi:[1,0]
	v_mul_f32_e32 v89, v35, v35
	v_pk_fma_f32 v[54:55], v[64:65], v[64:65], v[54:55] op_sel_hi:[1,1,0]
	v_pk_fma_f32 v[62:63], v[66:67], v[66:67], v[62:63] op_sel_hi:[1,1,0]
	v_mov_b32_e32 v55, v83
	v_mov_b32_e32 v63, v89
	v_cvt_pk_bf16_f32 v40, v40, v41
	v_cvt_pk_bf16_f32 v41, v42, v43
	v_pk_add_f32 v[54:55], v[54:55], v[62:63]
	global_store_dwordx2 v[60:61], v[40:41], off offset:512 sc1
	v_pk_add_f32 v[52:53], v[52:53], v[54:55]
	ds_read_b128 v[40:43], v97 offset:2048
	ds_read_b128 v[48:51], v97 offset:6144
	v_add_f32_e32 v52, v52, v53
	ds_bpermute_b32 v53, v91, v52
	v_pk_mul_f32 v[28:29], v[12:13], v[28:29]
	v_pk_mul_f32 v[30:31], v[14:15], v[30:31]
	s_waitcnt lgkmcnt(1)
	v_pk_fma_f32 v[28:29], v[48:49], v[28:29], v[40:41]
	v_pk_fma_f32 v[30:31], v[50:51], v[30:31], v[42:43]
	s_waitcnt lgkmcnt(0)
	v_add_f32_e32 v40, v52, v53
	ds_bpermute_b32 v41, v92, v40
	v_cvt_pk_bf16_f32 v28, v28, v29
	v_cvt_pk_bf16_f32 v29, v30, v31
	global_store_dwordx2 v[60:61], v[28:29], off offset:1024 sc1
	s_waitcnt lgkmcnt(0)
	v_add_f32_e32 v48, v40, v41
	ds_bpermute_b32 v49, v93, v48
	ds_read_b128 v[28:31], v97 offset:3072
	ds_read_b128 v[40:43], v97 offset:7168
	v_pk_mul_f32 v[20:21], v[20:21], v[88:89] op_sel_hi:[1,0]
	v_pk_mul_f32 v[22:23], v[22:23], v[88:89] op_sel_hi:[1,0]
	v_pk_mul_f32 v[20:21], v[16:17], v[20:21]
	s_waitcnt lgkmcnt(2)
	v_add_f32_e32 v48, v48, v49
	ds_bpermute_b32 v49, v94, v48
	s_waitcnt lgkmcnt(1)
	v_pk_fma_f32 v[20:21], v[20:21], v[40:41], v[28:29]
	v_pk_mul_f32 v[22:23], v[18:19], v[22:23]
	v_cvt_pk_bf16_f32 v20, v20, v21
	v_pk_fma_f32 v[22:23], v[22:23], v[42:43], v[30:31]
	s_waitcnt lgkmcnt(0)
	v_add_f32_e32 v28, v48, v49
	ds_bpermute_b32 v29, v95, v28
	v_cvt_pk_bf16_f32 v21, v22, v23
	v_add_u32_e32 v88, 32, v82
	v_ashrrev_i32_e32 v89, 31, v88
	global_store_dwordx2 v[60:61], v[20:21], off offset:1536 sc1
	s_waitcnt lgkmcnt(0)
	v_add_f32_e32 v22, v28, v29
	ds_bpermute_b32 v23, v96, v22
	v_lshlrev_b64 v[20:21], 12, v[88:89]
	v_lshl_add_u64 v[20:21], v[78:79], 0, v[20:21]
	global_load_dwordx4 v[60:63], v[20:21], off nt
	global_load_dwordx4 v[48:51], v[20:21], off offset:1024 nt
	global_load_dwordx4 v[40:43], v[20:21], off offset:2048 nt
	global_load_dwordx4 v[28:31], v[20:21], off offset:3072 nt
	s_waitcnt lgkmcnt(0)
; #define LAS __attribute__((address_space(3)))
; DI unsigned pk2(float lo, float hi) { f32x2_t v = {lo, hi}; bf16x2_t b = __builtin_convertvector(v, bf16x2_t); return __builtin_bit_cast(unsigned, b); }
; DI void phase_modulate(const float* xin, const float* norm_w, const float* modp, const float* adab,
;                        bf16* H, LAS unsigned char* lds, int tid, int G, float* MODF, const float* MODP_all, const float* adab_all) {
;     ...
; #pragma unroll
;         for (int pre = 0; pre < 2; ++pre) { const f32x4* xr = (const f32x4*)(xin + (size_t)(rb * 64 + wave + 8 * pre) * 1024) + lane;
; #pragma unroll
;             for (int j = 0; j < 4; ++j) vbuf[pre][j] = __builtin_nontemporal_load(xr + 64 * j); }
; #pragma unroll
;         for (int it = 0; it < 8; ++it) {
;             const int row = rb * 64 + wave + 8 * it;
;             if (it + 2 < 8) { const f32x4* xr = (const f32x4*)(xin + (size_t)(row + 16) * 1024) + lane;
; #pragma unroll
;                 for (int j = 0; j < 4; ++j) vbuf[(it + 2) % 3][j] = __builtin_nontemporal_load(xr + 64 * j); }
;             f32x4 v[4]; float ss = 0.f;
; #pragma unroll
;             for (int j = 0; j < 4; ++j) { v[j] = vbuf[it % 3][j]; ss += (v[j][0] * v[j][0] + v[j][1] * v[j][1]) + (v[j][2] * v[j][2] + v[j][3] * v[j][3]); }
;             const float rstd = rsqrtf(wave_sum(ss) * (1.f / 1024.f) + EPS);
; #pragma unroll
;             for (int j = 0; j < 4; ++j) { const int col = 4 * lane + 256 * j;
;                 const f32x4 shv = *(const LAS f32x4*)(sh + col), scv = *(const LAS f32x4*)(sc + col);
;                 const f32x4 hv = v[j] * rstd * nw[j] * scv + shv;
;                 u32x2 o; o.x = pk2(hv[0], hv[1]); o.y = pk2(hv[2], hv[3]);
;                 *(u32x2*)(H + (size_t)row * 1024 + col) = o; asm volatile("" ::: "memory"); }
	v_add_f32_e32 v22, v22, v23
	v_fmamk_f32 v22, v22, 0x3a800000, v190
	v_mul_f32_e32 v23, 0x4b800000, v22
	v_cmp_gt_f32_e32 vcc, s15, v22
	s_waitcnt vmcnt(8)
	v_mul_f32_e32 v83, v26, v26
	v_lshlrev_b64 v[88:89], 11, v[88:89]
	v_cndmask_b32_e32 v22, v22, v23, vcc
	v_rsq_f32_e32 v22, v22
	s_waitcnt vmcnt(0)
	v_mul_f32_e32 v101, v31, v31
	v_mul_f32_e32 v20, 0x45800000, v22
	v_cndmask_b32_e32 v102, v22, v20, vcc
	ds_read_b128 v[20:23], v97
	ds_read_b128 v[52:55], v97 offset:4096
	v_pk_mul_f32 v[74:75], v[74:75], v[102:103] op_sel_hi:[1,0]
	v_pk_mul_f32 v[72:73], v[72:73], v[102:103] op_sel_hi:[1,0]
	v_pk_mul_f32 v[74:75], v[6:7], v[74:75]
	v_pk_mul_f32 v[72:73], v[4:5], v[72:73]
	s_waitcnt lgkmcnt(0)
	v_pk_fma_f32 v[22:23], v[54:55], v[74:75], v[22:23]
	v_pk_fma_f32 v[20:21], v[52:53], v[72:73], v[20:21]
	v_lshl_add_u64 v[72:73], v[80:81], 0, v[86:87]
	v_cvt_pk_bf16_f32 v20, v20, v21
	v_cvt_pk_bf16_f32 v21, v22, v23
	global_store_dwordx2 v[72:73], v[20:21], off sc1
	ds_read_b128 v[20:23], v97 offset:1024
	ds_read_b128 v[52:55], v97 offset:5120
	v_pk_mul_f32 v[70:71], v[70:71], v[102:103] op_sel_hi:[1,0]
	v_pk_mul_f32 v[68:69], v[68:69], v[102:103] op_sel_hi:[1,0]
	v_pk_mul_f32 v[70:71], v[10:11], v[70:71]
	v_pk_mul_f32 v[68:69], v[8:9], v[68:69]
	s_waitcnt lgkmcnt(0)
	v_pk_fma_f32 v[22:23], v[54:55], v[70:71], v[22:23]
	v_pk_fma_f32 v[20:21], v[52:53], v[68:69], v[20:21]
	v_pk_mul_f32 v[68:69], v[58:59], v[58:59]
	v_pk_mul_f32 v[70:71], v[56:57], v[56:57]
	v_cvt_pk_bf16_f32 v20, v20, v21
	v_pk_mov_b32 v[74:75], v[70:71], v[68:69] op_sel:[1,0]
	v_mov_b32_e32 v71, v69
	v_pk_add_f32 v[68:69], v[74:75], v[70:71]
	v_pk_mul_f32 v[70:71], v[46:47], v[46:47]
	v_pk_mul_f32 v[74:75], v[44:45], v[44:45]
	v_pk_add_f32 v[68:69], v[68:69], v[68:69] op_sel:[0,1] op_sel_hi:[1,0]
	v_pk_mov_b32 v[86:87], v[74:75], v[70:71] op_sel:[1,0]
	v_mov_b32_e32 v75, v71
	v_pk_add_f32 v[70:71], v[86:87], v[74:75]
	v_mul_f32_e32 v74, v24, v24
	v_mul_f32_e32 v75, v25, v25
	v_pk_add_f32 v[70:71], v[70:71], v[70:71] op_sel:[0,1] op_sel_hi:[1,0]
	v_mov_b32_e32 v69, v74
	v_mov_b32_e32 v71, v75
	v_pk_add_f32 v[68:69], v[68:69], v[70:71]
	v_mul_f32_e32 v70, v37, v37
	v_mul_f32_e32 v74, v39, v39
	v_mul_f32_e32 v86, v27, v27
	v_pk_fma_f32 v[70:71], v[36:37], v[36:37], v[70:71] op_sel_hi:[1,1,0]
	v_pk_fma_f32 v[74:75], v[38:39], v[38:39], v[74:75] op_sel_hi:[1,1,0]
	v_mov_b32_e32 v71, v83
	v_mov_b32_e32 v75, v86
	v_cvt_pk_bf16_f32 v21, v22, v23
	v_pk_add_f32 v[70:71], v[70:71], v[74:75]
	global_store_dwordx2 v[72:73], v[20:21], off offset:512 sc1
	v_pk_add_f32 v[68:69], v[68:69], v[70:71]
	ds_read_b128 v[20:23], v97 offset:2048
	ds_read_b128 v[52:55], v97 offset:6144
	v_add_f32_e32 v68, v68, v69
	ds_bpermute_b32 v69, v91, v68
	v_pk_mul_f32 v[64:65], v[64:65], v[102:103] op_sel_hi:[1,0]
	v_pk_mul_f32 v[66:67], v[66:67], v[102:103] op_sel_hi:[1,0]
	v_pk_mul_f32 v[64:65], v[12:13], v[64:65]
	v_pk_mul_f32 v[66:67], v[14:15], v[66:67]
	s_waitcnt lgkmcnt(1)
	v_pk_fma_f32 v[20:21], v[52:53], v[64:65], v[20:21]
	s_waitcnt lgkmcnt(0)
	v_add_f32_e32 v52, v68, v69
	ds_bpermute_b32 v53, v92, v52
	v_pk_fma_f32 v[22:23], v[54:55], v[66:67], v[22:23]
	v_cvt_pk_bf16_f32 v20, v20, v21
	v_cvt_pk_bf16_f32 v21, v22, v23
	global_store_dwordx2 v[72:73], v[20:21], off offset:1024 sc1
	s_waitcnt lgkmcnt(0)
	v_add_f32_e32 v64, v52, v53
	ds_bpermute_b32 v65, v93, v64
	ds_read_b128 v[20:23], v97 offset:3072
	ds_read_b128 v[52:55], v97 offset:7168
	v_pk_mul_f32 v[32:33], v[32:33], v[102:103] op_sel_hi:[1,0]
	v_pk_mul_f32 v[34:35], v[34:35], v[102:103] op_sel_hi:[1,0]
	s_waitcnt lgkmcnt(2)
	v_add_f32_e32 v64, v64, v65
	ds_bpermute_b32 v65, v94, v64
	v_pk_mul_f32 v[32:33], v[16:17], v[32:33]
	v_pk_mul_f32 v[34:35], v[18:19], v[34:35]
	s_waitcnt lgkmcnt(1)
	v_pk_fma_f32 v[20:21], v[32:33], v[52:53], v[20:21]
	v_pk_fma_f32 v[22:23], v[34:35], v[54:55], v[22:23]
	s_waitcnt lgkmcnt(0)
	v_add_f32_e32 v32, v64, v65
	ds_bpermute_b32 v33, v95, v32
	v_cvt_pk_bf16_f32 v20, v20, v21
	v_cvt_pk_bf16_f32 v21, v22, v23
	v_add_u32_e32 v68, 40, v82
	v_ashrrev_i32_e32 v69, 31, v68
	s_waitcnt lgkmcnt(0)
	v_add_f32_e32 v22, v32, v33
	ds_bpermute_b32 v23, v96, v22
	global_store_dwordx2 v[72:73], v[20:21], off offset:1536 sc1
	v_lshlrev_b64 v[20:21], 12, v[68:69]
	v_lshl_add_u64 v[20:21], v[78:79], 0, v[20:21]
	s_waitcnt lgkmcnt(0)
	v_add_f32_e32 v22, v22, v23
	v_fmamk_f32 v22, v22, 0x3a800000, v190
	v_mul_f32_e32 v23, 0x4b800000, v22
	v_cmp_gt_f32_e32 vcc, s15, v22
	v_lshlrev_b64 v[102:103], 11, v[84:85]
	v_mul_f32_e32 v83, v29, v29
	v_cndmask_b32_e32 v22, v22, v23, vcc
	v_rsq_f32_e32 v70, v22
	global_load_dwordx4 v[64:67], v[20:21], off nt
	global_load_dwordx4 v[52:55], v[20:21], off offset:1024 nt
	global_load_dwordx4 v[32:35], v[20:21], off offset:2048 nt
	s_nop 0
	global_load_dwordx4 v[20:23], v[20:21], off offset:3072 nt
	v_lshlrev_b64 v[68:69], 11, v[68:69]
	v_lshl_add_u64 v[68:69], v[80:81], 0, v[68:69]
	v_mul_f32_e32 v71, 0x45800000, v70
	v_cndmask_b32_e32 v74, v70, v71, vcc
	ds_read_b128 v[70:73], v97
	ds_read_b128 v[84:87], v97 offset:4096
	v_pk_mul_f32 v[58:59], v[58:59], v[74:75] op_sel_hi:[1,0]
	v_pk_mul_f32 v[56:57], v[56:57], v[74:75] op_sel_hi:[1,0]
	v_pk_mul_f32 v[58:59], v[6:7], v[58:59]
	v_pk_mul_f32 v[56:57], v[4:5], v[56:57]
	s_waitcnt lgkmcnt(0)
	v_pk_fma_f32 v[58:59], v[86:87], v[58:59], v[72:73]
	v_pk_fma_f32 v[56:57], v[84:85], v[56:57], v[70:71]
	v_lshl_add_u64 v[84:85], v[80:81], 0, v[102:103]
	v_cvt_pk_bf16_f32 v56, v56, v57
	v_cvt_pk_bf16_f32 v57, v58, v59
	global_store_dwordx2 v[84:85], v[56:57], off sc1
	ds_read_b128 v[56:59], v97 offset:1024
	ds_read_b128 v[70:73], v97 offset:5120
	v_pk_mul_f32 v[46:47], v[46:47], v[74:75] op_sel_hi:[1,0]
	v_pk_mul_f32 v[44:45], v[44:45], v[74:75] op_sel_hi:[1,0]
	v_pk_mul_f32 v[46:47], v[10:11], v[46:47]
	v_pk_mul_f32 v[44:45], v[8:9], v[44:45]
	s_waitcnt lgkmcnt(0)
; #define LAS __attribute__((address_space(3)))
; DI unsigned pk2(float lo, float hi) { f32x2_t v = {lo, hi}; bf16x2_t b = __builtin_convertvector(v, bf16x2_t); return __builtin_bit_cast(unsigned, b); }
; DI void phase_modulate(const float* xin, const float* norm_w, const float* modp, const float* adab,
;                        bf16* H, LAS unsigned char* lds, int tid, int G, float* MODF, const float* MODP_all, const float* adab_all) {
;     ...
; #pragma unroll
;         for (int pre = 0; pre < 2; ++pre) { const f32x4* xr = (const f32x4*)(xin + (size_t)(rb * 64 + wave + 8 * pre) * 1024) + lane;
; #pragma unroll
;             for (int j = 0; j < 4; ++j) vbuf[pre][j] = __builtin_nontemporal_load(xr + 64 * j); }
; #pragma unroll
;         for (int it = 0; it < 8; ++it) {
;             const int row = rb * 64 + wave + 8 * it;
;             if (it + 2 < 8) { const f32x4* xr = (const f32x4*)(xin + (size_t)(row + 16) * 1024) + lane;
; #pragma unroll
;                 for (int j = 0; j < 4; ++j) vbuf[(it + 2) % 3][j] = __builtin_nontemporal_load(xr + 64 * j); }
;             f32x4 v[4]; float ss = 0.f;
; #pragma unroll
;             for (int j = 0; j < 4; ++j) { v[j] = vbuf[it % 3][j]; ss += (v[j][0] * v[j][0] + v[j][1] * v[j][1]) + (v[j][2] * v[j][2] + v[j][3] * v[j][3]); }
;             const float rstd = rsqrtf(wave_sum(ss) * (1.f / 1024.f) + EPS);
; #pragma unroll
;             for (int j = 0; j < 4; ++j) { const int col = 4 * lane + 256 * j;
;                 const f32x4 shv = *(const LAS f32x4*)(sh + col), scv = *(const LAS f32x4*)(sc + col);
;                 const f32x4 hv = v[j] * rstd * nw[j] * scv + shv;
;                 u32x2 o; o.x = pk2(hv[0], hv[1]); o.y = pk2(hv[2], hv[3]);
;                 *(u32x2*)(H + (size_t)row * 1024 + col) = o; asm volatile("" ::: "memory"); }
	v_pk_fma_f32 v[46:47], v[72:73], v[46:47], v[58:59]
	v_pk_fma_f32 v[44:45], v[70:71], v[44:45], v[56:57]
	v_pk_mul_f32 v[70:71], v[62:63], v[62:63]
	v_pk_mul_f32 v[72:73], v[60:61], v[60:61]
	v_pk_mul_f32 v[38:39], v[38:39], v[74:75] op_sel_hi:[1,0]
	v_pk_mov_b32 v[86:87], v[72:73], v[70:71] op_sel:[1,0]
	v_mov_b32_e32 v73, v71
	v_pk_add_f32 v[70:71], v[86:87], v[72:73]
	v_pk_mul_f32 v[72:73], v[50:51], v[50:51]
	v_pk_mul_f32 v[86:87], v[48:49], v[48:49]
	v_pk_mul_f32 v[36:37], v[36:37], v[74:75] op_sel_hi:[1,0]
	v_pk_mov_b32 v[102:103], v[86:87], v[72:73] op_sel:[1,0]
	v_mov_b32_e32 v87, v73
	v_pk_add_f32 v[72:73], v[102:103], v[86:87]
	v_mul_f32_e32 v75, v28, v28
	v_pk_add_f32 v[70:71], v[70:71], v[70:71] op_sel:[0,1] op_sel_hi:[1,0]
	v_pk_add_f32 v[72:73], v[72:73], v[72:73] op_sel:[0,1] op_sel_hi:[1,0]
	v_mov_b32_e32 v71, v75
	v_mov_b32_e32 v73, v83
	v_pk_add_f32 v[70:71], v[70:71], v[72:73]
	v_mul_f32_e32 v72, v41, v41
	v_mul_f32_e32 v86, v30, v30
	v_pk_fma_f32 v[72:73], v[40:41], v[40:41], v[72:73] op_sel_hi:[1,1,0]
	v_cvt_pk_bf16_f32 v44, v44, v45
	v_mov_b32_e32 v73, v86
	v_mul_f32_e32 v86, v43, v43
	v_pk_fma_f32 v[86:87], v[42:43], v[42:43], v[86:87] op_sel_hi:[1,1,0]
	v_cvt_pk_bf16_f32 v45, v46, v47
	v_mov_b32_e32 v87, v101
	v_pk_add_f32 v[72:73], v[72:73], v[86:87]
	global_store_dwordx2 v[84:85], v[44:45], off offset:512 sc1
	v_pk_add_f32 v[70:71], v[70:71], v[72:73]
	ds_read_b128 v[44:47], v97 offset:2048
	ds_read_b128 v[56:59], v97 offset:6144
	v_add_f32_e32 v70, v70, v71
	ds_bpermute_b32 v71, v91, v70
	v_pk_mul_f32 v[36:37], v[12:13], v[36:37]
	v_pk_mul_f32 v[38:39], v[14:15], v[38:39]
	s_waitcnt lgkmcnt(1)
	v_pk_fma_f32 v[36:37], v[56:57], v[36:37], v[44:45]
	v_pk_fma_f32 v[38:39], v[58:59], v[38:39], v[46:47]
	s_waitcnt lgkmcnt(0)
	v_add_f32_e32 v44, v70, v71
	ds_bpermute_b32 v45, v92, v44
	v_cvt_pk_bf16_f32 v36, v36, v37
	v_cvt_pk_bf16_f32 v37, v38, v39
	global_store_dwordx2 v[84:85], v[36:37], off offset:1024 sc1
	s_waitcnt lgkmcnt(0)
	v_add_f32_e32 v56, v44, v45
	ds_bpermute_b32 v57, v93, v56
	ds_read_b128 v[36:39], v97 offset:3072
	ds_read_b128 v[44:47], v97 offset:7168
	v_pk_mul_f32 v[24:25], v[24:25], v[74:75] op_sel_hi:[1,0]
	v_pk_mul_f32 v[26:27], v[26:27], v[74:75] op_sel_hi:[1,0]
	v_pk_mul_f32 v[24:25], v[16:17], v[24:25]
	s_waitcnt lgkmcnt(2)
	v_add_f32_e32 v56, v56, v57
	ds_bpermute_b32 v57, v94, v56
	s_waitcnt lgkmcnt(1)
	v_pk_fma_f32 v[24:25], v[24:25], v[44:45], v[36:37]
	v_pk_mul_f32 v[26:27], v[18:19], v[26:27]
	v_cvt_pk_bf16_f32 v24, v24, v25
	v_pk_fma_f32 v[26:27], v[26:27], v[46:47], v[38:39]
	s_waitcnt lgkmcnt(0)
	v_add_f32_e32 v36, v56, v57
	ds_bpermute_b32 v37, v95, v36
	v_cvt_pk_bf16_f32 v25, v26, v27
	v_add_u32_e32 v70, 48, v82
	v_ashrrev_i32_e32 v71, 31, v70
	global_store_dwordx2 v[84:85], v[24:25], off offset:1536 sc1
	s_waitcnt lgkmcnt(0)
	v_add_f32_e32 v26, v36, v37
	ds_bpermute_b32 v27, v96, v26
	v_lshlrev_b64 v[24:25], 12, v[70:71]
	v_lshl_add_u64 v[24:25], v[78:79], 0, v[24:25]
	s_waitcnt vmcnt(4)
	v_mul_f32_e32 v83, v20, v20
	s_waitcnt lgkmcnt(0)
	v_add_f32_e32 v26, v26, v27
	v_fmamk_f32 v26, v26, 0x3a800000, v190
	v_mul_f32_e32 v27, 0x4b800000, v26
	v_cmp_gt_f32_e32 vcc, s15, v26
	s_nop 1
	v_cndmask_b32_e32 v26, v26, v27, vcc
	v_rsq_f32_e32 v72, v26
	global_load_dwordx4 v[56:59], v[24:25], off nt
	global_load_dwordx4 v[44:47], v[24:25], off offset:1024 nt
	global_load_dwordx4 v[36:39], v[24:25], off offset:2048 nt
	s_nop 0
	global_load_dwordx4 v[24:27], v[24:25], off offset:3072 nt
	v_mul_f32_e32 v73, 0x45800000, v72
	v_cndmask_b32_e32 v102, v72, v73, vcc
	ds_read_b128 v[72:75], v97
	ds_read_b128 v[84:87], v97 offset:4096
	v_pk_mul_f32 v[62:63], v[62:63], v[102:103] op_sel_hi:[1,0]
	v_pk_mul_f32 v[60:61], v[60:61], v[102:103] op_sel_hi:[1,0]
	v_pk_mul_f32 v[62:63], v[6:7], v[62:63]
	v_pk_mul_f32 v[60:61], v[4:5], v[60:61]
	s_waitcnt lgkmcnt(0)
	v_pk_fma_f32 v[62:63], v[86:87], v[62:63], v[74:75]
	v_pk_fma_f32 v[60:61], v[84:85], v[60:61], v[72:73]
	v_lshl_add_u64 v[84:85], v[80:81], 0, v[88:89]
	v_cvt_pk_bf16_f32 v60, v60, v61
	v_cvt_pk_bf16_f32 v61, v62, v63
	global_store_dwordx2 v[84:85], v[60:61], off sc1
	ds_read_b128 v[60:63], v97 offset:1024
	ds_read_b128 v[72:75], v97 offset:5120
	v_pk_mul_f32 v[50:51], v[50:51], v[102:103] op_sel_hi:[1,0]
	v_pk_mul_f32 v[48:49], v[48:49], v[102:103] op_sel_hi:[1,0]
	v_pk_mul_f32 v[50:51], v[10:11], v[50:51]
	v_pk_mul_f32 v[48:49], v[8:9], v[48:49]
	s_waitcnt lgkmcnt(0)
	v_pk_fma_f32 v[50:51], v[74:75], v[50:51], v[62:63]
	v_pk_fma_f32 v[48:49], v[72:73], v[48:49], v[60:61]
	v_pk_mul_f32 v[72:73], v[66:67], v[66:67]
	v_pk_mul_f32 v[74:75], v[64:65], v[64:65]
	v_cvt_pk_bf16_f32 v48, v48, v49
	v_pk_mov_b32 v[86:87], v[74:75], v[72:73] op_sel:[1,0]
	v_mov_b32_e32 v75, v73
	v_pk_add_f32 v[72:73], v[86:87], v[74:75]
	v_pk_mul_f32 v[74:75], v[54:55], v[54:55]
	v_pk_mul_f32 v[86:87], v[52:53], v[52:53]
	v_pk_add_f32 v[72:73], v[72:73], v[72:73] op_sel:[0,1] op_sel_hi:[1,0]
	v_pk_mov_b32 v[88:89], v[86:87], v[74:75] op_sel:[1,0]
	v_mov_b32_e32 v87, v75
	v_pk_add_f32 v[74:75], v[88:89], v[86:87]
	v_mul_f32_e32 v86, v21, v21
	v_pk_add_f32 v[74:75], v[74:75], v[74:75] op_sel:[0,1] op_sel_hi:[1,0]
	v_mov_b32_e32 v73, v83
	v_mov_b32_e32 v75, v86
	v_pk_add_f32 v[72:73], v[72:73], v[74:75]
	v_mul_f32_e32 v74, v33, v33
	v_mul_f32_e32 v87, v22, v22
	v_pk_fma_f32 v[74:75], v[32:33], v[32:33], v[74:75] op_sel_hi:[1,1,0]
	v_mul_f32_e32 v86, v35, v35
	v_mul_f32_e32 v88, v23, v23
	v_mov_b32_e32 v75, v87
	v_pk_fma_f32 v[86:87], v[34:35], v[34:35], v[86:87] op_sel_hi:[1,1,0]
	v_cvt_pk_bf16_f32 v49, v50, v51
	v_mov_b32_e32 v87, v88
	v_pk_add_f32 v[74:75], v[74:75], v[86:87]
	global_store_dwordx2 v[84:85], v[48:49], off offset:512 sc1
	v_pk_add_f32 v[72:73], v[72:73], v[74:75]
	ds_read_b128 v[48:51], v97 offset:2048
	ds_read_b128 v[60:63], v97 offset:6144
	v_add_f32_e32 v72, v72, v73
	ds_bpermute_b32 v73, v91, v72
	v_pk_mul_f32 v[40:41], v[40:41], v[102:103] op_sel_hi:[1,0]
	v_pk_mul_f32 v[42:43], v[42:43], v[102:103] op_sel_hi:[1,0]
	v_pk_mul_f32 v[40:41], v[12:13], v[40:41]
	v_pk_mul_f32 v[42:43], v[14:15], v[42:43]
	s_waitcnt lgkmcnt(1)
; #define LAS __attribute__((address_space(3)))
; DI unsigned pk2(float lo, float hi) { f32x2_t v = {lo, hi}; bf16x2_t b = __builtin_convertvector(v, bf16x2_t); return __builtin_bit_cast(unsigned, b); }
; DI void phase_modulate(const float* xin, const float* norm_w, const float* modp, const float* adab,
;                        bf16* H, LAS unsigned char* lds, int tid, int G, float* MODF, const float* MODP_all, const float* adab_all) {
;     ...
; #pragma unroll
;         for (int pre = 0; pre < 2; ++pre) { const f32x4* xr = (const f32x4*)(xin + (size_t)(rb * 64 + wave + 8 * pre) * 1024) + lane;
; #pragma unroll
;             for (int j = 0; j < 4; ++j) vbuf[pre][j] = __builtin_nontemporal_load(xr + 64 * j); }
; #pragma unroll
;         for (int it = 0; it < 8; ++it) {
;             const int row = rb * 64 + wave + 8 * it;
;             if (it + 2 < 8) { const f32x4* xr = (const f32x4*)(xin + (size_t)(row + 16) * 1024) + lane;
; #pragma unroll
;                 for (int j = 0; j < 4; ++j) vbuf[(it + 2) % 3][j] = __builtin_nontemporal_load(xr + 64 * j); }
;             f32x4 v[4]; float ss = 0.f;
; #pragma unroll
;             for (int j = 0; j < 4; ++j) { v[j] = vbuf[it % 3][j]; ss += (v[j][0] * v[j][0] + v[j][1] * v[j][1]) + (v[j][2] * v[j][2] + v[j][3] * v[j][3]); }
;             const float rstd = rsqrtf(wave_sum(ss) * (1.f / 1024.f) + EPS);
; #pragma unroll
;             for (int j = 0; j < 4; ++j) { const int col = 4 * lane + 256 * j;
;                 const f32x4 shv = *(const LAS f32x4*)(sh + col), scv = *(const LAS f32x4*)(sc + col);
;                 const f32x4 hv = v[j] * rstd * nw[j] * scv + shv;
;                 u32x2 o; o.x = pk2(hv[0], hv[1]); o.y = pk2(hv[2], hv[3]);
;                 *(u32x2*)(H + (size_t)row * 1024 + col) = o; asm volatile("" ::: "memory"); }
	v_pk_fma_f32 v[40:41], v[60:61], v[40:41], v[48:49]
	s_waitcnt lgkmcnt(0)
	v_add_f32_e32 v48, v72, v73
	ds_bpermute_b32 v49, v92, v48
	v_pk_fma_f32 v[42:43], v[62:63], v[42:43], v[50:51]
	v_cvt_pk_bf16_f32 v40, v40, v41
	v_cvt_pk_bf16_f32 v41, v42, v43
	global_store_dwordx2 v[84:85], v[40:41], off offset:1024 sc1
	s_waitcnt lgkmcnt(0)
	v_add_f32_e32 v60, v48, v49
	ds_bpermute_b32 v61, v93, v60
	ds_read_b128 v[40:43], v97 offset:3072
	ds_read_b128 v[48:51], v97 offset:7168
	v_pk_mul_f32 v[28:29], v[28:29], v[102:103] op_sel_hi:[1,0]
	v_pk_mul_f32 v[30:31], v[30:31], v[102:103] op_sel_hi:[1,0]
	s_waitcnt lgkmcnt(2)
	v_add_f32_e32 v60, v60, v61
	ds_bpermute_b32 v61, v94, v60
	v_pk_mul_f32 v[28:29], v[16:17], v[28:29]
	v_pk_mul_f32 v[30:31], v[18:19], v[30:31]
	s_waitcnt lgkmcnt(1)
	v_pk_fma_f32 v[28:29], v[28:29], v[48:49], v[40:41]
	v_pk_fma_f32 v[30:31], v[30:31], v[50:51], v[42:43]
	s_waitcnt lgkmcnt(0)
	v_add_f32_e32 v40, v60, v61
	ds_bpermute_b32 v41, v95, v40
	v_cvt_pk_bf16_f32 v28, v28, v29
	v_cvt_pk_bf16_f32 v29, v30, v31
	v_add_u32_e32 v72, 56, v82
	v_ashrrev_i32_e32 v73, 31, v72
	s_waitcnt lgkmcnt(0)
	v_add_f32_e32 v30, v40, v41
	ds_bpermute_b32 v31, v96, v30
	global_store_dwordx2 v[84:85], v[28:29], off offset:1536 sc1
	v_lshlrev_b64 v[28:29], 12, v[72:73]
	v_lshl_add_u64 v[28:29], v[78:79], 0, v[28:29]
	s_waitcnt lgkmcnt(0)
	v_add_f32_e32 v30, v30, v31
	v_fmamk_f32 v30, v30, 0x3a800000, v190
	v_mul_f32_e32 v31, 0x4b800000, v30
	v_cmp_gt_f32_e32 vcc, s15, v30
	s_nop 1
	v_cndmask_b32_e32 v30, v30, v31, vcc
	v_rsq_f32_e32 v74, v30
	global_load_dwordx4 v[60:63], v[28:29], off nt
	global_load_dwordx4 v[48:51], v[28:29], off offset:1024 nt
	global_load_dwordx4 v[40:43], v[28:29], off offset:2048 nt
	s_nop 0
	global_load_dwordx4 v[28:31], v[28:29], off offset:3072 nt
	ds_read_b128 v[82:85], v97
	ds_read_b128 v[86:89], v97 offset:4096
	v_mul_f32_e32 v75, 0x45800000, v74
	v_cndmask_b32_e32 v74, v74, v75, vcc
	v_pk_mul_f32 v[66:67], v[66:67], v[74:75] op_sel_hi:[1,0]
	v_pk_mul_f32 v[64:65], v[64:65], v[74:75] op_sel_hi:[1,0]
	v_pk_mul_f32 v[66:67], v[6:7], v[66:67]
	v_pk_mul_f32 v[64:65], v[4:5], v[64:65]
	s_waitcnt lgkmcnt(0)
	v_pk_fma_f32 v[66:67], v[88:89], v[66:67], v[84:85]
	v_pk_fma_f32 v[64:65], v[86:87], v[64:65], v[82:83]
	v_pk_mul_f32 v[54:55], v[54:55], v[74:75] op_sel_hi:[1,0]
	v_cvt_pk_bf16_f32 v64, v64, v65
	v_cvt_pk_bf16_f32 v65, v66, v67
	global_store_dwordx2 v[68:69], v[64:65], off sc1
	ds_read_b128 v[64:67], v97 offset:1024
	ds_read_b128 v[82:85], v97 offset:5120
	v_pk_mul_f32 v[52:53], v[52:53], v[74:75] op_sel_hi:[1,0]
	v_pk_mul_f32 v[54:55], v[10:11], v[54:55]
	v_pk_mul_f32 v[52:53], v[8:9], v[52:53]
	s_waitcnt vmcnt(9)
	v_mul_f32_e32 v75, v24, v24
	s_waitcnt lgkmcnt(0)
	v_pk_fma_f32 v[54:55], v[84:85], v[54:55], v[66:67]
	v_pk_fma_f32 v[52:53], v[82:83], v[52:53], v[64:65]
	v_pk_mul_f32 v[64:65], v[58:59], v[58:59]
	v_pk_mul_f32 v[66:67], v[56:57], v[56:57]
	v_cvt_pk_bf16_f32 v52, v52, v53
	v_pk_mov_b32 v[82:83], v[66:67], v[64:65] op_sel:[1,0]
	v_mov_b32_e32 v67, v65
	v_pk_add_f32 v[64:65], v[82:83], v[66:67]
	v_pk_mul_f32 v[66:67], v[46:47], v[46:47]
	v_pk_mul_f32 v[82:83], v[44:45], v[44:45]
	v_pk_add_f32 v[64:65], v[64:65], v[64:65] op_sel:[0,1] op_sel_hi:[1,0]
	v_pk_mov_b32 v[84:85], v[82:83], v[66:67] op_sel:[1,0]
	v_mov_b32_e32 v83, v67
	v_pk_add_f32 v[66:67], v[84:85], v[82:83]
	v_mul_f32_e32 v82, v25, v25
	v_pk_add_f32 v[66:67], v[66:67], v[66:67] op_sel:[0,1] op_sel_hi:[1,0]
	v_mov_b32_e32 v65, v75
	v_mov_b32_e32 v67, v82
	v_pk_add_f32 v[64:65], v[64:65], v[66:67]
	v_mul_f32_e32 v66, v37, v37
	v_mul_f32_e32 v83, v26, v26
	v_pk_fma_f32 v[66:67], v[36:37], v[36:37], v[66:67] op_sel_hi:[1,1,0]
	v_mul_f32_e32 v82, v39, v39
	v_mul_f32_e32 v84, v27, v27
	v_mov_b32_e32 v67, v83
	v_pk_fma_f32 v[82:83], v[38:39], v[38:39], v[82:83] op_sel_hi:[1,1,0]
	v_cvt_pk_bf16_f32 v53, v54, v55
	v_mov_b32_e32 v83, v84
	v_pk_add_f32 v[66:67], v[66:67], v[82:83]
	global_store_dwordx2 v[68:69], v[52:53], off offset:512 sc1
	v_pk_add_f32 v[64:65], v[64:65], v[66:67]
	s_nop 0
	v_add_f32_e32 v64, v64, v65
	ds_bpermute_b32 v65, v91, v64
	s_waitcnt lgkmcnt(0)
	v_add_f32_e32 v75, v64, v65
	ds_bpermute_b32 v82, v92, v75
	v_pk_mul_f32 v[34:35], v[34:35], v[74:75] op_sel_hi:[1,0]
	v_pk_mul_f32 v[32:33], v[32:33], v[74:75] op_sel_hi:[1,0]
	ds_read_b128 v[52:55], v97 offset:2048
	ds_read_b128 v[64:67], v97 offset:6144
	v_pk_mul_f32 v[32:33], v[12:13], v[32:33]
	s_waitcnt lgkmcnt(2)
	v_add_f32_e32 v75, v75, v82
	ds_bpermute_b32 v82, v93, v75
	v_pk_mul_f32 v[34:35], v[14:15], v[34:35]
	s_waitcnt lgkmcnt(1)
	v_pk_fma_f32 v[32:33], v[64:65], v[32:33], v[52:53]
	v_pk_fma_f32 v[34:35], v[66:67], v[34:35], v[54:55]
	v_cvt_pk_bf16_f32 v32, v32, v33
	s_waitcnt lgkmcnt(0)
	v_add_f32_e32 v52, v75, v82
	ds_bpermute_b32 v53, v94, v52
	v_cvt_pk_bf16_f32 v33, v34, v35
	global_store_dwordx2 v[68:69], v[32:33], off offset:1024 sc1
	v_pk_mul_f32 v[20:21], v[20:21], v[74:75] op_sel_hi:[1,0]
	s_waitcnt lgkmcnt(0)
	v_add_f32_e32 v64, v52, v53
	ds_bpermute_b32 v65, v95, v64
	ds_read_b128 v[32:35], v97 offset:3072
	ds_read_b128 v[52:55], v97 offset:7168
	v_pk_mul_f32 v[20:21], v[16:17], v[20:21]
	v_pk_mul_f32 v[22:23], v[22:23], v[74:75] op_sel_hi:[1,0]
	s_waitcnt lgkmcnt(2)
	v_add_f32_e32 v64, v64, v65
	ds_bpermute_b32 v65, v96, v64
	s_waitcnt lgkmcnt(1)
	v_pk_fma_f32 v[20:21], v[20:21], v[52:53], v[32:33]
	v_pk_mul_f32 v[22:23], v[18:19], v[22:23]
	v_cvt_pk_bf16_f32 v20, v20, v21
	v_pk_fma_f32 v[22:23], v[22:23], v[54:55], v[34:35]
	s_waitcnt lgkmcnt(0)
; #define LAS __attribute__((address_space(3)))
; DI unsigned pk2(float lo, float hi) { f32x2_t v = {lo, hi}; bf16x2_t b = __builtin_convertvector(v, bf16x2_t); return __builtin_bit_cast(unsigned, b); }
; DI void phase_modulate(const float* xin, const float* norm_w, const float* modp, const float* adab,
;                        bf16* H, LAS unsigned char* lds, int tid, int G, float* MODF, const float* MODP_all, const float* adab_all) {
;     ...
; #pragma unroll
;         for (int pre = 0; pre < 2; ++pre) { const f32x4* xr = (const f32x4*)(xin + (size_t)(rb * 64 + wave + 8 * pre) * 1024) + lane;
; #pragma unroll
;             for (int j = 0; j < 4; ++j) vbuf[pre][j] = __builtin_nontemporal_load(xr + 64 * j); }
; #pragma unroll
;         for (int it = 0; it < 8; ++it) {
;             const int row = rb * 64 + wave + 8 * it;
;             if (it + 2 < 8) { const f32x4* xr = (const f32x4*)(xin + (size_t)(row + 16) * 1024) + lane;
; #pragma unroll
;                 for (int j = 0; j < 4; ++j) vbuf[(it + 2) % 3][j] = __builtin_nontemporal_load(xr + 64 * j); }
;             f32x4 v[4]; float ss = 0.f;
; #pragma unroll
;             for (int j = 0; j < 4; ++j) { v[j] = vbuf[it % 3][j]; ss += (v[j][0] * v[j][0] + v[j][1] * v[j][1]) + (v[j][2] * v[j][2] + v[j][3] * v[j][3]); }
;             const float rstd = rsqrtf(wave_sum(ss) * (1.f / 1024.f) + EPS);
; #pragma unroll
;             for (int j = 0; j < 4; ++j) { const int col = 4 * lane + 256 * j;
;                 const f32x4 shv = *(const LAS f32x4*)(sh + col), scv = *(const LAS f32x4*)(sc + col);
;                 const f32x4 hv = v[j] * rstd * nw[j] * scv + shv;
;                 u32x2 o; o.x = pk2(hv[0], hv[1]); o.y = pk2(hv[2], hv[3]);
;                 *(u32x2*)(H + (size_t)row * 1024 + col) = o; asm volatile("" ::: "memory"); }
	v_add_f32_e32 v21, v64, v65
	v_fmamk_f32 v21, v21, 0x3a800000, v190
	v_mul_f32_e32 v32, 0x4b800000, v21
	v_cmp_gt_f32_e32 vcc, s15, v21
	v_lshlrev_b64 v[54:55], 11, v[70:71]
	v_lshl_add_u64 v[54:55], v[80:81], 0, v[54:55]
	v_cndmask_b32_e32 v21, v21, v32, vcc
	v_rsq_f32_e32 v32, v21
	v_cvt_pk_bf16_f32 v21, v22, v23
	global_store_dwordx2 v[68:69], v[20:21], off offset:1536 sc1
	v_mul_f32_e32 v20, 0x45800000, v32
	v_cndmask_b32_e32 v52, v32, v20, vcc
	ds_read_b128 v[20:23], v97
	ds_read_b128 v[32:35], v97 offset:4096
	v_pk_mul_f32 v[58:59], v[58:59], v[52:53] op_sel_hi:[1,0]
	v_pk_mul_f32 v[56:57], v[56:57], v[52:53] op_sel_hi:[1,0]
	v_pk_mul_f32 v[58:59], v[6:7], v[58:59]
	v_pk_mul_f32 v[56:57], v[4:5], v[56:57]
	s_waitcnt lgkmcnt(0)
	v_pk_fma_f32 v[22:23], v[34:35], v[58:59], v[22:23]
	v_pk_fma_f32 v[20:21], v[32:33], v[56:57], v[20:21]
	v_pk_mul_f32 v[46:47], v[46:47], v[52:53] op_sel_hi:[1,0]
	v_cvt_pk_bf16_f32 v20, v20, v21
	v_cvt_pk_bf16_f32 v21, v22, v23
	global_store_dwordx2 v[54:55], v[20:21], off sc1
	ds_read_b128 v[20:23], v97 offset:1024
	ds_read_b128 v[32:35], v97 offset:5120
	v_pk_mul_f32 v[44:45], v[44:45], v[52:53] op_sel_hi:[1,0]
	v_pk_mul_f32 v[46:47], v[10:11], v[46:47]
	v_pk_mul_f32 v[44:45], v[8:9], v[44:45]
	v_pk_mul_f32 v[36:37], v[36:37], v[52:53] op_sel_hi:[1,0]
	s_waitcnt lgkmcnt(0)
	v_pk_fma_f32 v[22:23], v[34:35], v[46:47], v[22:23]
	v_pk_fma_f32 v[20:21], v[32:33], v[44:45], v[20:21]
	s_waitcnt vmcnt(8)
	v_pk_mul_f32 v[32:33], v[62:63], v[62:63]
	v_pk_mul_f32 v[34:35], v[60:61], v[60:61]
	v_cvt_pk_bf16_f32 v20, v20, v21
	v_pk_mov_b32 v[44:45], v[34:35], v[32:33] op_sel:[1,0]
	v_mov_b32_e32 v35, v33
	v_pk_add_f32 v[32:33], v[44:45], v[34:35]
	s_waitcnt vmcnt(7)
	v_pk_mul_f32 v[34:35], v[50:51], v[50:51]
	v_pk_mul_f32 v[44:45], v[48:49], v[48:49]
	v_pk_add_f32 v[32:33], v[32:33], v[32:33] op_sel:[0,1] op_sel_hi:[1,0]
	v_pk_mov_b32 v[46:47], v[44:45], v[34:35] op_sel:[1,0]
	v_mov_b32_e32 v45, v35
	v_pk_add_f32 v[34:35], v[46:47], v[44:45]
	s_waitcnt vmcnt(5)
	v_mul_f32_e32 v44, v28, v28
	v_mul_f32_e32 v45, v29, v29
	v_pk_add_f32 v[34:35], v[34:35], v[34:35] op_sel:[0,1] op_sel_hi:[1,0]
	v_mov_b32_e32 v33, v44
	v_mov_b32_e32 v35, v45
	v_pk_add_f32 v[32:33], v[32:33], v[34:35]
	v_mul_f32_e32 v34, v41, v41
	v_mul_f32_e32 v44, v43, v43
	v_mul_f32_e32 v46, v30, v30
	v_mul_f32_e32 v47, v31, v31
	v_pk_fma_f32 v[34:35], v[40:41], v[40:41], v[34:35] op_sel_hi:[1,1,0]
	v_pk_fma_f32 v[44:45], v[42:43], v[42:43], v[44:45] op_sel_hi:[1,1,0]
	v_mov_b32_e32 v35, v46
	v_mov_b32_e32 v45, v47
	v_pk_add_f32 v[34:35], v[34:35], v[44:45]
	v_cvt_pk_bf16_f32 v21, v22, v23
	v_pk_add_f32 v[32:33], v[32:33], v[34:35]
	global_store_dwordx2 v[54:55], v[20:21], off offset:512 sc1
	v_add_f32_e32 v32, v32, v33
	ds_bpermute_b32 v33, v91, v32
	v_pk_mul_f32 v[36:37], v[12:13], v[36:37]
	v_pk_mul_f32 v[38:39], v[38:39], v[52:53] op_sel_hi:[1,0]
	v_pk_mul_f32 v[24:25], v[24:25], v[52:53] op_sel_hi:[1,0]
	s_waitcnt lgkmcnt(0)
	v_add_f32_e32 v44, v32, v33
	ds_bpermute_b32 v45, v92, v44
	ds_read_b128 v[20:23], v97 offset:2048
	ds_read_b128 v[32:35], v97 offset:6144
	v_pk_mul_f32 v[38:39], v[14:15], v[38:39]
	v_pk_mul_f32 v[24:25], v[16:17], v[24:25]
	v_pk_mul_f32 v[26:27], v[26:27], v[52:53] op_sel_hi:[1,0]
	s_waitcnt lgkmcnt(2)
	v_add_f32_e32 v44, v44, v45
	ds_bpermute_b32 v45, v93, v44
	s_waitcnt lgkmcnt(1)
	v_pk_fma_f32 v[20:21], v[32:33], v[36:37], v[20:21]
	v_pk_fma_f32 v[22:23], v[34:35], v[38:39], v[22:23]
	v_cvt_pk_bf16_f32 v20, v20, v21
	v_cvt_pk_bf16_f32 v21, v22, v23
	s_waitcnt lgkmcnt(0)
	v_add_f32_e32 v32, v44, v45
	ds_bpermute_b32 v33, v94, v32
	global_store_dwordx2 v[54:55], v[20:21], off offset:1024 sc1
	v_pk_mul_f32 v[26:27], v[18:19], v[26:27]
	s_waitcnt lgkmcnt(0)
	v_add_f32_e32 v36, v32, v33
	ds_bpermute_b32 v37, v95, v36
	ds_read_b128 v[20:23], v97 offset:3072
	ds_read_b128 v[32:35], v97 offset:7168
	s_waitcnt lgkmcnt(2)
	v_add_f32_e32 v36, v36, v37
	ds_bpermute_b32 v37, v96, v36
	s_waitcnt lgkmcnt(1)
	v_pk_fma_f32 v[20:21], v[24:25], v[32:33], v[20:21]
	v_pk_fma_f32 v[22:23], v[26:27], v[34:35], v[22:23]
	v_cvt_pk_bf16_f32 v20, v20, v21
	v_lshlrev_b64 v[34:35], 11, v[72:73]
	s_waitcnt lgkmcnt(0)
	v_add_f32_e32 v21, v36, v37
	v_fmamk_f32 v21, v21, 0x3a800000, v190
	v_mul_f32_e32 v24, 0x4b800000, v21
	v_cmp_gt_f32_e32 vcc, s15, v21
	v_lshl_add_u64 v[34:35], v[80:81], 0, v[34:35]
	s_nop 0
	v_cndmask_b32_e32 v21, v21, v24, vcc
	v_rsq_f32_e32 v24, v21
	v_cvt_pk_bf16_f32 v21, v22, v23
	global_store_dwordx2 v[54:55], v[20:21], off offset:1536 sc1
	v_mul_f32_e32 v20, 0x45800000, v24
	v_cndmask_b32_e32 v32, v24, v20, vcc
	ds_read_b128 v[20:23], v97
	ds_read_b128 v[24:27], v97 offset:4096
	v_pk_mul_f32 v[36:37], v[62:63], v[32:33] op_sel_hi:[1,0]
	v_pk_mul_f32 v[38:39], v[60:61], v[32:33] op_sel_hi:[1,0]
	v_pk_mul_f32 v[36:37], v[6:7], v[36:37]
	v_pk_mul_f32 v[38:39], v[4:5], v[38:39]
	s_waitcnt lgkmcnt(0)
	v_pk_fma_f32 v[22:23], v[26:27], v[36:37], v[22:23]
	v_pk_fma_f32 v[20:21], v[24:25], v[38:39], v[20:21]
	v_pk_mul_f32 v[36:37], v[50:51], v[32:33] op_sel_hi:[1,0]
	v_cvt_pk_bf16_f32 v20, v20, v21
	v_cvt_pk_bf16_f32 v21, v22, v23
	global_store_dwordx2 v[34:35], v[20:21], off sc1
	ds_read_b128 v[20:23], v97 offset:1024
	ds_read_b128 v[24:27], v97 offset:5120
	v_pk_mul_f32 v[38:39], v[48:49], v[32:33] op_sel_hi:[1,0]
	v_pk_mul_f32 v[36:37], v[10:11], v[36:37]
	v_pk_mul_f32 v[38:39], v[8:9], v[38:39]
	v_pk_mul_f32 v[30:31], v[30:31], v[32:33] op_sel_hi:[1,0]
	s_waitcnt lgkmcnt(0)
	v_pk_fma_f32 v[22:23], v[26:27], v[36:37], v[22:23]
	v_pk_fma_f32 v[20:21], v[24:25], v[38:39], v[20:21]
	v_pk_mul_f32 v[36:37], v[42:43], v[32:33] op_sel_hi:[1,0]
	v_cvt_pk_bf16_f32 v20, v20, v21
	v_cvt_pk_bf16_f32 v21, v22, v23
	global_store_dwordx2 v[34:35], v[20:21], off offset:512 sc1
	ds_read_b128 v[20:23], v97 offset:2048
	ds_read_b128 v[24:27], v97 offset:6144
	v_pk_mul_f32 v[38:39], v[40:41], v[32:33] op_sel_hi:[1,0]
	v_pk_mul_f32 v[36:37], v[14:15], v[36:37]
	v_pk_mul_f32 v[38:39], v[12:13], v[38:39]
	v_pk_mul_f32 v[28:29], v[28:29], v[32:33] op_sel_hi:[1,0]
	s_waitcnt lgkmcnt(0)
	v_pk_fma_f32 v[22:23], v[26:27], v[36:37], v[22:23]
	v_pk_fma_f32 v[20:21], v[24:25], v[38:39], v[20:21]
	v_pk_mul_f32 v[28:29], v[16:17], v[28:29]
	v_cvt_pk_bf16_f32 v20, v20, v21
	v_cvt_pk_bf16_f32 v21, v22, v23
	global_store_dwordx2 v[34:35], v[20:21], off offset:1024 sc1
	ds_read_b128 v[20:23], v97 offset:3072
	ds_read_b128 v[24:27], v97 offset:7168
	v_pk_mul_f32 v[30:31], v[18:19], v[30:31]
	s_waitcnt lgkmcnt(0)
	v_pk_fma_f32 v[20:21], v[28:29], v[24:25], v[20:21]
	v_pk_fma_f32 v[22:23], v[30:31], v[26:27], v[22:23]
	v_cvt_pk_bf16_f32 v20, v20, v21
	v_cvt_pk_bf16_f32 v21, v22, v23
	global_store_dwordx2 v[34:35], v[20:21], off offset:1536 sc1
	s_cbranch_scc0 .LBB0_111

; #define PG8_LAS __attribute__((address_space(3)))
; __device__ __forceinline__ unsigned cvt_pk_bf16(float lo, float hi) { unsigned r; asm volatile("v_cvt_pk_bf16_f32 %0, %1, %2" : "=v"(r) : "v"(lo), "v"(hi)); return r; }
;     __device__ __forceinline__ void operator()(const f32x4 (&acc)[2][2][4][2], const Unit& u, int wr, int wc, int fr, int fq) const {
;     ...
;                 for (int bj = 0; bj < 2; ++bj) { const f32x4 v0 = acc[ai][bj][m][0], v1 = acc[ai][bj][m][1];
;                     u32x4 w; w.x = cvt_pk_bf16(v0[0], v0[1]); w.y = cvt_pk_bf16(v0[2], v0[3]); w.z = cvt_pk_bf16(v1[0], v1[1]); w.w = cvt_pk_bf16(v1[2], v1[3]);
;                     PG8_LAS unsigned char* tl = epl + (wr * 4 + wc) * 2048 + ((ai * 4 + m) * 2 + bj) % 2 * 1024;
;                     const int ln = fq * 16 + fr;
;                     *(PG8_LAS u32x4*)(tl + fr * 64 + ((fq ^ (fr >> 2)) & 3) * 16) = w;
;                     const int r2 = ln >> 2, p2 = ln & 3;
;                     const u32x4 w2 = *(const PG8_LAS u32x4*)(tl + r2 * 64 + ((p2 ^ (r2 >> 2)) & 3) * 16);
;                     const int cc = u.pn * BM + bj * HALF + wc * 32;
;                     bf16_t* dst = O + ((size_t)(cc >> 6) * 16384 + (size_t)(u.pm * BM + wr * 64 + ai * HALF + m * 16 + r2)) * 64 + (cc & 63) + p2 * 8;
;                     *(u32x4*)dst = w2; } }
;         if (u.pn == 1 || u.pn == 5 || u.pn == 13) {
.LBB0_178:
	s_lshl_b32 s31, s64, 8
	s_or_b32 s31, s31, s60
	s_ashr_i32 s48, s31, 6
	s_ashr_i32 s49, s48, 31
	s_lshl_b32 s31, s65, 8
	v_cvt_pk_bf16_f32 v154, v128, v129
	v_cvt_pk_bf16_f32 v155, v130, v131
	v_cvt_pk_bf16_f32 v156, v124, v125
	v_cvt_pk_bf16_f32 v157, v126, v127
	ds_write_b128 v152, v[154:157]
	v_add_u32_e32 v144, s31, v147
	s_lshl_b64 s[46:47], s[48:49], 21
	ds_read_b128 v[154:157], v153
	v_ashrrev_i32_e32 v145, 31, v144
	s_add_u32 s46, s10, s46
	s_addc_u32 s47, s11, s47
	v_lshlrev_b64 v[158:159], 7, v[144:145]
	v_lshl_add_u64 v[160:161], s[46:47], 0, v[158:159]
	v_lshl_add_u64 v[160:161], v[160:161], 0, s[34:35]
	s_or_b32 s48, s48, 2
	v_lshl_add_u64 v[160:161], v[160:161], 0, v[188:189]
	s_ashr_i32 s49, s48, 31
	s_waitcnt lgkmcnt(0)
	global_store_dwordx4 v[160:161], v[154:157], off sc1
	s_lshl_b64 s[48:49], s[48:49], 21
	s_add_u32 s48, s10, s48
	v_cvt_pk_bf16_f32 v154, v116, v117
	v_cvt_pk_bf16_f32 v155, v118, v119
	v_cvt_pk_bf16_f32 v156, v108, v109
	v_cvt_pk_bf16_f32 v157, v110, v111
	ds_write_b128 v152, v[154:157] offset:1024
	ds_read_b128 v[154:157], v153 offset:1024
	s_addc_u32 s49, s11, s49
	v_lshl_add_u64 v[158:159], s[48:49], 0, v[158:159]
	v_lshl_add_u64 v[158:159], v[158:159], 0, s[34:35]
	v_lshl_add_u64 v[158:159], v[158:159], 0, v[188:189]
	s_waitcnt lgkmcnt(0)
	global_store_dwordx4 v[158:159], v[154:157], off sc1
	v_add_u32_e32 v158, s31, v148
	v_ashrrev_i32_e32 v159, 31, v158
	v_cvt_pk_bf16_f32 v154, v120, v121
	v_cvt_pk_bf16_f32 v155, v122, v123
	v_cvt_pk_bf16_f32 v156, v112, v113
	v_cvt_pk_bf16_f32 v157, v114, v115
	ds_write_b128 v152, v[154:157]
	ds_read_b128 v[154:157], v153
	v_lshlrev_b64 v[158:159], 7, v[158:159]
	v_lshl_add_u64 v[160:161], s[46:47], 0, v[158:159]
	v_lshl_add_u64 v[160:161], v[160:161], 0, s[34:35]
	v_lshl_add_u64 v[160:161], v[160:161], 0, v[188:189]
	s_waitcnt lgkmcnt(0)
	global_store_dwordx4 v[160:161], v[154:157], off sc1
	v_lshl_add_u64 v[158:159], s[48:49], 0, v[158:159]
	v_lshl_add_u64 v[158:159], v[158:159], 0, s[34:35]
	v_cvt_pk_bf16_f32 v154, v100, v101
	v_cvt_pk_bf16_f32 v155, v102, v103
	v_cvt_pk_bf16_f32 v156, v92, v93
	v_cvt_pk_bf16_f32 v157, v94, v95
	ds_write_b128 v152, v[154:157] offset:1024
	ds_read_b128 v[154:157], v153 offset:1024
	v_lshl_add_u64 v[158:159], v[158:159], 0, v[188:189]
	v_readlane_b32 s75, v255, 25
	s_mov_b32 s89, 0x2aaaaaab
	s_cmp_lt_i32 s64, 5
	s_waitcnt lgkmcnt(0)
	global_store_dwordx4 v[158:159], v[154:157], off sc1
	v_add_u32_e32 v158, s31, v149
	v_ashrrev_i32_e32 v159, 31, v158
	v_cvt_pk_bf16_f32 v154, v104, v105
	v_cvt_pk_bf16_f32 v155, v106, v107
	v_cvt_pk_bf16_f32 v156, v96, v97
	v_cvt_pk_bf16_f32 v157, v98, v99
	ds_write_b128 v152, v[154:157]
	ds_read_b128 v[154:157], v153
	v_lshlrev_b64 v[158:159], 7, v[158:159]
	v_lshl_add_u64 v[160:161], s[46:47], 0, v[158:159]
	v_lshl_add_u64 v[160:161], v[160:161], 0, s[34:35]
	v_lshl_add_u64 v[160:161], v[160:161], 0, v[188:189]
	s_waitcnt lgkmcnt(0)
	global_store_dwordx4 v[160:161], v[154:157], off sc1
	v_lshl_add_u64 v[158:159], s[48:49], 0, v[158:159]
	v_lshl_add_u64 v[158:159], v[158:159], 0, s[34:35]
	v_cvt_pk_bf16_f32 v154, v84, v85
	v_cvt_pk_bf16_f32 v155, v86, v87
	v_cvt_pk_bf16_f32 v156, v76, v77
	v_cvt_pk_bf16_f32 v157, v78, v79
	ds_write_b128 v152, v[154:157] offset:1024
	ds_read_b128 v[154:157], v153 offset:1024
	v_lshl_add_u64 v[158:159], v[158:159], 0, v[188:189]
	s_waitcnt lgkmcnt(0)
	global_store_dwordx4 v[158:159], v[154:157], off sc1
	s_nop 1
	v_cvt_pk_bf16_f32 v154, v88, v89
	v_cvt_pk_bf16_f32 v155, v90, v91
	v_cvt_pk_bf16_f32 v156, v80, v81
	v_cvt_pk_bf16_f32 v157, v82, v83
	ds_write_b128 v152, v[154:157]
	v_add_u32_e32 v158, s31, v150
	ds_read_b128 v[154:157], v153
	v_ashrrev_i32_e32 v159, 31, v158
	v_lshlrev_b64 v[158:159], 7, v[158:159]
	v_lshl_add_u64 v[160:161], s[46:47], 0, v[158:159]
	v_lshl_add_u64 v[160:161], v[160:161], 0, s[34:35]
	v_lshl_add_u64 v[160:161], v[160:161], 0, v[188:189]
	s_waitcnt lgkmcnt(0)
	global_store_dwordx4 v[160:161], v[154:157], off sc1
	v_lshl_add_u64 v[158:159], s[48:49], 0, v[158:159]
	v_lshl_add_u64 v[158:159], v[158:159], 0, s[34:35]
	v_cvt_pk_bf16_f32 v154, v72, v73
	v_cvt_pk_bf16_f32 v155, v74, v75
	v_cvt_pk_bf16_f32 v156, v68, v69
	v_cvt_pk_bf16_f32 v157, v70, v71
	ds_write_b128 v152, v[154:157] offset:1024
	ds_read_b128 v[154:157], v153 offset:1024
	v_lshl_add_u64 v[158:159], v[158:159], 0, v[188:189]
	s_waitcnt lgkmcnt(0)
; #define PG8_LAS __attribute__((address_space(3)))
; __device__ __forceinline__ unsigned cvt_pk_bf16(float lo, float hi) { unsigned r; asm volatile("v_cvt_pk_bf16_f32 %0, %1, %2" : "=v"(r) : "v"(lo), "v"(hi)); return r; }
;     __device__ __forceinline__ void operator()(const f32x4 (&acc)[2][2][4][2], const Unit& u, int wr, int wc, int fr, int fq) const {
;     ...
;                 for (int bj = 0; bj < 2; ++bj) { const f32x4 v0 = acc[ai][bj][m][0], v1 = acc[ai][bj][m][1];
;                     u32x4 w; w.x = cvt_pk_bf16(v0[0], v0[1]); w.y = cvt_pk_bf16(v0[2], v0[3]); w.z = cvt_pk_bf16(v1[0], v1[1]); w.w = cvt_pk_bf16(v1[2], v1[3]);
;                     PG8_LAS unsigned char* tl = epl + (wr * 4 + wc) * 2048 + ((ai * 4 + m) * 2 + bj) % 2 * 1024;
;                     const int ln = fq * 16 + fr;
;                     *(PG8_LAS u32x4*)(tl + fr * 64 + ((fq ^ (fr >> 2)) & 3) * 16) = w;
;                     const int r2 = ln >> 2, p2 = ln & 3;
;                     const u32x4 w2 = *(const PG8_LAS u32x4*)(tl + r2 * 64 + ((p2 ^ (r2 >> 2)) & 3) * 16);
;                     const int cc = u.pn * BM + bj * HALF + wc * 32;
;                     bf16_t* dst = O + ((size_t)(cc >> 6) * 16384 + (size_t)(u.pm * BM + wr * 64 + ai * HALF + m * 16 + r2)) * 64 + (cc & 63) + p2 * 8;
;                     *(u32x4*)dst = w2; } }
;         if (u.pn == 1 || u.pn == 5 || u.pn == 13) {
	global_store_dwordx4 v[158:159], v[154:157], off sc1
	s_nop 1
	v_cvt_pk_bf16_f32 v154, v64, v65
	v_cvt_pk_bf16_f32 v155, v66, v67
	v_cvt_pk_bf16_f32 v156, v60, v61
	v_cvt_pk_bf16_f32 v157, v62, v63
	ds_write_b128 v152, v[154:157]
	v_add_u32_e32 v158, 0x80, v144
	ds_read_b128 v[154:157], v153
	v_ashrrev_i32_e32 v159, 31, v158
	v_lshlrev_b64 v[158:159], 7, v[158:159]
	v_lshl_add_u64 v[160:161], s[46:47], 0, v[158:159]
	v_lshl_add_u64 v[160:161], v[160:161], 0, s[34:35]
	v_lshl_add_u64 v[160:161], v[160:161], 0, v[188:189]
	s_waitcnt lgkmcnt(0)
	global_store_dwordx4 v[160:161], v[154:157], off sc1
	v_lshl_add_u64 v[158:159], s[48:49], 0, v[158:159]
	v_lshl_add_u64 v[158:159], v[158:159], 0, s[34:35]
	v_cvt_pk_bf16_f32 v154, v52, v53
	v_cvt_pk_bf16_f32 v155, v54, v55
	v_cvt_pk_bf16_f32 v156, v44, v45
	v_cvt_pk_bf16_f32 v157, v46, v47
	ds_write_b128 v152, v[154:157] offset:1024
	ds_read_b128 v[154:157], v153 offset:1024
	v_lshl_add_u64 v[158:159], v[158:159], 0, v[188:189]
	s_waitcnt lgkmcnt(0)
	global_store_dwordx4 v[158:159], v[154:157], off sc1
	s_nop 1
	v_cvt_pk_bf16_f32 v154, v56, v57
	v_cvt_pk_bf16_f32 v155, v58, v59
	v_cvt_pk_bf16_f32 v156, v48, v49
	v_cvt_pk_bf16_f32 v157, v50, v51
	ds_write_b128 v152, v[154:157]
	v_add_u32_e32 v158, 0x90, v144
	ds_read_b128 v[154:157], v153
	v_ashrrev_i32_e32 v159, 31, v158
	v_lshlrev_b64 v[158:159], 7, v[158:159]
	v_lshl_add_u64 v[160:161], s[46:47], 0, v[158:159]
	v_lshl_add_u64 v[160:161], v[160:161], 0, s[34:35]
	v_lshl_add_u64 v[160:161], v[160:161], 0, v[188:189]
	s_waitcnt lgkmcnt(0)
	global_store_dwordx4 v[160:161], v[154:157], off sc1
	v_lshl_add_u64 v[158:159], s[48:49], 0, v[158:159]
	v_lshl_add_u64 v[158:159], v[158:159], 0, s[34:35]
	v_cvt_pk_bf16_f32 v154, v36, v37
	v_cvt_pk_bf16_f32 v155, v38, v39
	v_cvt_pk_bf16_f32 v156, v28, v29
	v_cvt_pk_bf16_f32 v157, v30, v31
	ds_write_b128 v152, v[154:157] offset:1024
	ds_read_b128 v[154:157], v153 offset:1024
	v_lshl_add_u64 v[158:159], v[158:159], 0, v[188:189]
	s_waitcnt lgkmcnt(0)
	global_store_dwordx4 v[158:159], v[154:157], off sc1
	s_nop 1
	v_cvt_pk_bf16_f32 v154, v40, v41
	v_cvt_pk_bf16_f32 v155, v42, v43
	v_cvt_pk_bf16_f32 v156, v32, v33
	v_cvt_pk_bf16_f32 v157, v34, v35
	ds_write_b128 v152, v[154:157]
	v_add_u32_e32 v158, 0xa0, v144
	ds_read_b128 v[154:157], v153
	v_ashrrev_i32_e32 v159, 31, v158
	v_lshlrev_b64 v[158:159], 7, v[158:159]
	v_lshl_add_u64 v[160:161], s[46:47], 0, v[158:159]
	v_lshl_add_u64 v[160:161], v[160:161], 0, s[34:35]
	v_lshl_add_u64 v[160:161], v[160:161], 0, v[188:189]
	s_waitcnt lgkmcnt(0)
	global_store_dwordx4 v[160:161], v[154:157], off sc1
	v_lshl_add_u64 v[158:159], s[48:49], 0, v[158:159]
	v_lshl_add_u64 v[158:159], v[158:159], 0, s[34:35]
	v_cvt_pk_bf16_f32 v154, v20, v21
	v_cvt_pk_bf16_f32 v155, v22, v23
	v_cvt_pk_bf16_f32 v156, v12, v13
	v_cvt_pk_bf16_f32 v157, v14, v15
	ds_write_b128 v152, v[154:157] offset:1024
	ds_read_b128 v[154:157], v153 offset:1024
	v_lshl_add_u64 v[158:159], v[158:159], 0, v[188:189]
	v_add_u32_e32 v144, 0xb0, v144
	v_ashrrev_i32_e32 v145, 31, v144
	v_lshlrev_b64 v[144:145], 7, v[144:145]
	s_waitcnt lgkmcnt(0)
	global_store_dwordx4 v[158:159], v[154:157], off sc1
	v_lshl_add_u64 v[158:159], s[46:47], 0, v[144:145]
	v_lshl_add_u64 v[158:159], v[158:159], 0, s[34:35]
	v_cvt_pk_bf16_f32 v154, v24, v25
	v_cvt_pk_bf16_f32 v155, v26, v27
	v_cvt_pk_bf16_f32 v156, v16, v17
	v_cvt_pk_bf16_f32 v157, v18, v19
	ds_write_b128 v152, v[154:157]
	ds_read_b128 v[154:157], v153
	v_lshl_add_u64 v[158:159], v[158:159], 0, v[188:189]
	v_lshl_add_u64 v[144:145], s[48:49], 0, v[144:145]
	v_lshl_add_u64 v[144:145], v[144:145], 0, s[34:35]
	v_lshl_add_u64 v[144:145], v[144:145], 0, v[188:189]
	s_waitcnt lgkmcnt(0)
	global_store_dwordx4 v[158:159], v[154:157], off sc1
	s_nop 1
	v_cvt_pk_bf16_f32 v154, v8, v9
	v_cvt_pk_bf16_f32 v155, v10, v11
	v_cvt_pk_bf16_f32 v156, v4, v5
	v_cvt_pk_bf16_f32 v157, v6, v7
	ds_write_b128 v152, v[154:157] offset:1024
	ds_read_b128 v[154:157], v153 offset:1024
	s_waitcnt lgkmcnt(0)
	global_store_dwordx4 v[144:145], v[154:157], off sc1
	s_cbranch_scc1 .LBB0_181
	v_readlane_b32 s94, v255, 33
	v_readlane_b32 s96, v255, 19
	s_cmp_gt_i32 s64, 12
	v_readlane_b32 s95, v255, 34
	v_readlane_b32 s97, v255, 20
	s_cbranch_scc0 .LBB0_182
	s_cmp_eq_u32 s64, 13
	s_cselect_b64 s[46:47], -1, 0
	s_cbranch_execz .LBB0_183
	s_branch .LBB0_184

; #define LAS __attribute__((address_space(3)))
; DI void mixerB2_unit(int u, int l, const bf16* PROJ, bf16* YC, const float* dlam_l, const float* dnw_l, const float* kmax_l, LAS char* lds, int tid, int wave, int lane) {
;     ...
;     float pa = 0.f, pb = 0.f;
;     if (lane < 32) { pa = dlam_l[lane] * dlam_l[32 + lane]; pb = dlam_l[64 + lane] * dlam_l[96 + lane]; }
;     pa = wave_sum(pa); pb = wave_sum(pb);
;     const float lam_init = 0.8f - 0.6f * __expf(-0.3f * (float)l);
;     const float lam = __expf(pa) - __expf(pb) + lam_init;
;     LAS char* sc = lds + 4 * KV_TILE + wave * (16 * VT_PITCH);
; #pragma unroll
;     for (int qt = 0; qt < 2; ++qt) {
;         const int tok0 = q0w + 16 * qt;
;         const float i1 = 1.f / ol1[qt][0], i2 = lam / ol2[qt][0];
;         f32x4 o[4]; float ss = 0.f;
; #pragma unroll
;         for (int c = 0; c < 4; ++c) { o[c] = o1[qt][c] * i1 - o2[qt][c] * i2; ss += (o[c][0] * o[c][0] + o[c][1] * o[c][1]) + (o[c][2] * o[c][2] + o[c][3] * o[c][3]); }
;         ss += __shfl_xor(ss, 16); ss += __shfl_xor(ss, 32);
;         const float rstd = rsqrtf(ss * (1.f / 64.f) + EPS) * (1.f - lam_init);
;         rows16_load(sc, gbase, 64, tok0, 1, lane);
;         u32x2 gv[4];
; #pragma unroll
;         for (int c = 0; c < 4; ++c) gv[c] = *(const LAS u32x2*)(sc + r * VT_PITCH + (16 * c + 4 * g) * 2);
.LBB0_251:
	s_or_b64 exec, exec, s[0:1]
	ds_bpermute_b32 v6, v201, v4
	ds_bpermute_b32 v7, v201, v5
	s_or_b32 s0, s43, 16
	s_add_u32 s26, s42, s26
	v_or_b32_e32 v90, s43, v207
	s_waitcnt lgkmcnt(1)
	v_add_f32_e32 v4, v4, v6
	s_waitcnt lgkmcnt(0)
	v_add_f32_e32 v5, v5, v7
	ds_bpermute_b32 v6, v202, v4
	ds_bpermute_b32 v7, v202, v5
	v_or_b32_e32 v54, s43, v208
	s_addc_u32 s27, s34, s27
	v_ashrrev_i32_e32 v91, 31, v90
	s_waitcnt lgkmcnt(1)
	v_add_f32_e32 v4, v4, v6
	s_waitcnt lgkmcnt(0)
	v_add_f32_e32 v5, v5, v7
	ds_bpermute_b32 v6, v203, v4
	ds_bpermute_b32 v7, v203, v5
	v_ashrrev_i32_e32 v55, 31, v54
	s_lshl_b64 s[20:21], s[20:21], 22
	s_add_u32 s1, s8, s20
	s_waitcnt lgkmcnt(1)
	v_add_f32_e32 v4, v4, v6
	s_waitcnt lgkmcnt(0)
	v_add_f32_e32 v5, v5, v7
	ds_bpermute_b32 v6, v204, v4
	ds_bpermute_b32 v7, v204, v5
	s_waitcnt vmcnt(0) lgkmcnt(1)
	v_add_f32_e32 v8, v4, v6
	s_waitcnt lgkmcnt(0)
	v_add_f32_e32 v9, v5, v7
	ds_bpermute_b32 v10, v184, v8
	ds_bpermute_b32 v11, v184, v9
	v_lshlrev_b64 v[4:5], 7, v[90:91]
	v_lshlrev_b64 v[6:7], 7, v[54:55]
	s_waitcnt lgkmcnt(1)
	v_add_f32_e32 v10, v8, v10
	s_waitcnt lgkmcnt(0)
	v_add_f32_e32 v11, v9, v11
	ds_bpermute_b32 v49, v185, v10
	ds_bpermute_b32 v50, v185, v11
	v_lshl_add_u64 v[8:9], s[26:27], 0, v[188:189]
	s_mov_b64 s[26:27], 0x3800000
	v_lshl_add_u64 v[86:87], v[8:9], 0, s[26:27]
	s_waitcnt lgkmcnt(1)
	v_add_f32_e32 v8, v10, v49
	v_lshl_add_u64 v[4:5], v[86:87], 0, v[4:5]
	s_waitcnt lgkmcnt(0)
	v_add_f32_e32 v49, v11, v50
	v_mul_f32_e32 v50, 0x3fb8aa3b, v8
	v_lshl_add_u64 v[8:9], v[86:87], 0, v[6:7]
	global_load_dwordx4 v[4:7], v[4:5], off
	s_nop 0
	global_load_dwordx4 v[8:11], v[8:9], off
	s_addc_u32 s26, s9, s21
	v_div_scale_f32 v53, s[20:21], v88, v88, 1.0
	v_rcp_f32_e32 v85, v53
	v_mul_f32_e32 v49, 0x3fb8aa3b, v49
	v_exp_f32_e32 v50, v50
	v_exp_f32_e32 v49, v49
	v_fma_f32 v89, -v53, v85, 1.0
	v_fmac_f32_e32 v85, v89, v85
	v_div_scale_f32 v89, vcc, 1.0, v88, 1.0
	s_lshl_b32 s27, s33, 7
	v_mul_f32_e32 v92, v89, v85
	v_sub_f32_e32 v49, v50, v49
	s_add_u32 s20, s1, s27
	v_fma_f32 v93, -v53, v92, v89
	v_add_f32_e32 v49, v205, v49
	s_addc_u32 s21, s26, 0
	v_fmac_f32_e32 v92, v93, v85
	v_lshl_add_u64 v[50:51], s[20:21], 0, v[188:189]
	v_fma_f32 v53, -v53, v92, v89
	v_div_scale_f32 v89, s[20:21], v84, v84, v49
	v_rcp_f32_e32 v93, v89
	v_div_fmas_f32 v53, v53, v85, v92
	v_div_fixup_f32 v88, v53, v88, 1.0
	s_add_i32 s31, s31, s88
	v_fma_f32 v53, -v89, v93, 1.0
	v_fmac_f32_e32 v93, v53, v93
	v_div_scale_f32 v53, vcc, v49, v84, v49
	v_mul_f32_e32 v85, v53, v93
	v_fma_f32 v92, -v89, v85, v53
	v_fmac_f32_e32 v85, v92, v93
	v_fma_f32 v53, -v89, v85, v53
	v_div_fmas_f32 v53, v53, v93, v85
	v_div_fixup_f32 v84, v53, v84, v49
	v_pk_mul_f32 v[14:15], v[14:15], v[84:85] op_sel_hi:[1,0]
	v_pk_mul_f32 v[12:13], v[12:13], v[84:85] op_sel_hi:[1,0]
	v_pk_fma_f32 v[82:83], v[88:89], v[82:83], v[14:15] op_sel_hi:[0,1,1] neg_lo:[0,0,1] neg_hi:[0,0,1]
	v_pk_fma_f32 v[80:81], v[88:89], v[80:81], v[12:13] op_sel_hi:[0,1,1] neg_lo:[0,0,1] neg_hi:[0,0,1]
	v_pk_mul_f32 v[12:13], v[82:83], v[82:83]
	v_pk_mul_f32 v[14:15], v[80:81], v[80:81]
	v_pk_mul_f32 v[64:65], v[64:65], v[84:85] op_sel_hi:[1,0]
	v_pk_mov_b32 v[92:93], v[14:15], v[12:13] op_sel:[1,0]
	v_mov_b32_e32 v15, v13
	v_pk_add_f32 v[12:13], v[92:93], v[14:15]
	v_pk_mul_f32 v[14:15], v[66:67], v[84:85] op_sel_hi:[1,0]
	v_pk_fma_f32 v[64:65], v[88:89], v[76:77], v[64:65] op_sel_hi:[0,1,1] neg_lo:[0,0,1] neg_hi:[0,0,1]
	v_pk_fma_f32 v[66:67], v[88:89], v[78:79], v[14:15] op_sel_hi:[0,1,1] neg_lo:[0,0,1] neg_hi:[0,0,1]
	v_pk_mul_f32 v[14:15], v[66:67], v[66:67]
	v_pk_mul_f32 v[76:77], v[64:65], v[64:65]
	v_pk_add_f32 v[12:13], v[12:13], v[12:13] op_sel_hi:[0,1]
	v_pk_mov_b32 v[78:79], v[76:77], v[14:15] op_sel:[1,0]
	v_mov_b32_e32 v77, v15
	v_pk_add_f32 v[14:15], v[78:79], v[76:77]
	v_pk_mul_f32 v[76:77], v[60:61], v[84:85] op_sel_hi:[1,0]
	v_pk_mul_f32 v[60:61], v[62:63], v[84:85] op_sel_hi:[1,0]
	v_pk_fma_f32 v[62:63], v[88:89], v[72:73], v[76:77] op_sel_hi:[0,1,1] neg_lo:[0,0,1] neg_hi:[0,0,1]
	v_pk_mul_f32 v[76:77], v[56:57], v[84:85] op_sel_hi:[1,0]
	v_pk_mul_f32 v[56:57], v[58:59], v[84:85] op_sel_hi:[1,0]
	v_pk_fma_f32 v[58:59], v[88:89], v[68:69], v[76:77] op_sel_hi:[0,1,1] neg_lo:[0,0,1] neg_hi:[0,0,1]
	v_pk_fma_f32 v[60:61], v[88:89], v[74:75], v[60:61] op_sel_hi:[0,1,1] neg_lo:[0,0,1] neg_hi:[0,0,1]
	v_mul_f32_e32 v12, v62, v62
	v_pk_fma_f32 v[72:73], v[62:63], v[62:63], v[12:13] op_sel_hi:[1,1,0]
	v_mul_f32_e32 v12, v60, v60
	v_pk_fma_f32 v[74:75], v[60:61], v[60:61], v[12:13] op_sel_hi:[1,1,0]
	v_mul_f32_e32 v72, v58, v58
	v_mul_f32_e32 v74, v59, v59
	v_pk_fma_f32 v[56:57], v[88:89], v[70:71], v[56:57] op_sel_hi:[0,1,1] neg_lo:[0,0,1] neg_hi:[0,0,1]
	v_pk_add_f32 v[14:15], v[14:15], v[14:15] op_sel_hi:[0,1]
	s_waitcnt vmcnt(1)
	ds_write_b128 v167, v[4:7]
	s_waitcnt vmcnt(0)
	ds_write_b128 v167, v[8:11] offset:1152
	ds_read_b64 v[4:5], v209
	ds_read_b64 v[76:77], v209 offset:32
	ds_read_b64 v[78:79], v209 offset:64
	ds_read_b64 v[84:85], v209 offset:96
	v_mul_f32_e32 v12, v56, v56
	v_mul_f32_e32 v14, v57, v57
	v_pk_add_f32 v[12:13], v[12:13], v[14:15]
	s_waitcnt lgkmcnt(3)
	v_and_b32_e32 v7, 0xffff0000, v4
	v_mul_f32_e32 v8, 0xbfb8aa3b, v7
	v_exp_f32_e32 v10, v8
	v_and_b32_e32 v11, 0xffff0000, v5
	v_pk_add_f32 v[8:9], v[72:73], v[74:75]
	s_waitcnt lgkmcnt(2)
; #define LAS __attribute__((address_space(3)))
; DI unsigned pk2(float lo, float hi) { f32x2_t v = {lo, hi}; bf16x2_t b = __builtin_convertvector(v, bf16x2_t); return __builtin_bit_cast(unsigned, b); }
; DI float silu_f(float x) { return x * __builtin_amdgcn_rcpf(1.f + __expf(-x)); }
; DI void mixerB2_unit(int u, int l, const bf16* PROJ, bf16* YC, const float* dlam_l, const float* dnw_l, const float* kmax_l, LAS char* lds, int tid, int wave, int lane) {
;     ...
;     for (int qt = 0; qt < 2; ++qt) {
;         const int tok0 = q0w + 16 * qt;
;         const float i1 = 1.f / ol1[qt][0], i2 = lam / ol2[qt][0];
;         f32x4 o[4]; float ss = 0.f;
; #pragma unroll
;         for (int c = 0; c < 4; ++c) { o[c] = o1[qt][c] * i1 - o2[qt][c] * i2; ss += (o[c][0] * o[c][0] + o[c][1] * o[c][1]) + (o[c][2] * o[c][2] + o[c][3] * o[c][3]); }
;         ss += __shfl_xor(ss, 16); ss += __shfl_xor(ss, 32);
;         const float rstd = rsqrtf(ss * (1.f / 64.f) + EPS) * (1.f - lam_init);
;         rows16_load(sc, gbase, 64, tok0, 1, lane);
;         u32x2 gv[4];
; #pragma unroll
;         for (int c = 0; c < 4; ++c) gv[c] = *(const LAS u32x2*)(sc + r * VT_PITCH + (16 * c + 4 * g) * 2);
; #pragma unroll
;         for (int c = 0; c < 4; ++c) { const int dd = 16 * c + 4 * g;
;             const f32x4 nw = *(const f32x4*)(dnw_l + dd);
;             const f32x4 y = o[c] * rstd * nw;
;             u32x2 w; w.x = pk2(y[0] * silu_f(bflo(gv[c].x)), y[1] * silu_f(bfhi(gv[c].x))); w.y = pk2(y[2] * silu_f(bflo(gv[c].y)), y[3] * silu_f(bfhi(gv[c].y)));
	v_lshlrev_b32_e32 v72, 16, v77
	v_add_f32_e32 v53, 1.0, v10
	v_lshlrev_b32_e32 v10, 16, v5
	v_mul_f32_e32 v5, 0xbfb8aa3b, v10
	v_exp_f32_e32 v68, v5
	v_mul_f32_e32 v5, 0xbfb8aa3b, v11
	v_exp_f32_e32 v69, v5
	v_rcp_f32_e32 v5, v53
	v_add_f32_e32 v53, 1.0, v68
	v_rcp_f32_e32 v70, v53
	v_add_f32_e32 v53, 1.0, v69
	v_rcp_f32_e32 v71, v53
	v_and_b32_e32 v73, 0xffff0000, v77
	v_mul_f32_e32 v53, 0xbfb8aa3b, v72
	v_lshlrev_b32_e32 v6, 16, v4
	v_exp_f32_e32 v53, v53
	v_mul_f32_e32 v74, 0xbfb8aa3b, v73
	v_mul_f32_e32 v4, 0xbfb8aa3b, v6
	v_exp_f32_e32 v75, v74
	v_exp_f32_e32 v4, v4
	v_pk_add_f32 v[88:89], v[8:9], v[12:13]
	v_lshlrev_b32_e32 v12, 16, v76
	v_and_b32_e32 v13, 0xffff0000, v76
	v_add_f32_e32 v53, 1.0, v53
	s_waitcnt lgkmcnt(1)
	v_lshlrev_b32_e32 v76, 16, v78
	v_rcp_f32_e32 v74, v53
	v_add_f32_e32 v53, 1.0, v75
	v_and_b32_e32 v77, 0xffff0000, v78
	v_mul_f32_e32 v75, 0xbfb8aa3b, v76
	v_add_f32_e32 v4, 1.0, v4
	v_exp_f32_e32 v78, v75
	v_mul_f32_e32 v75, 0xbfb8aa3b, v77
	v_rcp_f32_e32 v4, v4
	v_exp_f32_e32 v92, v75
	v_rcp_f32_e32 v75, v53
	v_add_f32_e32 v53, 1.0, v78
	v_pk_mul_f32 v[68:69], v[4:5], v[6:7]
	v_mul_f32_e32 v4, 0xbfb8aa3b, v12
	v_rcp_f32_e32 v78, v53
	v_add_f32_e32 v53, 1.0, v92
	v_lshlrev_b32_e32 v92, 16, v79
	v_exp_f32_e32 v14, v4
	v_mul_f32_e32 v4, 0xbfb8aa3b, v13
	v_and_b32_e32 v93, 0xffff0000, v79
	v_mul_f32_e32 v79, 0xbfb8aa3b, v92
	v_pk_mul_f32 v[70:71], v[70:71], v[10:11]
	v_exp_f32_e32 v15, v4
	global_load_dwordx4 v[8:11], v[174:175], off
	global_load_dwordx4 v[4:7], v[174:175], off offset:64
	v_exp_f32_e32 v94, v79
	v_mul_f32_e32 v79, 0xbfb8aa3b, v93
	v_exp_f32_e32 v95, v79
	v_rcp_f32_e32 v79, v53
	v_add_f32_e32 v53, 1.0, v94
	v_rcp_f32_e32 v94, v53
	v_add_f32_e32 v53, 1.0, v95
	v_add_f32_e32 v14, 1.0, v14
	v_add_f32_e32 v15, 1.0, v15
	v_rcp_f32_e32 v95, v53
	v_rcp_f32_e32 v14, v14
	v_rcp_f32_e32 v15, v15
	v_pk_mul_f32 v[98:99], v[74:75], v[72:73]
	v_pk_mul_f32 v[100:101], v[78:79], v[76:77]
	global_load_dwordx4 v[72:75], v[174:175], off offset:128
	global_load_dwordx4 v[76:79], v[174:175], off offset:192
	v_pk_mul_f32 v[92:93], v[94:95], v[92:93]
	s_waitcnt lgkmcnt(0)
	v_lshlrev_b32_e32 v94, 16, v84
	v_pk_mul_f32 v[96:97], v[14:15], v[12:13]
	v_and_b32_e32 v95, 0xffff0000, v84
	v_mul_f32_e32 v12, 0xbfb8aa3b, v94
	v_exp_f32_e32 v12, v12
	v_mul_f32_e32 v13, 0xbfb8aa3b, v95
	v_exp_f32_e32 v13, v13
	v_lshlrev_b32_e32 v84, 16, v85
	v_add_f32_e32 v12, 1.0, v12
	v_rcp_f32_e32 v102, v12
	v_add_f32_e32 v12, 1.0, v13
	v_div_scale_f32 v13, s[20:21], v52, v52, 1.0
	v_rcp_f32_e32 v14, v13
	v_rcp_f32_e32 v103, v12
	v_and_b32_e32 v85, 0xffff0000, v85
	s_add_i32 s30, s30, s56
	v_fma_f32 v12, -v13, v14, 1.0
	v_fmac_f32_e32 v14, v12, v14
	v_div_scale_f32 v12, vcc, 1.0, v52, 1.0
	v_mul_f32_e32 v15, v12, v14
	v_fma_f32 v53, -v13, v15, v12
	v_fmac_f32_e32 v15, v53, v14
	v_fma_f32 v12, -v13, v15, v12
	v_div_scale_f32 v13, s[20:21], v48, v48, v49
	v_rcp_f32_e32 v53, v13
	v_div_fmas_f32 v12, v12, v14, v15
	v_div_fixup_f32 v14, v12, v52, 1.0
	s_mov_b32 s20, 0x3c800000
	v_fma_f32 v12, -v13, v53, 1.0
	v_fmac_f32_e32 v53, v12, v53
	v_div_scale_f32 v12, vcc, v49, v48, v49
	v_mul_f32_e32 v15, v12, v53
	v_fma_f32 v52, -v13, v15, v12
	v_fmac_f32_e32 v15, v52, v53
	v_fma_f32 v12, -v13, v15, v12
	v_div_fmas_f32 v12, v12, v53, v15
	v_div_fixup_f32 v12, v12, v48, v49
	v_pk_mul_f32 v[34:35], v[34:35], v[12:13] op_sel_hi:[1,0]
	v_pk_mul_f32 v[32:33], v[32:33], v[12:13] op_sel_hi:[1,0]
	v_pk_fma_f32 v[34:35], v[14:15], v[46:47], v[34:35] op_sel_hi:[0,1,1] neg_lo:[0,0,1] neg_hi:[0,0,1]
	v_pk_fma_f32 v[32:33], v[14:15], v[44:45], v[32:33] op_sel_hi:[0,1,1] neg_lo:[0,0,1] neg_hi:[0,0,1]
	v_pk_mul_f32 v[26:27], v[26:27], v[12:13] op_sel_hi:[1,0]
	v_pk_mul_f32 v[24:25], v[24:25], v[12:13] op_sel_hi:[1,0]
	v_pk_mul_f32 v[44:45], v[34:35], v[34:35]
	v_pk_mul_f32 v[46:47], v[32:33], v[32:33]
	v_pk_fma_f32 v[24:25], v[14:15], v[40:41], v[24:25] op_sel_hi:[0,1,1] neg_lo:[0,0,1] neg_hi:[0,0,1]
	v_pk_fma_f32 v[26:27], v[14:15], v[42:43], v[26:27] op_sel_hi:[0,1,1] neg_lo:[0,0,1] neg_hi:[0,0,1]
	v_pk_mov_b32 v[48:49], v[46:47], v[44:45] op_sel:[1,0]
	v_mov_b32_e32 v47, v45
	v_pk_mul_f32 v[40:41], v[26:27], v[26:27]
	v_pk_mul_f32 v[42:43], v[24:25], v[24:25]
	v_pk_add_f32 v[44:45], v[48:49], v[46:47]
	v_pk_mov_b32 v[46:47], v[42:43], v[40:41] op_sel:[1,0]
	v_mov_b32_e32 v43, v41
	v_pk_add_f32 v[40:41], v[46:47], v[42:43]
	v_pk_mul_f32 v[42:43], v[20:21], v[12:13] op_sel_hi:[1,0]
	v_pk_mul_f32 v[20:21], v[22:23], v[12:13] op_sel_hi:[1,0]
	v_pk_fma_f32 v[22:23], v[14:15], v[36:37], v[42:43] op_sel_hi:[0,1,1] neg_lo:[0,0,1] neg_hi:[0,0,1]
	v_mul_f32_e32 v36, v22, v22
	v_pk_fma_f32 v[20:21], v[14:15], v[38:39], v[20:21] op_sel_hi:[0,1,1] neg_lo:[0,0,1] neg_hi:[0,0,1]
	v_pk_fma_f32 v[36:37], v[22:23], v[22:23], v[36:37] op_sel_hi:[1,1,0]
	v_pk_mul_f32 v[16:17], v[16:17], v[12:13] op_sel_hi:[1,0]
	v_mul_f32_e32 v36, v20, v20
	v_pk_mul_f32 v[12:13], v[18:19], v[12:13] op_sel_hi:[1,0]
	v_pk_add_f32 v[44:45], v[44:45], v[44:45] op_sel_hi:[0,1]
	v_pk_add_f32 v[40:41], v[40:41], v[40:41] op_sel_hi:[0,1]
	v_pk_fma_f32 v[38:39], v[20:21], v[20:21], v[36:37] op_sel_hi:[1,1,0]
	v_pk_fma_f32 v[12:13], v[14:15], v[30:31], v[12:13] op_sel_hi:[0,1,1] neg_lo:[0,0,1] neg_hi:[0,0,1]
	v_pk_fma_f32 v[14:15], v[14:15], v[28:29], v[16:17] op_sel_hi:[0,1,1] neg_lo:[0,0,1] neg_hi:[0,0,1]
	v_mul_f32_e32 v36, v14, v14
	v_mul_f32_e32 v38, v15, v15
	v_mul_f32_e32 v44, v12, v12
	v_mul_f32_e32 v40, v13, v13
	v_pk_add_f32 v[16:17], v[36:37], v[38:39]
	v_pk_add_f32 v[18:19], v[44:45], v[40:41]
	v_mul_f32_e32 v28, 0xbfb8aa3b, v84
	v_pk_add_f32 v[16:17], v[16:17], v[18:19]
	v_mov_b32_e32 v19, v88
	v_mov_b32_e32 v18, v16
	v_mov_b32_e32 v88, v17
	v_pk_add_f32 v[16:17], v[18:19], v[88:89]
	ds_bpermute_b32 v19, v184, v17
	ds_bpermute_b32 v18, v184, v16
	v_mul_f32_e32 v29, 0xbfb8aa3b, v85
	v_exp_f32_e32 v28, v28
	v_exp_f32_e32 v29, v29
	s_cmpk_gt_i32 s31, 0xff
	s_waitcnt lgkmcnt(0)
; #define LAS __attribute__((address_space(3)))
; DI unsigned pk2(float lo, float hi) { f32x2_t v = {lo, hi}; bf16x2_t b = __builtin_convertvector(v, bf16x2_t); return __builtin_bit_cast(unsigned, b); }
; DI float silu_f(float x) { return x * __builtin_amdgcn_rcpf(1.f + __expf(-x)); }
; DI void mixerB2_unit(int u, int l, const bf16* PROJ, bf16* YC, const float* dlam_l, const float* dnw_l, const float* kmax_l, LAS char* lds, int tid, int wave, int lane) {
;     ...
;         const float i1 = 1.f / ol1[qt][0], i2 = lam / ol2[qt][0];
;         f32x4 o[4]; float ss = 0.f;
; #pragma unroll
;         for (int c = 0; c < 4; ++c) { o[c] = o1[qt][c] * i1 - o2[qt][c] * i2; ss += (o[c][0] * o[c][0] + o[c][1] * o[c][1]) + (o[c][2] * o[c][2] + o[c][3] * o[c][3]); }
;         ss += __shfl_xor(ss, 16); ss += __shfl_xor(ss, 32);
;         const float rstd = rsqrtf(ss * (1.f / 64.f) + EPS) * (1.f - lam_init);
;         rows16_load(sc, gbase, 64, tok0, 1, lane);
;         u32x2 gv[4];
; #pragma unroll
;         for (int c = 0; c < 4; ++c) gv[c] = *(const LAS u32x2*)(sc + r * VT_PITCH + (16 * c + 4 * g) * 2);
; #pragma unroll
;         for (int c = 0; c < 4; ++c) { const int dd = 16 * c + 4 * g;
;             const f32x4 nw = *(const f32x4*)(dnw_l + dd);
;             const f32x4 y = o[c] * rstd * nw;
;             u32x2 w; w.x = pk2(y[0] * silu_f(bflo(gv[c].x)), y[1] * silu_f(bfhi(gv[c].x))); w.y = pk2(y[2] * silu_f(bflo(gv[c].y)), y[3] * silu_f(bfhi(gv[c].y)));
;             *(LAS u32x2*)(sc + r * VT_PITCH + dd * 2) = w; }
;         rows16_store(sc, YC + (size_t)b * T * 1024 + 256 + h * 64, 1024, tok0, 1, lane);
	v_pk_add_f32 v[16:17], v[16:17], v[18:19]
	ds_bpermute_b32 v19, v185, v17
	ds_bpermute_b32 v18, v185, v16
	v_add_f32_e32 v28, 1.0, v28
	v_add_f32_e32 v29, 1.0, v29
	v_rcp_f32_e32 v28, v28
	v_rcp_f32_e32 v29, v29
	s_waitcnt lgkmcnt(0)
	v_pk_add_f32 v[16:17], v[16:17], v[18:19]
	v_pk_mul_f32 v[18:19], v[28:29], v[84:85]
	v_pk_fma_f32 v[44:45], v[16:17], s[20:21], v[190:191] op_sel_hi:[1,0,0]
	v_lshlrev_b64 v[28:29], 11, v[90:91]
	v_mul_f32_e32 v16, 0x4b800000, v45
	v_cmp_gt_f32_e32 vcc, s15, v45
	s_nop 1
	v_cndmask_b32_e32 v16, v45, v16, vcc
	v_rsq_f32_e32 v30, v16
	v_pk_mul_f32 v[16:17], v[102:103], v[94:95]
	v_mul_f32_e32 v45, 0x4b800000, v44
	v_mul_f32_e32 v31, 0x45800000, v30
	v_cndmask_b32_e32 v30, v30, v31, vcc
	v_mul_f32_e32 v30, v206, v30
	v_pk_mul_f32 v[36:37], v[80:81], v[30:31] op_sel_hi:[1,0]
	v_pk_mul_f32 v[38:39], v[82:83], v[30:31] op_sel_hi:[1,0]
	s_waitcnt vmcnt(3)
	v_pk_mul_f32 v[8:9], v[8:9], v[36:37]
	v_pk_mul_f32 v[10:11], v[10:11], v[38:39]
	v_pk_mul_f32 v[8:9], v[68:69], v[8:9]
	v_pk_mul_f32 v[10:11], v[70:71], v[10:11]
	v_cvt_pk_bf16_f32 v8, v8, v9
	v_cvt_pk_bf16_f32 v9, v10, v11
	ds_write_b64 v209, v[8:9]
	v_pk_mul_f32 v[8:9], v[64:65], v[30:31] op_sel_hi:[1,0]
	v_pk_mul_f32 v[10:11], v[66:67], v[30:31] op_sel_hi:[1,0]
	s_waitcnt vmcnt(2)
	v_pk_mul_f32 v[4:5], v[4:5], v[8:9]
	v_pk_mul_f32 v[6:7], v[6:7], v[10:11]
	v_pk_mul_f32 v[4:5], v[96:97], v[4:5]
	v_pk_mul_f32 v[6:7], v[98:99], v[6:7]
	v_cvt_pk_bf16_f32 v4, v4, v5
	v_cvt_pk_bf16_f32 v5, v6, v7
	ds_write_b64 v210, v[4:5]
	v_pk_mul_f32 v[4:5], v[62:63], v[30:31] op_sel_hi:[1,0]
	v_pk_mul_f32 v[6:7], v[60:61], v[30:31] op_sel_hi:[1,0]
	s_waitcnt vmcnt(1)
	v_pk_mul_f32 v[4:5], v[72:73], v[4:5]
	v_pk_mul_f32 v[6:7], v[74:75], v[6:7]
	v_pk_mul_f32 v[4:5], v[100:101], v[4:5]
	v_pk_mul_f32 v[6:7], v[92:93], v[6:7]
	v_cvt_pk_bf16_f32 v4, v4, v5
	v_cvt_pk_bf16_f32 v5, v6, v7
	ds_write_b64 v211, v[4:5]
	v_pk_mul_f32 v[4:5], v[58:59], v[30:31] op_sel_hi:[1,0]
	v_pk_mul_f32 v[6:7], v[56:57], v[30:31] op_sel_hi:[1,0]
	s_waitcnt vmcnt(0)
	v_pk_mul_f32 v[4:5], v[76:77], v[4:5]
	v_pk_mul_f32 v[6:7], v[78:79], v[6:7]
	v_pk_mul_f32 v[4:5], v[16:17], v[4:5]
	v_pk_mul_f32 v[6:7], v[18:19], v[6:7]
	v_cvt_pk_bf16_f32 v4, v4, v5
	v_cvt_pk_bf16_f32 v5, v6, v7
	ds_write_b64 v212, v[4:5]
	ds_read_b128 v[4:7], v167
	ds_read_b128 v[8:11], v167 offset:1152
	v_lshl_add_u64 v[16:17], v[50:51], 0, v[28:29]
	v_lshlrev_b64 v[18:19], 11, v[54:55]
	v_lshl_add_u64 v[18:19], v[50:51], 0, v[18:19]
	s_waitcnt lgkmcnt(1)
	global_store_dwordx4 v[16:17], v[4:7], off offset:512 sc1
	s_waitcnt lgkmcnt(0)
	global_store_dwordx4 v[18:19], v[8:11], off offset:512 sc1
	v_or_b32_e32 v4, s0, v207
	v_ashrrev_i32_e32 v5, 31, v4
	v_lshlrev_b64 v[6:7], 7, v[4:5]
	v_lshl_add_u64 v[8:9], v[86:87], 0, v[6:7]
	v_or_b32_e32 v6, s0, v208
	v_ashrrev_i32_e32 v7, 31, v6
	v_lshlrev_b64 v[10:11], 7, v[6:7]
	v_lshl_add_u64 v[16:17], v[86:87], 0, v[10:11]
	global_load_dwordx4 v[8:11], v[8:9], off
	s_nop 0
	global_load_dwordx4 v[16:19], v[16:17], off
	s_nop 0
	global_load_dwordx4 v[28:31], v[174:175], off
	global_load_dwordx4 v[36:39], v[174:175], off offset:64
	v_cmp_gt_f32_e32 vcc, s15, v44
	global_load_dwordx4 v[40:43], v[174:175], off offset:128
	s_waitcnt vmcnt(4)
	ds_write_b128 v167, v[8:11]
	s_waitcnt vmcnt(3)
	ds_write_b128 v167, v[16:19] offset:1152
	v_cndmask_b32_e32 v44, v44, v45, vcc
	v_rsq_f32_e32 v44, v44
	v_lshlrev_b64 v[4:5], 11, v[4:5]
	v_lshl_add_u64 v[4:5], v[50:51], 0, v[4:5]
	v_mul_f32_e32 v45, 0x45800000, v44
	v_cndmask_b32_e32 v46, v44, v45, vcc
	ds_read_b64 v[8:9], v209
	ds_read_b64 v[16:17], v209 offset:32
	ds_read_b64 v[18:19], v209 offset:64
	ds_read_b64 v[44:45], v209 offset:96
	v_mul_f32_e32 v46, v206, v46
	v_pk_mul_f32 v[10:11], v[32:33], v[46:47] op_sel_hi:[1,0]
	v_pk_mul_f32 v[32:33], v[34:35], v[46:47] op_sel_hi:[1,0]
	s_waitcnt vmcnt(2)
	v_pk_mul_f32 v[28:29], v[28:29], v[10:11]
	v_pk_mul_f32 v[30:31], v[30:31], v[32:33]
	s_waitcnt lgkmcnt(3)
; #define LAS __attribute__((address_space(3)))
; DI unsigned pk2(float lo, float hi) { f32x2_t v = {lo, hi}; bf16x2_t b = __builtin_convertvector(v, bf16x2_t); return __builtin_bit_cast(unsigned, b); }
; DI float silu_f(float x) { return x * __builtin_amdgcn_rcpf(1.f + __expf(-x)); }
; DI void mixerB2_unit(int u, int l, const bf16* PROJ, bf16* YC, const float* dlam_l, const float* dnw_l, const float* kmax_l, LAS char* lds, int tid, int wave, int lane) {
;     ...
;         rows16_load(sc, gbase, 64, tok0, 1, lane);
;         u32x2 gv[4];
; #pragma unroll
;         for (int c = 0; c < 4; ++c) gv[c] = *(const LAS u32x2*)(sc + r * VT_PITCH + (16 * c + 4 * g) * 2);
; #pragma unroll
;         for (int c = 0; c < 4; ++c) { const int dd = 16 * c + 4 * g;
;             const f32x4 nw = *(const f32x4*)(dnw_l + dd);
;             const f32x4 y = o[c] * rstd * nw;
;             u32x2 w; w.x = pk2(y[0] * silu_f(bflo(gv[c].x)), y[1] * silu_f(bfhi(gv[c].x))); w.y = pk2(y[2] * silu_f(bflo(gv[c].y)), y[3] * silu_f(bfhi(gv[c].y)));
;             *(LAS u32x2*)(sc + r * VT_PITCH + dd * 2) = w; }
;         rows16_store(sc, YC + (size_t)b * T * 1024 + 256 + h * 64, 1024, tok0, 1, lane);
	v_lshlrev_b32_e32 v32, 16, v8
	v_and_b32_e32 v33, 0xffff0000, v8
	v_mul_f32_e32 v8, 0xbfb8aa3b, v32
	v_exp_f32_e32 v8, v8
	v_mul_f32_e32 v34, 0xbfb8aa3b, v33
	v_exp_f32_e32 v35, v34
	v_lshlrev_b32_e32 v48, 16, v9
	v_add_f32_e32 v8, 1.0, v8
	v_rcp_f32_e32 v34, v8
	v_and_b32_e32 v49, 0xffff0000, v9
	global_load_dwordx4 v[8:11], v[174:175], off offset:192
	v_mul_f32_e32 v47, 0xbfb8aa3b, v48
	v_exp_f32_e32 v47, v47
	v_mul_f32_e32 v52, 0xbfb8aa3b, v49
	v_exp_f32_e32 v53, v52
	v_add_f32_e32 v35, 1.0, v35
	v_add_f32_e32 v47, 1.0, v47
	v_rcp_f32_e32 v35, v35
	v_rcp_f32_e32 v52, v47
	v_add_f32_e32 v47, 1.0, v53
	v_rcp_f32_e32 v53, v47
	v_pk_mul_f32 v[32:33], v[34:35], v[32:33]
	v_pk_mul_f32 v[24:25], v[24:25], v[46:47] op_sel_hi:[1,0]
	v_pk_mul_f32 v[28:29], v[32:33], v[28:29]
	v_pk_mul_f32 v[32:33], v[52:53], v[48:49]
	v_cvt_pk_bf16_f32 v28, v28, v29
	v_pk_mul_f32 v[30:31], v[32:33], v[30:31]
	v_pk_mul_f32 v[26:27], v[26:27], v[46:47] op_sel_hi:[1,0]
	v_cvt_pk_bf16_f32 v29, v30, v31
	ds_write_b64 v209, v[28:29]
	s_waitcnt lgkmcnt(3)
	v_and_b32_e32 v29, 0xffff0000, v16
	v_mul_f32_e32 v30, 0xbfb8aa3b, v29
	v_exp_f32_e32 v30, v30
	v_lshlrev_b32_e32 v28, 16, v16
	v_mul_f32_e32 v16, 0xbfb8aa3b, v28
	v_and_b32_e32 v31, 0xffff0000, v17
	v_add_f32_e32 v32, 1.0, v30
	v_lshlrev_b32_e32 v30, 16, v17
	v_mul_f32_e32 v17, 0xbfb8aa3b, v30
	v_exp_f32_e32 v16, v16
	v_exp_f32_e32 v33, v17
	v_mul_f32_e32 v17, 0xbfb8aa3b, v31
	v_exp_f32_e32 v34, v17
	v_add_f32_e32 v16, 1.0, v16
	v_rcp_f32_e32 v16, v16
	v_rcp_f32_e32 v17, v32
	v_add_f32_e32 v32, 1.0, v33
	v_add_f32_e32 v33, 1.0, v34
	v_rcp_f32_e32 v32, v32
	v_rcp_f32_e32 v33, v33
	s_waitcnt vmcnt(2)
	v_pk_mul_f32 v[24:25], v[36:37], v[24:25]
	v_pk_mul_f32 v[16:17], v[16:17], v[28:29]
	v_pk_mul_f32 v[26:27], v[38:39], v[26:27]
	v_pk_mul_f32 v[16:17], v[16:17], v[24:25]
	v_pk_mul_f32 v[24:25], v[32:33], v[30:31]
	v_cvt_pk_bf16_f32 v16, v16, v17
	v_pk_mul_f32 v[24:25], v[24:25], v[26:27]
	v_pk_mul_f32 v[20:21], v[20:21], v[46:47] op_sel_hi:[1,0]
	v_cvt_pk_bf16_f32 v17, v24, v25
	ds_write_b64 v210, v[16:17]
	v_pk_mul_f32 v[16:17], v[22:23], v[46:47] op_sel_hi:[1,0]
	s_waitcnt lgkmcnt(3)
	v_and_b32_e32 v23, 0xffff0000, v18
	v_mul_f32_e32 v24, 0xbfb8aa3b, v23
	v_exp_f32_e32 v24, v24
	v_lshlrev_b32_e32 v22, 16, v18
	v_mul_f32_e32 v18, 0xbfb8aa3b, v22
	v_and_b32_e32 v25, 0xffff0000, v19
	v_add_f32_e32 v26, 1.0, v24
	v_lshlrev_b32_e32 v24, 16, v19
	v_mul_f32_e32 v19, 0xbfb8aa3b, v24
	v_exp_f32_e32 v18, v18
	v_exp_f32_e32 v27, v19
	v_mul_f32_e32 v19, 0xbfb8aa3b, v25
	v_exp_f32_e32 v28, v19
	v_add_f32_e32 v18, 1.0, v18
	v_rcp_f32_e32 v18, v18
	v_rcp_f32_e32 v19, v26
	v_add_f32_e32 v26, 1.0, v27
	v_add_f32_e32 v27, 1.0, v28
	v_rcp_f32_e32 v26, v26
	v_rcp_f32_e32 v27, v27
	s_waitcnt vmcnt(1)
	v_pk_mul_f32 v[16:17], v[40:41], v[16:17]
	v_pk_mul_f32 v[18:19], v[18:19], v[22:23]
	v_pk_mul_f32 v[20:21], v[42:43], v[20:21]
	v_pk_mul_f32 v[16:17], v[16:17], v[18:19]
	v_pk_mul_f32 v[18:19], v[26:27], v[24:25]
	v_pk_mul_f32 v[12:13], v[12:13], v[46:47] op_sel_hi:[1,0]
	v_pk_mul_f32 v[18:19], v[20:21], v[18:19]
	v_cvt_pk_bf16_f32 v16, v16, v17
	v_cvt_pk_bf16_f32 v17, v18, v19
	s_waitcnt vmcnt(0)
	v_pk_mul_f32 v[10:11], v[12:13], v[10:11]
	s_waitcnt lgkmcnt(2)
	v_lshlrev_b32_e32 v12, 16, v44
	v_and_b32_e32 v13, 0xffff0000, v44
	ds_write_b64 v211, v[16:17]
	v_mul_f32_e32 v16, 0xbfb8aa3b, v12
	v_mul_f32_e32 v17, 0xbfb8aa3b, v13
	v_exp_f32_e32 v16, v16
	v_exp_f32_e32 v17, v17
	v_pk_mul_f32 v[14:15], v[14:15], v[46:47] op_sel_hi:[1,0]
	s_nop 0
	v_pk_mul_f32 v[8:9], v[14:15], v[8:9]
	v_add_f32_e32 v14, 1.0, v16
	v_add_f32_e32 v15, 1.0, v17
	v_lshlrev_b32_e32 v16, 16, v45
	v_and_b32_e32 v17, 0xffff0000, v45
	v_mul_f32_e32 v18, 0xbfb8aa3b, v16
	v_mul_f32_e32 v19, 0xbfb8aa3b, v17
	v_exp_f32_e32 v18, v18
	v_exp_f32_e32 v19, v19
	v_rcp_f32_e32 v14, v14
	v_rcp_f32_e32 v15, v15
	v_add_f32_e32 v18, 1.0, v18
	v_add_f32_e32 v19, 1.0, v19
	v_rcp_f32_e32 v18, v18
	v_rcp_f32_e32 v19, v19
	v_pk_mul_f32 v[12:13], v[14:15], v[12:13]
	s_nop 0
	v_pk_mul_f32 v[8:9], v[12:13], v[8:9]
	v_pk_mul_f32 v[12:13], v[18:19], v[16:17]
	v_cvt_pk_bf16_f32 v8, v8, v9
	v_pk_mul_f32 v[10:11], v[12:13], v[10:11]
	s_nop 0
	v_cvt_pk_bf16_f32 v9, v10, v11
	ds_write_b64 v212, v[8:9]
	ds_read_b128 v[8:11], v167
	ds_read_b128 v[12:15], v167 offset:1152
	s_waitcnt lgkmcnt(1)
	global_store_dwordx4 v[4:5], v[8:11], off offset:512 sc1
	v_lshlrev_b64 v[4:5], 11, v[6:7]
	v_lshl_add_u64 v[4:5], v[50:51], 0, v[4:5]
	s_waitcnt lgkmcnt(0)
	global_store_dwordx4 v[4:5], v[12:15], off offset:512 sc1
	s_cbranch_scc1 .LBB0_262

; #define LAS __attribute__((address_space(3)))
; #define MFMA16(a, b, c) __builtin_amdgcn_mfma_f32_16x16x32_bf16((a), (b), (c), 0, 0, 0)
; DI unsigned pk2(float lo, float hi) { f32x2_t v = {lo, hi}; bf16x2_t b = __builtin_convertvector(v, bf16x2_t); return __builtin_bit_cast(unsigned, b); }
; DI s16x4 vtr(const LAS char* p) { return __builtin_bit_cast(s16x4, __builtin_amdgcn_ds_read_tr16_b64_v4i16((LAS s16x4*)p)); }
; DI bf16x8 cat8(s16x4 lo, s16x4 hi) { return __builtin_shufflevector(lo, hi, 0, 1, 2, 3, 4, 5, 6, 7); }
; DI void ssd_part1_unit(int u, const bf16* PROJ, float* DT, const bf16* H, const bf16* wdtb_l, const float* dt_bias_l, const float* cw, const float* cb, const float* a_log_l, float* STATES, float* TOT,
;                        LAS unsigned char* ldsu, int tid, int wave, int lane) {
;     ...
;     __syncthreads();
;     bf16x8 bfr[4];
; #pragma unroll
;     for (int ks = 0; ks < 4; ++ks) { const LAS char* bp = BM + (32 * ks + 8 * g + q) * IMG_PITCH + 32 * wave + 8 * p; bfr[ks] = cat8(vtr(bp), vtr(bp + 4 * IMG_PITCH)); }
; #pragma unroll
;     for (int combo = 0; combo < 4; ++combo) {
;         const int hh = combo >> 1, dir = combo & 1, h = 2 * grp + hh;
;         f32x4 acc[4];
; #pragma unroll
;         for (int pt = 0; pt < 4; ++pt) acc[pt] = (f32x4){0.f, 0.f, 0.f, 0.f};
; #pragma unroll
;         for (int ks = 0; ks < 4; ++ks) {
;             const f32x4 w0 = *(const LAS f32x4*)(wtab + combo * 128 + 32 * ks + 8 * g), w1 = *(const LAS f32x4*)(wtab + combo * 128 + 32 * ks + 8 * g + 4);
; #pragma unroll
;             for (int pt = 0; pt < 4; ++pt) {
;                 const LAS char* xp = XS + (32 * ks + 8 * g + q) * IMG_PITCH + (hh * 64 + 16 * pt) * 2 + 8 * p;
;                 const u32x2 lo = __builtin_bit_cast(u32x2, vtr(xp)), hi = __builtin_bit_cast(u32x2, vtr(xp + 4 * IMG_PITCH));
;                 u32x4 af; af.x = pk2(bflo(lo.x) * w0[0], bfhi(lo.x) * w0[1]); af.y = pk2(bflo(lo.y) * w0[2], bfhi(lo.y) * w0[3]);
;                 af.z = pk2(bflo(hi.x) * w1[0], bfhi(hi.x) * w1[1]); af.w = pk2(bflo(hi.y) * w1[2], bfhi(hi.y) * w1[3]);
;                 acc[pt] = MFMA16(__builtin_bit_cast(bf16x8, af), bfr[ks], acc[pt]);
;             }
;         }
.LBB0_265:
	s_waitcnt lgkmcnt(0)
	s_barrier
	ds_read_b64_tr_b16 v[16:17], v243 offset:34816
	ds_read_b64_tr_b16 v[18:19], v243 offset:35904
	ds_read_b64_tr_b16 v[12:13], v243 offset:43520
	ds_read_b64_tr_b16 v[14:15], v243 offset:44608
	ds_read_b64_tr_b16 v[8:9], v243 offset:52224
	ds_read_b64_tr_b16 v[10:11], v243 offset:53312
	ds_read_b64_tr_b16 v[4:5], v243 offset:60928
	ds_read_b64_tr_b16 v[6:7], v243 offset:62016
	ds_read_b128 v[28:31], v231
	ds_read_b128 v[24:27], v231 offset:16
	ds_read_b64_tr_b16 v[22:23], v232 offset:1088
	ds_read_b64_tr_b16 v[20:21], v232
	ds_read_b64_tr_b16 v[32:33], v232 offset:32
	s_lshl_b32 s0, s62, 6
	s_lshl_b32 s1, s34, 2
	s_waitcnt lgkmcnt(2)
	v_lshlrev_b32_e32 v64, 16, v22
	s_waitcnt lgkmcnt(1)
	v_lshlrev_b32_e32 v58, 16, v20
	v_and_b32_e32 v59, 0xffff0000, v20
	v_pk_mul_f32 v[34:35], v[28:29], v[58:59]
	v_lshlrev_b32_e32 v56, 16, v21
	v_and_b32_e32 v57, 0xffff0000, v21
	v_cvt_pk_bf16_f32 v20, v34, v35
	v_pk_mul_f32 v[34:35], v[30:31], v[56:57]
	v_and_b32_e32 v65, 0xffff0000, v22
	v_cvt_pk_bf16_f32 v21, v34, v35
	v_pk_mul_f32 v[34:35], v[24:25], v[64:65]
	v_lshlrev_b32_e32 v62, 16, v23
	v_and_b32_e32 v63, 0xffff0000, v23
	v_cvt_pk_bf16_f32 v22, v34, v35
	v_pk_mul_f32 v[34:35], v[26:27], v[62:63]
	s_waitcnt lgkmcnt(0)
	v_lshlrev_b32_e32 v52, 16, v32
	v_cvt_pk_bf16_f32 v23, v34, v35
	v_and_b32_e32 v53, 0xffff0000, v32
	v_lshlrev_b32_e32 v54, 16, v33
	v_mfma_f32_16x16x32_bf16 v[36:39], v[20:23], v[16:19], 0
	ds_read_b64_tr_b16 v[22:23], v232 offset:1120
	v_and_b32_e32 v55, 0xffff0000, v33
	v_pk_mul_f32 v[20:21], v[28:29], v[52:53]
	v_pk_mul_f32 v[32:33], v[30:31], v[54:55]
	v_cvt_pk_bf16_f32 v20, v20, v21
	s_waitcnt lgkmcnt(0)
	v_lshlrev_b32_e32 v60, 16, v22
	v_and_b32_e32 v61, 0xffff0000, v22
	v_cvt_pk_bf16_f32 v21, v32, v33
	v_pk_mul_f32 v[32:33], v[24:25], v[60:61]
	v_lshlrev_b32_e32 v66, 16, v23
	v_and_b32_e32 v67, 0xffff0000, v23
	v_cvt_pk_bf16_f32 v22, v32, v33
	v_pk_mul_f32 v[32:33], v[26:27], v[66:67]
	s_or_b32 s0, s1, s0
	v_cvt_pk_bf16_f32 v23, v32, v33
	ds_read_b64_tr_b16 v[32:33], v232 offset:64
	ds_read_b64_tr_b16 v[34:35], v232 offset:1152
	v_mfma_f32_16x16x32_bf16 v[20:23], v[20:23], v[16:19], 0
	s_waitcnt lgkmcnt(1)
	v_lshlrev_b32_e32 v68, 16, v32
	v_and_b32_e32 v69, 0xffff0000, v32
	v_pk_mul_f32 v[40:41], v[28:29], v[68:69]
	v_lshlrev_b32_e32 v70, 16, v33
	v_and_b32_e32 v71, 0xffff0000, v33
	v_cvt_pk_bf16_f32 v32, v40, v41
	v_pk_mul_f32 v[40:41], v[30:31], v[70:71]
	s_waitcnt lgkmcnt(0)
	v_lshlrev_b32_e32 v72, 16, v34
	v_and_b32_e32 v73, 0xffff0000, v34
	v_cvt_pk_bf16_f32 v33, v40, v41
	v_pk_mul_f32 v[40:41], v[24:25], v[72:73]
	v_lshlrev_b32_e32 v74, 16, v35
	v_and_b32_e32 v75, 0xffff0000, v35
	v_cvt_pk_bf16_f32 v34, v40, v41
	v_pk_mul_f32 v[40:41], v[26:27], v[74:75]
	s_or_b32 s0, s64, s0
	v_cvt_pk_bf16_f32 v35, v40, v41
	ds_read_b64_tr_b16 v[40:41], v232 offset:96
	ds_read_b64_tr_b16 v[42:43], v232 offset:1184
	v_mfma_f32_16x16x32_bf16 v[32:35], v[32:35], v[16:19], 0
	s_waitcnt lgkmcnt(1)
	v_lshlrev_b32_e32 v76, 16, v40
	v_and_b32_e32 v77, 0xffff0000, v40
	v_lshlrev_b32_e32 v78, 16, v41
	v_and_b32_e32 v79, 0xffff0000, v41
	s_waitcnt lgkmcnt(0)
	v_lshlrev_b32_e32 v84, 16, v42
	v_and_b32_e32 v85, 0xffff0000, v42
	v_pk_mul_f32 v[28:29], v[28:29], v[76:77]
	v_pk_mul_f32 v[30:31], v[30:31], v[78:79]
	v_pk_mul_f32 v[24:25], v[24:25], v[84:85]
	v_lshlrev_b32_e32 v90, 16, v43
	v_and_b32_e32 v91, 0xffff0000, v43
	v_cvt_pk_bf16_f32 v28, v28, v29
	v_cvt_pk_bf16_f32 v29, v30, v31
	v_cvt_pk_bf16_f32 v30, v24, v25
	v_pk_mul_f32 v[24:25], v[26:27], v[90:91]
	s_lshl_b32 s0, s0, 1
	v_cvt_pk_bf16_f32 v31, v24, v25
	s_ashr_i32 s1, s0, 31
	s_lshl_b64 s[60:61], s[0:1], 15
	v_mfma_f32_16x16x32_bf16 v[24:27], v[28:31], v[16:19], 0
	ds_read_b128 v[48:51], v231 offset:128
	ds_read_b128 v[44:47], v231 offset:144
	ds_read_b64_tr_b16 v[28:29], v232 offset:8704
	ds_read_b64_tr_b16 v[30:31], v232 offset:9792
	v_mov_b32_e32 v123, v189
	v_mov_b32_e32 v125, v189
	v_mov_b32_e32 v127, v189
	s_waitcnt lgkmcnt(1)
	v_lshlrev_b32_e32 v82, 16, v28
	v_and_b32_e32 v83, 0xffff0000, v28
	v_pk_mul_f32 v[40:41], v[48:49], v[82:83]
	v_lshlrev_b32_e32 v80, 16, v29
	v_and_b32_e32 v81, 0xffff0000, v29
	v_cvt_pk_bf16_f32 v28, v40, v41
	v_pk_mul_f32 v[40:41], v[50:51], v[80:81]
	s_waitcnt lgkmcnt(0)
	v_lshlrev_b32_e32 v88, 16, v30
	v_and_b32_e32 v89, 0xffff0000, v30
	v_cvt_pk_bf16_f32 v29, v40, v41
	v_pk_mul_f32 v[40:41], v[44:45], v[88:89]
	v_lshlrev_b32_e32 v86, 16, v31
	v_and_b32_e32 v87, 0xffff0000, v31
	v_cvt_pk_bf16_f32 v30, v40, v41
	v_pk_mul_f32 v[40:41], v[46:47], v[86:87]
	v_mov_b32_e32 v129, v189
	v_cvt_pk_bf16_f32 v31, v40, v41
	v_mov_b32_e32 v131, v189
	v_mov_b32_e32 v133, v189
	v_mfma_f32_16x16x32_bf16 v[28:31], v[28:31], v[12:15], v[36:39]
	s_nop 2
	ds_read_b64_tr_b16 v[36:37], v232 offset:8736
	ds_read_b64_tr_b16 v[38:39], v232 offset:9824
	v_mov_b32_e32 v135, v189
	v_mov_b32_e32 v137, v189
	v_mov_b32_e32 v139, v189
	s_waitcnt lgkmcnt(1)
	v_lshlrev_b32_e32 v92, 16, v36
	v_and_b32_e32 v93, 0xffff0000, v36
	v_pk_mul_f32 v[40:41], v[48:49], v[92:93]
	v_lshlrev_b32_e32 v94, 16, v37
	v_and_b32_e32 v95, 0xffff0000, v37
	v_cvt_pk_bf16_f32 v36, v40, v41
	v_pk_mul_f32 v[40:41], v[50:51], v[94:95]
	s_waitcnt lgkmcnt(0)
	v_lshlrev_b32_e32 v96, 16, v38
	v_and_b32_e32 v97, 0xffff0000, v38
	v_cvt_pk_bf16_f32 v37, v40, v41
	v_pk_mul_f32 v[40:41], v[44:45], v[96:97]
	v_lshlrev_b32_e32 v98, 16, v39
	v_and_b32_e32 v99, 0xffff0000, v39
	v_cvt_pk_bf16_f32 v38, v40, v41
	v_pk_mul_f32 v[40:41], v[46:47], v[98:99]
	v_mov_b32_e32 v141, v189
	v_cvt_pk_bf16_f32 v39, v40, v41
	v_mov_b32_e32 v143, v189
	v_mov_b32_e32 v145, v189
	v_mfma_f32_16x16x32_bf16 v[40:43], v[36:39], v[12:15], v[20:23]
	s_nop 2
	ds_read_b64_tr_b16 v[20:21], v232 offset:8768
	ds_read_b64_tr_b16 v[22:23], v232 offset:9856
	v_mov_b32_e32 v147, v189
	s_add_i32 s31, s31, s88
	s_waitcnt lgkmcnt(1)
; #define LAS __attribute__((address_space(3)))
; #define MFMA16(a, b, c) __builtin_amdgcn_mfma_f32_16x16x32_bf16((a), (b), (c), 0, 0, 0)
; DI unsigned pk2(float lo, float hi) { f32x2_t v = {lo, hi}; bf16x2_t b = __builtin_convertvector(v, bf16x2_t); return __builtin_bit_cast(unsigned, b); }
; DI s16x4 vtr(const LAS char* p) { return __builtin_bit_cast(s16x4, __builtin_amdgcn_ds_read_tr16_b64_v4i16((LAS s16x4*)p)); }
; DI void ssd_part1_unit(int u, const bf16* PROJ, float* DT, const bf16* H, const bf16* wdtb_l, const float* dt_bias_l, const float* cw, const float* cb, const float* a_log_l, float* STATES, float* TOT,
;                        LAS unsigned char* ldsu, int tid, int wave, int lane) {
;     ...
;         const int hh = combo >> 1, dir = combo & 1, h = 2 * grp + hh;
;         f32x4 acc[4];
; #pragma unroll
;         for (int pt = 0; pt < 4; ++pt) acc[pt] = (f32x4){0.f, 0.f, 0.f, 0.f};
; #pragma unroll
;         for (int ks = 0; ks < 4; ++ks) {
;             const f32x4 w0 = *(const LAS f32x4*)(wtab + combo * 128 + 32 * ks + 8 * g), w1 = *(const LAS f32x4*)(wtab + combo * 128 + 32 * ks + 8 * g + 4);
; #pragma unroll
;             for (int pt = 0; pt < 4; ++pt) {
;                 const LAS char* xp = XS + (32 * ks + 8 * g + q) * IMG_PITCH + (hh * 64 + 16 * pt) * 2 + 8 * p;
;                 const u32x2 lo = __builtin_bit_cast(u32x2, vtr(xp)), hi = __builtin_bit_cast(u32x2, vtr(xp + 4 * IMG_PITCH));
;                 u32x4 af; af.x = pk2(bflo(lo.x) * w0[0], bfhi(lo.x) * w0[1]); af.y = pk2(bflo(lo.y) * w0[2], bfhi(lo.y) * w0[3]);
;                 af.z = pk2(bflo(hi.x) * w1[0], bfhi(hi.x) * w1[1]); af.w = pk2(bflo(hi.y) * w1[2], bfhi(hi.y) * w1[3]);
;                 acc[pt] = MFMA16(__builtin_bit_cast(bf16x8, af), bfr[ks], acc[pt]);
;             }
;         }
	v_lshlrev_b32_e32 v148, 16, v20
	v_and_b32_e32 v149, 0xffff0000, v20
	v_pk_mul_f32 v[36:37], v[48:49], v[148:149]
	v_lshlrev_b32_e32 v150, 16, v21
	v_and_b32_e32 v151, 0xffff0000, v21
	v_cvt_pk_bf16_f32 v20, v36, v37
	v_pk_mul_f32 v[36:37], v[50:51], v[150:151]
	s_waitcnt lgkmcnt(0)
	v_lshlrev_b32_e32 v152, 16, v22
	v_and_b32_e32 v153, 0xffff0000, v22
	v_cvt_pk_bf16_f32 v21, v36, v37
	v_pk_mul_f32 v[36:37], v[44:45], v[152:153]
	v_lshlrev_b32_e32 v154, 16, v23
	v_and_b32_e32 v155, 0xffff0000, v23
	v_cvt_pk_bf16_f32 v22, v36, v37
	v_pk_mul_f32 v[36:37], v[46:47], v[154:155]
	s_nop 0
	v_cvt_pk_bf16_f32 v23, v36, v37
	s_nop 1
	v_mfma_f32_16x16x32_bf16 v[32:35], v[20:23], v[12:15], v[32:35]
	ds_read_b64_tr_b16 v[20:21], v232 offset:8800
	ds_read_b64_tr_b16 v[22:23], v232 offset:9888
	s_waitcnt lgkmcnt(1)
	v_lshlrev_b32_e32 v156, 16, v20
	v_and_b32_e32 v157, 0xffff0000, v20
	v_pk_mul_f32 v[36:37], v[48:49], v[156:157]
	v_lshlrev_b32_e32 v48, 16, v21
	v_and_b32_e32 v49, 0xffff0000, v21
	v_cvt_pk_bf16_f32 v20, v36, v37
	v_pk_mul_f32 v[36:37], v[50:51], v[48:49]
	s_waitcnt lgkmcnt(0)
	v_lshlrev_b32_e32 v160, 16, v22
	v_and_b32_e32 v161, 0xffff0000, v22
	v_cvt_pk_bf16_f32 v21, v36, v37
	v_pk_mul_f32 v[36:37], v[44:45], v[160:161]
	v_lshlrev_b32_e32 v166, 16, v23
	v_and_b32_e32 v167, 0xffff0000, v23
	v_cvt_pk_bf16_f32 v22, v36, v37
	v_pk_mul_f32 v[36:37], v[46:47], v[166:167]
	s_nop 0
	v_cvt_pk_bf16_f32 v23, v36, v37
	s_nop 1
	v_mfma_f32_16x16x32_bf16 v[20:23], v[20:23], v[12:15], v[24:27]
	ds_read_b128 v[44:47], v231 offset:256
	ds_read_b128 v[36:39], v231 offset:272
	s_nop 0
	ds_read_b64_tr_b16 v[24:25], v232 offset:17408
	ds_read_b64_tr_b16 v[26:27], v232 offset:18496
	s_waitcnt lgkmcnt(1)
	v_lshlrev_b32_e32 v158, 16, v24
	v_and_b32_e32 v159, 0xffff0000, v24
	v_pk_mul_f32 v[50:51], v[44:45], v[158:159]
	s_waitcnt lgkmcnt(0)
	v_lshlrev_b32_e32 v164, 16, v26
	v_cvt_pk_bf16_f32 v24, v50, v51
	v_lshlrev_b32_e32 v50, 16, v25
	v_and_b32_e32 v51, 0xffff0000, v25
	v_pk_mul_f32 v[162:163], v[46:47], v[50:51]
	v_and_b32_e32 v165, 0xffff0000, v26
	v_cvt_pk_bf16_f32 v25, v162, v163
	v_pk_mul_f32 v[162:163], v[36:37], v[164:165]
	s_nop 0
	v_cvt_pk_bf16_f32 v26, v162, v163
	v_lshlrev_b32_e32 v162, 16, v27
	v_and_b32_e32 v163, 0xffff0000, v27
	v_pk_mul_f32 v[168:169], v[38:39], v[162:163]
	s_nop 0
	v_cvt_pk_bf16_f32 v27, v168, v169
	s_nop 1
	v_mfma_f32_16x16x32_bf16 v[24:27], v[24:27], v[8:11], v[28:31]
	s_nop 2
	ds_read_b64_tr_b16 v[28:29], v232 offset:17440
	ds_read_b64_tr_b16 v[30:31], v232 offset:18528
	s_waitcnt lgkmcnt(1)
	v_lshlrev_b32_e32 v168, 16, v28
	v_and_b32_e32 v169, 0xffff0000, v28
	v_pk_mul_f32 v[170:171], v[44:45], v[168:169]
	s_nop 0
	v_cvt_pk_bf16_f32 v28, v170, v171
	v_lshlrev_b32_e32 v170, 16, v29
	v_and_b32_e32 v171, 0xffff0000, v29
	v_pk_mul_f32 v[172:173], v[46:47], v[170:171]
	s_nop 0
	v_cvt_pk_bf16_f32 v29, v172, v173
	s_waitcnt lgkmcnt(0)
	v_lshlrev_b32_e32 v172, 16, v30
	v_and_b32_e32 v173, 0xffff0000, v30
	v_pk_mul_f32 v[174:175], v[36:37], v[172:173]
	s_nop 0
	v_cvt_pk_bf16_f32 v30, v174, v175
	v_lshlrev_b32_e32 v174, 16, v31
	v_and_b32_e32 v175, 0xffff0000, v31
	v_pk_mul_f32 v[176:177], v[38:39], v[174:175]
	s_nop 0
	v_cvt_pk_bf16_f32 v31, v176, v177
	s_nop 1
	v_mfma_f32_16x16x32_bf16 v[28:31], v[28:31], v[8:11], v[40:43]
	s_nop 2
	ds_read_b64_tr_b16 v[40:41], v232 offset:17472
	ds_read_b64_tr_b16 v[42:43], v232 offset:18560
	s_waitcnt lgkmcnt(1)
	v_lshlrev_b32_e32 v176, 16, v40
	v_and_b32_e32 v177, 0xffff0000, v40
	v_pk_mul_f32 v[178:179], v[44:45], v[176:177]
	s_nop 0
	v_cvt_pk_bf16_f32 v40, v178, v179
	v_lshlrev_b32_e32 v178, 16, v41
	v_and_b32_e32 v179, 0xffff0000, v41
	v_pk_mul_f32 v[180:181], v[46:47], v[178:179]
	s_nop 0
	v_cvt_pk_bf16_f32 v41, v180, v181
	s_waitcnt lgkmcnt(0)
	v_lshlrev_b32_e32 v180, 16, v42
	v_and_b32_e32 v181, 0xffff0000, v42
	v_pk_mul_f32 v[182:183], v[36:37], v[180:181]
	s_nop 0
	v_cvt_pk_bf16_f32 v42, v182, v183
	v_lshlrev_b32_e32 v182, 16, v43
	v_and_b32_e32 v183, 0xffff0000, v43
	v_pk_mul_f32 v[184:185], v[38:39], v[182:183]
	s_nop 0
	v_cvt_pk_bf16_f32 v43, v184, v185
	s_nop 1
	v_mfma_f32_16x16x32_bf16 v[32:35], v[40:43], v[8:11], v[32:35]
	ds_read_b64_tr_b16 v[40:41], v232 offset:17504
	ds_read_b64_tr_b16 v[42:43], v232 offset:18592
	s_waitcnt lgkmcnt(1)
	v_lshlrev_b32_e32 v184, 16, v40
	v_and_b32_e32 v185, 0xffff0000, v40
	v_pk_mul_f32 v[44:45], v[44:45], v[184:185]
	s_waitcnt lgkmcnt(0)
	v_lshlrev_b32_e32 v198, 16, v42
	v_and_b32_e32 v199, 0xffff0000, v42
	v_cvt_pk_bf16_f32 v40, v44, v45
	v_lshlrev_b32_e32 v44, 16, v41
	v_and_b32_e32 v45, 0xffff0000, v41
	v_pk_mul_f32 v[36:37], v[36:37], v[198:199]
	v_lshlrev_b32_e32 v204, 16, v43
	v_and_b32_e32 v205, 0xffff0000, v43
	v_pk_mul_f32 v[46:47], v[46:47], v[44:45]
	v_cvt_pk_bf16_f32 v42, v36, v37
	v_pk_mul_f32 v[36:37], v[38:39], v[204:205]
	v_cvt_pk_bf16_f32 v41, v46, v47
	v_cvt_pk_bf16_f32 v43, v36, v37
	s_nop 1
	v_mfma_f32_16x16x32_bf16 v[20:23], v[40:43], v[8:11], v[20:23]
	ds_read_b128 v[40:43], v231 offset:384
	ds_read_b128 v[36:39], v231 offset:400
	ds_read_b64_tr_b16 v[46:47], v232 offset:26112
	ds_read_b64_tr_b16 v[200:201], v232 offset:27200
	s_waitcnt lgkmcnt(1)
	v_lshlrev_b32_e32 v186, 16, v46
	v_and_b32_e32 v187, 0xffff0000, v46
	v_pk_mul_f32 v[202:203], v[40:41], v[186:187]
	v_lshlrev_b32_e32 v46, 16, v47
	v_and_b32_e32 v47, 0xffff0000, v47
	v_cvt_pk_bf16_f32 v206, v202, v203
	v_pk_mul_f32 v[202:203], v[42:43], v[46:47]
	s_nop 0
	v_cvt_pk_bf16_f32 v207, v202, v203
	s_waitcnt lgkmcnt(0)
; #define LAS __attribute__((address_space(3)))
; #define MFMA16(a, b, c) __builtin_amdgcn_mfma_f32_16x16x32_bf16((a), (b), (c), 0, 0, 0)
; DI unsigned pk2(float lo, float hi) { f32x2_t v = {lo, hi}; bf16x2_t b = __builtin_convertvector(v, bf16x2_t); return __builtin_bit_cast(unsigned, b); }
; DI s16x4 vtr(const LAS char* p) { return __builtin_bit_cast(s16x4, __builtin_amdgcn_ds_read_tr16_b64_v4i16((LAS s16x4*)p)); }
; DI void ssd_part1_unit(int u, const bf16* PROJ, float* DT, const bf16* H, const bf16* wdtb_l, const float* dt_bias_l, const float* cw, const float* cb, const float* a_log_l, float* STATES, float* TOT,
;                        LAS unsigned char* ldsu, int tid, int wave, int lane) {
;     ...
;         const int hh = combo >> 1, dir = combo & 1, h = 2 * grp + hh;
;         f32x4 acc[4];
; #pragma unroll
;         for (int pt = 0; pt < 4; ++pt) acc[pt] = (f32x4){0.f, 0.f, 0.f, 0.f};
; #pragma unroll
;         for (int ks = 0; ks < 4; ++ks) {
;             const f32x4 w0 = *(const LAS f32x4*)(wtab + combo * 128 + 32 * ks + 8 * g), w1 = *(const LAS f32x4*)(wtab + combo * 128 + 32 * ks + 8 * g + 4);
; #pragma unroll
;             for (int pt = 0; pt < 4; ++pt) {
;                 const LAS char* xp = XS + (32 * ks + 8 * g + q) * IMG_PITCH + (hh * 64 + 16 * pt) * 2 + 8 * p;
;                 const u32x2 lo = __builtin_bit_cast(u32x2, vtr(xp)), hi = __builtin_bit_cast(u32x2, vtr(xp + 4 * IMG_PITCH));
;                 u32x4 af; af.x = pk2(bflo(lo.x) * w0[0], bfhi(lo.x) * w0[1]); af.y = pk2(bflo(lo.y) * w0[2], bfhi(lo.y) * w0[3]);
;                 af.z = pk2(bflo(hi.x) * w1[0], bfhi(hi.x) * w1[1]); af.w = pk2(bflo(hi.y) * w1[2], bfhi(hi.y) * w1[3]);
;                 acc[pt] = MFMA16(__builtin_bit_cast(bf16x8, af), bfr[ks], acc[pt]);
;             }
;         }
;         float* sb = STATES + ((size_t)(((b * 16 + c) * 4 + h) * 2 + dir) * 64) * 128;
; #pragma unroll
;         for (int pt = 0; pt < 4; ++pt)
; #pragma unroll
;             for (int i = 0; i < 4; ++i) sb[(size_t)(16 * pt + 4 * g + i) * 128 + 16 * wave + r] = acc[pt][i];
	v_lshlrev_b32_e32 v202, 16, v200
	v_and_b32_e32 v203, 0xffff0000, v200
	v_lshlrev_b32_e32 v200, 16, v201
	v_and_b32_e32 v201, 0xffff0000, v201
	v_pk_mul_f32 v[208:209], v[36:37], v[202:203]
	v_pk_mul_f32 v[210:211], v[38:39], v[200:201]
	v_cvt_pk_bf16_f32 v208, v208, v209
	v_cvt_pk_bf16_f32 v209, v210, v211
	s_nop 1
	v_mfma_f32_16x16x32_bf16 v[24:27], v[206:209], v[4:7], v[24:27]
	ds_read_b64_tr_b16 v[208:209], v232 offset:26144
	ds_read_b64_tr_b16 v[212:213], v232 offset:27232
	s_waitcnt lgkmcnt(1)
	v_lshlrev_b32_e32 v206, 16, v208
	v_and_b32_e32 v207, 0xffff0000, v208
	v_pk_mul_f32 v[210:211], v[40:41], v[206:207]
	v_lshlrev_b32_e32 v208, 16, v209
	v_and_b32_e32 v209, 0xffff0000, v209
	v_cvt_pk_bf16_f32 v214, v210, v211
	v_pk_mul_f32 v[210:211], v[42:43], v[208:209]
	s_nop 0
	v_cvt_pk_bf16_f32 v215, v210, v211
	s_waitcnt lgkmcnt(0)
	v_lshlrev_b32_e32 v210, 16, v212
	v_and_b32_e32 v211, 0xffff0000, v212
	v_lshlrev_b32_e32 v212, 16, v213
	v_and_b32_e32 v213, 0xffff0000, v213
	v_pk_mul_f32 v[216:217], v[36:37], v[210:211]
	v_pk_mul_f32 v[218:219], v[38:39], v[212:213]
	v_cvt_pk_bf16_f32 v216, v216, v217
	v_cvt_pk_bf16_f32 v217, v218, v219
	s_nop 1
	v_mfma_f32_16x16x32_bf16 v[28:31], v[214:217], v[4:7], v[28:31]
	ds_read_b64_tr_b16 v[216:217], v232 offset:26176
	ds_read_b64_tr_b16 v[220:221], v232 offset:27264
	s_waitcnt lgkmcnt(1)
	v_lshlrev_b32_e32 v214, 16, v216
	v_and_b32_e32 v215, 0xffff0000, v216
	v_pk_mul_f32 v[218:219], v[40:41], v[214:215]
	v_lshlrev_b32_e32 v216, 16, v217
	v_and_b32_e32 v217, 0xffff0000, v217
	v_cvt_pk_bf16_f32 v248, v218, v219
	v_pk_mul_f32 v[218:219], v[42:43], v[216:217]
	s_nop 0
	v_cvt_pk_bf16_f32 v249, v218, v219
	s_waitcnt lgkmcnt(0)
	v_lshlrev_b32_e32 v218, 16, v220
	v_and_b32_e32 v219, 0xffff0000, v220
	v_pk_mul_f32 v[222:223], v[36:37], v[218:219]
	v_lshlrev_b32_e32 v220, 16, v221
	v_and_b32_e32 v221, 0xffff0000, v221
	v_cvt_pk_bf16_f32 v250, v222, v223
	v_pk_mul_f32 v[222:223], v[38:39], v[220:221]
	s_nop 0
	v_cvt_pk_bf16_f32 v251, v222, v223
	s_nop 1
	v_mfma_f32_16x16x32_bf16 v[32:35], v[248:251], v[4:7], v[32:35]
	ds_read_b64_tr_b16 v[248:249], v232 offset:26208
	ds_read_b64_tr_b16 v[250:251], v232 offset:27296
	s_waitcnt lgkmcnt(1)
	v_lshlrev_b32_e32 v222, 16, v248
	v_and_b32_e32 v223, 0xffff0000, v248
	v_pk_mul_f32 v[40:41], v[40:41], v[222:223]
	s_nop 0
	v_cvt_pk_bf16_f32 v248, v40, v41
	v_lshlrev_b32_e32 v40, 16, v249
	v_and_b32_e32 v41, 0xffff0000, v249
	v_pk_mul_f32 v[42:43], v[42:43], v[40:41]
	s_nop 0
	v_cvt_pk_bf16_f32 v249, v42, v43
	s_waitcnt lgkmcnt(0)
	v_lshlrev_b32_e32 v42, 16, v250
	v_and_b32_e32 v43, 0xffff0000, v250
	v_pk_mul_f32 v[36:37], v[36:37], v[42:43]
	s_nop 0
	v_cvt_pk_bf16_f32 v250, v36, v37
	v_lshlrev_b32_e32 v36, 16, v251
	v_and_b32_e32 v37, 0xffff0000, v251
	v_pk_mul_f32 v[38:39], v[38:39], v[36:37]
	s_nop 0
	v_cvt_pk_bf16_f32 v251, v38, v39
	v_lshl_add_u64 v[38:39], v[112:113], 0, s[60:61]
	s_or_b32 s60, s0, 1
	v_mfma_f32_16x16x32_bf16 v[20:23], v[248:251], v[4:7], v[20:23]
	v_lshl_add_u64 v[248:249], v[38:39], 0, v[122:123]
	global_store_dword v[248:249], v24, off sc1
	global_store_dword v[248:249], v25, off offset:512 sc1
	global_store_dword v[248:249], v26, off offset:1024 sc1
	global_store_dword v[248:249], v27, off offset:1536 sc1
	v_lshl_add_u64 v[24:25], v[38:39], 0, v[124:125]
	global_store_dword v[24:25], v28, off sc1
	v_lshl_add_u64 v[24:25], v[38:39], 0, v[126:127]
	global_store_dword v[24:25], v29, off sc1
	v_lshl_add_u64 v[24:25], v[38:39], 0, v[128:129]
	global_store_dword v[24:25], v30, off sc1
	v_lshl_add_u64 v[24:25], v[38:39], 0, v[130:131]
	global_store_dword v[24:25], v31, off sc1
	v_lshl_add_u64 v[24:25], v[38:39], 0, v[132:133]
	global_store_dword v[24:25], v32, off sc1
	v_lshl_add_u64 v[24:25], v[38:39], 0, v[134:135]
	global_store_dword v[24:25], v33, off sc1
	v_lshl_add_u64 v[24:25], v[38:39], 0, v[136:137]
	global_store_dword v[24:25], v34, off sc1
	v_lshl_add_u64 v[24:25], v[38:39], 0, v[138:139]
	global_store_dword v[24:25], v35, off sc1
	v_lshl_add_u64 v[24:25], v[38:39], 0, v[140:141]
	global_store_dword v[24:25], v20, off sc1
	v_lshl_add_u64 v[24:25], v[38:39], 0, v[142:143]
	global_store_dword v[24:25], v21, off sc1
	v_lshl_add_u64 v[20:21], v[38:39], 0, v[144:145]
	global_store_dword v[20:21], v22, off sc1
	v_lshl_add_u64 v[20:21], v[38:39], 0, v[146:147]
	global_store_dword v[20:21], v23, off sc1
	ds_read_b128 v[20:23], v231 offset:512
	ds_read_b128 v[24:27], v231 offset:528
	s_ashr_i32 s61, s60, 31
	s_lshl_b64 s[60:61], s[60:61], 15
	s_waitcnt lgkmcnt(1)
	v_pk_mul_f32 v[28:29], v[20:21], v[58:59]
	v_pk_mul_f32 v[30:31], v[22:23], v[56:57]
	v_cvt_pk_bf16_f32 v28, v28, v29
	v_cvt_pk_bf16_f32 v29, v30, v31
	s_waitcnt lgkmcnt(0)
	v_pk_mul_f32 v[30:31], v[24:25], v[64:65]
	v_pk_mul_f32 v[32:33], v[26:27], v[62:63]
	v_cvt_pk_bf16_f32 v30, v30, v31
	v_cvt_pk_bf16_f32 v31, v32, v33
	v_pk_mul_f32 v[32:33], v[20:21], v[52:53]
	v_pk_mul_f32 v[34:35], v[22:23], v[54:55]
	v_cvt_pk_bf16_f32 v32, v32, v33
	v_cvt_pk_bf16_f32 v33, v34, v35
	v_pk_mul_f32 v[34:35], v[24:25], v[60:61]
	v_pk_mul_f32 v[38:39], v[26:27], v[66:67]
	v_cvt_pk_bf16_f32 v34, v34, v35
	v_cvt_pk_bf16_f32 v35, v38, v39
	v_pk_mul_f32 v[38:39], v[20:21], v[68:69]
	v_pk_mul_f32 v[20:21], v[20:21], v[76:77]
	v_cvt_pk_bf16_f32 v52, v38, v39
	v_pk_mul_f32 v[38:39], v[22:23], v[70:71]
	v_pk_mul_f32 v[22:23], v[22:23], v[78:79]
	v_cvt_pk_bf16_f32 v53, v38, v39
	v_pk_mul_f32 v[38:39], v[24:25], v[72:73]
	v_cvt_pk_bf16_f32 v20, v20, v21
	v_cvt_pk_bf16_f32 v21, v22, v23
	v_pk_mul_f32 v[22:23], v[24:25], v[84:85]
	v_pk_mul_f32 v[24:25], v[26:27], v[90:91]
	v_cvt_pk_bf16_f32 v54, v38, v39
	v_pk_mul_f32 v[38:39], v[26:27], v[74:75]
	v_cvt_pk_bf16_f32 v22, v22, v23
	v_cvt_pk_bf16_f32 v23, v24, v25
	ds_read_b128 v[24:27], v231 offset:640
	ds_read_b128 v[56:59], v231 offset:656
	v_cvt_pk_bf16_f32 v55, v38, v39
	v_mfma_f32_16x16x32_bf16 v[28:31], v[28:31], v[16:19], 0
	s_waitcnt lgkmcnt(1)
; #define LAS __attribute__((address_space(3)))
; #define MFMA16(a, b, c) __builtin_amdgcn_mfma_f32_16x16x32_bf16((a), (b), (c), 0, 0, 0)
; DI unsigned pk2(float lo, float hi) { f32x2_t v = {lo, hi}; bf16x2_t b = __builtin_convertvector(v, bf16x2_t); return __builtin_bit_cast(unsigned, b); }
; DI s16x4 vtr(const LAS char* p) { return __builtin_bit_cast(s16x4, __builtin_amdgcn_ds_read_tr16_b64_v4i16((LAS s16x4*)p)); }
; DI void ssd_part1_unit(int u, const bf16* PROJ, float* DT, const bf16* H, const bf16* wdtb_l, const float* dt_bias_l, const float* cw, const float* cb, const float* a_log_l, float* STATES, float* TOT,
;                        LAS unsigned char* ldsu, int tid, int wave, int lane) {
;     ...
;         const int hh = combo >> 1, dir = combo & 1, h = 2 * grp + hh;
;         f32x4 acc[4];
; #pragma unroll
;         for (int pt = 0; pt < 4; ++pt) acc[pt] = (f32x4){0.f, 0.f, 0.f, 0.f};
; #pragma unroll
;         for (int ks = 0; ks < 4; ++ks) {
;             const f32x4 w0 = *(const LAS f32x4*)(wtab + combo * 128 + 32 * ks + 8 * g), w1 = *(const LAS f32x4*)(wtab + combo * 128 + 32 * ks + 8 * g + 4);
; #pragma unroll
;             for (int pt = 0; pt < 4; ++pt) {
;                 const LAS char* xp = XS + (32 * ks + 8 * g + q) * IMG_PITCH + (hh * 64 + 16 * pt) * 2 + 8 * p;
;                 const u32x2 lo = __builtin_bit_cast(u32x2, vtr(xp)), hi = __builtin_bit_cast(u32x2, vtr(xp + 4 * IMG_PITCH));
;                 u32x4 af; af.x = pk2(bflo(lo.x) * w0[0], bfhi(lo.x) * w0[1]); af.y = pk2(bflo(lo.y) * w0[2], bfhi(lo.y) * w0[3]);
;                 af.z = pk2(bflo(hi.x) * w1[0], bfhi(hi.x) * w1[1]); af.w = pk2(bflo(hi.y) * w1[2], bfhi(hi.y) * w1[3]);
;                 acc[pt] = MFMA16(__builtin_bit_cast(bf16x8, af), bfr[ks], acc[pt]);
;             }
;         }
;         float* sb = STATES + ((size_t)(((b * 16 + c) * 4 + h) * 2 + dir) * 64) * 128;
; #pragma unroll
;         for (int pt = 0; pt < 4; ++pt)
; #pragma unroll
;             for (int i = 0; i < 4; ++i) sb[(size_t)(16 * pt + 4 * g + i) * 128 + 16 * wave + r] = acc[pt][i];
	v_pk_mul_f32 v[38:39], v[24:25], v[82:83]
	s_nop 0
	v_cvt_pk_bf16_f32 v60, v38, v39
	v_pk_mul_f32 v[38:39], v[26:27], v[80:81]
	v_mfma_f32_16x16x32_bf16 v[32:35], v[32:35], v[16:19], 0
	v_cvt_pk_bf16_f32 v61, v38, v39
	s_waitcnt lgkmcnt(0)
	v_pk_mul_f32 v[38:39], v[56:57], v[88:89]
	s_nop 0
	v_cvt_pk_bf16_f32 v62, v38, v39
	v_pk_mul_f32 v[38:39], v[58:59], v[86:87]
	v_mfma_f32_16x16x32_bf16 v[20:23], v[20:23], v[16:19], 0
	v_cvt_pk_bf16_f32 v63, v38, v39
	v_pk_mul_f32 v[38:39], v[24:25], v[92:93]
	s_nop 0
	v_mfma_f32_16x16x32_bf16 v[28:31], v[60:63], v[12:15], v[28:31]
	v_cvt_pk_bf16_f32 v60, v38, v39
	v_pk_mul_f32 v[38:39], v[26:27], v[94:95]
	s_nop 0
	v_cvt_pk_bf16_f32 v61, v38, v39
	v_pk_mul_f32 v[38:39], v[56:57], v[96:97]
	v_mfma_f32_16x16x32_bf16 v[52:55], v[52:55], v[16:19], 0
	v_cvt_pk_bf16_f32 v62, v38, v39
	v_pk_mul_f32 v[38:39], v[58:59], v[98:99]
	s_nop 0
	v_cvt_pk_bf16_f32 v63, v38, v39
	v_pk_mul_f32 v[38:39], v[24:25], v[148:149]
	v_pk_mul_f32 v[24:25], v[24:25], v[156:157]
	v_mfma_f32_16x16x32_bf16 v[32:35], v[60:63], v[12:15], v[32:35]
	v_cvt_pk_bf16_f32 v60, v38, v39
	v_pk_mul_f32 v[38:39], v[26:27], v[150:151]
	v_pk_mul_f32 v[26:27], v[26:27], v[48:49]
	v_cvt_pk_bf16_f32 v61, v38, v39
	v_pk_mul_f32 v[38:39], v[56:57], v[152:153]
	v_cvt_pk_bf16_f32 v24, v24, v25
	v_cvt_pk_bf16_f32 v62, v38, v39
	v_pk_mul_f32 v[38:39], v[58:59], v[154:155]
	v_cvt_pk_bf16_f32 v25, v26, v27
	v_cvt_pk_bf16_f32 v63, v38, v39
	v_pk_mul_f32 v[26:27], v[56:57], v[160:161]
	v_pk_mul_f32 v[38:39], v[58:59], v[166:167]
	v_cvt_pk_bf16_f32 v26, v26, v27
	v_cvt_pk_bf16_f32 v27, v38, v39
	v_mfma_f32_16x16x32_bf16 v[52:55], v[60:63], v[12:15], v[52:55]
	s_nop 0
	v_mfma_f32_16x16x32_bf16 v[20:23], v[24:27], v[12:15], v[20:23]
	ds_read_b128 v[24:27], v231 offset:768
	ds_read_b128 v[56:59], v231 offset:784
	s_waitcnt lgkmcnt(1)
	v_pk_mul_f32 v[38:39], v[24:25], v[158:159]
	s_nop 0
	v_cvt_pk_bf16_f32 v48, v38, v39
	v_pk_mul_f32 v[38:39], v[26:27], v[50:51]
	s_nop 0
	v_cvt_pk_bf16_f32 v49, v38, v39
	s_waitcnt lgkmcnt(0)
	v_pk_mul_f32 v[38:39], v[56:57], v[164:165]
	s_nop 0
	v_cvt_pk_bf16_f32 v50, v38, v39
	v_pk_mul_f32 v[38:39], v[58:59], v[162:163]
	s_nop 0
	v_cvt_pk_bf16_f32 v51, v38, v39
	v_pk_mul_f32 v[38:39], v[24:25], v[168:169]
	s_nop 0
	v_mfma_f32_16x16x32_bf16 v[28:31], v[48:51], v[8:11], v[28:31]
	v_cvt_pk_bf16_f32 v48, v38, v39
	v_pk_mul_f32 v[38:39], v[26:27], v[170:171]
	s_nop 0
	v_cvt_pk_bf16_f32 v49, v38, v39
	v_pk_mul_f32 v[38:39], v[56:57], v[172:173]
	s_nop 0
	v_cvt_pk_bf16_f32 v50, v38, v39
	v_pk_mul_f32 v[38:39], v[58:59], v[174:175]
	s_nop 0
	v_cvt_pk_bf16_f32 v51, v38, v39
	v_pk_mul_f32 v[38:39], v[24:25], v[176:177]
	v_pk_mul_f32 v[24:25], v[24:25], v[184:185]
	v_mfma_f32_16x16x32_bf16 v[32:35], v[48:51], v[8:11], v[32:35]
	v_cvt_pk_bf16_f32 v48, v38, v39
	v_pk_mul_f32 v[38:39], v[26:27], v[178:179]
	v_pk_mul_f32 v[26:27], v[26:27], v[44:45]
	v_cvt_pk_bf16_f32 v49, v38, v39
	v_pk_mul_f32 v[38:39], v[56:57], v[180:181]
	v_cvt_pk_bf16_f32 v24, v24, v25
	v_cvt_pk_bf16_f32 v50, v38, v39
	v_pk_mul_f32 v[38:39], v[58:59], v[182:183]
	v_cvt_pk_bf16_f32 v25, v26, v27
	v_cvt_pk_bf16_f32 v51, v38, v39
	v_pk_mul_f32 v[26:27], v[56:57], v[198:199]
	v_pk_mul_f32 v[38:39], v[58:59], v[204:205]
	v_cvt_pk_bf16_f32 v26, v26, v27
	v_cvt_pk_bf16_f32 v27, v38, v39
	v_mfma_f32_16x16x32_bf16 v[48:51], v[48:51], v[8:11], v[52:55]
	s_nop 0
	v_mfma_f32_16x16x32_bf16 v[20:23], v[24:27], v[8:11], v[20:23]
	ds_read_b128 v[24:27], v231 offset:896
	ds_read_b128 v[52:55], v231 offset:912
	s_waitcnt lgkmcnt(1)
	v_pk_mul_f32 v[38:39], v[24:25], v[186:187]
	s_nop 0
	v_cvt_pk_bf16_f32 v44, v38, v39
	v_pk_mul_f32 v[38:39], v[26:27], v[46:47]
	s_waitcnt lgkmcnt(0)
	v_pk_mul_f32 v[36:37], v[54:55], v[36:37]
	v_cvt_pk_bf16_f32 v45, v38, v39
	v_pk_mul_f32 v[38:39], v[52:53], v[202:203]
	s_nop 0
	v_cvt_pk_bf16_f32 v46, v38, v39
	v_pk_mul_f32 v[38:39], v[54:55], v[200:201]
	s_nop 0
	v_cvt_pk_bf16_f32 v47, v38, v39
	v_pk_mul_f32 v[38:39], v[24:25], v[206:207]
	s_nop 0
	v_mfma_f32_16x16x32_bf16 v[28:31], v[44:47], v[4:7], v[28:31]
	v_cvt_pk_bf16_f32 v44, v38, v39
	v_pk_mul_f32 v[38:39], v[26:27], v[208:209]
	s_nop 0
	v_cvt_pk_bf16_f32 v45, v38, v39
	v_pk_mul_f32 v[38:39], v[52:53], v[210:211]
	s_nop 0
	v_cvt_pk_bf16_f32 v46, v38, v39
	v_pk_mul_f32 v[38:39], v[54:55], v[212:213]
	s_nop 0
	v_cvt_pk_bf16_f32 v47, v38, v39
	v_pk_mul_f32 v[38:39], v[24:25], v[214:215]
	v_pk_mul_f32 v[24:25], v[24:25], v[222:223]
	v_mfma_f32_16x16x32_bf16 v[32:35], v[44:47], v[4:7], v[32:35]
	v_cvt_pk_bf16_f32 v44, v38, v39
	v_pk_mul_f32 v[38:39], v[26:27], v[216:217]
	v_pk_mul_f32 v[26:27], v[26:27], v[40:41]
	v_cvt_pk_bf16_f32 v24, v24, v25
	v_cvt_pk_bf16_f32 v25, v26, v27
	v_pk_mul_f32 v[26:27], v[52:53], v[42:43]
	v_cvt_pk_bf16_f32 v45, v38, v39
	v_cvt_pk_bf16_f32 v26, v26, v27
	v_cvt_pk_bf16_f32 v27, v36, v37
	v_pk_mul_f32 v[38:39], v[52:53], v[218:219]
	s_nop 0
	v_cvt_pk_bf16_f32 v46, v38, v39
	v_pk_mul_f32 v[38:39], v[54:55], v[220:221]
	v_mfma_f32_16x16x32_bf16 v[20:23], v[24:27], v[4:7], v[20:23]
	v_cvt_pk_bf16_f32 v47, v38, v39
	v_lshl_add_u64 v[24:25], v[112:113], 0, s[60:61]
	v_lshl_add_u64 v[26:27], v[24:25], 0, v[122:123]
	global_store_dword v[26:27], v28, off sc1
	global_store_dword v[26:27], v29, off offset:512 sc1
	global_store_dword v[26:27], v30, off offset:1024 sc1
	global_store_dword v[26:27], v31, off offset:1536 sc1
	v_lshl_add_u64 v[26:27], v[24:25], 0, v[124:125]
	v_mfma_f32_16x16x32_bf16 v[44:47], v[44:47], v[4:7], v[48:51]
	global_store_dword v[26:27], v32, off sc1
	v_lshl_add_u64 v[26:27], v[24:25], 0, v[126:127]
	global_store_dword v[26:27], v33, off sc1
	v_lshl_add_u64 v[26:27], v[24:25], 0, v[128:129]
	global_store_dword v[26:27], v34, off sc1
	v_lshl_add_u64 v[26:27], v[24:25], 0, v[130:131]
	global_store_dword v[26:27], v35, off sc1
	v_lshl_add_u64 v[26:27], v[24:25], 0, v[132:133]
	global_store_dword v[26:27], v44, off sc1
	v_lshl_add_u64 v[26:27], v[24:25], 0, v[134:135]
	global_store_dword v[26:27], v45, off sc1
	v_lshl_add_u64 v[26:27], v[24:25], 0, v[136:137]
	global_store_dword v[26:27], v46, off sc1
	v_lshl_add_u64 v[26:27], v[24:25], 0, v[138:139]
	global_store_dword v[26:27], v47, off sc1
	v_lshl_add_u64 v[26:27], v[24:25], 0, v[140:141]
	global_store_dword v[26:27], v20, off sc1
	v_lshl_add_u64 v[26:27], v[24:25], 0, v[142:143]
	global_store_dword v[26:27], v21, off sc1
	v_lshl_add_u64 v[20:21], v[24:25], 0, v[144:145]
	global_store_dword v[20:21], v22, off sc1
	v_lshl_add_u64 v[20:21], v[24:25], 0, v[146:147]
	global_store_dword v[20:21], v23, off sc1
	ds_read_b128 v[28:31], v231 offset:1024
	ds_read_b128 v[24:27], v231 offset:1040
	ds_read_b64_tr_b16 v[22:23], v232 offset:1216
	ds_read_b64_tr_b16 v[20:21], v232 offset:128
	ds_read_b64_tr_b16 v[32:33], v232 offset:160
	s_or_b32 s60, s0, 2
	s_ashr_i32 s61, s60, 31
	s_waitcnt lgkmcnt(2)
; #define LAS __attribute__((address_space(3)))
; #define MFMA16(a, b, c) __builtin_amdgcn_mfma_f32_16x16x32_bf16((a), (b), (c), 0, 0, 0)
; DI unsigned pk2(float lo, float hi) { f32x2_t v = {lo, hi}; bf16x2_t b = __builtin_convertvector(v, bf16x2_t); return __builtin_bit_cast(unsigned, b); }
; DI s16x4 vtr(const LAS char* p) { return __builtin_bit_cast(s16x4, __builtin_amdgcn_ds_read_tr16_b64_v4i16((LAS s16x4*)p)); }
; DI void ssd_part1_unit(int u, const bf16* PROJ, float* DT, const bf16* H, const bf16* wdtb_l, const float* dt_bias_l, const float* cw, const float* cb, const float* a_log_l, float* STATES, float* TOT,
;                        LAS unsigned char* ldsu, int tid, int wave, int lane) {
;     ...
;         const int hh = combo >> 1, dir = combo & 1, h = 2 * grp + hh;
;         f32x4 acc[4];
; #pragma unroll
;         for (int pt = 0; pt < 4; ++pt) acc[pt] = (f32x4){0.f, 0.f, 0.f, 0.f};
; #pragma unroll
;         for (int ks = 0; ks < 4; ++ks) {
;             const f32x4 w0 = *(const LAS f32x4*)(wtab + combo * 128 + 32 * ks + 8 * g), w1 = *(const LAS f32x4*)(wtab + combo * 128 + 32 * ks + 8 * g + 4);
; #pragma unroll
;             for (int pt = 0; pt < 4; ++pt) {
;                 const LAS char* xp = XS + (32 * ks + 8 * g + q) * IMG_PITCH + (hh * 64 + 16 * pt) * 2 + 8 * p;
;                 const u32x2 lo = __builtin_bit_cast(u32x2, vtr(xp)), hi = __builtin_bit_cast(u32x2, vtr(xp + 4 * IMG_PITCH));
;                 u32x4 af; af.x = pk2(bflo(lo.x) * w0[0], bfhi(lo.x) * w0[1]); af.y = pk2(bflo(lo.y) * w0[2], bfhi(lo.y) * w0[3]);
;                 af.z = pk2(bflo(hi.x) * w1[0], bfhi(hi.x) * w1[1]); af.w = pk2(bflo(hi.y) * w1[2], bfhi(hi.y) * w1[3]);
;                 acc[pt] = MFMA16(__builtin_bit_cast(bf16x8, af), bfr[ks], acc[pt]);
;             }
;         }
	v_lshlrev_b32_e32 v60, 16, v22
	s_waitcnt lgkmcnt(1)
	v_lshlrev_b32_e32 v54, 16, v20
	v_and_b32_e32 v55, 0xffff0000, v20
	v_pk_mul_f32 v[34:35], v[28:29], v[54:55]
	v_lshlrev_b32_e32 v52, 16, v21
	v_and_b32_e32 v53, 0xffff0000, v21
	v_cvt_pk_bf16_f32 v20, v34, v35
	v_pk_mul_f32 v[34:35], v[30:31], v[52:53]
	v_and_b32_e32 v61, 0xffff0000, v22
	v_cvt_pk_bf16_f32 v21, v34, v35
	v_pk_mul_f32 v[34:35], v[24:25], v[60:61]
	v_lshlrev_b32_e32 v58, 16, v23
	v_and_b32_e32 v59, 0xffff0000, v23
	v_cvt_pk_bf16_f32 v22, v34, v35
	v_pk_mul_f32 v[34:35], v[26:27], v[58:59]
	s_waitcnt lgkmcnt(0)
	v_lshlrev_b32_e32 v48, 16, v32
	v_cvt_pk_bf16_f32 v23, v34, v35
	v_and_b32_e32 v49, 0xffff0000, v32
	v_lshlrev_b32_e32 v50, 16, v33
	v_mfma_f32_16x16x32_bf16 v[36:39], v[20:23], v[16:19], 0
	ds_read_b64_tr_b16 v[22:23], v232 offset:1248
	v_and_b32_e32 v51, 0xffff0000, v33
	v_pk_mul_f32 v[20:21], v[28:29], v[48:49]
	v_pk_mul_f32 v[32:33], v[30:31], v[50:51]
	v_cvt_pk_bf16_f32 v20, v20, v21
	s_waitcnt lgkmcnt(0)
	v_lshlrev_b32_e32 v56, 16, v22
	v_and_b32_e32 v57, 0xffff0000, v22
	v_cvt_pk_bf16_f32 v21, v32, v33
	v_pk_mul_f32 v[32:33], v[24:25], v[56:57]
	v_lshlrev_b32_e32 v62, 16, v23
	v_and_b32_e32 v63, 0xffff0000, v23
	v_cvt_pk_bf16_f32 v22, v32, v33
	v_pk_mul_f32 v[32:33], v[26:27], v[62:63]
	s_lshl_b64 s[60:61], s[60:61], 15
	v_cvt_pk_bf16_f32 v23, v32, v33
	ds_read_b64_tr_b16 v[32:33], v232 offset:192
	ds_read_b64_tr_b16 v[34:35], v232 offset:1280
	v_mfma_f32_16x16x32_bf16 v[20:23], v[20:23], v[16:19], 0
	s_waitcnt lgkmcnt(1)
	v_lshlrev_b32_e32 v64, 16, v32
	v_and_b32_e32 v65, 0xffff0000, v32
	v_pk_mul_f32 v[40:41], v[28:29], v[64:65]
	v_lshlrev_b32_e32 v66, 16, v33
	v_and_b32_e32 v67, 0xffff0000, v33
	v_cvt_pk_bf16_f32 v32, v40, v41
	v_pk_mul_f32 v[40:41], v[30:31], v[66:67]
	s_waitcnt lgkmcnt(0)
	v_lshlrev_b32_e32 v68, 16, v34
	v_and_b32_e32 v69, 0xffff0000, v34
	v_cvt_pk_bf16_f32 v33, v40, v41
	v_pk_mul_f32 v[40:41], v[24:25], v[68:69]
	v_lshlrev_b32_e32 v70, 16, v35
	v_and_b32_e32 v71, 0xffff0000, v35
	v_cvt_pk_bf16_f32 v34, v40, v41
	v_pk_mul_f32 v[40:41], v[26:27], v[70:71]
	s_or_b32 s0, s0, 3
	v_cvt_pk_bf16_f32 v35, v40, v41
	ds_read_b64_tr_b16 v[40:41], v232 offset:224
	ds_read_b64_tr_b16 v[42:43], v232 offset:1312
	v_mfma_f32_16x16x32_bf16 v[32:35], v[32:35], v[16:19], 0
	s_waitcnt lgkmcnt(1)
	v_lshlrev_b32_e32 v72, 16, v40
	v_and_b32_e32 v73, 0xffff0000, v40
	v_lshlrev_b32_e32 v74, 16, v41
	v_and_b32_e32 v75, 0xffff0000, v41
	s_waitcnt lgkmcnt(0)
	v_lshlrev_b32_e32 v76, 16, v42
	v_and_b32_e32 v77, 0xffff0000, v42
	v_pk_mul_f32 v[28:29], v[28:29], v[72:73]
	v_pk_mul_f32 v[30:31], v[30:31], v[74:75]
	v_pk_mul_f32 v[24:25], v[24:25], v[76:77]
	v_lshlrev_b32_e32 v78, 16, v43
	v_and_b32_e32 v79, 0xffff0000, v43
	v_cvt_pk_bf16_f32 v28, v28, v29
	v_cvt_pk_bf16_f32 v29, v30, v31
	v_cvt_pk_bf16_f32 v30, v24, v25
	v_pk_mul_f32 v[24:25], v[26:27], v[78:79]
	s_ashr_i32 s1, s0, 31
	v_cvt_pk_bf16_f32 v31, v24, v25
	s_lshl_b64 s[0:1], s[0:1], 15
	s_cmpk_gt_i32 s31, 0xff
	v_mfma_f32_16x16x32_bf16 v[24:27], v[28:31], v[16:19], 0
	ds_read_b128 v[44:47], v231 offset:1152
	ds_read_b128 v[40:43], v231 offset:1168
	ds_read_b64_tr_b16 v[28:29], v232 offset:8832
	ds_read_b64_tr_b16 v[30:31], v232 offset:9920
	s_waitcnt lgkmcnt(1)
	v_lshlrev_b32_e32 v82, 16, v28
	v_and_b32_e32 v83, 0xffff0000, v28
	v_pk_mul_f32 v[80:81], v[44:45], v[82:83]
	s_waitcnt lgkmcnt(0)
	v_lshlrev_b32_e32 v86, 16, v30
	v_cvt_pk_bf16_f32 v28, v80, v81
	v_lshlrev_b32_e32 v80, 16, v29
	v_and_b32_e32 v81, 0xffff0000, v29
	v_pk_mul_f32 v[84:85], v[46:47], v[80:81]
	v_and_b32_e32 v87, 0xffff0000, v30
	v_cvt_pk_bf16_f32 v29, v84, v85
	v_pk_mul_f32 v[84:85], v[40:41], v[86:87]
	s_nop 0
	v_cvt_pk_bf16_f32 v30, v84, v85
	v_lshlrev_b32_e32 v84, 16, v31
	v_and_b32_e32 v85, 0xffff0000, v31
	v_pk_mul_f32 v[88:89], v[42:43], v[84:85]
	s_nop 0
	v_cvt_pk_bf16_f32 v31, v88, v89
	s_nop 1
	v_mfma_f32_16x16x32_bf16 v[28:31], v[28:31], v[12:15], v[36:39]
	s_nop 2
	ds_read_b64_tr_b16 v[36:37], v232 offset:8864
	ds_read_b64_tr_b16 v[38:39], v232 offset:9952
	s_waitcnt lgkmcnt(1)
	v_lshlrev_b32_e32 v88, 16, v36
	v_and_b32_e32 v89, 0xffff0000, v36
	v_pk_mul_f32 v[90:91], v[44:45], v[88:89]
	s_nop 0
	v_cvt_pk_bf16_f32 v36, v90, v91
	v_lshlrev_b32_e32 v90, 16, v37
	v_and_b32_e32 v91, 0xffff0000, v37
	v_pk_mul_f32 v[92:93], v[46:47], v[90:91]
	s_nop 0
	v_cvt_pk_bf16_f32 v37, v92, v93
	s_waitcnt lgkmcnt(0)
	v_lshlrev_b32_e32 v92, 16, v38
	v_and_b32_e32 v93, 0xffff0000, v38
	v_pk_mul_f32 v[94:95], v[40:41], v[92:93]
	s_nop 0
	v_cvt_pk_bf16_f32 v38, v94, v95
	v_lshlrev_b32_e32 v94, 16, v39
	v_and_b32_e32 v95, 0xffff0000, v39
	v_pk_mul_f32 v[96:97], v[42:43], v[94:95]
	s_nop 0
	v_cvt_pk_bf16_f32 v39, v96, v97
	s_nop 1
	v_mfma_f32_16x16x32_bf16 v[20:23], v[36:39], v[12:15], v[20:23]
	ds_read_b64_tr_b16 v[36:37], v232 offset:8896
	ds_read_b64_tr_b16 v[38:39], v232 offset:9984
	s_waitcnt lgkmcnt(1)
	v_lshlrev_b32_e32 v96, 16, v36
	v_and_b32_e32 v97, 0xffff0000, v36
	v_pk_mul_f32 v[98:99], v[44:45], v[96:97]
	s_nop 0
	v_cvt_pk_bf16_f32 v36, v98, v99
	v_lshlrev_b32_e32 v98, 16, v37
	v_and_b32_e32 v99, 0xffff0000, v37
	v_pk_mul_f32 v[148:149], v[46:47], v[98:99]
	s_nop 0
	v_cvt_pk_bf16_f32 v37, v148, v149
	s_waitcnt lgkmcnt(0)
	v_lshlrev_b32_e32 v148, 16, v38
	v_and_b32_e32 v149, 0xffff0000, v38
	v_pk_mul_f32 v[150:151], v[40:41], v[148:149]
	s_nop 0
	v_cvt_pk_bf16_f32 v38, v150, v151
	v_lshlrev_b32_e32 v150, 16, v39
	v_and_b32_e32 v151, 0xffff0000, v39
	v_pk_mul_f32 v[152:153], v[42:43], v[150:151]
	s_nop 0
	v_cvt_pk_bf16_f32 v39, v152, v153
	s_nop 1
	v_mfma_f32_16x16x32_bf16 v[32:35], v[36:39], v[12:15], v[32:35]
	ds_read_b64_tr_b16 v[36:37], v232 offset:8928
	ds_read_b64_tr_b16 v[38:39], v232 offset:10016
	s_waitcnt lgkmcnt(1)
; #define LAS __attribute__((address_space(3)))
; #define MFMA16(a, b, c) __builtin_amdgcn_mfma_f32_16x16x32_bf16((a), (b), (c), 0, 0, 0)
; DI unsigned pk2(float lo, float hi) { f32x2_t v = {lo, hi}; bf16x2_t b = __builtin_convertvector(v, bf16x2_t); return __builtin_bit_cast(unsigned, b); }
; DI s16x4 vtr(const LAS char* p) { return __builtin_bit_cast(s16x4, __builtin_amdgcn_ds_read_tr16_b64_v4i16((LAS s16x4*)p)); }
; DI void ssd_part1_unit(int u, const bf16* PROJ, float* DT, const bf16* H, const bf16* wdtb_l, const float* dt_bias_l, const float* cw, const float* cb, const float* a_log_l, float* STATES, float* TOT,
;                        LAS unsigned char* ldsu, int tid, int wave, int lane) {
;     ...
;         const int hh = combo >> 1, dir = combo & 1, h = 2 * grp + hh;
;         f32x4 acc[4];
; #pragma unroll
;         for (int pt = 0; pt < 4; ++pt) acc[pt] = (f32x4){0.f, 0.f, 0.f, 0.f};
; #pragma unroll
;         for (int ks = 0; ks < 4; ++ks) {
;             const f32x4 w0 = *(const LAS f32x4*)(wtab + combo * 128 + 32 * ks + 8 * g), w1 = *(const LAS f32x4*)(wtab + combo * 128 + 32 * ks + 8 * g + 4);
; #pragma unroll
;             for (int pt = 0; pt < 4; ++pt) {
;                 const LAS char* xp = XS + (32 * ks + 8 * g + q) * IMG_PITCH + (hh * 64 + 16 * pt) * 2 + 8 * p;
;                 const u32x2 lo = __builtin_bit_cast(u32x2, vtr(xp)), hi = __builtin_bit_cast(u32x2, vtr(xp + 4 * IMG_PITCH));
;                 u32x4 af; af.x = pk2(bflo(lo.x) * w0[0], bfhi(lo.x) * w0[1]); af.y = pk2(bflo(lo.y) * w0[2], bfhi(lo.y) * w0[3]);
;                 af.z = pk2(bflo(hi.x) * w1[0], bfhi(hi.x) * w1[1]); af.w = pk2(bflo(hi.y) * w1[2], bfhi(hi.y) * w1[3]);
;                 acc[pt] = MFMA16(__builtin_bit_cast(bf16x8, af), bfr[ks], acc[pt]);
;             }
;         }
	v_lshlrev_b32_e32 v152, 16, v36
	v_and_b32_e32 v153, 0xffff0000, v36
	s_waitcnt lgkmcnt(0)
	v_lshlrev_b32_e32 v156, 16, v38
	v_and_b32_e32 v157, 0xffff0000, v38
	v_pk_mul_f32 v[44:45], v[44:45], v[152:153]
	v_lshlrev_b32_e32 v154, 16, v37
	v_and_b32_e32 v155, 0xffff0000, v37
	v_pk_mul_f32 v[40:41], v[40:41], v[156:157]
	v_lshlrev_b32_e32 v158, 16, v39
	v_and_b32_e32 v159, 0xffff0000, v39
	v_cvt_pk_bf16_f32 v36, v44, v45
	v_pk_mul_f32 v[44:45], v[46:47], v[154:155]
	v_cvt_pk_bf16_f32 v38, v40, v41
	v_pk_mul_f32 v[40:41], v[42:43], v[158:159]
	v_cvt_pk_bf16_f32 v37, v44, v45
	v_cvt_pk_bf16_f32 v39, v40, v41
	s_nop 1
	v_mfma_f32_16x16x32_bf16 v[24:27], v[36:39], v[12:15], v[24:27]
	ds_read_b128 v[44:47], v231 offset:1280
	ds_read_b128 v[40:43], v231 offset:1296
	ds_read_b64_tr_b16 v[36:37], v232 offset:17536
	ds_read_b64_tr_b16 v[38:39], v232 offset:18624
	s_waitcnt lgkmcnt(1)
	v_lshlrev_b32_e32 v162, 16, v36
	v_and_b32_e32 v163, 0xffff0000, v36
	v_pk_mul_f32 v[160:161], v[44:45], v[162:163]
	s_waitcnt lgkmcnt(0)
	v_lshlrev_b32_e32 v166, 16, v38
	v_cvt_pk_bf16_f32 v36, v160, v161
	v_lshlrev_b32_e32 v160, 16, v37
	v_and_b32_e32 v161, 0xffff0000, v37
	v_pk_mul_f32 v[164:165], v[46:47], v[160:161]
	v_and_b32_e32 v167, 0xffff0000, v38
	v_cvt_pk_bf16_f32 v37, v164, v165
	v_pk_mul_f32 v[164:165], v[40:41], v[166:167]
	s_nop 0
	v_cvt_pk_bf16_f32 v38, v164, v165
	v_lshlrev_b32_e32 v164, 16, v39
	v_and_b32_e32 v165, 0xffff0000, v39
	v_pk_mul_f32 v[168:169], v[42:43], v[164:165]
	s_nop 0
	v_cvt_pk_bf16_f32 v39, v168, v169
	s_nop 1
	v_mfma_f32_16x16x32_bf16 v[28:31], v[36:39], v[8:11], v[28:31]
	ds_read_b64_tr_b16 v[36:37], v232 offset:17568
	ds_read_b64_tr_b16 v[38:39], v232 offset:18656
	s_waitcnt lgkmcnt(1)
	v_lshlrev_b32_e32 v168, 16, v36
	v_and_b32_e32 v169, 0xffff0000, v36
	v_pk_mul_f32 v[170:171], v[44:45], v[168:169]
	s_nop 0
	v_cvt_pk_bf16_f32 v36, v170, v171
	v_lshlrev_b32_e32 v170, 16, v37
	v_and_b32_e32 v171, 0xffff0000, v37
	v_pk_mul_f32 v[172:173], v[46:47], v[170:171]
	s_nop 0
	v_cvt_pk_bf16_f32 v37, v172, v173
	s_waitcnt lgkmcnt(0)
	v_lshlrev_b32_e32 v172, 16, v38
	v_and_b32_e32 v173, 0xffff0000, v38
	v_pk_mul_f32 v[174:175], v[40:41], v[172:173]
	s_nop 0
	v_cvt_pk_bf16_f32 v38, v174, v175
	v_lshlrev_b32_e32 v174, 16, v39
	v_and_b32_e32 v175, 0xffff0000, v39
	v_pk_mul_f32 v[176:177], v[42:43], v[174:175]
	s_nop 0
	v_cvt_pk_bf16_f32 v39, v176, v177
	s_nop 1
	v_mfma_f32_16x16x32_bf16 v[36:39], v[36:39], v[8:11], v[20:23]
	s_nop 2
	ds_read_b64_tr_b16 v[20:21], v232 offset:17600
	ds_read_b64_tr_b16 v[22:23], v232 offset:18688
	s_waitcnt lgkmcnt(1)
	v_lshlrev_b32_e32 v176, 16, v20
	v_and_b32_e32 v177, 0xffff0000, v20
	v_pk_mul_f32 v[178:179], v[44:45], v[176:177]
	s_nop 0
	v_cvt_pk_bf16_f32 v20, v178, v179
	v_lshlrev_b32_e32 v178, 16, v21
	v_and_b32_e32 v179, 0xffff0000, v21
	v_pk_mul_f32 v[180:181], v[46:47], v[178:179]
	s_nop 0
	v_cvt_pk_bf16_f32 v21, v180, v181
	s_waitcnt lgkmcnt(0)
	v_lshlrev_b32_e32 v180, 16, v22
	v_and_b32_e32 v181, 0xffff0000, v22
	v_pk_mul_f32 v[182:183], v[40:41], v[180:181]
	s_nop 0
	v_cvt_pk_bf16_f32 v22, v182, v183
	v_lshlrev_b32_e32 v182, 16, v23
	v_and_b32_e32 v183, 0xffff0000, v23
	v_pk_mul_f32 v[184:185], v[42:43], v[182:183]
	s_nop 0
	v_cvt_pk_bf16_f32 v23, v184, v185
	s_nop 1
	v_mfma_f32_16x16x32_bf16 v[32:35], v[20:23], v[8:11], v[32:35]
	ds_read_b64_tr_b16 v[20:21], v232 offset:17632
	ds_read_b64_tr_b16 v[22:23], v232 offset:18720
	s_waitcnt lgkmcnt(1)
	v_lshlrev_b32_e32 v184, 16, v20
	v_and_b32_e32 v185, 0xffff0000, v20
	v_pk_mul_f32 v[44:45], v[44:45], v[184:185]
	s_waitcnt lgkmcnt(0)
	v_lshlrev_b32_e32 v186, 16, v23
	v_cvt_pk_bf16_f32 v20, v44, v45
	v_lshlrev_b32_e32 v44, 16, v21
	v_and_b32_e32 v45, 0xffff0000, v21
	v_pk_mul_f32 v[46:47], v[46:47], v[44:45]
	v_and_b32_e32 v187, 0xffff0000, v23
	v_cvt_pk_bf16_f32 v21, v46, v47
	v_lshlrev_b32_e32 v46, 16, v22
	v_and_b32_e32 v47, 0xffff0000, v22
	v_pk_mul_f32 v[40:41], v[40:41], v[46:47]
	s_nop 0
	v_cvt_pk_bf16_f32 v22, v40, v41
	v_pk_mul_f32 v[40:41], v[42:43], v[186:187]
	s_nop 0
	v_cvt_pk_bf16_f32 v23, v40, v41
	s_nop 1
	v_mfma_f32_16x16x32_bf16 v[20:23], v[20:23], v[8:11], v[24:27]
	ds_read_b128 v[40:43], v231 offset:1408
	s_nop 1
	ds_read_b128 v[24:27], v231 offset:1424
	ds_read_b64_tr_b16 v[198:199], v232 offset:26240
	ds_read_b64_tr_b16 v[202:203], v232 offset:27328
	s_waitcnt lgkmcnt(1)
	v_lshlrev_b32_e32 v200, 16, v198
	v_and_b32_e32 v201, 0xffff0000, v198
	v_pk_mul_f32 v[204:205], v[40:41], v[200:201]
	v_lshlrev_b32_e32 v198, 16, v199
	v_and_b32_e32 v199, 0xffff0000, v199
	v_cvt_pk_bf16_f32 v206, v204, v205
	v_pk_mul_f32 v[204:205], v[42:43], v[198:199]
	s_nop 0
	v_cvt_pk_bf16_f32 v207, v204, v205
	s_waitcnt lgkmcnt(0)
	v_lshlrev_b32_e32 v204, 16, v202
	v_and_b32_e32 v205, 0xffff0000, v202
	v_lshlrev_b32_e32 v202, 16, v203
	v_and_b32_e32 v203, 0xffff0000, v203
	v_pk_mul_f32 v[208:209], v[24:25], v[204:205]
	v_pk_mul_f32 v[210:211], v[26:27], v[202:203]
	v_cvt_pk_bf16_f32 v208, v208, v209
	v_cvt_pk_bf16_f32 v209, v210, v211
	s_nop 1
	v_mfma_f32_16x16x32_bf16 v[28:31], v[206:209], v[4:7], v[28:31]
	ds_read_b64_tr_b16 v[208:209], v232 offset:26272
	ds_read_b64_tr_b16 v[212:213], v232 offset:27360
	s_waitcnt lgkmcnt(1)
	v_lshlrev_b32_e32 v206, 16, v208
	v_and_b32_e32 v207, 0xffff0000, v208
	v_pk_mul_f32 v[210:211], v[40:41], v[206:207]
	v_lshlrev_b32_e32 v208, 16, v209
	v_and_b32_e32 v209, 0xffff0000, v209
	v_cvt_pk_bf16_f32 v214, v210, v211
	v_pk_mul_f32 v[210:211], v[42:43], v[208:209]
	s_nop 0
	v_cvt_pk_bf16_f32 v215, v210, v211
	s_waitcnt lgkmcnt(0)
; #define LAS __attribute__((address_space(3)))
; #define MFMA16(a, b, c) __builtin_amdgcn_mfma_f32_16x16x32_bf16((a), (b), (c), 0, 0, 0)
; DI unsigned pk2(float lo, float hi) { f32x2_t v = {lo, hi}; bf16x2_t b = __builtin_convertvector(v, bf16x2_t); return __builtin_bit_cast(unsigned, b); }
; DI s16x4 vtr(const LAS char* p) { return __builtin_bit_cast(s16x4, __builtin_amdgcn_ds_read_tr16_b64_v4i16((LAS s16x4*)p)); }
; DI void ssd_part1_unit(int u, const bf16* PROJ, float* DT, const bf16* H, const bf16* wdtb_l, const float* dt_bias_l, const float* cw, const float* cb, const float* a_log_l, float* STATES, float* TOT,
;                        LAS unsigned char* ldsu, int tid, int wave, int lane) {
;     ...
;         const int hh = combo >> 1, dir = combo & 1, h = 2 * grp + hh;
;         f32x4 acc[4];
; #pragma unroll
;         for (int pt = 0; pt < 4; ++pt) acc[pt] = (f32x4){0.f, 0.f, 0.f, 0.f};
; #pragma unroll
;         for (int ks = 0; ks < 4; ++ks) {
;             const f32x4 w0 = *(const LAS f32x4*)(wtab + combo * 128 + 32 * ks + 8 * g), w1 = *(const LAS f32x4*)(wtab + combo * 128 + 32 * ks + 8 * g + 4);
; #pragma unroll
;             for (int pt = 0; pt < 4; ++pt) {
;                 const LAS char* xp = XS + (32 * ks + 8 * g + q) * IMG_PITCH + (hh * 64 + 16 * pt) * 2 + 8 * p;
;                 const u32x2 lo = __builtin_bit_cast(u32x2, vtr(xp)), hi = __builtin_bit_cast(u32x2, vtr(xp + 4 * IMG_PITCH));
;                 u32x4 af; af.x = pk2(bflo(lo.x) * w0[0], bfhi(lo.x) * w0[1]); af.y = pk2(bflo(lo.y) * w0[2], bfhi(lo.y) * w0[3]);
;                 af.z = pk2(bflo(hi.x) * w1[0], bfhi(hi.x) * w1[1]); af.w = pk2(bflo(hi.y) * w1[2], bfhi(hi.y) * w1[3]);
;                 acc[pt] = MFMA16(__builtin_bit_cast(bf16x8, af), bfr[ks], acc[pt]);
;             }
;         }
;         float* sb = STATES + ((size_t)(((b * 16 + c) * 4 + h) * 2 + dir) * 64) * 128;
; #pragma unroll
;         for (int pt = 0; pt < 4; ++pt)
; #pragma unroll
;             for (int i = 0; i < 4; ++i) sb[(size_t)(16 * pt + 4 * g + i) * 128 + 16 * wave + r] = acc[pt][i];
	v_lshlrev_b32_e32 v210, 16, v212
	v_and_b32_e32 v211, 0xffff0000, v212
	v_lshlrev_b32_e32 v212, 16, v213
	v_and_b32_e32 v213, 0xffff0000, v213
	v_pk_mul_f32 v[216:217], v[24:25], v[210:211]
	v_pk_mul_f32 v[218:219], v[26:27], v[212:213]
	v_cvt_pk_bf16_f32 v216, v216, v217
	v_cvt_pk_bf16_f32 v217, v218, v219
	s_nop 1
	v_mfma_f32_16x16x32_bf16 v[36:39], v[214:217], v[4:7], v[36:39]
	ds_read_b64_tr_b16 v[216:217], v232 offset:26304
	ds_read_b64_tr_b16 v[220:221], v232 offset:27392
	s_waitcnt lgkmcnt(1)
	v_lshlrev_b32_e32 v214, 16, v216
	v_and_b32_e32 v215, 0xffff0000, v216
	v_pk_mul_f32 v[218:219], v[40:41], v[214:215]
	v_lshlrev_b32_e32 v216, 16, v217
	v_and_b32_e32 v217, 0xffff0000, v217
	v_cvt_pk_bf16_f32 v248, v218, v219
	v_pk_mul_f32 v[218:219], v[42:43], v[216:217]
	s_nop 0
	v_cvt_pk_bf16_f32 v249, v218, v219
	s_waitcnt lgkmcnt(0)
	v_lshlrev_b32_e32 v218, 16, v220
	v_and_b32_e32 v219, 0xffff0000, v220
	v_pk_mul_f32 v[222:223], v[24:25], v[218:219]
	v_lshlrev_b32_e32 v220, 16, v221
	v_and_b32_e32 v221, 0xffff0000, v221
	v_cvt_pk_bf16_f32 v250, v222, v223
	v_pk_mul_f32 v[222:223], v[26:27], v[220:221]
	s_nop 0
	v_cvt_pk_bf16_f32 v251, v222, v223
	s_nop 1
	v_mfma_f32_16x16x32_bf16 v[32:35], v[248:251], v[4:7], v[32:35]
	ds_read_b64_tr_b16 v[248:249], v232 offset:26336
	ds_read_b64_tr_b16 v[250:251], v232 offset:27424
	s_waitcnt lgkmcnt(1)
	v_lshlrev_b32_e32 v222, 16, v248
	v_and_b32_e32 v223, 0xffff0000, v248
	v_pk_mul_f32 v[40:41], v[40:41], v[222:223]
	s_nop 0
	v_cvt_pk_bf16_f32 v248, v40, v41
	v_lshlrev_b32_e32 v40, 16, v249
	v_and_b32_e32 v41, 0xffff0000, v249
	v_pk_mul_f32 v[42:43], v[42:43], v[40:41]
	s_nop 0
	v_cvt_pk_bf16_f32 v249, v42, v43
	s_waitcnt lgkmcnt(0)
	v_lshlrev_b32_e32 v42, 16, v250
	v_and_b32_e32 v43, 0xffff0000, v250
	v_pk_mul_f32 v[24:25], v[24:25], v[42:43]
	s_nop 0
	v_cvt_pk_bf16_f32 v250, v24, v25
	v_lshlrev_b32_e32 v24, 16, v251
	v_and_b32_e32 v25, 0xffff0000, v251
	v_pk_mul_f32 v[26:27], v[26:27], v[24:25]
	s_nop 0
	v_cvt_pk_bf16_f32 v251, v26, v27
	v_lshl_add_u64 v[26:27], v[112:113], 0, s[60:61]
	s_nop 0
	v_mfma_f32_16x16x32_bf16 v[20:23], v[248:251], v[4:7], v[20:23]
	v_lshl_add_u64 v[248:249], v[26:27], 0, v[122:123]
	global_store_dword v[248:249], v28, off sc1
	global_store_dword v[248:249], v29, off offset:512 sc1
	global_store_dword v[248:249], v30, off offset:1024 sc1
	global_store_dword v[248:249], v31, off offset:1536 sc1
	v_lshl_add_u64 v[28:29], v[26:27], 0, v[124:125]
	global_store_dword v[28:29], v36, off sc1
	v_lshl_add_u64 v[28:29], v[26:27], 0, v[126:127]
	global_store_dword v[28:29], v37, off sc1
	v_lshl_add_u64 v[28:29], v[26:27], 0, v[128:129]
	global_store_dword v[28:29], v38, off sc1
	v_lshl_add_u64 v[28:29], v[26:27], 0, v[130:131]
	global_store_dword v[28:29], v39, off sc1
	v_lshl_add_u64 v[28:29], v[26:27], 0, v[132:133]
	global_store_dword v[28:29], v32, off sc1
	v_lshl_add_u64 v[28:29], v[26:27], 0, v[134:135]
	global_store_dword v[28:29], v33, off sc1
	v_lshl_add_u64 v[28:29], v[26:27], 0, v[136:137]
	global_store_dword v[28:29], v34, off sc1
	v_lshl_add_u64 v[28:29], v[26:27], 0, v[138:139]
	global_store_dword v[28:29], v35, off sc1
	v_lshl_add_u64 v[28:29], v[26:27], 0, v[140:141]
	global_store_dword v[28:29], v20, off sc1
	v_lshl_add_u64 v[28:29], v[26:27], 0, v[142:143]
	global_store_dword v[28:29], v21, off sc1
	v_lshl_add_u64 v[20:21], v[26:27], 0, v[144:145]
	global_store_dword v[20:21], v22, off sc1
	v_lshl_add_u64 v[20:21], v[26:27], 0, v[146:147]
	global_store_dword v[20:21], v23, off sc1
	ds_read_b128 v[20:23], v231 offset:1536
	ds_read_b128 v[26:29], v231 offset:1552
	s_waitcnt lgkmcnt(1)
	v_pk_mul_f32 v[30:31], v[20:21], v[54:55]
	v_pk_mul_f32 v[32:33], v[22:23], v[52:53]
	v_cvt_pk_bf16_f32 v30, v30, v31
	v_cvt_pk_bf16_f32 v31, v32, v33
	s_waitcnt lgkmcnt(0)
	v_pk_mul_f32 v[32:33], v[26:27], v[60:61]
	v_pk_mul_f32 v[34:35], v[28:29], v[58:59]
	v_cvt_pk_bf16_f32 v32, v32, v33
	v_cvt_pk_bf16_f32 v33, v34, v35
	v_pk_mul_f32 v[34:35], v[20:21], v[48:49]
	v_pk_mul_f32 v[36:37], v[22:23], v[50:51]
	v_cvt_pk_bf16_f32 v34, v34, v35
	v_cvt_pk_bf16_f32 v35, v36, v37
	v_pk_mul_f32 v[36:37], v[26:27], v[56:57]
	v_pk_mul_f32 v[38:39], v[28:29], v[62:63]
	v_cvt_pk_bf16_f32 v36, v36, v37
	v_cvt_pk_bf16_f32 v37, v38, v39
	v_pk_mul_f32 v[38:39], v[20:21], v[64:65]
	v_pk_mul_f32 v[20:21], v[20:21], v[72:73]
	v_cvt_pk_bf16_f32 v48, v38, v39
	v_pk_mul_f32 v[38:39], v[22:23], v[66:67]
	v_pk_mul_f32 v[22:23], v[22:23], v[74:75]
	v_cvt_pk_bf16_f32 v49, v38, v39
	v_pk_mul_f32 v[38:39], v[26:27], v[68:69]
	v_cvt_pk_bf16_f32 v20, v20, v21
	v_cvt_pk_bf16_f32 v50, v38, v39
	v_pk_mul_f32 v[38:39], v[28:29], v[70:71]
	v_cvt_pk_bf16_f32 v21, v22, v23
	v_pk_mul_f32 v[22:23], v[26:27], v[76:77]
	v_pk_mul_f32 v[26:27], v[28:29], v[78:79]
	v_cvt_pk_bf16_f32 v51, v38, v39
	v_cvt_pk_bf16_f32 v22, v22, v23
	v_cvt_pk_bf16_f32 v23, v26, v27
	v_mfma_f32_16x16x32_bf16 v[30:33], v[30:33], v[16:19], 0
	v_mfma_f32_16x16x32_bf16 v[34:37], v[34:37], v[16:19], 0
	v_mfma_f32_16x16x32_bf16 v[48:51], v[48:51], v[16:19], 0
	v_mfma_f32_16x16x32_bf16 v[16:19], v[20:23], v[16:19], 0
	ds_read_b128 v[20:23], v231 offset:1664
	ds_read_b128 v[26:29], v231 offset:1680
	s_waitcnt lgkmcnt(1)
	v_pk_mul_f32 v[38:39], v[20:21], v[82:83]
	s_nop 0
	v_cvt_pk_bf16_f32 v52, v38, v39
	v_pk_mul_f32 v[38:39], v[22:23], v[80:81]
	s_nop 0
	v_cvt_pk_bf16_f32 v53, v38, v39
	s_waitcnt lgkmcnt(0)
; #define LAS __attribute__((address_space(3)))
; #define MFMA16(a, b, c) __builtin_amdgcn_mfma_f32_16x16x32_bf16((a), (b), (c), 0, 0, 0)
; DI unsigned pk2(float lo, float hi) { f32x2_t v = {lo, hi}; bf16x2_t b = __builtin_convertvector(v, bf16x2_t); return __builtin_bit_cast(unsigned, b); }
; DI s16x4 vtr(const LAS char* p) { return __builtin_bit_cast(s16x4, __builtin_amdgcn_ds_read_tr16_b64_v4i16((LAS s16x4*)p)); }
; DI void ssd_part1_unit(int u, const bf16* PROJ, float* DT, const bf16* H, const bf16* wdtb_l, const float* dt_bias_l, const float* cw, const float* cb, const float* a_log_l, float* STATES, float* TOT,
;                        LAS unsigned char* ldsu, int tid, int wave, int lane) {
;     ...
;         const int hh = combo >> 1, dir = combo & 1, h = 2 * grp + hh;
;         f32x4 acc[4];
; #pragma unroll
;         for (int pt = 0; pt < 4; ++pt) acc[pt] = (f32x4){0.f, 0.f, 0.f, 0.f};
; #pragma unroll
;         for (int ks = 0; ks < 4; ++ks) {
;             const f32x4 w0 = *(const LAS f32x4*)(wtab + combo * 128 + 32 * ks + 8 * g), w1 = *(const LAS f32x4*)(wtab + combo * 128 + 32 * ks + 8 * g + 4);
; #pragma unroll
;             for (int pt = 0; pt < 4; ++pt) {
;                 const LAS char* xp = XS + (32 * ks + 8 * g + q) * IMG_PITCH + (hh * 64 + 16 * pt) * 2 + 8 * p;
;                 const u32x2 lo = __builtin_bit_cast(u32x2, vtr(xp)), hi = __builtin_bit_cast(u32x2, vtr(xp + 4 * IMG_PITCH));
;                 u32x4 af; af.x = pk2(bflo(lo.x) * w0[0], bfhi(lo.x) * w0[1]); af.y = pk2(bflo(lo.y) * w0[2], bfhi(lo.y) * w0[3]);
;                 af.z = pk2(bflo(hi.x) * w1[0], bfhi(hi.x) * w1[1]); af.w = pk2(bflo(hi.y) * w1[2], bfhi(hi.y) * w1[3]);
;                 acc[pt] = MFMA16(__builtin_bit_cast(bf16x8, af), bfr[ks], acc[pt]);
;             }
;         }
;         float* sb = STATES + ((size_t)(((b * 16 + c) * 4 + h) * 2 + dir) * 64) * 128;
; #pragma unroll
;         for (int pt = 0; pt < 4; ++pt)
; #pragma unroll
;             for (int i = 0; i < 4; ++i) sb[(size_t)(16 * pt + 4 * g + i) * 128 + 16 * wave + r] = acc[pt][i];
	v_pk_mul_f32 v[38:39], v[26:27], v[86:87]
	s_nop 0
	v_cvt_pk_bf16_f32 v54, v38, v39
	v_pk_mul_f32 v[38:39], v[28:29], v[84:85]
	s_nop 0
	v_cvt_pk_bf16_f32 v55, v38, v39
	v_pk_mul_f32 v[38:39], v[20:21], v[88:89]
	s_nop 0
	v_mfma_f32_16x16x32_bf16 v[30:33], v[52:55], v[12:15], v[30:33]
	v_cvt_pk_bf16_f32 v52, v38, v39
	v_pk_mul_f32 v[38:39], v[22:23], v[90:91]
	s_nop 0
	v_cvt_pk_bf16_f32 v53, v38, v39
	v_pk_mul_f32 v[38:39], v[26:27], v[92:93]
	s_nop 0
	v_cvt_pk_bf16_f32 v54, v38, v39
	v_pk_mul_f32 v[38:39], v[28:29], v[94:95]
	s_nop 0
	v_cvt_pk_bf16_f32 v55, v38, v39
	v_pk_mul_f32 v[38:39], v[20:21], v[96:97]
	v_pk_mul_f32 v[20:21], v[20:21], v[152:153]
	v_mfma_f32_16x16x32_bf16 v[34:37], v[52:55], v[12:15], v[34:37]
	v_cvt_pk_bf16_f32 v52, v38, v39
	v_pk_mul_f32 v[38:39], v[22:23], v[98:99]
	v_pk_mul_f32 v[22:23], v[22:23], v[154:155]
	v_cvt_pk_bf16_f32 v53, v38, v39
	v_pk_mul_f32 v[38:39], v[26:27], v[148:149]
	v_cvt_pk_bf16_f32 v20, v20, v21
	v_cvt_pk_bf16_f32 v54, v38, v39
	v_pk_mul_f32 v[38:39], v[28:29], v[150:151]
	v_cvt_pk_bf16_f32 v21, v22, v23
	v_pk_mul_f32 v[22:23], v[26:27], v[156:157]
	v_pk_mul_f32 v[26:27], v[28:29], v[158:159]
	v_cvt_pk_bf16_f32 v55, v38, v39
	v_cvt_pk_bf16_f32 v22, v22, v23
	v_cvt_pk_bf16_f32 v23, v26, v27
	v_mfma_f32_16x16x32_bf16 v[48:51], v[52:55], v[12:15], v[48:51]
	s_nop 0
	v_mfma_f32_16x16x32_bf16 v[12:15], v[20:23], v[12:15], v[16:19]
	s_nop 2
	ds_read_b128 v[16:19], v231 offset:1792
	ds_read_b128 v[20:23], v231 offset:1808
	s_waitcnt lgkmcnt(1)
	v_pk_mul_f32 v[26:27], v[16:17], v[162:163]
	v_pk_mul_f32 v[28:29], v[18:19], v[160:161]
	v_cvt_pk_bf16_f32 v26, v26, v27
	v_cvt_pk_bf16_f32 v27, v28, v29
	s_waitcnt lgkmcnt(0)
	v_pk_mul_f32 v[28:29], v[20:21], v[166:167]
	v_pk_mul_f32 v[38:39], v[22:23], v[164:165]
	v_cvt_pk_bf16_f32 v28, v28, v29
	v_cvt_pk_bf16_f32 v29, v38, v39
	v_pk_mul_f32 v[38:39], v[22:23], v[174:175]
	s_nop 0
	v_mfma_f32_16x16x32_bf16 v[26:29], v[26:29], v[8:11], v[30:33]
	s_nop 2
	v_mul_f32_e64 v30, v16, v168
	v_mul_f32_e64 v31, v17, v169
	v_pk_mul_f32 v[32:33], v[18:19], v[170:171]
	v_cvt_pk_bf16_f32 v30, v30, v31
	v_cvt_pk_bf16_f32 v31, v32, v33
	v_pk_mul_f32 v[32:33], v[20:21], v[172:173]
	s_nop 0
	v_cvt_pk_bf16_f32 v32, v32, v33
	v_cvt_pk_bf16_f32 v33, v38, v39
	v_pk_mul_f32 v[38:39], v[22:23], v[182:183]
	s_nop 0
	v_mfma_f32_16x16x32_bf16 v[30:33], v[30:33], v[8:11], v[34:37]
	s_nop 2
	v_mul_f32_e64 v34, v16, v176
	v_mul_f32_e64 v35, v17, v177
	v_pk_mul_f32 v[36:37], v[18:19], v[178:179]
	v_pk_mul_f32 v[16:17], v[16:17], v[184:185]
	v_pk_mul_f32 v[18:19], v[18:19], v[44:45]
	v_cvt_pk_bf16_f32 v34, v34, v35
	v_cvt_pk_bf16_f32 v35, v36, v37
	v_pk_mul_f32 v[36:37], v[20:21], v[180:181]
	v_cvt_pk_bf16_f32 v16, v16, v17
	v_cvt_pk_bf16_f32 v17, v18, v19
	v_pk_mul_f32 v[18:19], v[20:21], v[46:47]
	v_pk_mul_f32 v[20:21], v[22:23], v[186:187]
	v_cvt_pk_bf16_f32 v36, v36, v37
	v_cvt_pk_bf16_f32 v37, v38, v39
	v_cvt_pk_bf16_f32 v18, v18, v19
	v_cvt_pk_bf16_f32 v19, v20, v21
	v_mfma_f32_16x16x32_bf16 v[34:37], v[34:37], v[8:11], v[48:51]
	s_nop 0
	v_mfma_f32_16x16x32_bf16 v[8:11], v[16:19], v[8:11], v[12:15]
	s_nop 2
	ds_read_b128 v[12:15], v231 offset:1920
	ds_read_b128 v[16:19], v231 offset:1936
	s_waitcnt lgkmcnt(1)
	v_pk_mul_f32 v[20:21], v[12:13], v[200:201]
	v_pk_mul_f32 v[22:23], v[14:15], v[198:199]
	v_cvt_pk_bf16_f32 v20, v20, v21
	v_cvt_pk_bf16_f32 v21, v22, v23
	s_waitcnt lgkmcnt(0)
	v_pk_mul_f32 v[22:23], v[16:17], v[204:205]
	v_pk_mul_f32 v[38:39], v[18:19], v[202:203]
	v_cvt_pk_bf16_f32 v22, v22, v23
	v_cvt_pk_bf16_f32 v23, v38, v39
	v_pk_mul_f32 v[38:39], v[18:19], v[212:213]
	s_nop 0
	v_mfma_f32_16x16x32_bf16 v[20:23], v[20:23], v[4:7], v[26:29]
	s_nop 2
	v_mul_f32_e64 v26, v12, v206
	v_mul_f32_e64 v27, v13, v207
	v_pk_mul_f32 v[28:29], v[14:15], v[208:209]
	v_cvt_pk_bf16_f32 v26, v26, v27
	v_cvt_pk_bf16_f32 v27, v28, v29
	v_pk_mul_f32 v[28:29], v[16:17], v[210:211]
	s_nop 0
	v_cvt_pk_bf16_f32 v28, v28, v29
	v_cvt_pk_bf16_f32 v29, v38, v39
	v_pk_mul_f32 v[38:39], v[18:19], v[220:221]
	s_nop 0
	v_mfma_f32_16x16x32_bf16 v[26:29], v[26:29], v[4:7], v[30:33]
	s_nop 2
	v_mul_f32_e64 v30, v12, v214
	v_mul_f32_e64 v31, v13, v215
	v_pk_mul_f32 v[32:33], v[14:15], v[216:217]
	v_pk_mul_f32 v[12:13], v[12:13], v[222:223]
	v_pk_mul_f32 v[14:15], v[14:15], v[40:41]
	v_cvt_pk_bf16_f32 v30, v30, v31
	v_cvt_pk_bf16_f32 v31, v32, v33
	v_pk_mul_f32 v[32:33], v[16:17], v[218:219]
	v_cvt_pk_bf16_f32 v12, v12, v13
	v_cvt_pk_bf16_f32 v13, v14, v15
	v_pk_mul_f32 v[14:15], v[16:17], v[42:43]
	v_pk_mul_f32 v[16:17], v[18:19], v[24:25]
	v_cvt_pk_bf16_f32 v32, v32, v33
	v_cvt_pk_bf16_f32 v33, v38, v39
	v_cvt_pk_bf16_f32 v14, v14, v15
	v_cvt_pk_bf16_f32 v15, v16, v17
	v_mfma_f32_16x16x32_bf16 v[30:33], v[30:33], v[4:7], v[34:37]
	s_nop 0
	v_mfma_f32_16x16x32_bf16 v[4:7], v[12:15], v[4:7], v[8:11]
	s_nop 2
	v_lshl_add_u64 v[8:9], v[112:113], 0, s[0:1]
	v_lshl_add_u64 v[10:11], v[8:9], 0, v[122:123]
	global_store_dword v[10:11], v20, off sc1
	global_store_dword v[10:11], v21, off offset:512 sc1
	global_store_dword v[10:11], v22, off offset:1024 sc1
	global_store_dword v[10:11], v23, off offset:1536 sc1
	v_lshl_add_u64 v[10:11], v[8:9], 0, v[124:125]
	global_store_dword v[10:11], v26, off sc1
	v_lshl_add_u64 v[10:11], v[8:9], 0, v[126:127]
	global_store_dword v[10:11], v27, off sc1
	v_lshl_add_u64 v[10:11], v[8:9], 0, v[128:129]
	global_store_dword v[10:11], v28, off sc1
	v_lshl_add_u64 v[10:11], v[8:9], 0, v[130:131]
	global_store_dword v[10:11], v29, off sc1
	v_lshl_add_u64 v[10:11], v[8:9], 0, v[132:133]
	global_store_dword v[10:11], v30, off sc1
	v_lshl_add_u64 v[10:11], v[8:9], 0, v[134:135]
	global_store_dword v[10:11], v31, off sc1
	v_lshl_add_u64 v[10:11], v[8:9], 0, v[136:137]
	global_store_dword v[10:11], v32, off sc1
	v_lshl_add_u64 v[10:11], v[8:9], 0, v[138:139]
	global_store_dword v[10:11], v33, off sc1
	v_lshl_add_u64 v[10:11], v[8:9], 0, v[140:141]
	global_store_dword v[10:11], v4, off sc1
	v_lshl_add_u64 v[10:11], v[8:9], 0, v[142:143]
	global_store_dword v[10:11], v5, off sc1
	v_lshl_add_u64 v[4:5], v[8:9], 0, v[144:145]
	global_store_dword v[4:5], v6, off sc1
	v_lshl_add_u64 v[4:5], v[8:9], 0, v[146:147]
	global_store_dword v[4:5], v7, off sc1
	s_cbranch_scc1 .LBB0_356

; DI void ssd_part1_unit(int u, const bf16* PROJ, float* DT, const bf16* H, const bf16* wdtb_l, const float* dt_bias_l, const float* cw, const float* cb, const float* a_log_l, float* STATES, float* TOT,
;                        LAS unsigned char* ldsu, int tid, int wave, int lane) {
;     ...
;         if (r < 8) { const float bias = dt_bias_l[r];
; #pragma unroll
;             for (int i = 0; i < 4; ++i) { const float xx = dacc[i] + bias; DT[(size_t)(b * T + t0 + 16 * wave + 4 * g + i) * 8 + r] = xx > 20.f ? xx : log1pf(__expf(xx)); } }
.LBB0_336:
	s_or_b64 exec, exec, s[64:65]
	v_or_b32_e32 v8, s0, v111
	v_ashrrev_i32_e32 v9, 31, v8
	v_lshlrev_b64 v[12:13], 5, v[8:9]
	v_lshl_add_u64 v[12:13], v[108:109], 0, v[12:13]
	global_store_dword v[12:13], v4, off sc1
	v_add_f32_e32 v4, v5, v10
	s_mov_b32 s0, 0x41a00000
	v_cmp_nlt_f32_e32 vcc, s0, v4
	s_and_saveexec_b64 s[0:1], vcc
	s_cbranch_execz .LBB0_338
	v_mul_f32_e32 v4, 0x3fb8aa3b, v4
	v_exp_f32_e32 v9, v4
	s_mov_b32 s63, 0x3f2aaaab
	v_add_f32_e32 v11, 1.0, v9
	v_frexp_mant_f32_e32 v13, v11
	v_cvt_f64_f32_e32 v[4:5], v11
	v_frexp_exp_i32_f64_e32 v4, v[4:5]
	v_cmp_gt_f32_e32 vcc, s63, v13
	v_add_f32_e32 v12, -1.0, v11
	v_sub_f32_e32 v14, v12, v11
	v_subbrev_co_u32_e32 v18, vcc, 0, v4, vcc
	v_sub_u32_e32 v4, 0, v18
	v_sub_f32_e32 v12, v9, v12
	v_add_f32_e32 v14, 1.0, v14
	v_ldexp_f32 v5, v11, v4
	v_add_f32_e32 v12, v12, v14
	v_add_f32_e32 v11, -1.0, v5
	v_add_f32_e32 v13, 1.0, v5
	v_ldexp_f32 v4, v12, v4
	v_add_f32_e32 v12, 1.0, v11
	v_add_f32_e32 v14, -1.0, v13
	v_sub_f32_e32 v12, v5, v12
	v_sub_f32_e32 v5, v5, v14
	v_add_f32_e32 v12, v4, v12
	v_add_f32_e32 v4, v4, v5
	v_add_f32_e32 v19, v13, v4
	v_rcp_f32_e32 v21, v19
	v_sub_f32_e32 v5, v19, v13
	v_sub_f32_e32 v20, v4, v5
	v_add_f32_e32 v5, v11, v12
	v_sub_f32_e32 v4, v5, v11
	v_mul_f32_e32 v22, v5, v21
	v_sub_f32_e32 v11, v12, v4
	v_mul_f32_e32 v12, v19, v22
	v_fma_f32 v14, v22, v19, -v12
	v_fmac_f32_e32 v14, v22, v20
	v_add_f32_e32 v4, v12, v14
	v_sub_f32_e32 v13, v5, v4
	v_pk_add_f32 v[16:17], v[4:5], v[12:13] neg_lo:[0,1] neg_hi:[0,1]
	v_mov_b32_e32 v15, v4
	v_pk_add_f32 v[4:5], v[16:17], v[14:15] neg_lo:[0,1] neg_hi:[0,1]
	s_mov_b32 s63, 0x3f317218
	v_add_f32_e32 v5, v11, v5
	v_add_f32_e32 v4, v4, v5
	v_add_f32_e32 v5, v13, v4
	v_mul_f32_e32 v11, v21, v5
	v_mul_f32_e32 v12, v19, v11
	v_fma_f32 v14, v11, v19, -v12
	v_fmac_f32_e32 v14, v11, v20
	v_sub_f32_e32 v13, v13, v5
	v_add_f32_e32 v19, v4, v13
	v_add_f32_e32 v4, v12, v14
	v_sub_f32_e32 v13, v5, v4
	v_pk_add_f32 v[16:17], v[4:5], v[12:13] neg_lo:[0,1] neg_hi:[0,1]
	v_mov_b32_e32 v15, v4
	v_pk_add_f32 v[4:5], v[16:17], v[14:15] neg_lo:[0,1] neg_hi:[0,1]
	s_nop 0
	v_add_f32_e32 v5, v19, v5
	v_add_f32_e32 v4, v4, v5
	v_add_f32_e32 v5, v22, v11
	v_add_f32_e32 v4, v13, v4
	v_sub_f32_e32 v12, v5, v22
	v_mul_f32_e32 v4, v21, v4
	v_sub_f32_e32 v11, v11, v12
	v_add_f32_e32 v11, v11, v4
	v_add_f32_e32 v12, v5, v11
	v_mul_f32_e32 v14, v12, v12
	v_mov_b32_e32 v4, 0x3ecc95a3
	v_fmamk_f32 v4, v14, 0x3e9b6dac, v4
	v_fmaak_f32 v193, v14, v4, 0x3f2aaada
	v_cvt_f32_i32_e32 v4, v18
	v_sub_f32_e32 v5, v12, v5
	v_sub_f32_e32 v5, v11, v5
	v_ldexp_f32 v11, v5, 1
	v_mul_f32_e32 v5, v12, v14
	v_pk_mul_f32 v[14:15], v[4:5], v[192:193]
	v_ldexp_f32 v13, v12, 1
	v_fma_f32 v12, v4, s63, -v14
	v_fmac_f32_e32 v12, 0xb102e308, v4
	v_pk_add_f32 v[4:5], v[14:15], v[12:13]
	v_mov_b32_e32 v16, v14
	v_sub_f32_e32 v13, v5, v13
	v_sub_f32_e32 v13, v15, v13
	v_add_f32_e32 v17, v11, v13
	v_pk_add_f32 v[14:15], v[4:5], v[14:15] neg_lo:[0,1] neg_hi:[0,1]
	v_pk_add_f32 v[18:19], v[4:5], v[16:17]
	v_mov_b32_e32 v13, v4
	v_mov_b32_e32 v15, v19
	v_pk_add_f32 v[20:21], v[12:13], v[14:15] neg_lo:[0,1] neg_hi:[0,1]
	v_pk_add_f32 v[12:13], v[12:13], v[14:15]
	v_mov_b32_e32 v16, v17
	v_pk_add_f32 v[14:15], v[12:13], v[4:5] op_sel:[1,0] op_sel_hi:[0,1] neg_lo:[0,1] neg_hi:[0,1]
	v_pk_add_f32 v[22:23], v[18:19], v[14:15] op_sel_hi:[1,0] neg_lo:[0,1] neg_hi:[0,1]
	v_mov_b32_e32 v18, v19
	v_mov_b32_e32 v19, v13
	v_pk_mov_b32 v[14:15], v[4:5], v[14:15] op_sel:[1,0]
	v_mov_b32_e32 v17, v4
	v_pk_add_f32 v[14:15], v[18:19], v[14:15] neg_lo:[0,1] neg_hi:[0,1]
	v_mov_b32_e32 v22, v20
	v_pk_add_f32 v[4:5], v[16:17], v[14:15] neg_lo:[0,1] neg_hi:[0,1]
	v_mov_b32_e32 v21, v13
	v_pk_add_f32 v[14:15], v[22:23], v[4:5]
	s_mov_b32 s63, 0x7f800000
	v_pk_add_f32 v[16:17], v[14:15], v[14:15] op_sel:[0,1] op_sel_hi:[1,0]
	v_cmp_neq_f32_e32 vcc, s63, v9
	v_pk_add_f32 v[12:13], v[12:13], v[16:17] op_sel:[1,0] op_sel_hi:[0,1]
	v_mov_b32_e32 v15, v12
	v_pk_add_f32 v[18:19], v[14:15], v[20:21] neg_lo:[0,1] neg_hi:[0,1]
	v_mov_b32_e32 v5, v16
	v_sub_f32_e32 v11, v14, v18
	v_pk_add_f32 v[4:5], v[4:5], v[18:19] neg_lo:[0,1] neg_hi:[0,1]
	v_sub_f32_e32 v11, v20, v11
	v_add_f32_e32 v4, v4, v11
	v_add_f32_e32 v4, v4, v5
	v_add_f32_e32 v4, v12, v4
	v_mov_b32_e32 v5, 0x7f800000
	v_cndmask_b32_e32 v4, v5, v4, vcc
	v_cmp_ngt_f32_e32 vcc, -1.0, v9
	v_mov_b32_e32 v5, 0x7fc00000
	s_mov_b32 s63, 0x33800000
	v_cndmask_b32_e32 v4, v5, v4, vcc
	v_cmp_neq_f32_e32 vcc, -1.0, v9
	v_mov_b32_e32 v5, 0xff800000
	s_nop 0
	v_cndmask_b32_e32 v4, v5, v4, vcc
	v_cmp_lt_f32_e64 vcc, |v9|, s63
	s_nop 1
	v_cndmask_b32_e32 v4, v4, v9, vcc
; DI void ssd_part1_unit(int u, const bf16* PROJ, float* DT, const bf16* H, const bf16* wdtb_l, const float* dt_bias_l, const float* cw, const float* cb, const float* a_log_l, float* STATES, float* TOT,
;                        LAS unsigned char* ldsu, int tid, int wave, int lane) {
;     ...
;         if (r < 8) { const float bias = dt_bias_l[r];
; #pragma unroll
;             for (int i = 0; i < 4; ++i) { const float xx = dacc[i] + bias; DT[(size_t)(b * T + t0 + 16 * wave + 4 * g + i) * 8 + r] = xx > 20.f ? xx : log1pf(__expf(xx)); } }
.LBB0_338:
	s_or_b64 exec, exec, s[0:1]
	v_or_b32_e32 v12, 1, v8
	v_ashrrev_i32_e32 v13, 31, v12
	v_lshlrev_b64 v[12:13], 5, v[12:13]
	v_lshl_add_u64 v[12:13], v[108:109], 0, v[12:13]
	global_store_dword v[12:13], v4, off sc1
	v_add_f32_e32 v4, v6, v10
	s_mov_b32 s0, 0x41a00000
	v_cmp_nlt_f32_e32 vcc, s0, v4
	s_and_saveexec_b64 s[0:1], vcc
	s_cbranch_execz .LBB0_340
	v_mul_f32_e32 v4, 0x3fb8aa3b, v4
	v_exp_f32_e32 v6, v4
	s_mov_b32 s63, 0x3f2aaaab
	v_add_f32_e32 v9, 1.0, v6
	v_frexp_mant_f32_e32 v12, v9
	v_cvt_f64_f32_e32 v[4:5], v9
	v_frexp_exp_i32_f64_e32 v4, v[4:5]
	v_cmp_gt_f32_e32 vcc, s63, v12
	v_add_f32_e32 v11, -1.0, v9
	v_sub_f32_e32 v13, v11, v9
	v_subbrev_co_u32_e32 v18, vcc, 0, v4, vcc
	v_sub_u32_e32 v4, 0, v18
	v_sub_f32_e32 v11, v6, v11
	v_add_f32_e32 v13, 1.0, v13
	v_ldexp_f32 v5, v9, v4
	v_add_f32_e32 v11, v11, v13
	v_add_f32_e32 v9, -1.0, v5
	v_add_f32_e32 v12, 1.0, v5
	v_ldexp_f32 v4, v11, v4
	v_add_f32_e32 v11, 1.0, v9
	v_add_f32_e32 v13, -1.0, v12
	v_sub_f32_e32 v11, v5, v11
	v_sub_f32_e32 v5, v5, v13
	v_add_f32_e32 v11, v4, v11
	v_add_f32_e32 v4, v4, v5
	v_add_f32_e32 v19, v12, v4
	v_rcp_f32_e32 v21, v19
	v_sub_f32_e32 v5, v19, v12
	v_sub_f32_e32 v20, v4, v5
	v_add_f32_e32 v5, v9, v11
	v_sub_f32_e32 v4, v5, v9
	v_sub_f32_e32 v9, v11, v4
	v_mul_f32_e32 v11, v5, v21
	v_mul_f32_e32 v12, v19, v11
	v_fma_f32 v14, v11, v19, -v12
	v_fmac_f32_e32 v14, v11, v20
	v_add_f32_e32 v4, v12, v14
	v_sub_f32_e32 v13, v5, v4
	v_pk_add_f32 v[16:17], v[4:5], v[12:13] neg_lo:[0,1] neg_hi:[0,1]
	v_mov_b32_e32 v15, v4
	v_pk_add_f32 v[4:5], v[16:17], v[14:15] neg_lo:[0,1] neg_hi:[0,1]
	s_mov_b32 s63, 0x3f317218
	v_add_f32_e32 v5, v9, v5
	v_add_f32_e32 v4, v4, v5
	v_add_f32_e32 v5, v13, v4
	v_mul_f32_e32 v9, v21, v5
	v_mul_f32_e32 v12, v19, v9
	v_fma_f32 v14, v9, v19, -v12
	v_fmac_f32_e32 v14, v9, v20
	v_sub_f32_e32 v13, v13, v5
	v_add_f32_e32 v19, v4, v13
	v_add_f32_e32 v4, v12, v14
	v_sub_f32_e32 v13, v5, v4
	v_pk_add_f32 v[16:17], v[4:5], v[12:13] neg_lo:[0,1] neg_hi:[0,1]
	v_mov_b32_e32 v15, v4
	v_pk_add_f32 v[4:5], v[16:17], v[14:15] neg_lo:[0,1] neg_hi:[0,1]
	s_nop 0
	v_add_f32_e32 v5, v19, v5
	v_add_f32_e32 v4, v4, v5
	v_add_f32_e32 v5, v11, v9
	v_add_f32_e32 v4, v13, v4
	v_sub_f32_e32 v11, v5, v11
	v_mul_f32_e32 v4, v21, v4
	v_sub_f32_e32 v9, v9, v11
	v_add_f32_e32 v9, v9, v4
	v_add_f32_e32 v11, v5, v9
	v_mul_f32_e32 v12, v11, v11
	v_mov_b32_e32 v4, 0x3ecc95a3
	v_fmamk_f32 v4, v12, 0x3e9b6dac, v4
	v_fmaak_f32 v193, v12, v4, 0x3f2aaada
	v_cvt_f32_i32_e32 v4, v18
	v_sub_f32_e32 v5, v11, v5
	v_sub_f32_e32 v5, v9, v5
	v_ldexp_f32 v9, v5, 1
	v_mul_f32_e32 v5, v11, v12
	v_pk_mul_f32 v[14:15], v[4:5], v[192:193]
	v_ldexp_f32 v13, v11, 1
	v_fma_f32 v12, v4, s63, -v14
	v_fmac_f32_e32 v12, 0xb102e308, v4
	v_pk_add_f32 v[4:5], v[14:15], v[12:13]
	v_mov_b32_e32 v16, v14
	v_sub_f32_e32 v11, v5, v13
	v_sub_f32_e32 v11, v15, v11
	v_add_f32_e32 v17, v9, v11
	v_pk_add_f32 v[14:15], v[4:5], v[14:15] neg_lo:[0,1] neg_hi:[0,1]
	v_pk_add_f32 v[18:19], v[4:5], v[16:17]
	v_mov_b32_e32 v13, v4
	v_mov_b32_e32 v15, v19
	v_pk_add_f32 v[20:21], v[12:13], v[14:15] neg_lo:[0,1] neg_hi:[0,1]
	v_pk_add_f32 v[12:13], v[12:13], v[14:15]
	v_mov_b32_e32 v16, v17
	v_pk_add_f32 v[14:15], v[12:13], v[4:5] op_sel:[1,0] op_sel_hi:[0,1] neg_lo:[0,1] neg_hi:[0,1]
	v_pk_add_f32 v[22:23], v[18:19], v[14:15] op_sel_hi:[1,0] neg_lo:[0,1] neg_hi:[0,1]
	v_mov_b32_e32 v18, v19
	v_mov_b32_e32 v19, v13
	v_pk_mov_b32 v[14:15], v[4:5], v[14:15] op_sel:[1,0]
	v_mov_b32_e32 v17, v4
	v_pk_add_f32 v[14:15], v[18:19], v[14:15] neg_lo:[0,1] neg_hi:[0,1]
	v_mov_b32_e32 v22, v20
	v_pk_add_f32 v[4:5], v[16:17], v[14:15] neg_lo:[0,1] neg_hi:[0,1]
	v_mov_b32_e32 v21, v13
	v_pk_add_f32 v[14:15], v[22:23], v[4:5]
	s_mov_b32 s63, 0x7f800000
	v_pk_add_f32 v[16:17], v[14:15], v[14:15] op_sel:[0,1] op_sel_hi:[1,0]
	v_cmp_neq_f32_e32 vcc, s63, v6
	v_pk_add_f32 v[12:13], v[12:13], v[16:17] op_sel:[1,0] op_sel_hi:[0,1]
	v_mov_b32_e32 v15, v12
	v_pk_add_f32 v[18:19], v[14:15], v[20:21] neg_lo:[0,1] neg_hi:[0,1]
	v_mov_b32_e32 v5, v16
	v_sub_f32_e32 v9, v14, v18
	v_pk_add_f32 v[4:5], v[4:5], v[18:19] neg_lo:[0,1] neg_hi:[0,1]
	v_sub_f32_e32 v9, v20, v9
	v_add_f32_e32 v4, v4, v9
	v_add_f32_e32 v4, v4, v5
	v_add_f32_e32 v4, v12, v4
	v_mov_b32_e32 v5, 0x7f800000
	v_cndmask_b32_e32 v4, v5, v4, vcc
	v_cmp_ngt_f32_e32 vcc, -1.0, v6
	v_mov_b32_e32 v5, 0x7fc00000
	s_mov_b32 s63, 0x33800000
	v_cndmask_b32_e32 v4, v5, v4, vcc
	v_cmp_neq_f32_e32 vcc, -1.0, v6
	v_mov_b32_e32 v5, 0xff800000
	s_nop 0
	v_cndmask_b32_e32 v4, v5, v4, vcc
	v_cmp_lt_f32_e64 vcc, |v6|, s63
	s_nop 1
	v_cndmask_b32_e32 v4, v4, v6, vcc
; DI void ssd_part1_unit(int u, const bf16* PROJ, float* DT, const bf16* H, const bf16* wdtb_l, const float* dt_bias_l, const float* cw, const float* cb, const float* a_log_l, float* STATES, float* TOT,
;                        LAS unsigned char* ldsu, int tid, int wave, int lane) {
;     ...
;         if (r < 8) { const float bias = dt_bias_l[r];
; #pragma unroll
;             for (int i = 0; i < 4; ++i) { const float xx = dacc[i] + bias; DT[(size_t)(b * T + t0 + 16 * wave + 4 * g + i) * 8 + r] = xx > 20.f ? xx : log1pf(__expf(xx)); } }
.LBB0_340:
	s_or_b64 exec, exec, s[0:1]
	v_or_b32_e32 v12, 2, v8
	v_ashrrev_i32_e32 v13, 31, v12
	v_lshlrev_b64 v[12:13], 5, v[12:13]
	v_lshl_add_u64 v[12:13], v[108:109], 0, v[12:13]
	global_store_dword v[12:13], v4, off sc1
	v_add_f32_e32 v4, v7, v10
	s_mov_b32 s0, 0x41a00000
	v_cmp_nlt_f32_e32 vcc, s0, v4
	s_and_saveexec_b64 s[0:1], vcc
	s_cbranch_execz .LBB0_342
	v_mul_f32_e32 v4, 0x3fb8aa3b, v4
	v_exp_f32_e32 v9, v4
	s_mov_b32 s63, 0x3f2aaaab
	v_add_f32_e32 v6, 1.0, v9
	v_frexp_mant_f32_e32 v10, v6
	v_cvt_f64_f32_e32 v[4:5], v6
	v_frexp_exp_i32_f64_e32 v4, v[4:5]
	v_cmp_gt_f32_e32 vcc, s63, v10
	v_add_f32_e32 v7, -1.0, v6
	v_sub_f32_e32 v11, v7, v6
	v_subbrev_co_u32_e32 v14, vcc, 0, v4, vcc
	v_sub_u32_e32 v4, 0, v14
	v_sub_f32_e32 v7, v9, v7
	v_add_f32_e32 v11, 1.0, v11
	v_ldexp_f32 v5, v6, v4
	v_add_f32_e32 v7, v7, v11
	v_add_f32_e32 v6, -1.0, v5
	v_add_f32_e32 v10, 1.0, v5
	v_ldexp_f32 v4, v7, v4
	v_add_f32_e32 v7, 1.0, v6
	v_add_f32_e32 v11, -1.0, v10
	v_sub_f32_e32 v7, v5, v7
	v_sub_f32_e32 v5, v5, v11
	v_add_f32_e32 v7, v4, v7
	v_add_f32_e32 v4, v4, v5
	v_add_f32_e32 v15, v10, v4
	v_rcp_f32_e32 v17, v15
	v_sub_f32_e32 v5, v15, v10
	v_sub_f32_e32 v16, v4, v5
	v_add_f32_e32 v5, v6, v7
	v_mul_f32_e32 v19, v5, v17
	v_sub_f32_e32 v4, v5, v6
	v_mul_f32_e32 v6, v15, v19
	v_fma_f32 v10, v19, v15, -v6
	v_fmac_f32_e32 v10, v19, v16
	v_sub_f32_e32 v18, v7, v4
	v_add_f32_e32 v4, v6, v10
	v_sub_f32_e32 v7, v5, v4
	v_pk_add_f32 v[12:13], v[4:5], v[6:7] neg_lo:[0,1] neg_hi:[0,1]
	v_mov_b32_e32 v11, v4
	v_pk_add_f32 v[4:5], v[12:13], v[10:11] neg_lo:[0,1] neg_hi:[0,1]
	s_mov_b32 s63, 0x3f317218
	v_add_f32_e32 v5, v18, v5
	v_add_f32_e32 v4, v4, v5
	v_add_f32_e32 v5, v7, v4
	v_mul_f32_e32 v18, v17, v5
	v_mul_f32_e32 v6, v15, v18
	v_fma_f32 v10, v18, v15, -v6
	v_fmac_f32_e32 v10, v18, v16
	v_sub_f32_e32 v7, v7, v5
	v_add_f32_e32 v15, v4, v7
	v_add_f32_e32 v4, v6, v10
	v_sub_f32_e32 v7, v5, v4
	v_pk_add_f32 v[12:13], v[4:5], v[6:7] neg_lo:[0,1] neg_hi:[0,1]
	v_mov_b32_e32 v11, v4
	v_pk_add_f32 v[4:5], v[12:13], v[10:11] neg_lo:[0,1] neg_hi:[0,1]
	s_nop 0
	v_add_f32_e32 v5, v15, v5
	v_add_f32_e32 v4, v4, v5
	v_add_f32_e32 v5, v19, v18
	v_add_f32_e32 v4, v7, v4
	v_sub_f32_e32 v6, v5, v19
	v_mul_f32_e32 v4, v17, v4
	v_sub_f32_e32 v6, v18, v6
	v_add_f32_e32 v6, v6, v4
	v_add_f32_e32 v10, v5, v6
	v_mul_f32_e32 v11, v10, v10
	v_mov_b32_e32 v4, 0x3ecc95a3
	v_fmamk_f32 v4, v11, 0x3e9b6dac, v4
	v_fmaak_f32 v193, v11, v4, 0x3f2aaada
	v_cvt_f32_i32_e32 v4, v14
	v_sub_f32_e32 v5, v10, v5
	v_sub_f32_e32 v5, v6, v5
	v_ldexp_f32 v12, v5, 1
	v_mul_f32_e32 v5, v10, v11
	v_ldexp_f32 v7, v10, 1
	v_pk_mul_f32 v[10:11], v[4:5], v[192:193]
	s_nop 0
	v_fma_f32 v6, v4, s63, -v10
	v_fmac_f32_e32 v6, 0xb102e308, v4
	v_pk_add_f32 v[4:5], v[10:11], v[6:7]
	s_mov_b32 s63, 0x7f800000
	v_sub_f32_e32 v7, v5, v7
	v_sub_f32_e32 v7, v11, v7
	v_add_f32_e32 v13, v12, v7
	v_mov_b32_e32 v12, v10
	v_pk_add_f32 v[10:11], v[4:5], v[10:11] neg_lo:[0,1] neg_hi:[0,1]
	v_pk_add_f32 v[14:15], v[4:5], v[12:13]
	v_mov_b32_e32 v7, v4
	v_mov_b32_e32 v11, v15
	v_pk_add_f32 v[16:17], v[6:7], v[10:11] neg_lo:[0,1] neg_hi:[0,1]
	v_pk_add_f32 v[6:7], v[6:7], v[10:11]
	v_mov_b32_e32 v12, v13
	v_pk_add_f32 v[10:11], v[6:7], v[4:5] op_sel:[1,0] op_sel_hi:[0,1] neg_lo:[0,1] neg_hi:[0,1]
	v_pk_add_f32 v[18:19], v[14:15], v[10:11] op_sel_hi:[1,0] neg_lo:[0,1] neg_hi:[0,1]
	v_mov_b32_e32 v14, v15
	v_mov_b32_e32 v15, v7
	v_pk_mov_b32 v[10:11], v[4:5], v[10:11] op_sel:[1,0]
	v_mov_b32_e32 v13, v4
	v_pk_add_f32 v[10:11], v[14:15], v[10:11] neg_lo:[0,1] neg_hi:[0,1]
	v_mov_b32_e32 v18, v16
	v_pk_add_f32 v[4:5], v[12:13], v[10:11] neg_lo:[0,1] neg_hi:[0,1]
	v_mov_b32_e32 v17, v7
	v_pk_add_f32 v[10:11], v[18:19], v[4:5]
	v_cmp_neq_f32_e32 vcc, s63, v9
	v_pk_add_f32 v[12:13], v[10:11], v[10:11] op_sel:[0,1] op_sel_hi:[1,0]
	s_mov_b32 s63, 0x33800000
	v_pk_add_f32 v[6:7], v[6:7], v[12:13] op_sel:[1,0] op_sel_hi:[0,1]
	v_mov_b32_e32 v11, v6
	v_pk_add_f32 v[14:15], v[10:11], v[16:17] neg_lo:[0,1] neg_hi:[0,1]
	v_mov_b32_e32 v5, v12
	v_sub_f32_e32 v7, v10, v14
	v_pk_add_f32 v[4:5], v[4:5], v[14:15] neg_lo:[0,1] neg_hi:[0,1]
	v_sub_f32_e32 v7, v16, v7
	v_add_f32_e32 v4, v4, v7
	v_add_f32_e32 v4, v4, v5
	v_add_f32_e32 v4, v6, v4
	v_mov_b32_e32 v5, 0x7f800000
	v_cndmask_b32_e32 v4, v5, v4, vcc
	v_cmp_ngt_f32_e32 vcc, -1.0, v9
	v_mov_b32_e32 v5, 0x7fc00000
	s_nop 0
	v_cndmask_b32_e32 v4, v5, v4, vcc
	v_cmp_neq_f32_e32 vcc, -1.0, v9
	v_mov_b32_e32 v5, 0xff800000
	s_nop 0
	v_cndmask_b32_e32 v4, v5, v4, vcc
	v_cmp_lt_f32_e64 vcc, |v9|, s63
	s_nop 1
	v_cndmask_b32_e32 v4, v4, v9, vcc
.LBB0_342:
	s_or_b64 exec, exec, s[0:1]
	v_or_b32_e32 v6, 3, v8
	v_ashrrev_i32_e32 v7, 31, v6
	v_lshlrev_b64 v[6:7], 5, v[6:7]
	v_lshl_add_u64 v[6:7], v[108:109], 0, v[6:7]
	global_store_dword v[6:7], v4, off sc1

; #define LAS __attribute__((address_space(3)))
; DI unsigned pk2(float lo, float hi) { f32x2_t v = {lo, hi}; bf16x2_t b = __builtin_convertvector(v, bf16x2_t); return __builtin_bit_cast(unsigned, b); }
; DI float silu_f(float x) { return x * __builtin_amdgcn_rcpf(1.f + __expf(-x)); }
; DI void conv_image(LAS char* img, const bf16* PROJ, int b, int t0, int chan0, const float* cw, const float* cb, int item) {
;     ...
;     for (int ri = 0; ri < 12; ++ri) {
;         const int t = tb - 2 + ri;
;         u32x4 v = (u32x4){0u, 0u, 0u, 0u};
;         if (t >= 0 && t < T) v = *(const u32x4*)(base + (size_t)t * 64);
;         float in[8] = {bflo(v.x), bfhi(v.x), bflo(v.y), bfhi(v.y), bflo(v.z), bfhi(v.z), bflo(v.w), bfhi(v.w)};
; #pragma unroll
;         for (int k = 0; k < 5; ++k) { const int oi = ri - k;
;             if (oi >= 0 && oi < 8) {
; #pragma unroll
;                 for (int e = 0; e < 8; ++e) o[oi][e] += w[k][e] * in[e]; } }
;     }
; #pragma unroll
;     for (int oi = 0; oi < 8; ++oi) { u32x4 pk; pk.x = pk2(silu_f(o[oi][0]), silu_f(o[oi][1])); pk.y = pk2(silu_f(o[oi][2]), silu_f(o[oi][3]));
;         pk.z = pk2(silu_f(o[oi][4]), silu_f(o[oi][5])); pk.w = pk2(silu_f(o[oi][6]), silu_f(o[oi][7]));
;         *(LAS u32x4*)(img + (tg * 8 + oi) * IMG_PITCH + cgp * 16) = pk; }
.LBB0_353:
	s_or_b64 exec, exec, s[0:1]
	s_waitcnt vmcnt(8)
	v_lshlrev_b32_e32 v152, 16, v80
	v_and_b32_e32 v153, 0xffff0000, v80
	v_lshlrev_b32_e32 v166, 16, v84
	v_and_b32_e32 v167, 0xffff0000, v84
	v_pk_fma_f32 v[152:153], v[28:29], v[152:153], v[48:49]
	s_waitcnt vmcnt(7)
	v_lshlrev_b32_e32 v158, 16, v88
	v_and_b32_e32 v159, 0xffff0000, v88
	v_pk_fma_f32 v[152:153], v[32:33], v[166:167], v[152:153]
	s_waitcnt vmcnt(6)
	v_lshlrev_b32_e32 v150, 16, v92
	v_and_b32_e32 v151, 0xffff0000, v92
	v_pk_fma_f32 v[152:153], v[36:37], v[158:159], v[152:153]
	s_waitcnt vmcnt(5)
	v_lshlrev_b32_e32 v148, 16, v96
	v_and_b32_e32 v149, 0xffff0000, v96
	v_pk_fma_f32 v[152:153], v[40:41], v[150:151], v[152:153]
	v_lshlrev_b32_e32 v160, 16, v89
	v_pk_fma_f32 v[152:153], v[44:45], v[148:149], v[152:153]
	v_and_b32_e32 v161, 0xffff0000, v89
	v_mul_f32_e32 v80, 0xbfb8aa3b, v152
	v_exp_f32_e32 v80, v80
	v_lshlrev_b32_e32 v88, 16, v85
	v_and_b32_e32 v89, 0xffff0000, v85
	v_lshlrev_b32_e32 v96, 16, v97
	v_add_f32_e32 v80, 1.0, v80
	v_rcp_f32_e32 v154, v80
	v_mul_f32_e32 v80, 0xbfb8aa3b, v153
	v_exp_f32_e32 v80, v80
	v_and_b32_e32 v97, 0xffff0000, v97
	v_lshlrev_b32_e32 v168, 16, v86
	v_and_b32_e32 v169, 0xffff0000, v86
	v_add_f32_e32 v80, 1.0, v80
	v_rcp_f32_e32 v155, v80
	v_lshlrev_b32_e32 v80, 16, v81
	v_and_b32_e32 v81, 0xffff0000, v81
	v_pk_fma_f32 v[80:81], v[30:31], v[80:81], v[50:51]
	v_pk_mul_f32 v[152:153], v[152:153], v[154:155]
	v_pk_fma_f32 v[80:81], v[34:35], v[88:89], v[80:81]
	v_cvt_pk_bf16_f32 v92, v152, v153
	v_lshlrev_b32_e32 v152, 16, v93
	v_and_b32_e32 v153, 0xffff0000, v93
	v_pk_fma_f32 v[80:81], v[38:39], v[160:161], v[80:81]
	v_lshlrev_b32_e32 v162, 16, v90
	v_pk_fma_f32 v[80:81], v[42:43], v[152:153], v[80:81]
	v_and_b32_e32 v163, 0xffff0000, v90
	v_pk_fma_f32 v[80:81], v[46:47], v[96:97], v[80:81]
	v_lshlrev_b32_e32 v154, 16, v94
	v_mul_f32_e32 v84, 0xbfb8aa3b, v80
	v_mul_f32_e32 v85, 0xbfb8aa3b, v81
	v_exp_f32_e32 v84, v84
	v_exp_f32_e32 v85, v85
	v_and_b32_e32 v155, 0xffff0000, v94
	v_lshlrev_b32_e32 v86, 16, v87
	v_add_f32_e32 v84, 1.0, v84
	v_add_f32_e32 v85, 1.0, v85
	v_rcp_f32_e32 v84, v84
	v_rcp_f32_e32 v85, v85
	v_and_b32_e32 v87, 0xffff0000, v87
	v_lshlrev_b32_e32 v164, 16, v91
	v_and_b32_e32 v165, 0xffff0000, v91
	v_pk_mul_f32 v[80:81], v[80:81], v[84:85]
	v_lshlrev_b32_e32 v84, 16, v82
	v_and_b32_e32 v85, 0xffff0000, v82
	v_pk_fma_f32 v[84:85], v[4:5], v[84:85], v[24:25]
	v_cvt_pk_bf16_f32 v93, v80, v81
	v_pk_fma_f32 v[84:85], v[8:9], v[168:169], v[84:85]
	v_lshlrev_b32_e32 v80, 16, v98
	v_pk_fma_f32 v[84:85], v[12:13], v[162:163], v[84:85]
	v_and_b32_e32 v81, 0xffff0000, v98
	v_pk_fma_f32 v[84:85], v[16:17], v[154:155], v[84:85]
	s_waitcnt vmcnt(4)
	v_lshlrev_b32_e32 v98, 16, v76
	v_pk_fma_f32 v[84:85], v[20:21], v[80:81], v[84:85]
	s_lshl_b32 s64, s60, 1
	v_mul_f32_e32 v82, 0xbfb8aa3b, v84
	v_exp_f32_e32 v82, v82
	s_andn2_b64 vcc, exec, s[96:97]
	v_add_f32_e32 v82, 1.0, v82
	v_rcp_f32_e32 v156, v82
	v_mul_f32_e32 v82, 0xbfb8aa3b, v85
	v_exp_f32_e32 v82, v82
	s_nop 0
	v_add_f32_e32 v82, 1.0, v82
	v_rcp_f32_e32 v157, v82
	v_lshlrev_b32_e32 v82, 16, v83
	v_and_b32_e32 v83, 0xffff0000, v83
	v_pk_fma_f32 v[82:83], v[6:7], v[82:83], v[26:27]
	v_pk_mul_f32 v[84:85], v[84:85], v[156:157]
	v_pk_fma_f32 v[82:83], v[10:11], v[86:87], v[82:83]
	v_lshlrev_b32_e32 v156, 16, v95
	v_and_b32_e32 v157, 0xffff0000, v95
	v_pk_fma_f32 v[82:83], v[14:15], v[164:165], v[82:83]
	v_cvt_pk_bf16_f32 v94, v84, v85
	v_lshlrev_b32_e32 v84, 16, v99
	v_and_b32_e32 v85, 0xffff0000, v99
	v_pk_fma_f32 v[82:83], v[18:19], v[156:157], v[82:83]
	v_and_b32_e32 v99, 0xffff0000, v76
	v_pk_fma_f32 v[82:83], v[22:23], v[84:85], v[82:83]
	s_nop 0
	v_mul_f32_e32 v90, 0xbfb8aa3b, v82
	v_mul_f32_e32 v91, 0xbfb8aa3b, v83
	v_exp_f32_e32 v90, v90
	v_exp_f32_e32 v91, v91
	v_add_f32_e32 v90, 1.0, v90
	v_add_f32_e32 v91, 1.0, v91
	v_rcp_f32_e32 v90, v90
	v_rcp_f32_e32 v91, v91
	s_nop 0
	v_pk_mul_f32 v[82:83], v[82:83], v[90:91]
	s_nop 0
	v_cvt_pk_bf16_f32 v95, v82, v83
	v_pk_fma_f32 v[82:83], v[28:29], v[166:167], v[48:49]
	ds_write_b128 v242, v[92:95]
	v_pk_fma_f32 v[82:83], v[32:33], v[158:159], v[82:83]
	v_lshlrev_b32_e32 v94, 16, v77
	v_pk_fma_f32 v[82:83], v[36:37], v[150:151], v[82:83]
	v_and_b32_e32 v95, 0xffff0000, v77
	v_pk_fma_f32 v[82:83], v[40:41], v[148:149], v[82:83]
	v_lshlrev_b32_e32 v92, 16, v78
	v_pk_fma_f32 v[82:83], v[44:45], v[98:99], v[82:83]
	v_and_b32_e32 v93, 0xffff0000, v78
	v_mul_f32_e32 v76, 0xbfb8aa3b, v82
	v_exp_f32_e32 v76, v76
	s_nop 0
	v_add_f32_e32 v76, 1.0, v76
	v_rcp_f32_e32 v90, v76
	v_mul_f32_e32 v76, 0xbfb8aa3b, v83
	v_exp_f32_e32 v76, v76
	s_nop 0
	v_add_f32_e32 v76, 1.0, v76
	v_rcp_f32_e32 v91, v76
	s_nop 0
	v_pk_mul_f32 v[82:83], v[82:83], v[90:91]
	s_nop 0
	v_cvt_pk_bf16_f32 v76, v82, v83
	v_pk_fma_f32 v[82:83], v[30:31], v[88:89], v[50:51]
	v_lshlrev_b32_e32 v90, 16, v79
	v_pk_fma_f32 v[82:83], v[34:35], v[160:161], v[82:83]
	v_and_b32_e32 v91, 0xffff0000, v79
	v_pk_fma_f32 v[82:83], v[38:39], v[152:153], v[82:83]
	s_nop 0
	v_pk_fma_f32 v[82:83], v[42:43], v[96:97], v[82:83]
	s_nop 0
	v_pk_fma_f32 v[82:83], v[46:47], v[94:95], v[82:83]
	s_nop 0
	v_mul_f32_e32 v77, 0xbfb8aa3b, v82
	v_exp_f32_e32 v77, v77
	s_nop 0
	v_add_f32_e32 v77, 1.0, v77
	v_rcp_f32_e32 v88, v77
	v_mul_f32_e32 v77, 0xbfb8aa3b, v83
	v_exp_f32_e32 v77, v77
	s_nop 0
	v_add_f32_e32 v77, 1.0, v77
	v_rcp_f32_e32 v89, v77
	s_nop 0
	v_pk_mul_f32 v[82:83], v[82:83], v[88:89]
	s_nop 0
	v_cvt_pk_bf16_f32 v77, v82, v83
	v_pk_fma_f32 v[82:83], v[4:5], v[168:169], v[24:25]
	s_nop 0
	v_pk_fma_f32 v[82:83], v[8:9], v[162:163], v[82:83]
	s_nop 0
	v_pk_fma_f32 v[82:83], v[12:13], v[154:155], v[82:83]
	s_nop 0
	v_pk_fma_f32 v[82:83], v[16:17], v[80:81], v[82:83]
	s_nop 0
	v_pk_fma_f32 v[82:83], v[20:21], v[92:93], v[82:83]
	s_nop 0
	v_mul_f32_e32 v78, 0xbfb8aa3b, v82
	v_exp_f32_e32 v78, v78
	s_nop 0
	v_add_f32_e32 v78, 1.0, v78
	v_rcp_f32_e32 v88, v78
	v_mul_f32_e32 v78, 0xbfb8aa3b, v83
	v_exp_f32_e32 v78, v78
	s_nop 0
	v_add_f32_e32 v78, 1.0, v78
	v_rcp_f32_e32 v89, v78
	s_nop 0
	v_pk_mul_f32 v[82:83], v[82:83], v[88:89]
	s_nop 0
	v_cvt_pk_bf16_f32 v78, v82, v83
	v_pk_fma_f32 v[82:83], v[6:7], v[86:87], v[26:27]
	s_waitcnt vmcnt(3)
; #define LAS __attribute__((address_space(3)))
; DI unsigned pk2(float lo, float hi) { f32x2_t v = {lo, hi}; bf16x2_t b = __builtin_convertvector(v, bf16x2_t); return __builtin_bit_cast(unsigned, b); }
; DI float silu_f(float x) { return x * __builtin_amdgcn_rcpf(1.f + __expf(-x)); }
; DI void conv_image(LAS char* img, const bf16* PROJ, int b, int t0, int chan0, const float* cw, const float* cb, int item) {
;     ...
;     for (int ri = 0; ri < 12; ++ri) {
;         const int t = tb - 2 + ri;
;         u32x4 v = (u32x4){0u, 0u, 0u, 0u};
;         if (t >= 0 && t < T) v = *(const u32x4*)(base + (size_t)t * 64);
;         float in[8] = {bflo(v.x), bfhi(v.x), bflo(v.y), bfhi(v.y), bflo(v.z), bfhi(v.z), bflo(v.w), bfhi(v.w)};
; #pragma unroll
;         for (int k = 0; k < 5; ++k) { const int oi = ri - k;
;             if (oi >= 0 && oi < 8) {
; #pragma unroll
;                 for (int e = 0; e < 8; ++e) o[oi][e] += w[k][e] * in[e]; } }
;     }
; #pragma unroll
;     for (int oi = 0; oi < 8; ++oi) { u32x4 pk; pk.x = pk2(silu_f(o[oi][0]), silu_f(o[oi][1])); pk.y = pk2(silu_f(o[oi][2]), silu_f(o[oi][3]));
;         pk.z = pk2(silu_f(o[oi][4]), silu_f(o[oi][5])); pk.w = pk2(silu_f(o[oi][6]), silu_f(o[oi][7]));
;         *(LAS u32x4*)(img + (tg * 8 + oi) * IMG_PITCH + cgp * 16) = pk; }
	v_lshlrev_b32_e32 v88, 16, v72
	v_pk_fma_f32 v[82:83], v[10:11], v[164:165], v[82:83]
	v_and_b32_e32 v89, 0xffff0000, v72
	v_pk_fma_f32 v[82:83], v[14:15], v[156:157], v[82:83]
	s_nop 0
	v_pk_fma_f32 v[82:83], v[18:19], v[84:85], v[82:83]
	s_nop 0
	v_pk_fma_f32 v[82:83], v[22:23], v[90:91], v[82:83]
	s_nop 0
	v_mul_f32_e32 v79, 0xbfb8aa3b, v82
	v_exp_f32_e32 v79, v79
	s_nop 0
	v_add_f32_e32 v79, 1.0, v79
	v_rcp_f32_e32 v86, v79
	v_mul_f32_e32 v79, 0xbfb8aa3b, v83
	v_exp_f32_e32 v79, v79
	s_nop 0
	v_add_f32_e32 v79, 1.0, v79
	v_rcp_f32_e32 v87, v79
	s_nop 0
	v_pk_mul_f32 v[82:83], v[82:83], v[86:87]
	s_nop 0
	v_cvt_pk_bf16_f32 v79, v82, v83
	ds_write_b128 v242, v[76:79] offset:272
	v_pk_fma_f32 v[76:77], v[28:29], v[158:159], v[48:49]
	v_lshlrev_b32_e32 v86, 16, v73
	v_pk_fma_f32 v[76:77], v[32:33], v[150:151], v[76:77]
	v_and_b32_e32 v87, 0xffff0000, v73
	v_pk_fma_f32 v[76:77], v[36:37], v[148:149], v[76:77]
	v_lshlrev_b32_e32 v82, 16, v74
	v_pk_fma_f32 v[76:77], v[40:41], v[98:99], v[76:77]
	v_and_b32_e32 v83, 0xffff0000, v74
	v_pk_fma_f32 v[76:77], v[44:45], v[88:89], v[76:77]
	s_nop 0
	v_mul_f32_e32 v72, 0xbfb8aa3b, v76
	v_exp_f32_e32 v72, v72
	s_nop 0
	v_add_f32_e32 v72, 1.0, v72
	v_rcp_f32_e32 v78, v72
	v_mul_f32_e32 v72, 0xbfb8aa3b, v77
	v_exp_f32_e32 v72, v72
	s_nop 0
	v_add_f32_e32 v72, 1.0, v72
	v_rcp_f32_e32 v79, v72
	s_nop 0
	v_pk_mul_f32 v[76:77], v[76:77], v[78:79]
	s_nop 0
	v_cvt_pk_bf16_f32 v72, v76, v77
	v_pk_fma_f32 v[76:77], v[30:31], v[160:161], v[50:51]
	s_nop 0
	v_pk_fma_f32 v[76:77], v[34:35], v[152:153], v[76:77]
	s_nop 0
	v_pk_fma_f32 v[76:77], v[38:39], v[96:97], v[76:77]
	s_nop 0
	v_pk_fma_f32 v[76:77], v[42:43], v[94:95], v[76:77]
	s_nop 0
	v_pk_fma_f32 v[76:77], v[46:47], v[86:87], v[76:77]
	s_nop 0
	v_mul_f32_e32 v73, 0xbfb8aa3b, v76
	v_exp_f32_e32 v73, v73
	s_nop 0
	v_add_f32_e32 v73, 1.0, v73
	v_rcp_f32_e32 v78, v73
	v_mul_f32_e32 v73, 0xbfb8aa3b, v77
	v_exp_f32_e32 v73, v73
	s_nop 0
	v_add_f32_e32 v73, 1.0, v73
	v_rcp_f32_e32 v79, v73
	s_nop 0
	v_pk_mul_f32 v[76:77], v[76:77], v[78:79]
	s_nop 0
	v_cvt_pk_bf16_f32 v73, v76, v77
	v_pk_fma_f32 v[76:77], v[4:5], v[162:163], v[24:25]
	s_nop 0
	v_pk_fma_f32 v[76:77], v[8:9], v[154:155], v[76:77]
	s_nop 0
	v_pk_fma_f32 v[76:77], v[12:13], v[80:81], v[76:77]
	s_nop 0
	v_pk_fma_f32 v[76:77], v[16:17], v[92:93], v[76:77]
	s_nop 0
	v_pk_fma_f32 v[76:77], v[20:21], v[82:83], v[76:77]
	s_nop 0
	v_mul_f32_e32 v74, 0xbfb8aa3b, v76
	v_exp_f32_e32 v74, v74
	s_nop 0
	v_add_f32_e32 v74, 1.0, v74
	v_rcp_f32_e32 v78, v74
	v_mul_f32_e32 v74, 0xbfb8aa3b, v77
	v_exp_f32_e32 v74, v74
	s_nop 0
	v_add_f32_e32 v74, 1.0, v74
	v_rcp_f32_e32 v79, v74
	s_nop 0
	v_pk_mul_f32 v[76:77], v[76:77], v[78:79]
	s_nop 0
	v_cvt_pk_bf16_f32 v74, v76, v77
	v_pk_fma_f32 v[76:77], v[6:7], v[164:165], v[26:27]
	v_lshlrev_b32_e32 v78, 16, v75
	v_pk_fma_f32 v[76:77], v[10:11], v[156:157], v[76:77]
	v_and_b32_e32 v79, 0xffff0000, v75
	v_pk_fma_f32 v[76:77], v[14:15], v[84:85], v[76:77]
	s_nop 0
	v_pk_fma_f32 v[76:77], v[18:19], v[90:91], v[76:77]
	s_nop 0
	v_pk_fma_f32 v[76:77], v[22:23], v[78:79], v[76:77]
	s_nop 0
	v_mul_f32_e32 v75, 0xbfb8aa3b, v76
	v_exp_f32_e32 v75, v75
	s_nop 0
	v_add_f32_e32 v75, 1.0, v75
	v_rcp_f32_e32 v158, v75
	v_mul_f32_e32 v75, 0xbfb8aa3b, v77
	v_exp_f32_e32 v75, v75
	s_nop 0
	v_add_f32_e32 v75, 1.0, v75
	v_rcp_f32_e32 v159, v75
	s_nop 0
	v_pk_mul_f32 v[76:77], v[76:77], v[158:159]
	s_nop 0
	v_cvt_pk_bf16_f32 v75, v76, v77
	ds_write_b128 v242, v[72:75] offset:544
	v_pk_fma_f32 v[72:73], v[28:29], v[150:151], v[48:49]
	s_waitcnt vmcnt(2)
	v_lshlrev_b32_e32 v76, 16, v68
	v_pk_fma_f32 v[72:73], v[32:33], v[148:149], v[72:73]
	v_and_b32_e32 v77, 0xffff0000, v68
	v_pk_fma_f32 v[72:73], v[36:37], v[98:99], v[72:73]
	s_nop 0
	v_pk_fma_f32 v[72:73], v[40:41], v[88:89], v[72:73]
	s_nop 0
	v_pk_fma_f32 v[72:73], v[44:45], v[76:77], v[72:73]
	s_nop 0
	v_mul_f32_e32 v68, 0xbfb8aa3b, v72
	v_exp_f32_e32 v68, v68
	s_nop 0
	v_add_f32_e32 v68, 1.0, v68
	v_rcp_f32_e32 v74, v68
	v_mul_f32_e32 v68, 0xbfb8aa3b, v73
	v_exp_f32_e32 v68, v68
	s_nop 0
	v_add_f32_e32 v68, 1.0, v68
	v_rcp_f32_e32 v75, v68
	s_nop 0
	v_pk_mul_f32 v[72:73], v[72:73], v[74:75]
	v_lshlrev_b32_e32 v74, 16, v69
	v_and_b32_e32 v75, 0xffff0000, v69
	v_pk_fma_f32 v[68:69], v[30:31], v[152:153], v[50:51]
	v_cvt_pk_bf16_f32 v150, v72, v73
	v_pk_fma_f32 v[68:69], v[34:35], v[96:97], v[68:69]
	s_nop 0
	v_pk_fma_f32 v[68:69], v[38:39], v[94:95], v[68:69]
	s_nop 0
	v_pk_fma_f32 v[68:69], v[42:43], v[86:87], v[68:69]
	s_nop 0
	v_pk_fma_f32 v[68:69], v[46:47], v[74:75], v[68:69]
	s_nop 0
	v_mul_f32_e32 v72, 0xbfb8aa3b, v68
	v_mul_f32_e32 v73, 0xbfb8aa3b, v69
	v_exp_f32_e32 v72, v72
	v_exp_f32_e32 v73, v73
	v_add_f32_e32 v72, 1.0, v72
	v_add_f32_e32 v73, 1.0, v73
	v_rcp_f32_e32 v72, v72
	v_rcp_f32_e32 v73, v73
	s_nop 0
	v_pk_mul_f32 v[68:69], v[68:69], v[72:73]
	s_nop 0
	v_cvt_pk_bf16_f32 v151, v68, v69
	v_pk_fma_f32 v[68:69], v[4:5], v[154:155], v[24:25]
	v_lshlrev_b32_e32 v72, 16, v70
	v_pk_fma_f32 v[68:69], v[8:9], v[80:81], v[68:69]
	v_and_b32_e32 v73, 0xffff0000, v70
	v_pk_fma_f32 v[68:69], v[12:13], v[92:93], v[68:69]
	v_pk_fma_f32 v[80:81], v[4:5], v[80:81], v[24:25]
	v_pk_fma_f32 v[68:69], v[16:17], v[82:83], v[68:69]
	v_pk_fma_f32 v[80:81], v[8:9], v[92:93], v[80:81]
	v_pk_fma_f32 v[68:69], v[20:21], v[72:73], v[68:69]
	v_pk_fma_f32 v[80:81], v[12:13], v[82:83], v[80:81]
	v_mul_f32_e32 v70, 0xbfb8aa3b, v68
	v_exp_f32_e32 v70, v70
	v_pk_fma_f32 v[80:81], v[16:17], v[72:73], v[80:81]
	v_add_f32_e32 v70, 1.0, v70
	v_rcp_f32_e32 v152, v70
	v_mul_f32_e32 v70, 0xbfb8aa3b, v69
	v_exp_f32_e32 v70, v70
	s_nop 0
	v_add_f32_e32 v70, 1.0, v70
	v_rcp_f32_e32 v153, v70
	s_nop 0
	v_pk_mul_f32 v[68:69], v[68:69], v[152:153]
	s_nop 0
	v_cvt_pk_bf16_f32 v152, v68, v69
	v_lshlrev_b32_e32 v68, 16, v71
	v_and_b32_e32 v69, 0xffff0000, v71
	v_pk_fma_f32 v[70:71], v[6:7], v[156:157], v[26:27]
	s_nop 0
	v_pk_fma_f32 v[70:71], v[10:11], v[84:85], v[70:71]
	s_nop 0
	v_pk_fma_f32 v[70:71], v[14:15], v[90:91], v[70:71]
	s_nop 0
	v_pk_fma_f32 v[70:71], v[18:19], v[78:79], v[70:71]
	s_nop 0
	v_pk_fma_f32 v[70:71], v[22:23], v[68:69], v[70:71]
	s_nop 0
	v_mul_f32_e32 v115, 0xbfb8aa3b, v70
	v_exp_f32_e32 v115, v115
	s_nop 0
	v_add_f32_e32 v115, 1.0, v115
	v_rcp_f32_e32 v154, v115
	v_mul_f32_e32 v115, 0xbfb8aa3b, v71
	v_exp_f32_e32 v115, v115
	s_nop 0
	v_add_f32_e32 v115, 1.0, v115
	v_rcp_f32_e32 v155, v115
	s_nop 0
	v_pk_mul_f32 v[70:71], v[70:71], v[154:155]
	s_nop 0
	v_cvt_pk_bf16_f32 v153, v70, v71
	v_pk_fma_f32 v[70:71], v[28:29], v[148:149], v[48:49]
	ds_write_b128 v242, v[150:153] offset:816
	v_pk_fma_f32 v[70:71], v[32:33], v[98:99], v[70:71]
	s_waitcnt vmcnt(1)
; #define LAS __attribute__((address_space(3)))
; DI unsigned pk2(float lo, float hi) { f32x2_t v = {lo, hi}; bf16x2_t b = __builtin_convertvector(v, bf16x2_t); return __builtin_bit_cast(unsigned, b); }
; DI float silu_f(float x) { return x * __builtin_amdgcn_rcpf(1.f + __expf(-x)); }
; DI void conv_image(LAS char* img, const bf16* PROJ, int b, int t0, int chan0, const float* cw, const float* cb, int item) {
;     ...
;     for (int ri = 0; ri < 12; ++ri) {
;         const int t = tb - 2 + ri;
;         u32x4 v = (u32x4){0u, 0u, 0u, 0u};
;         if (t >= 0 && t < T) v = *(const u32x4*)(base + (size_t)t * 64);
;         float in[8] = {bflo(v.x), bfhi(v.x), bflo(v.y), bfhi(v.y), bflo(v.z), bfhi(v.z), bflo(v.w), bfhi(v.w)};
; #pragma unroll
;         for (int k = 0; k < 5; ++k) { const int oi = ri - k;
;             if (oi >= 0 && oi < 8) {
; #pragma unroll
;                 for (int e = 0; e < 8; ++e) o[oi][e] += w[k][e] * in[e]; } }
;     }
; #pragma unroll
;     for (int oi = 0; oi < 8; ++oi) { u32x4 pk; pk.x = pk2(silu_f(o[oi][0]), silu_f(o[oi][1])); pk.y = pk2(silu_f(o[oi][2]), silu_f(o[oi][3]));
;         pk.z = pk2(silu_f(o[oi][4]), silu_f(o[oi][5])); pk.w = pk2(silu_f(o[oi][6]), silu_f(o[oi][7]));
;         *(LAS u32x4*)(img + (tg * 8 + oi) * IMG_PITCH + cgp * 16) = pk; }
	v_lshlrev_b32_e32 v150, 16, v64
	v_pk_fma_f32 v[70:71], v[36:37], v[88:89], v[70:71]
	v_and_b32_e32 v151, 0xffff0000, v64
	v_pk_fma_f32 v[70:71], v[40:41], v[76:77], v[70:71]
	s_nop 0
	v_pk_fma_f32 v[70:71], v[44:45], v[150:151], v[70:71]
	s_nop 0
	v_mul_f32_e32 v64, 0xbfb8aa3b, v70
	v_exp_f32_e32 v64, v64
	s_nop 0
	v_add_f32_e32 v64, 1.0, v64
	v_rcp_f32_e32 v148, v64
	v_mul_f32_e32 v64, 0xbfb8aa3b, v71
	v_exp_f32_e32 v64, v64
	s_nop 0
	v_add_f32_e32 v64, 1.0, v64
	v_rcp_f32_e32 v149, v64
	v_lshlrev_b32_e32 v64, 16, v65
	v_and_b32_e32 v65, 0xffff0000, v65
	v_pk_mul_f32 v[70:71], v[70:71], v[148:149]
	s_nop 0
	v_cvt_pk_bf16_f32 v152, v70, v71
	v_pk_fma_f32 v[70:71], v[30:31], v[96:97], v[50:51]
	s_nop 0
	v_pk_fma_f32 v[70:71], v[34:35], v[94:95], v[70:71]
	s_nop 0
	v_pk_fma_f32 v[70:71], v[38:39], v[86:87], v[70:71]
	s_nop 0
	v_pk_fma_f32 v[70:71], v[42:43], v[74:75], v[70:71]
	s_nop 0
	v_pk_fma_f32 v[70:71], v[46:47], v[64:65], v[70:71]
	s_nop 0
	v_mul_f32_e32 v96, 0xbfb8aa3b, v70
	v_mul_f32_e32 v97, 0xbfb8aa3b, v71
	v_exp_f32_e32 v96, v96
	v_exp_f32_e32 v97, v97
	v_add_f32_e32 v96, 1.0, v96
	v_add_f32_e32 v97, 1.0, v97
	v_rcp_f32_e32 v96, v96
	v_rcp_f32_e32 v97, v97
	s_nop 0
	v_pk_mul_f32 v[70:71], v[70:71], v[96:97]
	s_nop 0
	v_cvt_pk_bf16_f32 v153, v70, v71
	v_lshlrev_b32_e32 v70, 16, v66
	v_and_b32_e32 v71, 0xffff0000, v66
	v_pk_fma_f32 v[80:81], v[20:21], v[70:71], v[80:81]
	s_nop 0
	v_mul_f32_e32 v66, 0xbfb8aa3b, v80
	v_exp_f32_e32 v66, v66
	s_nop 0
	v_add_f32_e32 v66, 1.0, v66
	v_rcp_f32_e32 v96, v66
	v_mul_f32_e32 v66, 0xbfb8aa3b, v81
	v_exp_f32_e32 v66, v66
	s_nop 0
	v_add_f32_e32 v66, 1.0, v66
	v_rcp_f32_e32 v97, v66
	v_lshlrev_b32_e32 v66, 16, v67
	v_and_b32_e32 v67, 0xffff0000, v67
	v_pk_mul_f32 v[80:81], v[80:81], v[96:97]
	s_nop 0
	v_cvt_pk_bf16_f32 v154, v80, v81
	v_pk_fma_f32 v[80:81], v[6:7], v[84:85], v[26:27]
	s_waitcnt vmcnt(0)
	v_lshlrev_b32_e32 v96, 16, v60
	v_pk_fma_f32 v[80:81], v[10:11], v[90:91], v[80:81]
	v_and_b32_e32 v97, 0xffff0000, v60
	v_pk_fma_f32 v[80:81], v[14:15], v[78:79], v[80:81]
	s_nop 0
	v_pk_fma_f32 v[80:81], v[18:19], v[68:69], v[80:81]
	s_nop 0
	v_pk_fma_f32 v[80:81], v[22:23], v[66:67], v[80:81]
	s_nop 0
	v_mul_f32_e32 v84, 0xbfb8aa3b, v80
	v_mul_f32_e32 v85, 0xbfb8aa3b, v81
	v_exp_f32_e32 v84, v84
	v_exp_f32_e32 v85, v85
	v_add_f32_e32 v84, 1.0, v84
	v_add_f32_e32 v85, 1.0, v85
	v_rcp_f32_e32 v84, v84
	v_rcp_f32_e32 v85, v85
	s_nop 0
	v_pk_mul_f32 v[80:81], v[80:81], v[84:85]
	s_nop 0
	v_cvt_pk_bf16_f32 v155, v80, v81
	v_pk_fma_f32 v[80:81], v[28:29], v[98:99], v[48:49]
	ds_write_b128 v242, v[152:155] offset:1088
	v_pk_fma_f32 v[80:81], v[32:33], v[88:89], v[80:81]
	v_pk_fma_f32 v[88:89], v[28:29], v[88:89], v[48:49]
	v_pk_fma_f32 v[80:81], v[36:37], v[76:77], v[80:81]
	v_pk_fma_f32 v[88:89], v[32:33], v[76:77], v[88:89]
	v_pk_fma_f32 v[80:81], v[40:41], v[150:151], v[80:81]
	v_pk_fma_f32 v[88:89], v[36:37], v[150:151], v[88:89]
	v_pk_fma_f32 v[80:81], v[44:45], v[96:97], v[80:81]
	v_pk_fma_f32 v[88:89], v[40:41], v[96:97], v[88:89]
	v_mul_f32_e32 v60, 0xbfb8aa3b, v80
	v_exp_f32_e32 v60, v60
	v_pk_fma_f32 v[28:29], v[28:29], v[76:77], v[48:49]
	v_add_f32_e32 v60, 1.0, v60
	v_rcp_f32_e32 v84, v60
	v_mul_f32_e32 v60, 0xbfb8aa3b, v81
	v_exp_f32_e32 v60, v60
	v_pk_fma_f32 v[28:29], v[32:33], v[150:151], v[28:29]
	v_add_f32_e32 v60, 1.0, v60
	v_rcp_f32_e32 v85, v60
	v_pk_fma_f32 v[28:29], v[36:37], v[96:97], v[28:29]
	v_pk_mul_f32 v[80:81], v[80:81], v[84:85]
	v_lshlrev_b32_e32 v84, 16, v61
	v_and_b32_e32 v85, 0xffff0000, v61
	v_pk_fma_f32 v[60:61], v[30:31], v[94:95], v[50:51]
	v_cvt_pk_bf16_f32 v152, v80, v81
	v_pk_fma_f32 v[60:61], v[34:35], v[86:87], v[60:61]
	v_pk_fma_f32 v[86:87], v[30:31], v[86:87], v[50:51]
	v_pk_fma_f32 v[60:61], v[38:39], v[74:75], v[60:61]
	v_pk_fma_f32 v[86:87], v[34:35], v[74:75], v[86:87]
	v_pk_fma_f32 v[60:61], v[42:43], v[64:65], v[60:61]
	v_pk_fma_f32 v[86:87], v[38:39], v[64:65], v[86:87]
	v_pk_fma_f32 v[60:61], v[46:47], v[84:85], v[60:61]
	v_pk_fma_f32 v[86:87], v[42:43], v[84:85], v[86:87]
	v_mul_f32_e32 v80, 0xbfb8aa3b, v60
	v_mul_f32_e32 v81, 0xbfb8aa3b, v61
	v_exp_f32_e32 v80, v80
	v_exp_f32_e32 v81, v81
	v_pk_fma_f32 v[30:31], v[30:31], v[74:75], v[50:51]
	v_add_f32_e32 v80, 1.0, v80
	v_add_f32_e32 v81, 1.0, v81
	v_rcp_f32_e32 v80, v80
	v_rcp_f32_e32 v81, v81
	v_pk_fma_f32 v[30:31], v[34:35], v[64:65], v[30:31]
	v_pk_mul_f32 v[60:61], v[60:61], v[80:81]
	s_nop 0
	v_cvt_pk_bf16_f32 v153, v60, v61
	v_pk_fma_f32 v[60:61], v[4:5], v[92:93], v[24:25]
	v_lshlrev_b32_e32 v80, 16, v62
	v_pk_fma_f32 v[60:61], v[8:9], v[82:83], v[60:61]
	v_and_b32_e32 v81, 0xffff0000, v62
	v_pk_fma_f32 v[60:61], v[12:13], v[72:73], v[60:61]
	v_pk_fma_f32 v[82:83], v[4:5], v[82:83], v[24:25]
	v_pk_fma_f32 v[60:61], v[16:17], v[70:71], v[60:61]
	v_pk_fma_f32 v[82:83], v[8:9], v[72:73], v[82:83]
	v_pk_fma_f32 v[60:61], v[20:21], v[80:81], v[60:61]
	v_pk_fma_f32 v[82:83], v[12:13], v[70:71], v[82:83]
	v_mul_f32_e32 v62, 0xbfb8aa3b, v60
	v_exp_f32_e32 v62, v62
	v_pk_fma_f32 v[82:83], v[16:17], v[80:81], v[82:83]
	v_pk_fma_f32 v[30:31], v[38:39], v[84:85], v[30:31]
	v_pk_fma_f32 v[4:5], v[4:5], v[72:73], v[24:25]
	v_add_f32_e32 v62, 1.0, v62
	v_rcp_f32_e32 v92, v62
	v_mul_f32_e32 v62, 0xbfb8aa3b, v61
	v_exp_f32_e32 v62, v62
	v_pk_fma_f32 v[4:5], v[8:9], v[70:71], v[4:5]
	v_add_f32_e32 v62, 1.0, v62
	v_rcp_f32_e32 v93, v62
	v_pk_fma_f32 v[4:5], v[12:13], v[80:81], v[4:5]
	v_pk_mul_f32 v[60:61], v[60:61], v[92:93]
	s_nop 0
	v_cvt_pk_bf16_f32 v154, v60, v61
	v_lshlrev_b32_e32 v60, 16, v63
	v_and_b32_e32 v61, 0xffff0000, v63
	v_pk_fma_f32 v[62:63], v[6:7], v[90:91], v[26:27]
	s_nop 0
; #define LAS __attribute__((address_space(3)))
; DI unsigned pk2(float lo, float hi) { f32x2_t v = {lo, hi}; bf16x2_t b = __builtin_convertvector(v, bf16x2_t); return __builtin_bit_cast(unsigned, b); }
; DI float silu_f(float x) { return x * __builtin_amdgcn_rcpf(1.f + __expf(-x)); }
; DI void conv_image(LAS char* img, const bf16* PROJ, int b, int t0, int chan0, const float* cw, const float* cb, int item) {
;     ...
;         for (int k = 0; k < 5; ++k) { const int oi = ri - k;
;             if (oi >= 0 && oi < 8) {
; #pragma unroll
;                 for (int e = 0; e < 8; ++e) o[oi][e] += w[k][e] * in[e]; } }
;     }
; #pragma unroll
;     for (int oi = 0; oi < 8; ++oi) { u32x4 pk; pk.x = pk2(silu_f(o[oi][0]), silu_f(o[oi][1])); pk.y = pk2(silu_f(o[oi][2]), silu_f(o[oi][3]));
;         pk.z = pk2(silu_f(o[oi][4]), silu_f(o[oi][5])); pk.w = pk2(silu_f(o[oi][6]), silu_f(o[oi][7]));
;         *(LAS u32x4*)(img + (tg * 8 + oi) * IMG_PITCH + cgp * 16) = pk; }
; DI void ssd_part1_unit(int u, const bf16* PROJ, float* DT, const bf16* H, const bf16* wdtb_l, const float* dt_bias_l, const float* cw, const float* cb, const float* a_log_l, float* STATES, float* TOT,
;                        LAS unsigned char* ldsu, int tid, int wave, int lane) {
;     ...
;     asm volatile("s_waitcnt vmcnt(0)" ::: "memory");
;     __syncthreads();
	v_pk_fma_f32 v[62:63], v[10:11], v[78:79], v[62:63]
	v_pk_fma_f32 v[78:79], v[6:7], v[78:79], v[26:27]
	v_pk_fma_f32 v[62:63], v[14:15], v[68:69], v[62:63]
	v_pk_fma_f32 v[78:79], v[10:11], v[68:69], v[78:79]
	v_pk_fma_f32 v[62:63], v[18:19], v[66:67], v[62:63]
	v_pk_fma_f32 v[78:79], v[14:15], v[66:67], v[78:79]
	v_pk_fma_f32 v[62:63], v[22:23], v[60:61], v[62:63]
	v_pk_fma_f32 v[78:79], v[18:19], v[60:61], v[78:79]
	v_mul_f32_e32 v90, 0xbfb8aa3b, v62
	v_mul_f32_e32 v91, 0xbfb8aa3b, v63
	v_exp_f32_e32 v90, v90
	v_exp_f32_e32 v91, v91
	v_pk_fma_f32 v[6:7], v[6:7], v[68:69], v[26:27]
	v_add_f32_e32 v90, 1.0, v90
	v_add_f32_e32 v91, 1.0, v91
	v_rcp_f32_e32 v90, v90
	v_rcp_f32_e32 v91, v91
	v_pk_fma_f32 v[6:7], v[10:11], v[66:67], v[6:7]
	v_pk_mul_f32 v[62:63], v[62:63], v[90:91]
	s_nop 0
	v_cvt_pk_bf16_f32 v155, v62, v63
	v_lshlrev_b32_e32 v62, 16, v56
	v_and_b32_e32 v63, 0xffff0000, v56
	v_pk_fma_f32 v[88:89], v[44:45], v[62:63], v[88:89]
	v_pk_fma_f32 v[28:29], v[40:41], v[62:63], v[28:29]
	v_mul_f32_e32 v56, 0xbfb8aa3b, v88
	v_exp_f32_e32 v56, v56
	v_pk_fma_f32 v[6:7], v[14:15], v[60:61], v[6:7]
	ds_write_b128 v242, v[152:155] offset:1360
	v_add_f32_e32 v56, 1.0, v56
	v_rcp_f32_e32 v90, v56
	v_mul_f32_e32 v56, 0xbfb8aa3b, v89
	v_exp_f32_e32 v56, v56
	s_nop 0
	v_add_f32_e32 v56, 1.0, v56
	v_rcp_f32_e32 v91, v56
	s_nop 0
	v_pk_mul_f32 v[88:89], v[88:89], v[90:91]
	s_nop 0
	v_cvt_pk_bf16_f32 v56, v88, v89
	v_lshlrev_b32_e32 v88, 16, v57
	v_and_b32_e32 v89, 0xffff0000, v57
	v_pk_fma_f32 v[86:87], v[46:47], v[88:89], v[86:87]
	v_pk_fma_f32 v[30:31], v[42:43], v[88:89], v[30:31]
	v_mul_f32_e32 v57, 0xbfb8aa3b, v86
	v_exp_f32_e32 v57, v57
	s_nop 0
	v_add_f32_e32 v57, 1.0, v57
	v_rcp_f32_e32 v90, v57
	v_mul_f32_e32 v57, 0xbfb8aa3b, v87
	v_exp_f32_e32 v57, v57
	s_nop 0
	v_add_f32_e32 v57, 1.0, v57
	v_rcp_f32_e32 v91, v57
	s_nop 0
	v_pk_mul_f32 v[86:87], v[86:87], v[90:91]
	s_nop 0
	v_cvt_pk_bf16_f32 v57, v86, v87
	v_lshlrev_b32_e32 v86, 16, v58
	v_and_b32_e32 v87, 0xffff0000, v58
	v_pk_fma_f32 v[82:83], v[20:21], v[86:87], v[82:83]
	v_pk_fma_f32 v[4:5], v[16:17], v[86:87], v[4:5]
	v_mul_f32_e32 v58, 0xbfb8aa3b, v82
	v_exp_f32_e32 v58, v58
	s_nop 0
	v_add_f32_e32 v58, 1.0, v58
	v_rcp_f32_e32 v90, v58
	v_mul_f32_e32 v58, 0xbfb8aa3b, v83
	v_exp_f32_e32 v58, v58
	s_nop 0
	v_add_f32_e32 v58, 1.0, v58
	v_rcp_f32_e32 v91, v58
	s_nop 0
	v_pk_mul_f32 v[82:83], v[82:83], v[90:91]
	s_nop 0
	v_cvt_pk_bf16_f32 v58, v82, v83
	v_lshlrev_b32_e32 v82, 16, v59
	v_and_b32_e32 v83, 0xffff0000, v59
	v_pk_fma_f32 v[78:79], v[22:23], v[82:83], v[78:79]
	v_pk_fma_f32 v[6:7], v[18:19], v[82:83], v[6:7]
	v_mul_f32_e32 v59, 0xbfb8aa3b, v78
	v_exp_f32_e32 v59, v59
	s_nop 0
	v_add_f32_e32 v59, 1.0, v59
	v_rcp_f32_e32 v90, v59
	v_mul_f32_e32 v59, 0xbfb8aa3b, v79
	v_exp_f32_e32 v59, v59
	s_nop 0
	v_add_f32_e32 v59, 1.0, v59
	v_rcp_f32_e32 v91, v59
	s_nop 0
	v_pk_mul_f32 v[78:79], v[78:79], v[90:91]
	s_nop 0
	v_cvt_pk_bf16_f32 v59, v78, v79
	ds_write_b128 v242, v[56:59] offset:1632
	v_lshlrev_b32_e32 v56, 16, v52
	v_and_b32_e32 v57, 0xffff0000, v52
	v_pk_fma_f32 v[28:29], v[44:45], v[56:57], v[28:29]
	s_nop 0
	v_mul_f32_e32 v32, 0xbfb8aa3b, v28
	v_mul_f32_e32 v33, 0xbfb8aa3b, v29
	v_exp_f32_e32 v32, v32
	v_exp_f32_e32 v33, v33
	v_add_f32_e32 v32, 1.0, v32
	v_add_f32_e32 v33, 1.0, v33
	v_rcp_f32_e32 v32, v32
	v_rcp_f32_e32 v33, v33
	s_nop 0
	v_pk_mul_f32 v[28:29], v[28:29], v[32:33]
	v_lshlrev_b32_e32 v32, 16, v53
	v_and_b32_e32 v33, 0xffff0000, v53
	v_pk_fma_f32 v[30:31], v[46:47], v[32:33], v[30:31]
	v_cvt_pk_bf16_f32 v28, v28, v29
	v_mul_f32_e32 v29, 0xbfb8aa3b, v30
	v_exp_f32_e32 v29, v29
	s_nop 0
	v_add_f32_e32 v29, 1.0, v29
	v_rcp_f32_e32 v32, v29
	v_mul_f32_e32 v29, 0xbfb8aa3b, v31
	v_exp_f32_e32 v29, v29
	s_nop 0
	v_add_f32_e32 v29, 1.0, v29
	v_rcp_f32_e32 v33, v29
	s_nop 0
	v_pk_mul_f32 v[30:31], v[30:31], v[32:33]
	s_nop 0
	v_cvt_pk_bf16_f32 v29, v30, v31
	v_lshlrev_b32_e32 v30, 16, v54
	v_and_b32_e32 v31, 0xffff0000, v54
	v_pk_fma_f32 v[4:5], v[20:21], v[30:31], v[4:5]
	s_nop 0
	v_mul_f32_e32 v8, 0xbfb8aa3b, v4
	v_mul_f32_e32 v9, 0xbfb8aa3b, v5
	v_exp_f32_e32 v8, v8
	v_exp_f32_e32 v9, v9
	v_add_f32_e32 v8, 1.0, v8
	v_add_f32_e32 v9, 1.0, v9
	v_rcp_f32_e32 v8, v8
	v_rcp_f32_e32 v9, v9
	s_nop 0
	v_pk_mul_f32 v[4:5], v[4:5], v[8:9]
	s_nop 0
	v_cvt_pk_bf16_f32 v30, v4, v5
	v_lshlrev_b32_e32 v4, 16, v55
	v_and_b32_e32 v5, 0xffff0000, v55
	v_pk_fma_f32 v[4:5], v[22:23], v[4:5], v[6:7]
	s_nop 0
	v_mul_f32_e32 v6, 0xbfb8aa3b, v4
	v_mul_f32_e32 v7, 0xbfb8aa3b, v5
	v_exp_f32_e32 v6, v6
	v_exp_f32_e32 v7, v7
	v_add_f32_e32 v6, 1.0, v6
	v_add_f32_e32 v7, 1.0, v7
	v_rcp_f32_e32 v6, v6
	v_rcp_f32_e32 v7, v7
	s_nop 0
	v_pk_mul_f32 v[4:5], v[4:5], v[6:7]
	s_nop 0
	v_cvt_pk_bf16_f32 v31, v4, v5
	ds_write_b128 v242, v[28:31] offset:1904
	s_waitcnt vmcnt(0)
	s_waitcnt lgkmcnt(0)
	s_barrier
; #define LAS __attribute__((address_space(3)))
; template <bool AUXW>
; DI void decay_tables(LAS float* gtab, LAS float* aux, const float* DT, const float* a_log_l, float* TOT, int b, int c, int grp, int combo, int lane) {
;     const int hh = combo >> 1, dir = combo & 1, h = 2 * grp + hh;
;     const float A = -__expf(a_log_l[dir * 4 + h]);
;     const size_t row = (size_t)b * T + c * 128 + 2 * lane;
;     const float dt0 = DT[row * 8 + dir * 4 + h], dt1 = DT[(row + 1) * 8 + dir * 4 + h];
;     const float a0 = A * dt0, a1 = A * dt1;
;     float s = a0 + a1;
; #pragma unroll
;     for (int o = 1; o < 64; o <<= 1) { const float v = __shfl_up(s, o); if (lane >= o) s += v; }
;     const float tot = __shfl(s, 63);
;     float g0, g1;
;     if (dir == 0) { g1 = s; g0 = s - a1; } else { g0 = tot - (s - a1) + a0; g1 = tot - s + a1; }
;     gtab[combo * 128 + 2 * lane] = g0; gtab[combo * 128 + 2 * lane + 1] = g1;
;     if (AUXW) { aux[combo * 128 + 2 * lane] = dt0 * __expf(tot - g0); aux[combo * 128 + 2 * lane + 1] = dt1 * __expf(tot - g1);
;         if (lane == 0) TOT[((b * 16 + c) * 4 + h) * 2 + dir] = tot; }
	s_cbranch_vccnz .LBB0_265
	s_add_i32 s0, s64, s5
	s_add_i32 s60, s0, s33
	s_ashr_i32 s61, s60, 31
	s_lshl_b64 s[60:61], s[60:61], 2
	s_add_u32 s60, s2, s60
	s_addc_u32 s61, s4, s61
	global_load_dword v8, v189, s[60:61]
	s_lshl_b64 s[60:61], s[62:63], 11
	s_or_b32 s1, s60, s57
	v_mov_b32_e32 v5, s61
	v_or_b32_e32 v4, s1, v110
	v_lshlrev_b64 v[4:5], 5, v[4:5]
	s_ashr_i32 s1, s0, 31
	v_lshl_add_u64 v[4:5], s[94:95], 0, v[4:5]
	v_lshl_add_u64 v[4:5], s[0:1], 2, v[4:5]
	global_load_dword v6, v[4:5], off
	global_load_dword v7, v[4:5], off offset:32
	v_and_b32_e32 v9, 64, v224
	v_add_u32_e32 v4, -1, v224
	v_cmp_lt_i32_e32 vcc, v4, v9
	v_add_u32_e32 v11, -2, v224
	s_waitcnt vmcnt(2)
	v_mul_f32_e32 v5, 0x3fb8aa3b, v8
	v_exp_f32_e32 v8, v5
	v_cndmask_b32_e32 v4, v4, v224, vcc
	v_lshlrev_b32_e32 v10, 2, v4
	v_cmp_lt_i32_e32 vcc, v11, v9
	s_waitcnt vmcnt(0)
	v_pk_mul_f32 v[4:5], v[6:7], v[8:9] op_sel_hi:[1,0] neg_lo:[0,1] neg_hi:[0,1]
	s_nop 0
	v_add_f32_e32 v4, v4, v5
	ds_bpermute_b32 v10, v10, v4
	v_cndmask_b32_e32 v11, v11, v224, vcc
	v_lshlrev_b32_e32 v11, 2, v11
	s_waitcnt lgkmcnt(0)
	v_add_f32_e32 v10, v4, v10
	v_cndmask_b32_e64 v4, v10, v4, s[42:43]
	ds_bpermute_b32 v10, v11, v4
	v_add_u32_e32 v11, -4, v224
	v_cmp_lt_i32_e32 vcc, v11, v9
	s_waitcnt lgkmcnt(0)
	v_add_f32_e32 v10, v4, v10
	v_cndmask_b32_e32 v11, v11, v224, vcc
	v_lshlrev_b32_e32 v11, 2, v11
	v_cndmask_b32_e64 v4, v10, v4, s[44:45]
	ds_bpermute_b32 v10, v11, v4
	v_add_u32_e32 v11, -8, v224
	v_cmp_lt_i32_e32 vcc, v11, v9
	s_waitcnt lgkmcnt(0)
	v_add_f32_e32 v10, v4, v10
	v_cndmask_b32_e32 v11, v11, v224, vcc
	v_lshlrev_b32_e32 v11, 2, v11
	v_cndmask_b32_e64 v4, v10, v4, s[46:47]
	ds_bpermute_b32 v10, v11, v4
	v_add_u32_e32 v11, -16, v224
	v_cmp_lt_i32_e32 vcc, v11, v9
	s_waitcnt lgkmcnt(0)
	v_add_f32_e32 v10, v4, v10
	v_cndmask_b32_e32 v11, v11, v224, vcc
	v_lshlrev_b32_e32 v11, 2, v11
	v_cndmask_b32_e64 v4, v10, v4, s[48:49]
	ds_bpermute_b32 v10, v11, v4
	v_subrev_u32_e32 v11, 32, v224
	v_cmp_lt_i32_e32 vcc, v11, v9
	s_waitcnt lgkmcnt(0)
	v_add_f32_e32 v10, v4, v10
	v_cndmask_b32_e32 v9, v11, v224, vcc
	v_lshlrev_b32_e32 v9, 2, v9
	v_cndmask_b32_e64 v4, v10, v4, s[50:51]
	ds_bpermute_b32 v9, v9, v4
	v_bfrev_b32_e32 v10, 0.5
	v_lshl_or_b32 v10, v224, 2, v10
	s_waitcnt lgkmcnt(0)
	v_add_f32_e32 v9, v4, v9
	v_cndmask_b32_e64 v11, v9, v4, s[52:53]
	ds_bpermute_b32 v4, v10, v11
	v_sub_f32_e32 v10, v11, v5
	s_waitcnt lgkmcnt(0)
	v_pk_add_f32 v[12:13], v[4:5], v[10:11] op_sel_hi:[0,1] neg_lo:[0,1] neg_hi:[0,1]
	v_pk_fma_f32 v[8:9], v[6:7], v[8:9], v[12:13] op_sel_hi:[1,0,1] neg_lo:[0,1,0] neg_hi:[0,1,0]
	s_nop 0
	v_cndmask_b32_e64 v9, v9, v11, s[54:55]
	v_cndmask_b32_e64 v8, v8, v10, s[54:55]
	v_sub_f32_e32 v5, v4, v8
	v_sub_f32_e32 v10, v4, v9
	v_mul_f32_e32 v5, 0x3fb8aa3b, v5
	v_mul_f32_e32 v11, 0x3fb8aa3b, v10
	v_exp_f32_e32 v10, v5
	v_exp_f32_e32 v11, v11
	ds_write_b64 v229, v[8:9]
	v_pk_mul_f32 v[6:7], v[6:7], v[10:11]
	ds_write_b64 v230, v[6:7]
	s_and_saveexec_b64 s[60:61], s[42:43]
	s_cbranch_execz .LBB0_264
	s_lshl_b32 s1, s62, 6
	s_lshl_b32 s57, s34, 2
	s_or_b32 s1, s57, s1
	s_add_i32 s1, s1, s0
	s_lshl_b32 s0, s1, 1
	s_or_b32 s0, s0, s16
	s_ashr_i32 s1, s0, 31
	s_lshl_b64 s[0:1], s[0:1], 2
	s_add_u32 s0, s70, s0
	s_addc_u32 s1, s71, s1
	global_store_dword v189, v4, s[0:1] sc1
	s_branch .LBB0_264

; #define LAS __attribute__((address_space(3)))
; DI float ex2(float x) { return __builtin_amdgcn_exp2f(x); }
; DI float a_bound(const bf16x8 (&qf)[2], const float* kmax_l, int b, int h) { return sqrtf(q_norm2(qf) * (kmax_l[b * 128 + 8 + 2 * h] + kmax_l[b * 128 + 9 + 2 * h])) * 1.01f + 0.05f; }
; DI void tile_load(TileRegs& R, const bf16* kb, const bf16* vb, int tokbase, int stride, int lane) {
; #pragma unroll
;     for (int it = 0; it < 4; ++it) { const int n = lane + 64 * it, row = n >> 3, ch = n & 7; int tok = tokbase + stride * row; tok = min(max(tok, 0), T - 1);
;         R.k[it] = *(const u32x4*)(kb + (size_t)tok * 64 + ch * 8); R.v[it] = *(const u32x4*)(vb + (size_t)tok * 64 + ch * 8); }
; DI void mixerA1_unit(int u, const bf16* PROJ, bf16* YC, float* LPA, const float* kmax_l, LAS char* vt, int wave, int lane) {
;     const int b = u >> 6, h = (u >> 4) & 3, qblk = u & 15, r = lane & 15, g = lane >> 4;
;     const bf16* kb = slab(PROJ, C_AK + h * 64, b); const bf16* vb = slab(PROJ, C_AV + h * 64, b);
;     const int t0 = qblk * 128 + wave * 16, tq = t0 + r;
;     bf16x8 qf[2];
; #pragma unroll
;     for (int ks = 0; ks < 2; ++ks) qf[ks] = *(const bf16x8*)(slab(PROJ, C_AQ + h * 64, b) + (size_t)tq * 64 + 32 * ks + 8 * g);
;     const float nslope2 = -ex2(-(float)(2 * h + 1)) * LOG2E;
;     const float bound = a_bound(qf, kmax_l, b, h);
;     const f32x4 cinit = {-bound, -bound, -bound, -bound};
;     f32x4 o[4], ol = {0.f, 0.f, 0.f, 0.f};
; #pragma unroll
;     for (int c = 0; c < 4; ++c) o[c] = ol;
;     TileRegs R0, R1, R2;
;     const int tb0 = t0 - 64;
;     tile_load(R0, kb, vb, tb0, 1, lane); tile_load(R1, kb, vb, tb0 + 32, 1, lane); tile_load(R2, kb, vb, tb0 + 64, 1, lane);
;     f32x4 sA[2], sB[2];
;     a_stage(sA, R0, vt, 0, qf, cinit, tb0, 1, 64, tq, nslope2, lane);        tile_load(R0, kb, vb, tb0 + 96, 1, lane);
.LBB0_359:
	s_ashr_i32 s20, s26, 6
	s_bfe_u32 s27, s26, 0x20004
	s_ashr_i32 s21, s20, 31
	s_lshl_b32 s0, s27, 21
	s_add_u32 s31, s10, s0
	s_addc_u32 s33, s11, 0
	s_and_b32 s30, s16, 0x780
	s_add_i32 s30, s30, s5
	s_lshl_b64 s[0:1], s[20:21], 18
	v_or_b32_e32 v114, s30, v109
	s_add_u32 s0, s31, s0
	v_ashrrev_i32_e32 v115, 31, v114
	s_addc_u32 s1, s33, s1
	v_lshlrev_b64 v[4:5], 7, v[114:115]
	v_lshl_add_u64 v[4:5], s[0:1], 0, v[4:5]
	v_lshlrev_b32_e32 v188, 1, v108
	v_lshl_add_u64 v[8:9], v[4:5], 0, v[188:189]
	global_load_dwordx4 v[4:7], v[8:9], off offset:64
	s_nop 0
	global_load_dwordx4 v[8:11], v[8:9], off
	s_lshl_b32 s31, s27, 1
	s_lshl_b32 s33, s20, 7
	s_or_b32 s38, s31, s33
	s_ashr_i32 s39, s38, 31
	s_or_b32 s34, s31, 1
	s_lshl_b64 s[38:39], s[38:39], 2
	s_add_u32 s38, s2, s38
	s_addc_u32 s39, s4, s39
	global_load_dwordx2 v[12:13], v189, s[38:39] offset:32
	v_mov_b32_e32 v111, v189
	v_lshl_add_u64 v[14:15], s[0:1], 0, v[110:111]
	s_mov_b64 s[0:1], 0x800000
	v_lshl_add_u64 v[120:121], v[14:15], 0, s[0:1]
	s_mov_b64 s[0:1], 0x1000000
	s_sub_i32 s33, s30, 64
	v_lshl_add_u64 v[122:123], v[14:15], 0, s[0:1]
	v_or_b32_e32 v14, s33, v126
	v_cvt_f32_ubyte0_e32 v16, s34
	v_or_b32_e32 v15, s33, v127
	v_med3_i32 v14, v14, 0, v233
	v_exp_f32_e64 v34, -v16
	v_add_u32_e32 v16, s33, v128
	v_med3_i32 v18, v15, 0, v233
	v_lshlrev_b32_e32 v188, 7, v14
	v_add_u32_e32 v17, s33, v129
	v_med3_i32 v22, v16, 0, v233
	v_lshl_add_u64 v[14:15], v[120:121], 0, v[188:189]
	v_lshl_add_u64 v[20:21], v[122:123], 0, v[188:189]
	v_lshlrev_b32_e32 v188, 7, v18
	v_med3_i32 v23, v17, 0, v233
	global_load_dwordx4 v[16:19], v[14:15], off
	global_load_dwordx4 v[36:39], v[20:21], off
	v_lshl_add_u64 v[14:15], v[120:121], 0, v[188:189]
	v_lshl_add_u64 v[20:21], v[122:123], 0, v[188:189]
	v_lshlrev_b32_e32 v188, 7, v22
	global_load_dwordx4 v[40:43], v[14:15], off
	global_load_dwordx4 v[44:47], v[20:21], off
	v_lshl_add_u64 v[14:15], v[120:121], 0, v[188:189]
	v_lshl_add_u64 v[20:21], v[122:123], 0, v[188:189]
	global_load_dwordx4 v[48:51], v[14:15], off
	global_load_dwordx4 v[52:55], v[20:21], off
	v_lshlrev_b32_e32 v188, 7, v23
	s_sub_i32 s31, s30, 32
	v_or_b32_e32 v35, s31, v126
	v_or_b32_e32 v116, s30, v126
	v_or_b32_e32 v118, s30, v127
	v_mul_f32_e32 v111, 0xbfb8aa3b, v34
	v_add_u32_e32 v64, s30, v128
	v_med3_i32 v64, v64, 0, v233
	s_cmpk_lt_u32 s33, 0x800
	s_waitcnt vmcnt(8)
	v_and_b32_e32 v21, 0xffff0000, v4
	s_waitcnt vmcnt(7)
	v_and_b32_e32 v20, 0xffff0000, v8
	v_and_b32_e32 v25, 0xffff0000, v5
	v_and_b32_e32 v24, 0xffff0000, v9
	v_lshlrev_b32_e32 v15, 16, v4
	v_lshlrev_b32_e32 v14, 16, v8
	v_lshlrev_b32_e32 v23, 16, v5
	v_lshlrev_b32_e32 v22, 16, v9
	v_and_b32_e32 v29, 0xffff0000, v6
	v_and_b32_e32 v28, 0xffff0000, v10
	v_pk_mul_f32 v[20:21], v[20:21], v[20:21]
	v_pk_mul_f32 v[24:25], v[24:25], v[24:25]
	v_lshlrev_b32_e32 v27, 16, v6
	v_lshlrev_b32_e32 v26, 16, v10
	v_and_b32_e32 v33, 0xffff0000, v7
	v_and_b32_e32 v32, 0xffff0000, v11
	v_pk_mul_f32 v[28:29], v[28:29], v[28:29]
	v_pk_fma_f32 v[14:15], v[14:15], v[14:15], v[20:21]
	v_pk_fma_f32 v[20:21], v[22:23], v[22:23], v[24:25]
	v_lshlrev_b32_e32 v31, 16, v7
	v_lshlrev_b32_e32 v30, 16, v11
	v_pk_mul_f32 v[32:33], v[32:33], v[32:33]
	v_pk_fma_f32 v[22:23], v[26:27], v[26:27], v[28:29]
	v_pk_add_f32 v[14:15], v[14:15], v[20:21]
	v_pk_fma_f32 v[24:25], v[30:31], v[30:31], v[32:33]
	v_pk_add_f32 v[14:15], v[22:23], v[14:15]
	v_lshl_add_u64 v[20:21], v[122:123], 0, v[188:189]
	v_pk_add_f32 v[14:15], v[24:25], v[14:15]
	v_med3_i32 v28, v118, 0, v233
	v_add_f32_e32 v22, v14, v15
	v_lshl_add_u64 v[14:15], v[120:121], 0, v[188:189]
	global_load_dwordx4 v[56:59], v[14:15], off
	global_load_dwordx4 v[60:63], v[20:21], off
	ds_bpermute_b32 v23, v124, v22
	s_waitcnt vmcnt(8)
	v_mov_b32_e32 v14, v12
	v_mov_b32_e32 v20, v13
	s_waitcnt lgkmcnt(0)
	v_add_f32_e32 v15, v22, v23
	ds_bpermute_b32 v21, v125, v15
	v_med3_i32 v22, v35, 0, v233
	v_lshlrev_b32_e32 v188, 7, v22
	v_lshl_add_u64 v[22:23], v[122:123], 0, v[188:189]
	s_waitcnt lgkmcnt(0)
	v_pk_add_f32 v[12:13], v[14:15], v[20:21]
	v_lshl_add_u64 v[20:21], v[120:121], 0, v[188:189]
	global_load_dwordx4 v[84:87], v[20:21], off
	global_load_dwordx4 v[88:91], v[22:23], off
	v_or_b32_e32 v20, s31, v127
	v_med3_i32 v20, v20, 0, v233
	v_lshlrev_b32_e32 v188, 7, v20
	v_lshl_add_u64 v[20:21], v[120:121], 0, v[188:189]
	v_lshl_add_u64 v[22:23], v[122:123], 0, v[188:189]
	global_load_dwordx4 v[92:95], v[20:21], off
	global_load_dwordx4 v[96:99], v[22:23], off
	v_add_u32_e32 v20, s31, v128
	v_med3_i32 v20, v20, 0, v233
	v_lshlrev_b32_e32 v188, 7, v20
	v_lshl_add_u64 v[20:21], v[120:121], 0, v[188:189]
	v_lshl_add_u64 v[22:23], v[122:123], 0, v[188:189]
	global_load_dwordx4 v[100:103], v[20:21], off
	global_load_dwordx4 v[104:107], v[22:23], off
	v_add_u32_e32 v20, s31, v129
	v_med3_i32 v20, v20, 0, v233
	v_lshlrev_b32_e32 v188, 7, v20
	v_lshl_add_u64 v[20:21], v[120:121], 0, v[188:189]
	v_lshl_add_u64 v[22:23], v[122:123], 0, v[188:189]
	global_load_dwordx4 v[146:149], v[20:21], off
	global_load_dwordx4 v[150:153], v[22:23], off
	v_mul_f32_e32 v12, v12, v13
	v_mul_f32_e32 v13, 0x4f800000, v12
	v_cmp_gt_f32_e64 s[0:1], s92, v12
	v_med3_i32 v20, v116, 0, v233
	v_lshlrev_b32_e32 v188, 7, v20
	v_cndmask_b32_e64 v12, v12, v13, s[0:1]
	v_sqrt_f32_e32 v13, v12
	v_lshl_add_u64 v[20:21], v[120:121], 0, v[188:189]
	v_add_u32_e32 v14, -1, v13
	v_add_u32_e32 v15, 1, v13
	v_fma_f32 v24, -v14, v13, v12
	v_fma_f32 v25, -v15, v13, v12
	v_cmp_ge_f32_e64 s[38:39], 0, v24
	s_nop 1
	v_cndmask_b32_e64 v13, v13, v14, s[38:39]
	v_cmp_lt_f32_e64 s[38:39], 0, v25
	v_lshl_add_u64 v[24:25], v[122:123], 0, v[188:189]
	v_lshlrev_b32_e32 v188, 7, v28
	v_lshl_add_u64 v[28:29], v[120:121], 0, v[188:189]
	v_lshl_add_u64 v[32:33], v[122:123], 0, v[188:189]
	global_load_dwordx4 v[20:23], v[20:21], off
	s_nop 0
	global_load_dwordx4 v[24:27], v[24:25], off
	s_nop 0
	global_load_dwordx4 v[28:31], v[28:29], off
	s_nop 0
	global_load_dwordx4 v[32:35], v[32:33], off
	s_waitcnt vmcnt(18)
; #define LAS __attribute__((address_space(3)))
; #define MFMA16(a, b, c) __builtin_amdgcn_mfma_f32_16x16x32_bf16((a), (b), (c), 0, 0, 0)
; template <bool EDGE>
; DI void a_scores(f32x4 (&st)[2], const LAS char* kt, const bf16x8 (&qf)[2], const f32x4 cinit, int tokbase, int stride, int maxd, int tq, float nslope2, int lane) {
;     const int g = lane >> 4;
;     const int base0 = tokbase + stride * 4 * g - tq;
; #pragma unroll
;     for (int t = 0; t < 2; ++t) {
;         st[t] = MFMA16(k_frag_at(kt, t, 0, lane), qf[0], cinit); st[t] = MFMA16(k_frag_at(kt, t, 1, lane), qf[1], st[t]);
; #pragma unroll
;         for (int i = 0; i < 4; ++i) { const int d = base0 + stride * (16 * t + i);
;             bool ok = (unsigned)(d + maxd) <= (unsigned)(2 * maxd);
;             if (EDGE) ok = ok && ((unsigned)(d + tq) < (unsigned)T);
;             const float v = __builtin_fmaf(__builtin_fabsf((float)d), nslope2, st[t][i]);
;             st[t][i] = ok ? v : -1e30f; }
;     }
; DI void a_stage(f32x4 (&st)[2], const TileRegs& R, LAS char* vt, int vpar, const bf16x8 (&qf)[2], const f32x4 cinit, int tokbase, int stride, int maxd, int tq, float nslope2, int lane) {
; #pragma unroll
;     for (int it = 0; it < 4; ++it) { const int n = lane + 64 * it, row = n >> 3, ch = n & 7;
;         *(LAS u32x4*)(vt + vpar * A_V1 + row * VT_PITCH + ch * 16) = R.v[it]; *(LAS u32x4*)(vt + A_K + row * VT_PITCH + ch * 16) = R.k[it]; }
;     a_scores<true>(st, vt + A_K, qf, cinit, tokbase, stride, maxd, tq, nslope2, lane);
; }
	ds_write_b128 v142, v[36:39]
	ds_write_b128 v142, v[16:19] offset:9216
	s_waitcnt vmcnt(16)
	ds_write_b128 v142, v[44:47] offset:1152
	ds_write_b128 v142, v[40:43] offset:10368
	s_waitcnt vmcnt(14)
	ds_write_b128 v142, v[52:55] offset:2304
	ds_write_b128 v142, v[48:51] offset:11520
	s_waitcnt vmcnt(12)
	ds_write_b128 v142, v[60:63] offset:3456
	ds_write_b128 v142, v[56:59] offset:12672
	ds_read_b128 v[16:19], v143 offset:9216
	v_cndmask_b32_e64 v13, v13, v15, s[38:39]
	v_lshlrev_b32_e32 v188, 7, v64
	v_mul_f32_e32 v14, 0x37800000, v13
	v_lshl_add_u64 v[64:65], v[120:121], 0, v[188:189]
	v_add_u32_e32 v36, s30, v129
	v_cndmask_b32_e64 v13, v13, v14, s[0:1]
	v_cmp_class_f32_e64 s[0:1], v12, v226
	v_lshl_add_u64 v[66:67], v[122:123], 0, v[188:189]
	global_load_dwordx4 v[40:43], v[64:65], off
	global_load_dwordx4 v[48:51], v[66:67], off
	v_med3_i32 v44, v36, 0, v233
	ds_read_b128 v[36:39], v143 offset:9280
	v_cndmask_b32_e64 v12, v13, v12, s[0:1]
	v_fmamk_f32 v12, v12, 0x3f8147ae, v227
	v_xor_b32_e32 v12, 0x80000000, v12
	v_mov_b32_e32 v13, v12
	v_mov_b32_e32 v14, v12
	v_mov_b32_e32 v15, v12
	v_or_b32_e32 v52, s33, v131
	v_sub_u32_e32 v53, v52, v114
	s_waitcnt lgkmcnt(1)
	v_mfma_f32_16x16x32_bf16 v[16:19], v[16:19], v[8:11], v[12:15]
	s_cselect_b64 s[38:39], -1, 0
	v_lshlrev_b32_e32 v188, 7, v44
	v_lshl_add_u64 v[44:45], v[120:121], 0, v[188:189]
	s_waitcnt lgkmcnt(0)
	v_mfma_f32_16x16x32_bf16 v[16:19], v[36:39], v[4:7], v[16:19]
	v_cvt_f32_i32_e32 v37, v53
	v_add_u32_e32 v36, 64, v53
	v_cmp_gt_u32_e64 s[0:1], s73, v36
	v_add_u32_e32 v36, 1, v53
	v_cvt_f32_i32_e32 v36, v36
	s_nop 2
	v_fma_f32 v16, |v37|, v111, v16
	s_and_b64 s[0:1], s[38:39], s[0:1]
	v_cndmask_b32_e64 v113, v234, v16, s[0:1]
	v_add_u32_e32 v16, 0x41, v53
	v_cmp_gt_u32_e64 s[0:1], s73, v16
	v_lshl_add_u64 v[46:47], v[122:123], 0, v[188:189]
	global_load_dwordx4 v[56:59], v[44:45], off
	global_load_dwordx4 v[64:67], v[46:47], off
	v_fma_f32 v16, |v36|, v111, v17
	s_and_b64 s[0:1], s[38:39], s[0:1]
	ds_read_b128 v[36:39], v143 offset:11520
	ds_read_b128 v[44:47], v143 offset:11584
	v_cndmask_b32_e64 v115, v234, v16, s[0:1]
	v_add_u32_e32 v16, 2, v53
	v_cvt_f32_i32_e32 v16, v16
	v_add_u32_e32 v17, 0x42, v53
	v_cmp_gt_u32_e64 s[0:1], s73, v17
	s_and_b64 s[0:1], s[38:39], s[0:1]
	v_fma_f32 v16, |v16|, v111, v18
	v_cndmask_b32_e64 v117, v234, v16, s[0:1]
	v_add_u32_e32 v16, 3, v53
	v_cvt_f32_i32_e32 v16, v16
	s_waitcnt lgkmcnt(1)
	v_mfma_f32_16x16x32_bf16 v[36:39], v[36:39], v[8:11], v[12:15]
	v_add_u32_e32 v17, 0x43, v53
	v_cmp_gt_u32_e64 s[0:1], s73, v17
	v_fma_f32 v16, |v16|, v111, v19
	s_and_b64 s[0:1], s[38:39], s[0:1]
	v_cndmask_b32_e64 v119, v234, v16, s[0:1]
	s_waitcnt lgkmcnt(0)
	v_mfma_f32_16x16x32_bf16 v[16:19], v[44:47], v[4:7], v[36:39]
	s_sub_i32 s33, s30, 48
	s_cmpk_lt_u32 s33, 0x800
	s_cselect_b64 s[38:39], -1, 0
	v_add_u32_e32 v36, 16, v53
	v_cvt_f32_i32_e32 v36, v36
	v_add_u32_e32 v37, 0x50, v53
	v_cmp_gt_u32_e64 s[0:1], s73, v37
	s_and_b64 s[0:1], s[38:39], s[0:1]
	v_fma_f32 v16, |v36|, v111, v16
	v_cndmask_b32_e64 v154, v234, v16, s[0:1]
	v_add_u32_e32 v16, 17, v53
	v_cvt_f32_i32_e32 v16, v16
	v_add_u32_e32 v36, 0x51, v53
	v_cmp_gt_u32_e64 s[0:1], s73, v36
	v_add_u32_e32 v36, 17, v52
	v_cmp_gt_u32_e64 s[38:39], s24, v36
	v_fma_f32 v16, |v16|, v111, v17
	s_and_b64 s[0:1], s[0:1], s[38:39]
	v_cndmask_b32_e64 v155, v234, v16, s[0:1]
	v_add_u32_e32 v16, 18, v53
	v_cvt_f32_i32_e32 v16, v16
	v_add_u32_e32 v17, 0x52, v53
	v_cmp_gt_u32_e64 s[0:1], s73, v17
	v_add_u32_e32 v17, 18, v52
	v_cmp_gt_u32_e64 s[38:39], s24, v17
	v_fma_f32 v16, |v16|, v111, v18
	s_and_b64 s[0:1], s[0:1], s[38:39]
	v_cndmask_b32_e64 v156, v234, v16, s[0:1]
	v_add_u32_e32 v16, 19, v53
	v_cvt_f32_i32_e32 v16, v16
	v_add_u32_e32 v17, 0x53, v53
	v_cmp_gt_u32_e64 s[0:1], s73, v17
	v_add_u32_e32 v17, 19, v52
	v_cmp_gt_u32_e64 s[38:39], s24, v17
	v_fma_f32 v16, |v16|, v111, v19
	s_and_b64 s[0:1], s[0:1], s[38:39]
	s_add_i32 s33, s30, 32
	v_cndmask_b32_e64 v157, v234, v16, s[0:1]
	v_or_b32_e32 v16, s33, v126
	v_med3_i32 v16, v16, 0, v233
	v_lshlrev_b32_e32 v188, 7, v16
	v_lshl_add_u64 v[16:17], v[120:121], 0, v[188:189]
	v_lshl_add_u64 v[18:19], v[122:123], 0, v[188:189]
	global_load_dwordx4 v[68:71], v[16:17], off
	global_load_dwordx4 v[72:75], v[18:19], off
	v_or_b32_e32 v16, s33, v127
	v_med3_i32 v16, v16, 0, v233
	v_lshlrev_b32_e32 v188, 7, v16
	v_lshl_add_u64 v[16:17], v[120:121], 0, v[188:189]
	v_lshl_add_u64 v[18:19], v[122:123], 0, v[188:189]
	global_load_dwordx4 v[76:79], v[16:17], off
	global_load_dwordx4 v[80:83], v[18:19], off
	v_add_u32_e32 v16, s33, v128
	v_med3_i32 v16, v16, 0, v233
	s_waitcnt vmcnt(18)
	ds_write_b128 v142, v[88:91] offset:4608
	ds_write_b128 v142, v[84:87] offset:9216
	s_waitcnt vmcnt(16)
	ds_write_b128 v142, v[96:99] offset:5760
	ds_write_b128 v142, v[92:95] offset:10368
	s_waitcnt vmcnt(14)
	ds_write_b128 v142, v[104:107] offset:6912
	ds_write_b128 v142, v[100:103] offset:11520
	s_waitcnt vmcnt(12)
	ds_write_b128 v142, v[150:153] offset:8064
	ds_write_b128 v142, v[146:149] offset:12672
	v_lshlrev_b32_e32 v188, 7, v16
	ds_read_b128 v[16:19], v143 offset:9216
	v_lshl_add_u64 v[36:37], v[120:121], 0, v[188:189]
	v_lshl_add_u64 v[38:39], v[122:123], 0, v[188:189]
	global_load_dwordx4 v[84:87], v[36:37], off
	global_load_dwordx4 v[88:91], v[38:39], off
	v_add_u32_e32 v36, s33, v129
	v_med3_i32 v44, v36, 0, v233
	ds_read_b128 v[36:39], v143 offset:9280
	s_waitcnt lgkmcnt(1)
	v_mfma_f32_16x16x32_bf16 v[16:19], v[16:19], v[8:11], v[12:15]
	v_or_b32_e32 v52, s31, v131
	v_sub_u32_e32 v53, v52, v114
	s_cmpk_lt_u32 s31, 0x800
	s_waitcnt lgkmcnt(0)
; #define LAS __attribute__((address_space(3)))
; #define MFMA16(a, b, c) __builtin_amdgcn_mfma_f32_16x16x32_bf16((a), (b), (c), 0, 0, 0)
; template <bool EDGE>
; DI void a_scores(f32x4 (&st)[2], const LAS char* kt, const bf16x8 (&qf)[2], const f32x4 cinit, int tokbase, int stride, int maxd, int tq, float nslope2, int lane) {
;     const int g = lane >> 4;
;     const int base0 = tokbase + stride * 4 * g - tq;
; #pragma unroll
;     for (int t = 0; t < 2; ++t) {
;         st[t] = MFMA16(k_frag_at(kt, t, 0, lane), qf[0], cinit); st[t] = MFMA16(k_frag_at(kt, t, 1, lane), qf[1], st[t]);
; #pragma unroll
;         for (int i = 0; i < 4; ++i) { const int d = base0 + stride * (16 * t + i);
;             bool ok = (unsigned)(d + maxd) <= (unsigned)(2 * maxd);
;             if (EDGE) ok = ok && ((unsigned)(d + tq) < (unsigned)T);
;             const float v = __builtin_fmaf(__builtin_fabsf((float)d), nslope2, st[t][i]);
;             st[t][i] = ok ? v : -1e30f; }
;     }
; }
; DI void mixerA1_unit(int u, const bf16* PROJ, bf16* YC, float* LPA, const float* kmax_l, LAS char* vt, int wave, int lane) {
;     ...
;     a_stage(sA, R0, vt, 0, qf, cinit, tb0, 1, 64, tq, nslope2, lane);        tile_load(R0, kb, vb, tb0 + 96, 1, lane);
;     a_stage(sB, R1, vt, 1, qf, cinit, tb0 + 32, 1, 64, tq, nslope2, lane);   tile_load(R1, kb, vb, tb0 + 128, 1, lane);
;     fb_update(o, ol, sA[0], sA[1], vt, lane);
;     a_stage(sA, R2, vt, 0, qf, cinit, tb0 + 64, 1, 64, tq, nslope2, lane);
;     fb_update(o, ol, sB[0], sB[1], vt + A_V1, lane);
;     a_stage(sB, R0, vt, 1, qf, cinit, tb0 + 96, 1, 64, tq, nslope2, lane);
;     fb_update(o, ol, sA[0], sA[1], vt, lane);
;     a_stage(sA, R1, vt, 0, qf, cinit, tb0 + 128, 1, 64, tq, nslope2, lane);
;     fb_update(o, ol, sB[0], sB[1], vt + A_V1, lane);
;     fb_update(o, ol, sA[0], sA[1], vt, lane);
	v_mfma_f32_16x16x32_bf16 v[16:19], v[36:39], v[4:7], v[16:19]
	v_cvt_f32_i32_e32 v37, v53
	v_add_u32_e32 v36, 64, v53
	v_cmp_gt_u32_e64 s[0:1], s73, v36
	v_add_u32_e32 v36, 1, v53
	s_cselect_b64 s[38:39], -1, 0
	v_cvt_f32_i32_e32 v36, v36
	s_nop 1
	v_fma_f32 v16, |v37|, v111, v16
	s_and_b64 s[0:1], s[38:39], s[0:1]
	v_lshlrev_b32_e32 v188, 7, v44
	v_cndmask_b32_e64 v162, v234, v16, s[0:1]
	v_add_u32_e32 v16, 0x41, v53
	v_lshl_add_u64 v[44:45], v[120:121], 0, v[188:189]
	v_cmp_gt_u32_e64 s[0:1], s73, v16
	v_lshl_add_u64 v[46:47], v[122:123], 0, v[188:189]
	global_load_dwordx4 v[92:95], v[44:45], off
	global_load_dwordx4 v[96:99], v[46:47], off
	v_fma_f32 v16, |v36|, v111, v17
	s_and_b64 s[0:1], s[38:39], s[0:1]
	ds_read_b128 v[36:39], v143 offset:11520
	ds_read_b128 v[44:47], v143 offset:11584
	v_cndmask_b32_e64 v163, v234, v16, s[0:1]
	v_add_u32_e32 v16, 2, v53
	v_cvt_f32_i32_e32 v16, v16
	v_add_u32_e32 v17, 0x42, v53
	v_cmp_gt_u32_e64 s[0:1], s73, v17
	s_and_b64 s[0:1], s[38:39], s[0:1]
	v_fma_f32 v16, |v16|, v111, v18
	v_cndmask_b32_e64 v164, v234, v16, s[0:1]
	v_add_u32_e32 v16, 3, v53
	v_cvt_f32_i32_e32 v16, v16
	s_waitcnt lgkmcnt(1)
	v_mfma_f32_16x16x32_bf16 v[36:39], v[36:39], v[8:11], v[12:15]
	v_add_u32_e32 v17, 0x43, v53
	v_cmp_gt_u32_e64 s[0:1], s73, v17
	v_fma_f32 v16, |v16|, v111, v19
	s_and_b64 s[0:1], s[38:39], s[0:1]
	v_cndmask_b32_e64 v165, v234, v16, s[0:1]
	s_waitcnt lgkmcnt(0)
	v_mfma_f32_16x16x32_bf16 v[16:19], v[44:47], v[4:7], v[36:39]
	s_add_i32 s31, s30, -16
	s_cmpk_lt_u32 s31, 0x800
	s_cselect_b64 s[38:39], -1, 0
	v_add_u32_e32 v36, 16, v53
	v_cvt_f32_i32_e32 v36, v36
	v_add_u32_e32 v37, 0x50, v53
	v_cmp_gt_u32_e64 s[0:1], s73, v37
	s_and_b64 s[0:1], s[38:39], s[0:1]
	v_fma_f32 v16, |v36|, v111, v16
	v_cndmask_b32_e64 v166, v234, v16, s[0:1]
	v_add_u32_e32 v16, 17, v53
	v_cvt_f32_i32_e32 v16, v16
	v_add_u32_e32 v36, 0x51, v53
	v_cmp_gt_u32_e64 s[0:1], s73, v36
	v_add_u32_e32 v36, 17, v52
	v_cmp_gt_u32_e64 s[38:39], s24, v36
	v_fma_f32 v16, |v16|, v111, v17
	s_and_b64 s[0:1], s[0:1], s[38:39]
	v_cndmask_b32_e64 v167, v234, v16, s[0:1]
	v_add_u32_e32 v16, 18, v53
	v_cvt_f32_i32_e32 v16, v16
	v_add_u32_e32 v17, 0x52, v53
	v_cmp_gt_u32_e64 s[0:1], s73, v17
	v_add_u32_e32 v17, 18, v52
	v_cmp_gt_u32_e64 s[38:39], s24, v17
	v_fma_f32 v16, |v16|, v111, v18
	s_and_b64 s[0:1], s[0:1], s[38:39]
	v_cndmask_b32_e64 v168, v234, v16, s[0:1]
	v_add_u32_e32 v16, 19, v53
	v_cvt_f32_i32_e32 v16, v16
	v_add_u32_e32 v17, 0x53, v53
	v_cmp_gt_u32_e64 s[0:1], s73, v17
	v_add_u32_e32 v17, 19, v52
	v_cmp_gt_u32_e64 s[38:39], s24, v17
	v_fma_f32 v16, |v16|, v111, v19
	s_and_b64 s[0:1], s[0:1], s[38:39]
	s_add_i32 s31, s30, 64
	v_cndmask_b32_e64 v169, v234, v16, s[0:1]
	v_or_b32_e32 v16, s31, v126
	v_med3_i32 v16, v16, 0, v233
	v_lshlrev_b32_e32 v188, 7, v16
	v_lshl_add_u64 v[16:17], v[120:121], 0, v[188:189]
	v_lshl_add_u64 v[18:19], v[122:123], 0, v[188:189]
	global_load_dwordx4 v[36:39], v[16:17], off
	global_load_dwordx4 v[44:47], v[18:19], off
	v_or_b32_e32 v16, s31, v127
	v_med3_i32 v16, v16, 0, v233
	v_lshlrev_b32_e32 v188, 7, v16
	v_lshl_add_u64 v[16:17], v[120:121], 0, v[188:189]
	v_lshl_add_u64 v[18:19], v[122:123], 0, v[188:189]
	global_load_dwordx4 v[52:55], v[16:17], off
	global_load_dwordx4 v[60:63], v[18:19], off
	v_add_u32_e32 v16, s31, v128
	v_med3_i32 v16, v16, 0, v233
	v_lshlrev_b32_e32 v188, 7, v16
	v_exp_f32_e32 v16, v113
	v_exp_f32_e32 v17, v115
	v_exp_f32_e32 v100, v117
	v_exp_f32_e32 v101, v119
	v_exp_f32_e32 v18, v154
	v_exp_f32_e32 v19, v155
	v_exp_f32_e32 v106, v156
	v_exp_f32_e32 v107, v157
	v_cvt_pk_bf16_f32 v16, v16, v17
	v_cvt_pk_bf16_f32 v17, v100, v101
	ds_read_b64_tr_b16 v[102:103], v144 offset:2304
	ds_read_b64_tr_b16 v[100:101], v144
	v_lshl_add_u64 v[104:105], v[120:121], 0, v[188:189]
	v_cvt_pk_bf16_f32 v18, v18, v19
	v_cvt_pk_bf16_f32 v19, v106, v107
	v_lshl_add_u64 v[106:107], v[122:123], 0, v[188:189]
	ds_read_b64_tr_b16 v[148:149], v144 offset:2336
	ds_read_b64_tr_b16 v[146:147], v144 offset:32
	ds_read_b64_tr_b16 v[150:151], v144 offset:64
	ds_read_b64_tr_b16 v[154:155], v144 offset:96
	ds_read_b64_tr_b16 v[152:153], v144 offset:2368
	ds_read_b64_tr_b16 v[156:157], v144 offset:2400
	s_waitcnt lgkmcnt(6)
	v_mfma_f32_16x16x32_bf16 v[158:161], v[100:103], v[16:19], 0
	global_load_dwordx4 v[100:103], v[104:105], off
	s_nop 0
	global_load_dwordx4 v[104:107], v[106:107], off
	s_waitcnt vmcnt(20)
	ds_write_b128 v142, v[24:27]
	ds_write_b128 v142, v[20:23] offset:9216
	s_waitcnt vmcnt(18)
	ds_write_b128 v142, v[32:35] offset:1152
	ds_write_b128 v142, v[28:31] offset:10368
	s_waitcnt vmcnt(16)
	ds_write_b128 v142, v[48:51] offset:2304
	ds_write_b128 v142, v[40:43] offset:11520
	s_waitcnt vmcnt(14)
	ds_write_b128 v142, v[64:67] offset:3456
	ds_write_b128 v142, v[56:59] offset:12672
	ds_read_b128 v[20:23], v143 offset:9216
	ds_read_b128 v[40:43], v143 offset:9280
	v_add_u32_e32 v28, s31, v129
	v_med3_i32 v28, v28, 0, v233
	v_lshlrev_b32_e32 v188, 7, v28
	v_lshl_add_u64 v[28:29], v[120:121], 0, v[188:189]
	v_lshl_add_u64 v[32:33], v[122:123], 0, v[188:189]
	global_load_dwordx4 v[28:31], v[28:29], off
	s_nop 0
	global_load_dwordx4 v[32:35], v[32:33], off
	s_waitcnt lgkmcnt(1)
	v_mfma_f32_16x16x32_bf16 v[20:23], v[20:23], v[8:11], v[12:15]
	ds_read_b128 v[56:59], v143 offset:11584
	s_cmpk_lt_u32 s30, 0x800
	s_cselect_b64 s[0:1], -1, 0
	s_waitcnt lgkmcnt(1)
	v_mfma_f32_16x16x32_bf16 v[20:23], v[40:43], v[4:7], v[20:23]
	ds_read_b128 v[40:43], v143 offset:11520
	v_exp_f32_e32 v64, v168
	v_exp_f32_e32 v65, v169
	s_waitcnt lgkmcnt(0)
; #define LAS __attribute__((address_space(3)))
; #define MFMA16(a, b, c) __builtin_amdgcn_mfma_f32_16x16x32_bf16((a), (b), (c), 0, 0, 0)
; DI float ex2(float x) { return __builtin_amdgcn_exp2f(x); }
; DI s16x4 vtr(const LAS char* p) { return __builtin_bit_cast(s16x4, __builtin_amdgcn_ds_read_tr16_b64_v4i16((LAS s16x4*)p)); }
; DI bf16x8 cat8(s16x4 lo, s16x4 hi) { return __builtin_shufflevector(lo, hi, 0, 1, 2, 3, 4, 5, 6, 7); }
; DI bf16x8 pack8(f32x4 a, f32x4 b) { u32x4 w; w.x = pk2(a[0], a[1]); w.y = pk2(a[2], a[3]); w.z = pk2(b[0], b[1]); w.w = pk2(b[2], b[3]); return __builtin_bit_cast(bf16x8, w); }
; DI void fb_update(f32x4 (&o)[4], f32x4& ol, const f32x4 st0, const f32x4 st1, const LAS char* vt, int lane) {
;     f32x4 p0, p1;
; #pragma unroll
;     for (int i = 0; i < 4; ++i) { p0[i] = ex2(st0[i]); p1[i] = ex2(st1[i]); }
;     const bf16x8 pf = pack8(p0, p1);
;     const bf16x8 ones = {0x3F80, 0x3F80, 0x3F80, 0x3F80, 0x3F80, 0x3F80, 0x3F80, 0x3F80};
;     ol = MFMA16(ones, pf, ol);
;     const int g = lane >> 4, q = (lane & 15) >> 2, p = lane & 3;
;     const LAS char* v0 = vt + (4 * g + q) * VT_PITCH + 8 * p;
;     const LAS char* v1 = v0 + 16 * VT_PITCH;
; #pragma unroll
;     for (int c = 0; c < 4; ++c) { const bf16x8 vf = cat8(vtr(v0 + 32 * c), vtr(v1 + 32 * c)); o[c] = MFMA16(vf, pf, o[c]); }
; }
; DI void mixerA1_unit(int u, const bf16* PROJ, bf16* YC, float* LPA, const float* kmax_l, LAS char* vt, int wave, int lane) {
;     ...
;     a_stage(sA, R0, vt, 0, qf, cinit, tb0, 1, 64, tq, nslope2, lane);        tile_load(R0, kb, vb, tb0 + 96, 1, lane);
;     a_stage(sB, R1, vt, 1, qf, cinit, tb0 + 32, 1, 64, tq, nslope2, lane);   tile_load(R1, kb, vb, tb0 + 128, 1, lane);
;     fb_update(o, ol, sA[0], sA[1], vt, lane);
;     a_stage(sA, R2, vt, 0, qf, cinit, tb0 + 64, 1, 64, tq, nslope2, lane);
;     fb_update(o, ol, sB[0], sB[1], vt + A_V1, lane);
;     a_stage(sB, R0, vt, 1, qf, cinit, tb0 + 96, 1, 64, tq, nslope2, lane);
;     fb_update(o, ol, sA[0], sA[1], vt, lane);
;     a_stage(sA, R1, vt, 0, qf, cinit, tb0 + 128, 1, 64, tq, nslope2, lane);
;     fb_update(o, ol, sB[0], sB[1], vt + A_V1, lane);
;     fb_update(o, ol, sA[0], sA[1], vt, lane);
	v_mfma_f32_16x16x32_bf16 v[40:43], v[40:43], v[8:11], v[12:15]
	s_nop 2
	v_fma_f32 v20, |v133|, v111, v20
	v_cndmask_b32_e64 v115, v234, v20, s[0:1]
	v_fma_f32 v20, |v134|, v111, v21
	v_cndmask_b32_e64 v117, v234, v20, s[0:1]
	v_fma_f32 v20, |v135|, v111, v22
	v_cndmask_b32_e64 v119, v234, v20, s[0:1]
	v_fma_f32 v20, |v136|, v111, v23
	v_mfma_f32_16x16x32_bf16 v[48:51], v[154:157], v[16:19], 0
	v_cndmask_b32_e64 v154, v234, v20, s[0:1]
	v_exp_f32_e32 v20, v162
	v_exp_f32_e32 v22, v166
	v_mfma_f32_16x16x32_bf16 v[40:43], v[56:59], v[4:7], v[40:43]
	v_exp_f32_e32 v21, v163
	v_exp_f32_e32 v23, v167
	v_exp_f32_e32 v56, v164
	v_exp_f32_e32 v57, v165
	v_mfma_f32_16x16x32_bf16 v[24:27], v[150:153], v[16:19], 0
	v_cvt_pk_bf16_f32 v20, v20, v21
	v_cvt_pk_bf16_f32 v22, v22, v23
	v_cvt_pk_bf16_f32 v21, v56, v57
	ds_read_b64_tr_b16 v[58:59], v144 offset:6912
	ds_read_b64_tr_b16 v[56:57], v144 offset:4608
	v_cvt_pk_bf16_f32 v23, v64, v65
	ds_read_b64_tr_b16 v[66:67], v144 offset:6944
	ds_read_b64_tr_b16 v[64:65], v144 offset:4640
	ds_read_b64_tr_b16 v[120:121], v144 offset:4672
	ds_read_b64_tr_b16 v[150:151], v144 offset:4704
	ds_read_b64_tr_b16 v[122:123], v144 offset:6976
	ds_read_b64_tr_b16 v[152:153], v144 offset:7008
	s_waitcnt vmcnt(14)
	ds_write_b128 v142, v[72:75] offset:4608
	ds_write_b128 v142, v[68:71] offset:9216
	s_waitcnt vmcnt(12)
	ds_write_b128 v142, v[80:83] offset:5760
	ds_write_b128 v142, v[76:79] offset:10368
	s_waitcnt vmcnt(10)
	ds_write_b128 v142, v[88:91] offset:6912
	ds_write_b128 v142, v[84:87] offset:11520
	s_waitcnt vmcnt(8)
	ds_write_b128 v142, v[96:99] offset:8064
	ds_write_b128 v142, v[92:95] offset:12672
	s_waitcnt lgkmcnt(9)
	v_mfma_f32_16x16x32_bf16 v[120:123], v[120:123], v[20:23], v[24:27]
	ds_read_b128 v[68:71], v143 offset:9280
	s_nop 1
	ds_read_b128 v[24:27], v143 offset:9216
	s_add_i32 s0, s30, 16
	v_mfma_f32_16x16x32_bf16 v[146:149], v[146:149], v[16:19], 0
	s_cmpk_lt_u32 s0, 0x800
	v_or_b32_e32 v113, s30, v131
	v_fma_f32 v40, v137, v111, v40
	s_cselect_b64 s[0:1], -1, 0
	s_waitcnt lgkmcnt(0)
	v_mfma_f32_16x16x32_bf16 v[24:27], v[24:27], v[8:11], v[12:15]
	v_cndmask_b32_e64 v155, v234, v40, s[0:1]
	v_add_u32_e32 v40, 17, v113
	v_fma_f32 v41, v138, v111, v41
	v_cmp_gt_u32_e64 s[0:1], s24, v40
	v_add_u32_e32 v40, 18, v113
	v_or_b32_e32 v84, s33, v131
	v_mfma_f32_16x16x32_bf16 v[64:67], v[64:67], v[20:23], v[146:149]
	v_sub_u32_e32 v85, v84, v114
	v_fmac_f32_e32 v43, v140, v111
	s_cmpk_lt_u32 s33, 0x800
	v_cndmask_b32_e64 v146, v234, v41, s[0:1]
	v_fma_f32 v41, v139, v111, v42
	v_cmp_gt_u32_e64 s[0:1], s24, v40
	v_add_u32_e32 v40, 19, v113
	v_mfma_f32_16x16x32_bf16 v[24:27], v[68:71], v[4:7], v[24:27]
	v_cndmask_b32_e64 v72, v234, v41, s[0:1]
	v_cvt_f32_i32_e32 v41, v85
	v_cmp_gt_u32_e64 s[0:1], s24, v40
	v_add_u32_e32 v40, 64, v85
	s_cselect_b64 s[38:39], -1, 0
	v_cndmask_b32_e64 v73, v234, v43, s[0:1]
	v_cmp_gt_u32_e64 s[0:1], s73, v40
	v_add_u32_e32 v40, 1, v85
	v_cvt_f32_i32_e32 v40, v40
	v_fma_f32 v24, |v41|, v111, v24
	s_and_b64 s[0:1], s[38:39], s[0:1]
	v_cndmask_b32_e64 v86, v234, v24, s[0:1]
	v_add_u32_e32 v24, 0x41, v85
	v_cmp_gt_u32_e64 s[0:1], s73, v24
	v_fma_f32 v24, |v40|, v111, v25
	s_and_b64 s[0:1], s[38:39], s[0:1]
	v_cndmask_b32_e64 v87, v234, v24, s[0:1]
	v_add_u32_e32 v24, 2, v85
	ds_read_b128 v[40:43], v143 offset:11520
	ds_read_b128 v[68:71], v143 offset:11584
	v_cvt_f32_i32_e32 v24, v24
	v_add_u32_e32 v25, 0x42, v85
	v_cmp_gt_u32_e64 s[0:1], s73, v25
	s_and_b64 s[0:1], s[38:39], s[0:1]
	v_fma_f32 v24, |v24|, v111, v26
	v_cndmask_b32_e64 v88, v234, v24, s[0:1]
	v_add_u32_e32 v24, 3, v85
	v_cvt_f32_i32_e32 v24, v24
	v_add_u32_e32 v25, 0x43, v85
	s_waitcnt lgkmcnt(1)
	v_mfma_f32_16x16x32_bf16 v[40:43], v[40:43], v[8:11], v[12:15]
	v_cmp_gt_u32_e64 s[0:1], s73, v25
	v_fma_f32 v24, |v24|, v111, v27
	s_and_b64 s[0:1], s[38:39], s[0:1]
	v_cndmask_b32_e64 v89, v234, v24, s[0:1]
	v_add_u32_e32 v24, 16, v85
	s_waitcnt lgkmcnt(0)
	v_mfma_f32_16x16x32_bf16 v[40:43], v[68:71], v[4:7], v[40:43]
	v_cvt_f32_i32_e32 v24, v24
	s_add_i32 s33, s30, 48
	v_add_u32_e32 v25, 0x50, v85
	s_cmpk_lt_u32 s33, 0x800
	v_cmp_gt_u32_e64 s[0:1], s73, v25
	s_cselect_b64 s[38:39], -1, 0
	s_nop 1
	v_fma_f32 v24, |v24|, v111, v40
	s_and_b64 s[0:1], s[38:39], s[0:1]
	v_cndmask_b32_e64 v90, v234, v24, s[0:1]
	v_add_u32_e32 v24, 17, v85
	v_cvt_f32_i32_e32 v24, v24
	v_add_u32_e32 v25, 0x51, v85
	v_cmp_gt_u32_e64 s[0:1], s73, v25
	v_add_u32_e32 v25, 17, v84
	v_cmp_gt_u32_e64 s[38:39], s24, v25
	v_fma_f32 v24, |v24|, v111, v41
	s_and_b64 s[0:1], s[0:1], s[38:39]
	v_cndmask_b32_e64 v91, v234, v24, s[0:1]
	v_add_u32_e32 v24, 18, v85
	v_add_u32_e32 v25, 0x52, v85
	v_cmp_gt_u32_e64 s[0:1], s73, v25
	v_cvt_f32_i32_e32 v40, v24
	v_exp_f32_e32 v24, v115
	v_exp_f32_e32 v26, v155
	v_exp_f32_e32 v25, v117
	v_exp_f32_e32 v27, v146
	v_exp_f32_e32 v41, v119
	v_exp_f32_e32 v68, v154
	v_exp_f32_e32 v72, v72
	v_exp_f32_e32 v73, v73
	v_cvt_pk_bf16_f32 v24, v24, v25
	v_cvt_pk_bf16_f32 v25, v41, v68
	ds_read_b64_tr_b16 v[70:71], v144 offset:2304
	ds_read_b64_tr_b16 v[68:69], v144
	v_cvt_pk_bf16_f32 v26, v26, v27
	v_cvt_pk_bf16_f32 v27, v72, v73
	ds_read_b64_tr_b16 v[74:75], v144 offset:2336
	ds_read_b64_tr_b16 v[72:73], v144 offset:32
	ds_read_b64_tr_b16 v[76:77], v144 offset:64
	ds_read_b64_tr_b16 v[80:81], v144 offset:96
	ds_read_b64_tr_b16 v[78:79], v144 offset:2368
	ds_read_b64_tr_b16 v[82:83], v144 offset:2400
	s_waitcnt vmcnt(6)
	ds_write_b128 v142, v[44:47]
	ds_write_b128 v142, v[36:39] offset:9216
	s_waitcnt vmcnt(4)
	ds_write_b128 v142, v[60:63] offset:1152
	ds_write_b128 v142, v[52:55] offset:10368
	s_waitcnt vmcnt(2)
; #define LAS __attribute__((address_space(3)))
; #define MFMA16(a, b, c) __builtin_amdgcn_mfma_f32_16x16x32_bf16((a), (b), (c), 0, 0, 0)
; DI float ex2(float x) { return __builtin_amdgcn_exp2f(x); }
; DI s16x4 vtr(const LAS char* p) { return __builtin_bit_cast(s16x4, __builtin_amdgcn_ds_read_tr16_b64_v4i16((LAS s16x4*)p)); }
; DI bf16x8 cat8(s16x4 lo, s16x4 hi) { return __builtin_shufflevector(lo, hi, 0, 1, 2, 3, 4, 5, 6, 7); }
; DI bf16x8 pack8(f32x4 a, f32x4 b) { u32x4 w; w.x = pk2(a[0], a[1]); w.y = pk2(a[2], a[3]); w.z = pk2(b[0], b[1]); w.w = pk2(b[2], b[3]); return __builtin_bit_cast(bf16x8, w); }
; DI void fb_update(f32x4 (&o)[4], f32x4& ol, const f32x4 st0, const f32x4 st1, const LAS char* vt, int lane) {
;     f32x4 p0, p1;
; #pragma unroll
;     for (int i = 0; i < 4; ++i) { p0[i] = ex2(st0[i]); p1[i] = ex2(st1[i]); }
;     const bf16x8 pf = pack8(p0, p1);
;     const bf16x8 ones = {0x3F80, 0x3F80, 0x3F80, 0x3F80, 0x3F80, 0x3F80, 0x3F80, 0x3F80};
;     ol = MFMA16(ones, pf, ol);
;     const int g = lane >> 4, q = (lane & 15) >> 2, p = lane & 3;
;     const LAS char* v0 = vt + (4 * g + q) * VT_PITCH + 8 * p;
;     const LAS char* v1 = v0 + 16 * VT_PITCH;
; #pragma unroll
;     for (int c = 0; c < 4; ++c) { const bf16x8 vf = cat8(vtr(v0 + 32 * c), vtr(v1 + 32 * c)); o[c] = MFMA16(vf, pf, o[c]); }
; }
; DI void mixerA1_unit(int u, const bf16* PROJ, bf16* YC, float* LPA, const float* kmax_l, LAS char* vt, int wave, int lane) {
;     ...
;     fb_update(o, ol, sA[0], sA[1], vt, lane);
;     a_stage(sA, R2, vt, 0, qf, cinit, tb0 + 64, 1, 64, tq, nslope2, lane);
;     fb_update(o, ol, sB[0], sB[1], vt + A_V1, lane);
;     a_stage(sB, R0, vt, 1, qf, cinit, tb0 + 96, 1, 64, tq, nslope2, lane);
;     fb_update(o, ol, sA[0], sA[1], vt, lane);
;     a_stage(sA, R1, vt, 0, qf, cinit, tb0 + 128, 1, 64, tq, nslope2, lane);
;     fb_update(o, ol, sB[0], sB[1], vt + A_V1, lane);
;     fb_update(o, ol, sA[0], sA[1], vt, lane);
	ds_write_b128 v142, v[104:107] offset:2304
	ds_write_b128 v142, v[100:103] offset:11520
	s_waitcnt vmcnt(0)
	ds_write_b128 v142, v[32:35] offset:3456
	ds_write_b128 v142, v[28:31] offset:12672
	ds_read_b128 v[28:31], v143 offset:9216
	ds_read_b128 v[36:39], v143 offset:9280
	v_add_u32_e32 v41, 18, v84
	v_cmp_gt_u32_e64 s[38:39], s24, v41
	v_fma_f32 v40, |v40|, v111, v42
	s_and_b64 s[0:1], s[0:1], s[38:39]
	s_waitcnt lgkmcnt(14)
	v_mfma_f32_16x16x32_bf16 v[64:67], v[72:75], v[24:27], v[64:67]
	v_cndmask_b32_e64 v72, v234, v40, s[0:1]
	v_add_u32_e32 v40, 19, v85
	v_cvt_f32_i32_e32 v40, v40
	s_waitcnt lgkmcnt(1)
	v_mfma_f32_16x16x32_bf16 v[28:31], v[28:31], v[8:11], v[12:15]
	v_add_u32_e32 v32, 0x53, v85
	v_add_u32_e32 v41, 19, v84
	v_or_b32_e32 v45, s31, v131
	v_cmp_gt_u32_e64 s[0:1], s73, v32
	v_cmp_gt_u32_e64 s[38:39], s24, v41
	v_sub_u32_e32 v46, v45, v114
	v_fma_f32 v40, |v40|, v111, v43
	s_and_b64 s[0:1], s[0:1], s[38:39]
	s_waitcnt lgkmcnt(0)
	v_mfma_f32_16x16x32_bf16 v[28:31], v[36:39], v[4:7], v[28:31]
	v_add_u32_e32 v36, 64, v46
	v_cvt_f32_i32_e32 v37, v46
	v_cndmask_b32_e64 v44, v234, v40, s[0:1]
	v_cmp_gt_u32_e64 s[0:1], s73, v36
	v_add_u32_e32 v36, 1, v46
	s_cmpk_lt_u32 s31, 0x800
	v_cvt_f32_i32_e32 v36, v36
	s_cselect_b64 s[38:39], -1, 0
	v_fma_f32 v28, |v37|, v111, v28
	s_and_b64 s[0:1], s[38:39], s[0:1]
	v_cndmask_b32_e64 v47, v234, v28, s[0:1]
	v_add_u32_e32 v28, 0x41, v46
	v_cmp_gt_u32_e64 s[0:1], s73, v28
	v_fma_f32 v28, |v36|, v111, v29
	ds_read_b128 v[36:39], v143 offset:11520
	ds_read_b128 v[40:43], v143 offset:11584
	v_mfma_f32_16x16x32_bf16 v[48:51], v[150:153], v[20:23], v[48:51]
	s_and_b64 s[0:1], s[38:39], s[0:1]
	v_add_u32_e32 v29, 0x42, v46
	s_addk_i32 s30, 0x50
	v_mfma_f32_16x16x32_bf16 v[32:35], v[80:83], v[24:27], v[48:51]
	v_mov_b32_e32 v113, v189
	v_ashrrev_i32_e32 v117, 31, v116
	v_ashrrev_i32_e32 v119, 31, v118
	s_nop 0
	v_cndmask_b32_e64 v48, v234, v28, s[0:1]
	v_add_u32_e32 v28, 2, v46
	v_cvt_f32_i32_e32 v28, v28
	v_cmp_gt_u32_e64 s[0:1], s73, v29
	s_waitcnt lgkmcnt(1)
	v_mfma_f32_16x16x32_bf16 v[8:11], v[36:39], v[8:11], v[12:15]
	s_and_b64 s[0:1], s[38:39], s[0:1]
	v_fma_f32 v28, |v28|, v111, v30
	v_cndmask_b32_e64 v49, v234, v28, s[0:1]
	v_add_u32_e32 v28, 3, v46
	v_cvt_f32_i32_e32 v28, v28
	v_add_u32_e32 v29, 0x43, v46
	s_waitcnt lgkmcnt(0)
	v_mfma_f32_16x16x32_bf16 v[4:7], v[40:43], v[4:7], v[8:11]
	v_cmp_gt_u32_e64 s[0:1], s73, v29
	s_and_b64 s[0:1], s[38:39], s[0:1]
	v_fma_f32 v12, |v28|, v111, v31
	v_add_u32_e32 v8, 16, v46
	v_cvt_f32_i32_e32 v8, v8
	v_add_u32_e32 v9, 0x50, v46
	s_cmpk_lt_u32 s30, 0x800
	v_cndmask_b32_e64 v50, v234, v12, s[0:1]
	v_cmp_gt_u32_e64 s[0:1], s73, v9
	s_cselect_b64 s[30:31], -1, 0
	v_fma_f32 v4, |v8|, v111, v4
	s_and_b64 s[0:1], s[30:31], s[0:1]
	v_cndmask_b32_e64 v51, v234, v4, s[0:1]
	v_add_u32_e32 v4, 17, v46
	v_cvt_f32_i32_e32 v4, v4
	v_add_u32_e32 v8, 0x51, v46
	v_cmp_gt_u32_e64 s[0:1], s73, v8
	v_add_u32_e32 v8, 17, v45
	v_cmp_gt_u32_e64 s[38:39], s24, v8
	v_fma_f32 v4, |v4|, v111, v5
	s_and_b64 s[0:1], s[0:1], s[38:39]
	v_cndmask_b32_e64 v52, v234, v4, s[0:1]
	v_add_u32_e32 v4, 18, v46
	v_cvt_f32_i32_e32 v4, v4
	v_add_u32_e32 v5, 0x52, v46
	v_cmp_gt_u32_e64 s[0:1], s73, v5
	v_add_u32_e32 v5, 18, v45
	v_cmp_gt_u32_e64 s[38:39], s24, v5
	v_fma_f32 v4, |v4|, v111, v6
	s_and_b64 s[0:1], s[0:1], s[38:39]
	v_cndmask_b32_e64 v53, v234, v4, s[0:1]
	v_exp_f32_e32 v4, v86
	v_exp_f32_e32 v6, v87
	v_exp_f32_e32 v9, v88
	v_exp_f32_e32 v11, v89
	v_exp_f32_e32 v28, v72
	v_exp_f32_e32 v29, v44
	v_exp_f32_e32 v5, v90
	v_exp_f32_e32 v10, v91
	v_cvt_pk_bf16_f32 v8, v4, v6
	v_add_u32_e32 v4, 19, v46
	v_cvt_pk_bf16_f32 v9, v9, v11
	ds_read_b64_tr_b16 v[12:13], v144 offset:4608
	ds_read_b64_tr_b16 v[14:15], v144 offset:6912
	v_cvt_pk_bf16_f32 v11, v28, v29
	ds_read_b64_tr_b16 v[30:31], v144 offset:6944
	ds_read_b64_tr_b16 v[28:29], v144 offset:4640
	ds_read_b64_tr_b16 v[36:37], v144 offset:4672
	ds_read_b64_tr_b16 v[40:41], v144 offset:4704
	ds_read_b64_tr_b16 v[38:39], v144 offset:6976
	ds_read_b64_tr_b16 v[42:43], v144 offset:7008
	v_cvt_f32_i32_e32 v4, v4
	v_cvt_pk_bf16_f32 v10, v5, v10
	v_add_u32_e32 v5, 0x53, v46
	v_mfma_f32_16x16x32_bf16 v[56:59], v[56:59], v[20:23], v[158:161]
	v_cmp_gt_u32_e64 s[0:1], s73, v5
	v_add_u32_e32 v5, 19, v45
	v_cmp_gt_u32_e64 s[38:39], s24, v5
	v_fma_f32 v4, |v4|, v111, v7
	s_and_b64 s[0:1], s[0:1], s[38:39]
	v_cndmask_b32_e64 v44, v234, v4, s[0:1]
	s_waitcnt lgkmcnt(0)
; #define LAS __attribute__((address_space(3)))
; DI unsigned pk2(float lo, float hi) { f32x2_t v = {lo, hi}; bf16x2_t b = __builtin_convertvector(v, bf16x2_t); return __builtin_bit_cast(unsigned, b); }
; DI void mixerA1_unit(int u, const bf16* PROJ, bf16* YC, float* LPA, const float* kmax_l, LAS char* vt, int wave, int lane) {
;     ...
;     fb_update(o, ol, sB[0], sB[1], vt + A_V1, lane);
;     fb_update(o, ol, sA[0], sA[1], vt, lane);
;     LAS char* sc = vt + SC_OFF;
; #pragma unroll
;     for (int c = 0; c < 4; ++c) { u32x2 w; w.x = pk2(o[c][0], o[c][1]); w.y = pk2(o[c][2], o[c][3]);
;         *(LAS u32x2*)(sc + r * VT_PITCH + (16 * c + 4 * g) * 2) = w; }
;     rows16_store(sc, YC + (size_t)b * T * 1024 + h * 64, 1024, t0, 1, lane);
;     if (g == 0) LPA[(size_t)(b * T + tq) * 4 + h] = ol[0];
	v_mfma_f32_16x16x32_bf16 v[4:7], v[40:43], v[8:11], v[32:35]
	v_exp_f32_e32 v40, v49
	v_exp_f32_e32 v41, v50
	v_exp_f32_e32 v45, v53
	v_exp_f32_e32 v32, v47
	v_exp_f32_e32 v33, v48
	v_mfma_f32_16x16x32_bf16 v[56:59], v[68:71], v[24:27], v[56:59]
	v_exp_f32_e32 v34, v51
	v_exp_f32_e32 v35, v52
	v_exp_f32_e32 v44, v44
	v_cvt_pk_bf16_f32 v32, v32, v33
	v_cvt_pk_bf16_f32 v33, v40, v41
	ds_read_b64_tr_b16 v[42:43], v144 offset:2304
	ds_read_b64_tr_b16 v[40:41], v144
	v_mfma_f32_16x16x32_bf16 v[12:15], v[12:15], v[8:11], v[56:59]
	v_cvt_pk_bf16_f32 v34, v34, v35
	v_cvt_pk_bf16_f32 v35, v45, v44
	ds_read_b64_tr_b16 v[46:47], v144 offset:2336
	ds_read_b64_tr_b16 v[44:45], v144 offset:32
	ds_read_b64_tr_b16 v[48:49], v144 offset:64
	ds_read_b64_tr_b16 v[52:53], v144 offset:96
	ds_read_b64_tr_b16 v[50:51], v144 offset:2368
	ds_read_b64_tr_b16 v[54:55], v144 offset:2400
	s_waitcnt lgkmcnt(6)
	v_mfma_f32_16x16x32_bf16 v[12:15], v[40:43], v[32:35], v[12:15]
	v_mov_b64_e32 v[40:41], s[84:85]
	v_mov_b64_e32 v[42:43], s[86:87]
	s_lshl_b64 s[0:1], s[20:21], 22
	v_mfma_f32_16x16x32_bf16 v[28:31], v[28:31], v[8:11], v[64:67]
	s_add_u32 s0, s8, s0
	s_addc_u32 s1, s9, s1
	s_lshl_b32 s21, s27, 7
	v_mfma_f32_16x16x32_bf16 v[16:19], v[40:43], v[16:19], 0
	s_add_u32 s0, s0, s21
	s_addc_u32 s1, s1, 0
	v_mfma_f32_16x16x32_bf16 v[68:71], v[76:79], v[24:27], v[120:123]
	s_waitcnt lgkmcnt(4)
	v_mfma_f32_16x16x32_bf16 v[28:31], v[44:47], v[32:35], v[28:31]
	v_cvt_pk_bf16_f32 v44, v12, v13
	v_cvt_pk_bf16_f32 v45, v14, v15
	v_add_u32_e32 v46, v132, v108
	v_mfma_f32_16x16x32_bf16 v[12:15], v[40:43], v[20:23], v[16:19]
	v_mfma_f32_16x16x32_bf16 v[36:39], v[36:39], v[8:11], v[68:71]
	s_nop 2
	v_cvt_pk_bf16_f32 v16, v28, v29
	v_cvt_pk_bf16_f32 v17, v30, v31
	v_add_u32_e32 v18, 0x2000, v46
	v_mfma_f32_16x16x32_bf16 v[12:15], v[40:43], v[24:27], v[12:15]
	ds_write2_b64 v18, v[44:45], v[16:17] offset0:128 offset1:132
	s_waitcnt lgkmcnt(2)
	v_mfma_f32_16x16x32_bf16 v[36:39], v[48:51], v[32:35], v[36:39]
	s_waitcnt lgkmcnt(1)
	v_mfma_f32_16x16x32_bf16 v[4:7], v[52:55], v[32:35], v[4:7]
	v_mfma_f32_16x16x32_bf16 v[8:11], v[40:43], v[8:11], v[12:15]
	s_nop 4
	v_cvt_pk_bf16_f32 v16, v36, v37
	v_cvt_pk_bf16_f32 v17, v38, v39
	v_cvt_pk_bf16_f32 v4, v4, v5
	v_cvt_pk_bf16_f32 v5, v6, v7
	ds_write2_b64 v18, v[16:17], v[4:5] offset0:136 offset1:140
	v_mfma_f32_16x16x32_bf16 v[4:7], v[40:43], v[32:35], v[8:11]
	v_lshl_add_u64 v[14:15], s[0:1], 0, v[112:113]
	s_nop 1
	v_lshlrev_b64 v[10:11], 11, v[116:117]
	v_lshl_add_u64 v[16:17], v[14:15], 0, v[10:11]
	s_nop 2
	v_add_u32_e32 v5, v141, v130
	ds_read_b128 v[6:9], v5 offset:9216
	ds_read_b128 v[10:13], v145 offset:9216
	s_waitcnt lgkmcnt(1)
	global_store_dwordx4 v[16:17], v[6:9], off sc1
	s_nop 1
	v_lshlrev_b64 v[6:7], 11, v[118:119]
	v_lshl_add_u64 v[6:7], v[14:15], 0, v[6:7]
	s_waitcnt lgkmcnt(0)
	global_store_dwordx4 v[6:7], v[10:13], off sc1
	s_and_saveexec_b64 s[0:1], vcc
	s_cbranch_execz .LBB0_358
	v_lshl_add_u32 v6, s20, 11, v114
	v_ashrrev_i32_e32 v7, 31, v6
	v_lshl_add_u64 v[6:7], v[6:7], 4, s[96:97]
	s_lshl_b32 s34, s27, 2
	v_lshl_add_u64 v[6:7], v[6:7], 0, s[34:35]
	global_store_dword v[6:7], v4, off sc1
	s_branch .LBB0_358

; #define LAS __attribute__((address_space(3)))
; DI float q_norm2(const bf16x8 (&qf)[2]) { float a = sumsq8(qf[0]) + sumsq8(qf[1]); a += __shfl_xor(a, 16); a += __shfl_xor(a, 32); return a; }
; DI void mixerD2_unit(int u, const bf16* PROJ, bf16* YC, float rmax, const float* kmax_l, LAS char* vt, int wave, int lane) {
;     const int b = u >> 6, h = (u >> 4) & 3, wu = (u & 15) * 8 + wave, rr = wu >> 2, cb = wu & 3, r = lane & 15, g = lane >> 4;
;     const bf16* kb = slab(PROJ, C_DK + h * 64, b); const bf16* vb = slab(PROJ, C_DV + h * 64, b);
;     const int qcol = 16 * cb + r, tq = 64 * rr + qcol;
;     const int cs = min(max(qcol - 8, 0), 48), rs = min(max(rr - 4, 0), 24), c0 = min(max(16 * cb - 8, 0), 32);
;     LAS float* rp = (LAS float*)(vt + 12288);
;     bf16x8 qf[2];
; #pragma unroll
;     for (int ks = 0; ks < 2; ++ks) qf[ks] = *(const bf16x8*)(slab(PROJ, C_DQ + h * 64, b) + (size_t)tq * 64 + 32 * ks + 8 * g);
;     const float bound = sqrtf(q_norm2(qf) * (kmax_l[b * 128 + 104 + 2 * h] + kmax_l[b * 128 + 105 + 2 * h])) * 1.01f + 0.05f + rmax;
;     const f32x4 cinit = {-bound, -bound, -bound, -bound};
;     f32x4 o[4], ol = {0.f, 0.f, 0.f, 0.f};
; #pragma unroll
;     for (int c = 0; c < 4; ++c) o[c] = ol;
;     const int tb0 = 64 * rs + c0, dr0 = rs - rr + 7;
;     const int kc0 = c0 + 4 * g - cs;
;     const LAS float* rpl = rp + dr0 * 31 + (c0 + 4 * g - qcol + 15);
;     TileRegs R0, R1, R2;
;     tile_load(R0, kb, vb, tb0, 1, lane); tile_load(R1, kb, vb, tb0 + 64, 1, lane); tile_load(R2, kb, vb, tb0 + 128, 1, lane);
;     d_compute(o, ol, R0, qf, cinit, 0, kc0, rpl, vt, lane); tile_load(R0, kb, vb, tb0 + 192, 1, lane);
;     d_compute(o, ol, R1, qf, cinit, 1, kc0, rpl, vt, lane); tile_load(R1, kb, vb, tb0 + 256, 1, lane);
.LBB0_363:
	s_lshl_b32 s0, s52, 3
	s_and_b32 s0, s0, 0x78
	s_ashr_i32 s26, s52, 6
	s_add_i32 s0, s0, s2
	s_ashr_i32 s0, s0, 2
	s_ashr_i32 s27, s26, 31
	s_lshl_b32 s1, s53, 21
	s_add_u32 s1, s10, s1
	s_addc_u32 s55, s11, 0
	s_lshl_b32 s54, s0, 6
	s_max_i32 s57, s0, 4
	s_lshl_b64 s[30:31], s[26:27], 18
	v_or_b32_e32 v4, s54, v78
	s_add_i32 s57, s57, -4
	v_ashrrev_i32_e32 v5, 31, v4
	s_add_u32 s30, s1, s30
	v_lshlrev_b64 v[4:5], 7, v[4:5]
	s_addc_u32 s31, s55, s31
	v_lshl_add_u64 v[4:5], s[30:31], 0, v[4:5]
	v_lshlrev_b32_e32 v188, 1, v68
	v_lshl_add_u64 v[4:5], v[4:5], 0, v[188:189]
	s_mov_b64 s[60:61], 0x6000000
	s_mov_b32 s1, 0x6000000
	v_lshl_add_u64 v[8:9], v[4:5], 0, s[60:61]
	v_add_co_u32_e32 v4, vcc, s1, v4
	s_min_u32 s1, s57, 24
	s_nop 0
	v_addc_co_u32_e32 v5, vcc, 0, v5, vcc
	global_load_dwordx4 v[4:7], v[4:5], off
	s_nop 0
	global_load_dwordx4 v[8:11], v[8:9], off offset:64
	s_lshl_b32 s55, s26, 7
	s_lshl_b32 s57, s53, 1
	s_or_b32 s60, s57, s55
	s_ashr_i32 s61, s60, 31
	s_lshl_b64 s[60:61], s[60:61], 2
	s_add_u32 s60, s4, s60
	s_addc_u32 s61, s5, s61
	global_load_dwordx2 v[12:13], v189, s[60:61] offset:416
	v_mov_b32_e32 v71, v189
	v_lshl_add_u64 v[14:15], s[30:31], 0, v[70:71]
	s_mov_b64 s[60:61], 0x6800000
	s_lshl_b32 s55, s1, 6
	v_lshl_add_u64 v[74:75], v[14:15], 0, s[60:61]
	s_mov_b64 s[60:61], 0x7000000
	s_or_b32 s55, s55, s33
	v_lshl_add_u64 v[76:77], v[14:15], 0, s[60:61]
	v_or_b32_e32 v14, s55, v82
	v_lshlrev_b32_e32 v188, 7, v14
	v_lshl_add_u64 v[14:15], v[74:75], 0, v[188:189]
	v_lshl_add_u64 v[20:21], v[76:77], 0, v[188:189]
	v_add_lshl_u32 v188, s55, v83, 7
	global_load_dwordx4 v[16:19], v[14:15], off
	s_nop 0
	global_load_dwordx4 v[20:23], v[20:21], off
	v_lshl_add_u64 v[14:15], v[74:75], 0, v[188:189]
	v_lshl_add_u64 v[28:29], v[76:77], 0, v[188:189]
	v_add_lshl_u32 v188, s55, v84, 7
	global_load_dwordx4 v[24:27], v[14:15], off
	s_nop 0
	global_load_dwordx4 v[28:31], v[28:29], off
	v_lshl_add_u64 v[14:15], v[74:75], 0, v[188:189]
	v_lshl_add_u64 v[36:37], v[76:77], 0, v[188:189]
	v_add_lshl_u32 v188, s55, v85, 7
	global_load_dwordx4 v[32:35], v[14:15], off
	s_nop 0
	global_load_dwordx4 v[36:39], v[36:37], off
	v_lshl_add_u64 v[14:15], v[74:75], 0, v[188:189]
	v_lshl_add_u64 v[44:45], v[76:77], 0, v[188:189]
	global_load_dwordx4 v[40:43], v[14:15], off
	s_nop 0
	global_load_dwordx4 v[44:47], v[44:45], off
	s_add_i32 s57, s55, 64
	s_sub_i32 s0, s1, s0
	s_mulk_i32 s0, 0x7c
	v_add_u32_e32 v71, s0, v81
	v_add_u32_e32 v73, 0x33a0, v71
	s_or_b32 s54, s54, s16
	s_waitcnt vmcnt(10)
	v_and_b32_e32 v48, 0xffff0000, v4
	s_waitcnt vmcnt(9)
	v_and_b32_e32 v49, 0xffff0000, v8
	v_and_b32_e32 v53, 0xffff0000, v9
	v_and_b32_e32 v52, 0xffff0000, v5
	v_lshlrev_b32_e32 v14, 16, v4
	v_lshlrev_b32_e32 v15, 16, v8
	v_lshlrev_b32_e32 v50, 16, v5
	v_lshlrev_b32_e32 v51, 16, v9
	v_and_b32_e32 v57, 0xffff0000, v10
	v_and_b32_e32 v56, 0xffff0000, v6
	v_pk_mul_f32 v[48:49], v[48:49], v[48:49]
	v_pk_mul_f32 v[52:53], v[52:53], v[52:53]
	v_lshlrev_b32_e32 v54, 16, v6
	v_lshlrev_b32_e32 v55, 16, v10
	v_and_b32_e32 v61, 0xffff0000, v11
	v_and_b32_e32 v60, 0xffff0000, v7
	v_pk_mul_f32 v[56:57], v[56:57], v[56:57]
	v_pk_fma_f32 v[14:15], v[14:15], v[14:15], v[48:49]
	v_pk_fma_f32 v[48:49], v[50:51], v[50:51], v[52:53]
	v_lshlrev_b32_e32 v58, 16, v7
	v_lshlrev_b32_e32 v59, 16, v11
	v_pk_mul_f32 v[60:61], v[60:61], v[60:61]
	v_pk_fma_f32 v[50:51], v[54:55], v[54:55], v[56:57]
	v_pk_add_f32 v[14:15], v[14:15], v[48:49]
	v_pk_fma_f32 v[52:53], v[58:59], v[58:59], v[60:61]
	v_pk_add_f32 v[14:15], v[50:51], v[14:15]
	s_waitcnt vmcnt(8)
	v_mov_b32_e32 v48, v13
	v_pk_add_f32 v[14:15], v[52:53], v[14:15]
	s_nop 0
	v_add_f32_e32 v14, v14, v15
	ds_bpermute_b32 v15, v79, v14
	s_waitcnt lgkmcnt(0)
	v_add_f32_e32 v15, v14, v15
	ds_bpermute_b32 v49, v80, v15
	v_mov_b32_e32 v14, v12
	s_waitcnt lgkmcnt(0)
	v_pk_add_f32 v[12:13], v[14:15], v[48:49]
	s_nop 0
	v_mul_f32_e32 v12, v12, v13
	v_mul_f32_e32 v13, 0x4f800000, v12
	v_cmp_gt_f32_e32 vcc, s92, v12
	v_or_b32_e32 v14, s57, v82
	v_lshlrev_b32_e32 v188, 7, v14
	v_cndmask_b32_e32 v12, v12, v13, vcc
	v_sqrt_f32_e32 v13, v12
	v_lshl_add_u64 v[48:49], v[74:75], 0, v[188:189]
	v_lshl_add_u64 v[52:53], v[76:77], 0, v[188:189]
	v_add_lshl_u32 v188, s57, v83, 7
	v_add_u32_e32 v14, -1, v13
	v_lshl_add_u64 v[56:57], v[74:75], 0, v[188:189]
	v_lshl_add_u64 v[60:61], v[76:77], 0, v[188:189]
	v_add_lshl_u32 v188, s57, v84, 7
	v_add_u32_e32 v15, 1, v13
	v_fma_f32 v50, -v14, v13, v12
	v_lshl_add_u64 v[64:65], v[74:75], 0, v[188:189]
	v_lshl_add_u64 v[100:101], v[76:77], 0, v[188:189]
	v_add_lshl_u32 v188, s57, v85, 7
	v_fma_f32 v51, -v15, v13, v12
	v_cmp_ge_f32_e64 s[0:1], 0, v50
	v_lshl_add_u64 v[104:105], v[74:75], 0, v[188:189]
	v_lshl_add_u64 v[108:109], v[76:77], 0, v[188:189]
	v_cndmask_b32_e64 v13, v13, v14, s[0:1]
	v_cmp_lt_f32_e64 s[0:1], 0, v51
	global_load_dwordx4 v[48:51], v[48:49], off
	s_nop 0
	global_load_dwordx4 v[52:55], v[52:53], off
	s_nop 0
	global_load_dwordx4 v[56:59], v[56:57], off
	s_nop 0
	global_load_dwordx4 v[60:63], v[60:61], off
	s_nop 0
	global_load_dwordx4 v[64:67], v[64:65], off
	s_nop 0
	global_load_dwordx4 v[100:103], v[100:101], off
	s_nop 0
	global_load_dwordx4 v[104:107], v[104:105], off
	s_nop 0
	global_load_dwordx4 v[108:111], v[108:109], off
	s_waitcnt vmcnt(14)
	ds_write_b128 v95, v[20:23]
	ds_write_b128 v95, v[16:19] offset:4608
	s_waitcnt vmcnt(12)
	ds_write_b128 v95, v[28:31] offset:1152
	ds_write_b128 v95, v[24:27] offset:5760
	s_waitcnt vmcnt(10)
	ds_write_b128 v95, v[36:39] offset:2304
	ds_write_b128 v95, v[32:35] offset:6912
	s_waitcnt vmcnt(8)
; #define LAS __attribute__((address_space(3)))
; #define MFMA16(a, b, c) __builtin_amdgcn_mfma_f32_16x16x32_bf16((a), (b), (c), 0, 0, 0)
; DI bf16x8 k_frag(const LAS char* vt, int t, int ks, int lane) { return k_frag_at(vt + KT_OFF, t, ks, lane); }
; DI void d_compute(f32x4 (&o)[4], f32x4& ol, const TileRegs& R, const bf16x8 (&qf)[2], const f32x4 cinit, int kr, int kc0, const LAS float* rpl, LAS char* vt, int lane) {
;     tile_v_to_lds(R, vt, lane);
;     const LAS float* rr_ = rpl + kr * 31;
;     f32x4 st[2];
; #pragma unroll
;     for (int t = 0; t < 2; ++t) {
;         st[t] = MFMA16(k_frag(vt, t, 0, lane), qf[0], cinit); st[t] = MFMA16(k_frag(vt, t, 1, lane), qf[1], st[t]);
; #pragma unroll
;         for (int i = 0; i < 4; ++i) { const bool ok = (unsigned)(kc0 + 16 * t + i) <= 15u;
;             const float v = st[t][i] + rr_[16 * t + i];
;             st[t][i] = ok ? v : -1e30f; }
;     }
;     fb_update(o, ol, st[0], st[1], vt, lane);
;     asm volatile("" ::: "memory");
; }
; DI void mixerD2_unit(int u, const bf16* PROJ, bf16* YC, float rmax, const float* kmax_l, LAS char* vt, int wave, int lane) {
;     ...
;     d_compute(o, ol, R0, qf, cinit, 0, kc0, rpl, vt, lane); tile_load(R0, kb, vb, tb0 + 192, 1, lane);
;     d_compute(o, ol, R1, qf, cinit, 1, kc0, rpl, vt, lane); tile_load(R1, kb, vb, tb0 + 256, 1, lane);
;     d_compute(o, ol, R2, qf, cinit, 2, kc0, rpl, vt, lane); tile_load(R2, kb, vb, tb0 + 320, 1, lane);
;     d_compute(o, ol, R0, qf, cinit, 3, kc0, rpl, vt, lane); tile_load(R0, kb, vb, tb0 + 384, 1, lane);
;     d_compute(o, ol, R1, qf, cinit, 4, kc0, rpl, vt, lane); tile_load(R1, kb, vb, tb0 + 448, 1, lane);
	ds_write_b128 v95, v[44:47] offset:3456
	ds_write_b128 v95, v[40:43] offset:8064
	ds_read_b128 v[16:19], v96 offset:4608
	ds_read_b128 v[36:39], v96 offset:4672
	v_cndmask_b32_e64 v13, v13, v15, s[0:1]
	v_mul_f32_e32 v14, 0x37800000, v13
	v_cndmask_b32_e32 v13, v13, v14, vcc
	v_cmp_class_f32_e32 vcc, v12, v226
	s_add_i32 s0, s55, 0x80
	v_or_b32_e32 v112, s0, v82
	v_cndmask_b32_e32 v12, v13, v12, vcc
	v_fmamk_f32 v12, v12, 0x3f8147ae, v227
	v_add_f32_e32 v12, v99, v12
	v_xor_b32_e32 v12, 0x80000000, v12
	v_mov_b32_e32 v13, v12
	v_mov_b32_e32 v14, v12
	v_mov_b32_e32 v15, v12
	v_lshlrev_b32_e32 v188, 7, v112
	v_lshl_add_u64 v[20:21], v[74:75], 0, v[188:189]
	s_waitcnt lgkmcnt(1)
	v_mfma_f32_16x16x32_bf16 v[16:19], v[16:19], v[4:7], v[12:15]
	v_lshl_add_u64 v[24:25], v[76:77], 0, v[188:189]
	v_add_lshl_u32 v188, s0, v83, 7
	v_lshl_add_u64 v[28:29], v[74:75], 0, v[188:189]
	v_lshl_add_u64 v[32:33], v[76:77], 0, v[188:189]
	global_load_dwordx4 v[20:23], v[20:21], off
	s_nop 0
	global_load_dwordx4 v[24:27], v[24:25], off
	s_nop 0
	global_load_dwordx4 v[28:31], v[28:29], off
	s_nop 0
	global_load_dwordx4 v[32:35], v[32:33], off
	ds_read2_b32 v[40:41], v73 offset1:1
	s_waitcnt lgkmcnt(1)
	v_mfma_f32_16x16x32_bf16 v[16:19], v[36:39], v[8:11], v[16:19]
	v_add_u32_e32 v44, 0x33e0, v71
	v_add_u32_e32 v45, 0x33e8, v71
	v_add_lshl_u32 v188, s0, v84, 7
	s_waitcnt lgkmcnt(0)
	s_nop 3
	v_add_f32_e32 v16, v16, v40
	v_cndmask_b32_e64 v73, v234, v16, s[36:37]
	v_add_f32_e32 v16, v17, v41
	v_cndmask_b32_e64 v114, v234, v16, s[38:39]
	v_add_u32_e32 v16, 0x33a8, v71
	ds_read_b128 v[36:39], v96 offset:6912
	ds_read2_b32 v[16:17], v16 offset1:1
	ds_read_b128 v[40:43], v96 offset:6976
	s_waitcnt lgkmcnt(2)
	v_mfma_f32_16x16x32_bf16 v[36:39], v[36:39], v[4:7], v[12:15]
	s_waitcnt lgkmcnt(1)
	v_add_f32_e32 v16, v18, v16
	v_cndmask_b32_e64 v115, v234, v16, s[40:41]
	v_add_f32_e32 v16, v19, v17
	v_cndmask_b32_e64 v116, v234, v16, s[42:43]
	s_waitcnt lgkmcnt(0)
	v_mfma_f32_16x16x32_bf16 v[16:19], v[40:43], v[8:11], v[36:39]
	ds_read2_b32 v[46:47], v44 offset1:1
	ds_read2_b32 v[112:113], v45 offset1:1
	ds_read_b64_tr_b16 v[44:45], v97
	v_exp_f32_e32 v36, v73
	v_exp_f32_e32 v37, v115
	s_waitcnt lgkmcnt(2)
	s_nop 1
	v_add_f32_e32 v16, v16, v46
	v_add_f32_e32 v17, v17, v47
	ds_read_b64_tr_b16 v[46:47], v97 offset:2304
	s_waitcnt lgkmcnt(2)
	v_add_f32_e32 v18, v18, v112
	v_add_f32_e32 v19, v19, v113
	v_cndmask_b32_e64 v16, v234, v16, s[44:45]
	v_cndmask_b32_e64 v17, v234, v17, s[46:47]
	v_cndmask_b32_e64 v18, v234, v18, s[48:49]
	v_cndmask_b32_e64 v19, v234, v19, s[50:51]
	v_exp_f32_e32 v38, v16
	v_exp_f32_e32 v16, v114
	v_exp_f32_e32 v39, v17
	v_exp_f32_e32 v40, v18
	v_exp_f32_e32 v41, v116
	v_exp_f32_e32 v42, v19
	v_cvt_pk_bf16_f32 v36, v36, v16
	v_cvt_pk_bf16_f32 v38, v38, v39
	v_cvt_pk_bf16_f32 v37, v37, v41
	v_cvt_pk_bf16_f32 v39, v40, v42
	ds_read_b64_tr_b16 v[112:113], v97 offset:32
	ds_read_b64_tr_b16 v[114:115], v97 offset:2336
	s_waitcnt lgkmcnt(2)
	v_mfma_f32_16x16x32_bf16 v[124:127], v[44:47], v[36:39], 0
	v_lshl_add_u64 v[44:45], v[74:75], 0, v[188:189]
	v_lshl_add_u64 v[46:47], v[76:77], 0, v[188:189]
	v_add_lshl_u32 v188, s0, v85, 7
	ds_read_b64_tr_b16 v[116:117], v97 offset:64
	ds_read_b64_tr_b16 v[120:121], v97 offset:96
	ds_read_b64_tr_b16 v[118:119], v97 offset:2368
	ds_read_b64_tr_b16 v[122:123], v97 offset:2400
	global_load_dwordx4 v[128:131], v[44:45], off
	global_load_dwordx4 v[132:135], v[46:47], off
	v_lshl_add_u64 v[44:45], v[74:75], 0, v[188:189]
	v_lshl_add_u64 v[46:47], v[76:77], 0, v[188:189]
	global_load_dwordx4 v[136:139], v[44:45], off
	global_load_dwordx4 v[140:143], v[46:47], off
	s_waitcnt vmcnt(14)
	ds_write_b128 v95, v[52:55]
	ds_write_b128 v95, v[48:51] offset:4608
	s_waitcnt vmcnt(12)
	ds_write_b128 v95, v[60:63] offset:1152
	ds_write_b128 v95, v[56:59] offset:5760
	s_waitcnt vmcnt(10)
	ds_write_b128 v95, v[100:103] offset:2304
	ds_write_b128 v95, v[64:67] offset:6912
	s_waitcnt vmcnt(8)
	ds_write_b128 v95, v[108:111] offset:3456
	ds_write_b128 v95, v[104:107] offset:8064
	ds_read_b128 v[48:51], v96 offset:4608
	ds_read_b128 v[56:59], v96 offset:4672
	v_mov_b64_e32 v[16:17], s[84:85]
	v_mov_b64_e32 v[18:19], s[86:87]
	s_add_i32 s0, s55, 0xc0
	s_waitcnt lgkmcnt(14)
	v_mfma_f32_16x16x32_bf16 v[112:115], v[112:115], v[36:39], 0
	v_add_u32_e32 v64, 0x341c, v71
	v_add_u32_e32 v65, 0x345c, v71
	v_add_u32_e32 v66, 0x3464, v71
	v_mfma_f32_16x16x32_bf16 v[40:43], v[16:19], v[36:39], 0
	s_waitcnt lgkmcnt(11)
	v_mfma_f32_16x16x32_bf16 v[116:119], v[116:119], v[36:39], 0
	s_waitcnt lgkmcnt(10)
	v_mfma_f32_16x16x32_bf16 v[120:123], v[120:123], v[36:39], 0
	v_or_b32_e32 v36, s0, v82
	v_lshlrev_b32_e32 v188, 7, v36
	v_lshl_add_u64 v[36:37], v[74:75], 0, v[188:189]
	s_waitcnt lgkmcnt(1)
	v_mfma_f32_16x16x32_bf16 v[48:51], v[48:51], v[4:7], v[12:15]
	v_lshl_add_u64 v[44:45], v[76:77], 0, v[188:189]
	v_add_lshl_u32 v188, s0, v83, 7
	v_lshl_add_u64 v[52:53], v[74:75], 0, v[188:189]
	v_lshl_add_u64 v[60:61], v[76:77], 0, v[188:189]
	global_load_dwordx4 v[36:39], v[36:37], off
	s_nop 0
	global_load_dwordx4 v[44:47], v[44:45], off
	s_nop 0
	global_load_dwordx4 v[52:55], v[52:53], off
	s_nop 0
	global_load_dwordx4 v[60:63], v[60:61], off
	s_waitcnt lgkmcnt(0)
	v_mfma_f32_16x16x32_bf16 v[48:51], v[56:59], v[8:11], v[48:51]
	ds_read2_b32 v[100:101], v64 offset1:1
	ds_read_b128 v[56:59], v96 offset:6912
	v_add_u32_e32 v64, 0x3424, v71
	ds_read2_b32 v[102:103], v64 offset1:1
	ds_read2_b32 v[104:105], v65 offset1:1
	ds_read2_b32 v[106:107], v66 offset1:1
	ds_read_b128 v[64:67], v96 offset:6976
	s_waitcnt lgkmcnt(5)
	v_add_f32_e32 v48, v48, v100
	s_waitcnt lgkmcnt(4)
; #define LAS __attribute__((address_space(3)))
; #define MFMA16(a, b, c) __builtin_amdgcn_mfma_f32_16x16x32_bf16((a), (b), (c), 0, 0, 0)
; DI bf16x8 k_frag(const LAS char* vt, int t, int ks, int lane) { return k_frag_at(vt + KT_OFF, t, ks, lane); }
; DI void d_compute(f32x4 (&o)[4], f32x4& ol, const TileRegs& R, const bf16x8 (&qf)[2], const f32x4 cinit, int kr, int kc0, const LAS float* rpl, LAS char* vt, int lane) {
;     tile_v_to_lds(R, vt, lane);
;     const LAS float* rr_ = rpl + kr * 31;
;     f32x4 st[2];
; #pragma unroll
;     for (int t = 0; t < 2; ++t) {
;         st[t] = MFMA16(k_frag(vt, t, 0, lane), qf[0], cinit); st[t] = MFMA16(k_frag(vt, t, 1, lane), qf[1], st[t]);
; #pragma unroll
;         for (int i = 0; i < 4; ++i) { const bool ok = (unsigned)(kc0 + 16 * t + i) <= 15u;
;             const float v = st[t][i] + rr_[16 * t + i];
;             st[t][i] = ok ? v : -1e30f; }
;     }
;     fb_update(o, ol, st[0], st[1], vt, lane);
;     asm volatile("" ::: "memory");
; }
; DI void mixerD2_unit(int u, const bf16* PROJ, bf16* YC, float rmax, const float* kmax_l, LAS char* vt, int wave, int lane) {
;     ...
;     d_compute(o, ol, R1, qf, cinit, 1, kc0, rpl, vt, lane); tile_load(R1, kb, vb, tb0 + 256, 1, lane);
;     d_compute(o, ol, R2, qf, cinit, 2, kc0, rpl, vt, lane); tile_load(R2, kb, vb, tb0 + 320, 1, lane);
;     d_compute(o, ol, R0, qf, cinit, 3, kc0, rpl, vt, lane); tile_load(R0, kb, vb, tb0 + 384, 1, lane);
;     d_compute(o, ol, R1, qf, cinit, 4, kc0, rpl, vt, lane); tile_load(R1, kb, vb, tb0 + 448, 1, lane);
	v_mfma_f32_16x16x32_bf16 v[56:59], v[56:59], v[4:7], v[12:15]
	v_cndmask_b32_e64 v73, v234, v48, s[36:37]
	v_add_f32_e32 v48, v49, v101
	v_cndmask_b32_e64 v100, v234, v48, s[38:39]
	s_waitcnt lgkmcnt(3)
	v_add_f32_e32 v48, v50, v102
	v_cndmask_b32_e64 v101, v234, v48, s[40:41]
	v_add_f32_e32 v48, v51, v103
	v_cndmask_b32_e64 v102, v234, v48, s[42:43]
	s_waitcnt lgkmcnt(0)
	v_mfma_f32_16x16x32_bf16 v[48:51], v[64:67], v[8:11], v[56:59]
	v_add_lshl_u32 v188, s0, v84, 7
	s_nop 1
	v_exp_f32_e32 v56, v73
	v_exp_f32_e32 v59, v102
	s_nop 2
	v_add_f32_e32 v48, v48, v104
	v_add_f32_e32 v49, v49, v105
	v_cndmask_b32_e64 v48, v234, v48, s[44:45]
	v_cndmask_b32_e64 v49, v234, v49, s[46:47]
	v_exp_f32_e32 v57, v48
	v_exp_f32_e32 v48, v100
	v_exp_f32_e32 v58, v49
	v_exp_f32_e32 v49, v101
	v_add_f32_e32 v50, v50, v106
	v_add_f32_e32 v51, v51, v107
	v_cndmask_b32_e64 v50, v234, v50, s[48:49]
	v_cndmask_b32_e64 v51, v234, v51, s[50:51]
	v_exp_f32_e32 v64, v50
	v_exp_f32_e32 v51, v51
	v_cvt_pk_bf16_f32 v48, v56, v48
	v_cvt_pk_bf16_f32 v49, v49, v59
	v_cvt_pk_bf16_f32 v50, v57, v58
	ds_read_b64_tr_b16 v[58:59], v97 offset:2304
	ds_read_b64_tr_b16 v[56:57], v97
	v_cvt_pk_bf16_f32 v51, v64, v51
	v_add_u32_e32 v73, 0x3590, v71
	s_nop 0
	v_mfma_f32_16x16x32_bf16 v[100:103], v[16:19], v[48:51], v[40:43]
	s_nop 2
	ds_read_b64_tr_b16 v[42:43], v97 offset:2336
	ds_read_b64_tr_b16 v[40:41], v97 offset:32
	ds_read_b64_tr_b16 v[64:65], v97 offset:64
	ds_read_b64_tr_b16 v[104:105], v97 offset:96
	ds_read_b64_tr_b16 v[66:67], v97 offset:2368
	ds_read_b64_tr_b16 v[106:107], v97 offset:2400
	s_waitcnt lgkmcnt(6)
	v_mfma_f32_16x16x32_bf16 v[108:111], v[56:59], v[48:51], v[124:127]
	v_lshl_add_u64 v[56:57], v[74:75], 0, v[188:189]
	v_lshl_add_u64 v[58:59], v[76:77], 0, v[188:189]
	v_add_lshl_u32 v188, s0, v85, 7
	s_waitcnt lgkmcnt(4)
	v_mfma_f32_16x16x32_bf16 v[112:115], v[40:43], v[48:51], v[112:115]
	v_lshl_add_u64 v[40:41], v[74:75], 0, v[188:189]
	global_load_dwordx4 v[124:127], v[56:57], off
	global_load_dwordx4 v[144:147], v[58:59], off
	v_lshl_add_u64 v[42:43], v[76:77], 0, v[188:189]
	global_load_dwordx4 v[148:151], v[40:41], off
	global_load_dwordx4 v[152:155], v[42:43], off
	s_waitcnt vmcnt(14)
	ds_write_b128 v95, v[24:27]
	ds_write_b128 v95, v[20:23] offset:4608
	s_waitcnt vmcnt(12)
	ds_write_b128 v95, v[32:35] offset:1152
	ds_write_b128 v95, v[28:31] offset:5760
	s_waitcnt vmcnt(10)
	ds_write_b128 v95, v[132:135] offset:2304
	ds_write_b128 v95, v[128:131] offset:6912
	s_waitcnt vmcnt(8)
	ds_write_b128 v95, v[140:143] offset:3456
	ds_write_b128 v95, v[136:139] offset:8064
	ds_read_b128 v[20:23], v96 offset:4608
	ds_read_b128 v[24:27], v96 offset:4672
	s_add_i32 s0, s55, 0x100
	v_or_b32_e32 v40, s0, v82
	v_lshlrev_b32_e32 v188, 7, v40
	s_waitcnt lgkmcnt(1)
	v_mfma_f32_16x16x32_bf16 v[20:23], v[20:23], v[4:7], v[12:15]
	v_lshl_add_u64 v[28:29], v[74:75], 0, v[188:189]
	v_lshl_add_u64 v[30:31], v[76:77], 0, v[188:189]
	v_add_lshl_u32 v188, s0, v83, 7
	v_mfma_f32_16x16x32_bf16 v[116:119], v[64:67], v[48:51], v[116:119]
	v_mfma_f32_16x16x32_bf16 v[104:107], v[104:107], v[48:51], v[120:123]
	global_load_dwordx4 v[40:43], v[28:29], off
	global_load_dwordx4 v[48:51], v[30:31], off
	v_lshl_add_u64 v[28:29], v[74:75], 0, v[188:189]
	v_lshl_add_u64 v[30:31], v[76:77], 0, v[188:189]
	global_load_dwordx4 v[56:59], v[28:29], off
	global_load_dwordx4 v[64:67], v[30:31], off
	v_add_u32_e32 v28, 0x3498, v71
	s_waitcnt lgkmcnt(0)
	v_mfma_f32_16x16x32_bf16 v[20:23], v[24:27], v[8:11], v[20:23]
	ds_read2_b32 v[32:33], v28 offset1:1
	ds_read_b128 v[24:27], v96 offset:6912
	v_add_u32_e32 v28, 0x34a0, v71
	v_add_u32_e32 v29, 0x34d8, v71
	v_add_u32_e32 v30, 0x34e0, v71
	ds_read2_b32 v[34:35], v28 offset1:1
	ds_read2_b32 v[120:121], v29 offset1:1
	ds_read2_b32 v[122:123], v30 offset1:1
	ds_read_b128 v[28:31], v96 offset:6976
	s_waitcnt lgkmcnt(5)
	v_add_f32_e32 v20, v20, v32
	s_waitcnt lgkmcnt(4)
	v_mfma_f32_16x16x32_bf16 v[24:27], v[24:27], v[4:7], v[12:15]
	v_cndmask_b32_e64 v32, v234, v20, s[36:37]
	v_add_f32_e32 v20, v21, v33
	v_cndmask_b32_e64 v33, v234, v20, s[38:39]
	s_waitcnt lgkmcnt(3)
	v_add_f32_e32 v20, v22, v34
	v_cndmask_b32_e64 v34, v234, v20, s[40:41]
	v_add_f32_e32 v20, v23, v35
	v_cndmask_b32_e64 v35, v234, v20, s[42:43]
	s_waitcnt lgkmcnt(0)
	v_mfma_f32_16x16x32_bf16 v[20:23], v[28:31], v[8:11], v[24:27]
	v_add_lshl_u32 v188, s0, v84, 7
	s_nop 1
	v_exp_f32_e32 v24, v32
	v_exp_f32_e32 v27, v35
	s_nop 2
	v_add_f32_e32 v20, v20, v120
	v_add_f32_e32 v21, v21, v121
	v_cndmask_b32_e64 v20, v234, v20, s[44:45]
	v_cndmask_b32_e64 v21, v234, v21, s[46:47]
	v_exp_f32_e32 v25, v20
	v_exp_f32_e32 v20, v33
	v_exp_f32_e32 v26, v21
	v_exp_f32_e32 v21, v34
	v_add_f32_e32 v22, v22, v122
	v_add_f32_e32 v23, v23, v123
	v_cndmask_b32_e64 v22, v234, v22, s[48:49]
	v_cndmask_b32_e64 v23, v234, v23, s[50:51]
	v_exp_f32_e32 v28, v22
	v_exp_f32_e32 v23, v23
	v_cvt_pk_bf16_f32 v20, v24, v20
	v_cvt_pk_bf16_f32 v21, v21, v27
	v_cvt_pk_bf16_f32 v22, v25, v26
	ds_read_b64_tr_b16 v[26:27], v97 offset:2304
	ds_read_b64_tr_b16 v[24:25], v97
	v_cvt_pk_bf16_f32 v23, v28, v23
	ds_read_b64_tr_b16 v[30:31], v97 offset:2336
	ds_read_b64_tr_b16 v[28:29], v97 offset:32
	ds_read_b64_tr_b16 v[32:33], v97 offset:64
	ds_read_b64_tr_b16 v[120:121], v97 offset:96
	ds_read_b64_tr_b16 v[34:35], v97 offset:2368
	ds_read_b64_tr_b16 v[122:123], v97 offset:2400
	s_waitcnt lgkmcnt(6)
; #define LAS __attribute__((address_space(3)))
; #define MFMA16(a, b, c) __builtin_amdgcn_mfma_f32_16x16x32_bf16((a), (b), (c), 0, 0, 0)
; DI bf16x8 k_frag(const LAS char* vt, int t, int ks, int lane) { return k_frag_at(vt + KT_OFF, t, ks, lane); }
; DI void d_compute(f32x4 (&o)[4], f32x4& ol, const TileRegs& R, const bf16x8 (&qf)[2], const f32x4 cinit, int kr, int kc0, const LAS float* rpl, LAS char* vt, int lane) {
;     tile_v_to_lds(R, vt, lane);
;     const LAS float* rr_ = rpl + kr * 31;
;     f32x4 st[2];
; #pragma unroll
;     for (int t = 0; t < 2; ++t) {
;         st[t] = MFMA16(k_frag(vt, t, 0, lane), qf[0], cinit); st[t] = MFMA16(k_frag(vt, t, 1, lane), qf[1], st[t]);
; #pragma unroll
;         for (int i = 0; i < 4; ++i) { const bool ok = (unsigned)(kc0 + 16 * t + i) <= 15u;
;             const float v = st[t][i] + rr_[16 * t + i];
;             st[t][i] = ok ? v : -1e30f; }
;     }
;     fb_update(o, ol, st[0], st[1], vt, lane);
;     asm volatile("" ::: "memory");
; }
; DI void mixerD2_unit(int u, const bf16* PROJ, bf16* YC, float rmax, const float* kmax_l, LAS char* vt, int wave, int lane) {
;     ...
;     d_compute(o, ol, R2, qf, cinit, 2, kc0, rpl, vt, lane); tile_load(R2, kb, vb, tb0 + 320, 1, lane);
;     d_compute(o, ol, R0, qf, cinit, 3, kc0, rpl, vt, lane); tile_load(R0, kb, vb, tb0 + 384, 1, lane);
;     d_compute(o, ol, R1, qf, cinit, 4, kc0, rpl, vt, lane); tile_load(R1, kb, vb, tb0 + 448, 1, lane);
;     d_compute(o, ol, R2, qf, cinit, 5, kc0, rpl, vt, lane);
	v_mfma_f32_16x16x32_bf16 v[108:111], v[24:27], v[20:23], v[108:111]
	v_lshl_add_u64 v[24:25], v[74:75], 0, v[188:189]
	v_lshl_add_u64 v[26:27], v[76:77], 0, v[188:189]
	v_add_lshl_u32 v188, s0, v85, 7
	global_load_dwordx4 v[128:131], v[24:25], off
	global_load_dwordx4 v[132:135], v[26:27], off
	v_lshl_add_u64 v[24:25], v[74:75], 0, v[188:189]
	v_lshl_add_u64 v[26:27], v[76:77], 0, v[188:189]
	global_load_dwordx4 v[136:139], v[24:25], off
	global_load_dwordx4 v[140:143], v[26:27], off
	s_waitcnt vmcnt(14)
	ds_write_b128 v95, v[44:47]
	ds_write_b128 v95, v[36:39] offset:4608
	s_waitcnt vmcnt(12)
	ds_write_b128 v95, v[60:63] offset:1152
	ds_write_b128 v95, v[52:55] offset:5760
	s_waitcnt vmcnt(10)
	ds_write_b128 v95, v[144:147] offset:2304
	ds_write_b128 v95, v[124:127] offset:6912
	s_waitcnt vmcnt(8)
	ds_write_b128 v95, v[152:155] offset:3456
	ds_write_b128 v95, v[148:151] offset:8064
	s_waitcnt lgkmcnt(12)
	v_mfma_f32_16x16x32_bf16 v[112:115], v[28:31], v[20:23], v[112:115]
	ds_read_b128 v[28:31], v96 offset:4608
	ds_read_b128 v[36:39], v96 offset:4672
	s_add_i32 s0, s55, 0x140
	v_mfma_f32_16x16x32_bf16 v[100:103], v[16:19], v[20:23], v[100:103]
	v_add_u32_e32 v52, 0x3514, v71
	v_add_u32_e32 v53, 0x3554, v71
	v_add_u32_e32 v54, 0x355c, v71
	s_waitcnt lgkmcnt(11)
	v_mfma_f32_16x16x32_bf16 v[116:119], v[32:35], v[20:23], v[116:119]
	s_waitcnt lgkmcnt(10)
	v_mfma_f32_16x16x32_bf16 v[104:107], v[120:123], v[20:23], v[104:107]
	v_or_b32_e32 v20, s0, v82
	v_lshlrev_b32_e32 v188, 7, v20
	v_lshl_add_u64 v[20:21], v[74:75], 0, v[188:189]
	s_waitcnt lgkmcnt(1)
	v_mfma_f32_16x16x32_bf16 v[44:47], v[28:31], v[4:7], v[12:15]
	v_lshl_add_u64 v[24:25], v[76:77], 0, v[188:189]
	v_add_lshl_u32 v188, s0, v83, 7
	v_lshl_add_u64 v[32:33], v[74:75], 0, v[188:189]
	v_lshl_add_u64 v[34:35], v[76:77], 0, v[188:189]
	global_load_dwordx4 v[20:23], v[20:21], off
	s_nop 0
	global_load_dwordx4 v[24:27], v[24:25], off
	s_nop 0
	global_load_dwordx4 v[28:31], v[32:33], off
	s_nop 0
	global_load_dwordx4 v[32:35], v[34:35], off
	s_waitcnt lgkmcnt(0)
	v_mfma_f32_16x16x32_bf16 v[36:39], v[36:39], v[8:11], v[44:47]
	ds_read2_b32 v[60:61], v52 offset1:1
	v_add_lshl_u32 v188, s0, v84, 7
	s_nop 0
	ds_read_b128 v[44:47], v96 offset:6912
	v_add_u32_e32 v52, 0x351c, v71
	ds_read2_b32 v[62:63], v52 offset1:1
	ds_read2_b32 v[120:121], v53 offset1:1
	ds_read2_b32 v[122:123], v54 offset1:1
	ds_read_b128 v[52:55], v96 offset:6976
	s_waitcnt lgkmcnt(5)
	v_add_f32_e32 v36, v36, v60
	s_waitcnt lgkmcnt(4)
	v_mfma_f32_16x16x32_bf16 v[44:47], v[44:47], v[4:7], v[12:15]
	v_cndmask_b32_e64 v60, v234, v36, s[36:37]
	v_add_f32_e32 v36, v37, v61
	v_cndmask_b32_e64 v61, v234, v36, s[38:39]
	s_waitcnt lgkmcnt(3)
	v_add_f32_e32 v36, v38, v62
	v_cndmask_b32_e64 v62, v234, v36, s[40:41]
	v_add_f32_e32 v36, v39, v63
	v_cndmask_b32_e64 v63, v234, v36, s[42:43]
	s_waitcnt lgkmcnt(0)
	v_mfma_f32_16x16x32_bf16 v[36:39], v[52:55], v[8:11], v[44:47]
	s_nop 2
	v_exp_f32_e32 v44, v60
	v_exp_f32_e32 v47, v63
	s_nop 2
	v_add_f32_e32 v36, v36, v120
	v_add_f32_e32 v37, v37, v121
	v_cndmask_b32_e64 v36, v234, v36, s[44:45]
	v_cndmask_b32_e64 v37, v234, v37, s[46:47]
	v_add_f32_e32 v38, v38, v122
	v_add_f32_e32 v39, v39, v123
	v_exp_f32_e32 v45, v36
	v_exp_f32_e32 v36, v61
	v_exp_f32_e32 v46, v37
	v_exp_f32_e32 v37, v62
	v_cndmask_b32_e64 v38, v234, v38, s[48:49]
	v_cndmask_b32_e64 v39, v234, v39, s[50:51]
	v_exp_f32_e32 v52, v38
	v_exp_f32_e32 v39, v39
	v_cvt_pk_bf16_f32 v36, v44, v36
	v_cvt_pk_bf16_f32 v37, v37, v47
	v_cvt_pk_bf16_f32 v38, v45, v46
	ds_read_b64_tr_b16 v[46:47], v97 offset:2304
	ds_read_b64_tr_b16 v[44:45], v97
	v_cvt_pk_bf16_f32 v39, v52, v39
	s_nop 1
	v_mfma_f32_16x16x32_bf16 v[60:63], v[16:19], v[36:39], v[100:103]
	ds_read_b64_tr_b16 v[54:55], v97 offset:2336
	ds_read_b64_tr_b16 v[52:53], v97 offset:32
	s_nop 0
	ds_read_b64_tr_b16 v[100:101], v97 offset:64
	ds_read_b64_tr_b16 v[120:121], v97 offset:96
	ds_read_b64_tr_b16 v[102:103], v97 offset:2368
	ds_read_b64_tr_b16 v[122:123], v97 offset:2400
	s_waitcnt lgkmcnt(6)
	v_mfma_f32_16x16x32_bf16 v[108:111], v[44:47], v[36:39], v[108:111]
	v_lshl_add_u64 v[44:45], v[74:75], 0, v[188:189]
	v_lshl_add_u64 v[46:47], v[76:77], 0, v[188:189]
	v_add_lshl_u32 v188, s0, v85, 7
	global_load_dwordx4 v[124:127], v[44:45], off
	global_load_dwordx4 v[144:147], v[46:47], off
	v_lshl_add_u64 v[44:45], v[74:75], 0, v[188:189]
	s_waitcnt lgkmcnt(1)
	v_mfma_f32_16x16x32_bf16 v[100:103], v[100:103], v[36:39], v[116:119]
	v_lshl_add_u64 v[46:47], v[76:77], 0, v[188:189]
	s_nop 1
	global_load_dwordx4 v[116:119], v[44:45], off
	global_load_dwordx4 v[148:151], v[46:47], off
	s_waitcnt vmcnt(14)
	ds_write_b128 v95, v[48:51]
	ds_write_b128 v95, v[40:43] offset:4608
	s_waitcnt vmcnt(12)
	ds_write_b128 v95, v[64:67] offset:1152
	ds_write_b128 v95, v[56:59] offset:5760
	s_waitcnt vmcnt(10)
	ds_write_b128 v95, v[132:135] offset:2304
	ds_write_b128 v95, v[128:131] offset:6912
	s_waitcnt vmcnt(8)
	ds_write_b128 v95, v[140:143] offset:3456
	ds_write_b128 v95, v[136:139] offset:8064
	ds_read_b128 v[40:43], v96 offset:4608
	ds_read_b128 v[64:67], v96 offset:4672
	s_add_i32 s0, s55, 0x180
	v_or_b32_e32 v44, s0, v82
	s_waitcnt lgkmcnt(1)
	v_mfma_f32_16x16x32_bf16 v[40:43], v[40:43], v[4:7], v[12:15]
	v_lshlrev_b32_e32 v188, 7, v44
	v_lshl_add_u64 v[44:45], v[74:75], 0, v[188:189]
	v_lshl_add_u64 v[48:49], v[76:77], 0, v[188:189]
	v_add_lshl_u32 v188, s0, v83, 7
	v_mfma_f32_16x16x32_bf16 v[112:115], v[52:55], v[36:39], v[112:115]
	v_lshl_add_u64 v[52:53], v[74:75], 0, v[188:189]
	v_lshl_add_u64 v[56:57], v[76:77], 0, v[188:189]
	global_load_dwordx4 v[44:47], v[44:45], off
	s_nop 0
	global_load_dwordx4 v[48:51], v[48:49], off
	v_mfma_f32_16x16x32_bf16 v[36:39], v[120:123], v[36:39], v[104:107]
	global_load_dwordx4 v[52:55], v[52:53], off
	s_nop 0
	global_load_dwordx4 v[56:59], v[56:57], off
	ds_read2_b32 v[120:121], v73 offset1:1
	v_add_u32_e32 v104, 0x35d0, v71
	s_waitcnt lgkmcnt(1)
; #define LAS __attribute__((address_space(3)))
; #define MFMA16(a, b, c) __builtin_amdgcn_mfma_f32_16x16x32_bf16((a), (b), (c), 0, 0, 0)
; DI bf16x8 k_frag(const LAS char* vt, int t, int ks, int lane) { return k_frag_at(vt + KT_OFF, t, ks, lane); }
; DI void d_compute(f32x4 (&o)[4], f32x4& ol, const TileRegs& R, const bf16x8 (&qf)[2], const f32x4 cinit, int kr, int kc0, const LAS float* rpl, LAS char* vt, int lane) {
;     tile_v_to_lds(R, vt, lane);
;     const LAS float* rr_ = rpl + kr * 31;
;     f32x4 st[2];
; #pragma unroll
;     for (int t = 0; t < 2; ++t) {
;         st[t] = MFMA16(k_frag(vt, t, 0, lane), qf[0], cinit); st[t] = MFMA16(k_frag(vt, t, 1, lane), qf[1], st[t]);
; #pragma unroll
;         for (int i = 0; i < 4; ++i) { const bool ok = (unsigned)(kc0 + 16 * t + i) <= 15u;
;             const float v = st[t][i] + rr_[16 * t + i];
;             st[t][i] = ok ? v : -1e30f; }
;     }
;     fb_update(o, ol, st[0], st[1], vt, lane);
;     asm volatile("" ::: "memory");
; }
; DI void mixerD2_unit(int u, const bf16* PROJ, bf16* YC, float rmax, const float* kmax_l, LAS char* vt, int wave, int lane) {
;     ...
;     d_compute(o, ol, R0, qf, cinit, 3, kc0, rpl, vt, lane); tile_load(R0, kb, vb, tb0 + 384, 1, lane);
;     d_compute(o, ol, R1, qf, cinit, 4, kc0, rpl, vt, lane); tile_load(R1, kb, vb, tb0 + 448, 1, lane);
;     d_compute(o, ol, R2, qf, cinit, 5, kc0, rpl, vt, lane);
;     d_compute(o, ol, R0, qf, cinit, 6, kc0, rpl, vt, lane);
	v_mfma_f32_16x16x32_bf16 v[40:43], v[64:67], v[8:11], v[40:43]
	ds_read_b128 v[64:67], v96 offset:6912
	v_add_u32_e32 v73, 0x3598, v71
	v_add_u32_e32 v105, 0x35d8, v71
	ds_read2_b32 v[122:123], v73 offset1:1
	ds_read2_b32 v[128:129], v104 offset1:1
	ds_read2_b32 v[130:131], v105 offset1:1
	ds_read_b128 v[104:107], v96 offset:6976
	s_waitcnt lgkmcnt(5)
	v_add_f32_e32 v40, v40, v120
	s_waitcnt lgkmcnt(4)
	v_mfma_f32_16x16x32_bf16 v[64:67], v[64:67], v[4:7], v[12:15]
	v_cndmask_b32_e64 v73, v234, v40, s[36:37]
	v_add_f32_e32 v40, v41, v121
	v_cndmask_b32_e64 v120, v234, v40, s[38:39]
	s_waitcnt lgkmcnt(3)
	v_add_f32_e32 v40, v42, v122
	v_cndmask_b32_e64 v121, v234, v40, s[40:41]
	v_add_f32_e32 v40, v43, v123
	v_cndmask_b32_e64 v122, v234, v40, s[42:43]
	s_waitcnt lgkmcnt(0)
	v_mfma_f32_16x16x32_bf16 v[40:43], v[104:107], v[8:11], v[64:67]
	v_add_lshl_u32 v188, s0, v84, 7
	s_addk_i32 s55, 0x1c0
	v_lshl_add_u64 v[132:133], v[76:77], 0, v[188:189]
	v_exp_f32_e32 v64, v73
	v_exp_f32_e32 v67, v122
	s_nop 2
	v_add_f32_e32 v40, v40, v128
	v_add_f32_e32 v41, v41, v129
	v_cndmask_b32_e64 v40, v234, v40, s[44:45]
	v_cndmask_b32_e64 v41, v234, v41, s[46:47]
	v_exp_f32_e32 v65, v40
	v_exp_f32_e32 v40, v120
	v_exp_f32_e32 v66, v41
	v_exp_f32_e32 v41, v121
	v_add_f32_e32 v42, v42, v130
	v_add_f32_e32 v43, v43, v131
	v_cndmask_b32_e64 v42, v234, v42, s[48:49]
	v_cndmask_b32_e64 v43, v234, v43, s[50:51]
	v_exp_f32_e32 v73, v42
	v_exp_f32_e32 v43, v43
	v_cvt_pk_bf16_f32 v40, v64, v40
	v_cvt_pk_bf16_f32 v41, v41, v67
	v_cvt_pk_bf16_f32 v42, v65, v66
	ds_read_b64_tr_b16 v[66:67], v97 offset:2304
	ds_read_b64_tr_b16 v[64:65], v97
	ds_read_b64_tr_b16 v[106:107], v97 offset:2336
	ds_read_b64_tr_b16 v[104:105], v97 offset:32
	ds_read_b64_tr_b16 v[120:121], v97 offset:64
	ds_read_b64_tr_b16 v[128:129], v97 offset:96
	ds_read_b64_tr_b16 v[122:123], v97 offset:2368
	ds_read_b64_tr_b16 v[130:131], v97 offset:2400
	v_cvt_pk_bf16_f32 v43, v73, v43
	v_add_u32_e32 v73, s55, v83
	v_min_u32_e32 v73, 0x7ff, v73
	s_waitcnt lgkmcnt(6)
	v_mfma_f32_16x16x32_bf16 v[64:67], v[64:67], v[40:43], v[108:111]
	s_nop 2
	v_lshl_add_u64 v[108:109], v[74:75], 0, v[188:189]
	v_add_lshl_u32 v188, s0, v85, 7
	s_waitcnt lgkmcnt(0)
	v_mfma_f32_16x16x32_bf16 v[128:131], v[128:131], v[40:43], v[36:39]
	v_lshl_add_u64 v[134:135], v[76:77], 0, v[188:189]
	s_mov_b64 s[0:1], 0x7800000
	s_nop 0
	v_or_b32_e32 v36, s55, v82
	v_mfma_f32_16x16x32_bf16 v[104:107], v[104:107], v[40:43], v[112:115]
	global_load_dwordx4 v[108:111], v[108:109], off
	s_nop 1
	global_load_dwordx4 v[112:115], v[132:133], off
	v_lshl_add_u64 v[132:133], v[74:75], 0, v[188:189]
	v_lshlrev_b32_e32 v188, 7, v36
	v_mfma_f32_16x16x32_bf16 v[60:63], v[16:19], v[40:43], v[60:63]
	v_lshl_add_u64 v[36:37], v[74:75], 0, v[188:189]
	v_mfma_f32_16x16x32_bf16 v[100:103], v[120:123], v[40:43], v[100:103]
	global_load_dwordx4 v[120:123], v[132:133], off
	s_nop 0
	global_load_dwordx4 v[132:135], v[134:135], off
	v_lshl_add_u64 v[40:41], v[76:77], 0, v[188:189]
	global_load_dwordx4 v[36:39], v[36:37], off
	s_nop 0
	global_load_dwordx4 v[40:43], v[40:41], off
	s_waitcnt vmcnt(16)
	ds_write_b128 v95, v[24:27]
	ds_write_b128 v95, v[20:23] offset:4608
	s_waitcnt vmcnt(14)
	ds_write_b128 v95, v[32:35] offset:1152
	ds_write_b128 v95, v[28:31] offset:5760
	s_waitcnt vmcnt(12)
	ds_write_b128 v95, v[144:147] offset:2304
	ds_write_b128 v95, v[124:127] offset:6912
	s_waitcnt vmcnt(10)
	ds_write_b128 v95, v[148:151] offset:3456
	ds_write_b128 v95, v[116:119] offset:8064
	ds_read_b128 v[24:27], v96 offset:4608
	v_lshlrev_b32_e32 v188, 7, v73
	v_lshl_add_u64 v[136:137], v[74:75], 0, v[188:189]
	v_add_u32_e32 v32, s55, v84
	v_lshl_add_u64 v[138:139], v[76:77], 0, v[188:189]
	global_load_dwordx4 v[20:23], v[136:137], off
	global_load_dwordx4 v[28:31], v[138:139], off
	v_min_u32_e32 v73, 0x7ff, v32
	ds_read_b128 v[32:35], v96 offset:4672
	s_waitcnt lgkmcnt(1)
	v_mfma_f32_16x16x32_bf16 v[24:27], v[24:27], v[4:7], v[12:15]
	v_lshlrev_b32_e32 v188, 7, v73
	v_lshl_add_u64 v[116:117], v[74:75], 0, v[188:189]
	v_lshl_add_u64 v[124:125], v[76:77], 0, v[188:189]
	v_add_u32_e32 v136, 0x360c, v71
	global_load_dwordx4 v[116:119], v[116:117], off
	s_nop 0
	global_load_dwordx4 v[124:127], v[124:125], off
	s_waitcnt lgkmcnt(0)
	v_mfma_f32_16x16x32_bf16 v[24:27], v[32:35], v[8:11], v[24:27]
	ds_read2_b32 v[140:141], v136 offset1:1
	ds_read_b128 v[32:35], v96 offset:6912
	v_add_u32_e32 v136, 0x3614, v71
	v_add_u32_e32 v137, 0x364c, v71
	v_add_u32_e32 v138, 0x3654, v71
	ds_read2_b32 v[142:143], v136 offset1:1
	ds_read2_b32 v[144:145], v137 offset1:1
	ds_read2_b32 v[146:147], v138 offset1:1
	ds_read_b128 v[136:139], v96 offset:6976
	s_waitcnt lgkmcnt(5)
	v_add_f32_e32 v24, v24, v140
	s_waitcnt lgkmcnt(4)
	v_mfma_f32_16x16x32_bf16 v[32:35], v[32:35], v[4:7], v[12:15]
	v_cndmask_b32_e64 v140, v234, v24, s[36:37]
	v_add_f32_e32 v24, v25, v141
	v_cndmask_b32_e64 v141, v234, v24, s[38:39]
	s_waitcnt lgkmcnt(3)
	v_add_f32_e32 v24, v26, v142
	v_cndmask_b32_e64 v142, v234, v24, s[40:41]
	v_add_f32_e32 v24, v27, v143
	v_cndmask_b32_e64 v143, v234, v24, s[42:43]
	s_waitcnt lgkmcnt(0)
; #define LAS __attribute__((address_space(3)))
; #define MFMA16(a, b, c) __builtin_amdgcn_mfma_f32_16x16x32_bf16((a), (b), (c), 0, 0, 0)
; DI bf16x8 k_frag(const LAS char* vt, int t, int ks, int lane) { return k_frag_at(vt + KT_OFF, t, ks, lane); }
; DI void d_compute(f32x4 (&o)[4], f32x4& ol, const TileRegs& R, const bf16x8 (&qf)[2], const f32x4 cinit, int kr, int kc0, const LAS float* rpl, LAS char* vt, int lane) {
;     tile_v_to_lds(R, vt, lane);
;     const LAS float* rr_ = rpl + kr * 31;
;     f32x4 st[2];
; #pragma unroll
;     for (int t = 0; t < 2; ++t) {
;         st[t] = MFMA16(k_frag(vt, t, 0, lane), qf[0], cinit); st[t] = MFMA16(k_frag(vt, t, 1, lane), qf[1], st[t]);
; #pragma unroll
;         for (int i = 0; i < 4; ++i) { const bool ok = (unsigned)(kc0 + 16 * t + i) <= 15u;
;             const float v = st[t][i] + rr_[16 * t + i];
;             st[t][i] = ok ? v : -1e30f; }
;     }
;     fb_update(o, ol, st[0], st[1], vt, lane);
;     asm volatile("" ::: "memory");
; }
; DI void mixerD2_unit(int u, const bf16* PROJ, bf16* YC, float rmax, const float* kmax_l, LAS char* vt, int wave, int lane) {
;     ...
;     d_compute(o, ol, R1, qf, cinit, 4, kc0, rpl, vt, lane); tile_load(R1, kb, vb, tb0 + 448, 1, lane);
;     d_compute(o, ol, R2, qf, cinit, 5, kc0, rpl, vt, lane);
;     d_compute(o, ol, R0, qf, cinit, 6, kc0, rpl, vt, lane);
;     d_compute(o, ol, R1, qf, cinit, 7, kc0, rpl, vt, lane);
	v_mfma_f32_16x16x32_bf16 v[24:27], v[136:139], v[8:11], v[32:35]
	v_add_u32_e32 v73, s55, v85
	s_nop 1
	v_exp_f32_e32 v32, v140
	v_exp_f32_e32 v35, v143
	s_nop 2
	v_add_f32_e32 v24, v24, v144
	v_add_f32_e32 v25, v25, v145
	v_cndmask_b32_e64 v24, v234, v24, s[44:45]
	v_cndmask_b32_e64 v25, v234, v25, s[46:47]
	v_exp_f32_e32 v33, v24
	v_exp_f32_e32 v24, v141
	v_exp_f32_e32 v34, v25
	v_exp_f32_e32 v25, v142
	v_add_f32_e32 v26, v26, v146
	v_add_f32_e32 v27, v27, v147
	v_cndmask_b32_e64 v26, v234, v26, s[48:49]
	v_cndmask_b32_e64 v27, v234, v27, s[50:51]
	v_exp_f32_e32 v136, v26
	v_exp_f32_e32 v27, v27
	v_cvt_pk_bf16_f32 v24, v32, v24
	v_cvt_pk_bf16_f32 v25, v25, v35
	v_cvt_pk_bf16_f32 v26, v33, v34
	ds_read_b64_tr_b16 v[34:35], v97 offset:2304
	ds_read_b64_tr_b16 v[32:33], v97
	v_cvt_pk_bf16_f32 v27, v136, v27
	ds_read_b64_tr_b16 v[138:139], v97 offset:2336
	ds_read_b64_tr_b16 v[136:137], v97 offset:32
	ds_read_b64_tr_b16 v[140:141], v97 offset:64
	ds_read_b64_tr_b16 v[144:145], v97 offset:96
	ds_read_b64_tr_b16 v[142:143], v97 offset:2368
	ds_read_b64_tr_b16 v[146:147], v97 offset:2400
	s_waitcnt lgkmcnt(6)
	v_mfma_f32_16x16x32_bf16 v[32:35], v[32:35], v[24:27], v[64:67]
	s_nop 2
	v_min_u32_e32 v64, 0x7ff, v73
	v_lshlrev_b32_e32 v188, 7, v64
	v_lshl_add_u64 v[74:75], v[74:75], 0, v[188:189]
	s_waitcnt lgkmcnt(4)
	v_mfma_f32_16x16x32_bf16 v[64:67], v[136:139], v[24:27], v[104:107]
	v_mov_b32_e32 v73, v189
	s_nop 1
	v_lshl_add_u64 v[104:105], v[76:77], 0, v[188:189]
	global_load_dwordx4 v[74:77], v[74:75], off
	s_nop 0
	global_load_dwordx4 v[104:107], v[104:105], off
	s_waitcnt vmcnt(14)
	ds_write_b128 v95, v[48:51]
	ds_write_b128 v95, v[44:47] offset:4608
	s_waitcnt vmcnt(12)
	ds_write_b128 v95, v[56:59] offset:1152
	ds_write_b128 v95, v[52:55] offset:5760
	s_waitcnt vmcnt(10)
	ds_write_b128 v95, v[112:115] offset:2304
	ds_write_b128 v95, v[108:111] offset:6912
	s_waitcnt vmcnt(8)
	ds_write_b128 v95, v[132:135] offset:3456
	ds_write_b128 v95, v[120:123] offset:8064
	ds_read_b128 v[44:47], v96 offset:4608
	ds_read_b128 v[48:51], v96 offset:4672
	v_add_u32_e32 v52, 0x3688, v71
	ds_read2_b32 v[56:57], v52 offset1:1
	s_waitcnt lgkmcnt(2)
	v_mfma_f32_16x16x32_bf16 v[44:47], v[44:47], v[4:7], v[12:15]
	v_add_u32_e32 v52, 0x3690, v71
	v_add_u32_e32 v53, 0x36c8, v71
	v_add_u32_e32 v54, 0x36d0, v71
	s_waitcnt lgkmcnt(1)
	v_mfma_f32_16x16x32_bf16 v[44:47], v[48:51], v[8:11], v[44:47]
	ds_read_b128 v[48:51], v96 offset:6912
	ds_read2_b32 v[58:59], v52 offset1:1
	ds_read2_b32 v[108:109], v53 offset1:1
	ds_read2_b32 v[110:111], v54 offset1:1
	ds_read_b128 v[52:55], v96 offset:6976
	s_waitcnt lgkmcnt(5)
	s_nop 1
	v_add_f32_e32 v44, v44, v56
	s_waitcnt lgkmcnt(4)
	v_mfma_f32_16x16x32_bf16 v[48:51], v[48:51], v[4:7], v[12:15]
	v_cndmask_b32_e64 v56, v234, v44, s[36:37]
	v_add_f32_e32 v44, v45, v57
	v_cndmask_b32_e64 v57, v234, v44, s[38:39]
	s_waitcnt lgkmcnt(3)
	v_add_f32_e32 v44, v46, v58
	v_cndmask_b32_e64 v58, v234, v44, s[40:41]
	v_add_f32_e32 v44, v47, v59
	v_cndmask_b32_e64 v59, v234, v44, s[42:43]
	s_waitcnt lgkmcnt(0)
	v_mfma_f32_16x16x32_bf16 v[44:47], v[52:55], v[8:11], v[48:51]
	s_nop 2
	v_exp_f32_e32 v48, v56
	v_exp_f32_e32 v51, v59
	s_nop 2
	v_add_f32_e32 v44, v44, v108
	v_add_f32_e32 v45, v45, v109
	v_add_f32_e32 v46, v46, v110
	v_add_f32_e32 v47, v47, v111
	v_cndmask_b32_e64 v44, v234, v44, s[44:45]
	v_cndmask_b32_e64 v45, v234, v45, s[46:47]
	v_cndmask_b32_e64 v46, v234, v46, s[48:49]
	v_cndmask_b32_e64 v47, v234, v47, s[50:51]
	v_exp_f32_e32 v49, v44
	v_exp_f32_e32 v44, v57
	v_exp_f32_e32 v50, v45
	v_exp_f32_e32 v45, v58
	v_exp_f32_e32 v52, v46
	v_exp_f32_e32 v47, v47
	v_mfma_f32_16x16x32_bf16 v[60:63], v[16:19], v[24:27], v[60:63]
	v_cvt_pk_bf16_f32 v44, v48, v44
	v_cvt_pk_bf16_f32 v45, v45, v51
	v_cvt_pk_bf16_f32 v46, v49, v50
	v_cvt_pk_bf16_f32 v47, v52, v47
	ds_read_b64_tr_b16 v[50:51], v97 offset:2304
	ds_read_b64_tr_b16 v[48:49], v97
	v_mfma_f32_16x16x32_bf16 v[52:55], v[16:19], v[44:47], v[60:63]
	ds_read_b64_tr_b16 v[58:59], v97 offset:2336
	ds_read_b64_tr_b16 v[56:57], v97 offset:32
	s_nop 0
	ds_read_b64_tr_b16 v[60:61], v97 offset:64
	ds_read_b64_tr_b16 v[108:109], v97 offset:96
	ds_read_b64_tr_b16 v[62:63], v97 offset:2368
	ds_read_b64_tr_b16 v[110:111], v97 offset:2400
	s_waitcnt vmcnt(6)
	ds_write_b128 v95, v[40:43]
	ds_write_b128 v95, v[36:39] offset:4608
	s_waitcnt vmcnt(4)
	ds_write_b128 v95, v[28:31] offset:1152
	ds_write_b128 v95, v[20:23] offset:5760
	s_waitcnt vmcnt(2)
	ds_write_b128 v95, v[124:127] offset:2304
	ds_write_b128 v95, v[116:119] offset:6912
	s_waitcnt vmcnt(0)
	ds_write_b128 v95, v[104:107] offset:3456
	ds_write_b128 v95, v[74:77] offset:8064
	ds_read_b128 v[20:23], v96 offset:4608
	ds_read_b128 v[28:31], v96 offset:4672
	v_add_u32_e32 v36, 0x3704, v71
	ds_read2_b32 v[40:41], v36 offset1:1
	s_waitcnt lgkmcnt(2)
	v_mfma_f32_16x16x32_bf16 v[20:23], v[20:23], v[4:7], v[12:15]
	v_add_u32_e32 v36, 0x370c, v71
	v_add_u32_e32 v37, 0x3744, v71
	v_add_u32_e32 v38, 0x374c, v71
	v_mfma_f32_16x16x32_bf16 v[100:103], v[140:143], v[24:27], v[100:103]
	v_mfma_f32_16x16x32_bf16 v[24:27], v[144:147], v[24:27], v[128:131]
	s_waitcnt lgkmcnt(1)
	v_mfma_f32_16x16x32_bf16 v[20:23], v[28:31], v[8:11], v[20:23]
	ds_read_b128 v[28:31], v96 offset:6912
	v_mfma_f32_16x16x32_bf16 v[32:35], v[48:51], v[44:47], v[32:35]
	v_mfma_f32_16x16x32_bf16 v[48:51], v[56:59], v[44:47], v[64:67]
	s_waitcnt lgkmcnt(1)
; #define LAS __attribute__((address_space(3)))
; DI void mixerD2_unit(int u, const bf16* PROJ, bf16* YC, float rmax, const float* kmax_l, LAS char* vt, int wave, int lane) {
;     ...
;     d_compute(o, ol, R1, qf, cinit, 7, kc0, rpl, vt, lane);
;     const float inv = 1.f / ol[0];
;     LAS char* sc = vt + SC_OFF; const int tok0 = 64 * rr + 16 * cb;
;     u32x2 gv[4];
;     rows16_load(sc, slab(PROJ, C_DG + h * 64, b), 64, tok0, 1, lane);
; #pragma unroll
;     for (int c = 0; c < 4; ++c) gv[c] = *(const LAS u32x2*)(sc + r * VT_PITCH + (16 * c + 4 * g) * 2);
	s_nop 3
	v_add_f32_e32 v20, v20, v40
	v_add_f32_e32 v21, v21, v41
	v_cndmask_b32_e64 v20, v234, v20, s[36:37]
	v_mfma_f32_16x16x32_bf16 v[56:59], v[60:63], v[44:47], v[100:103]
	v_cndmask_b32_e64 v21, v234, v21, s[38:39]
	v_or_b32_e32 v40, s54, v83
	v_ashrrev_i32_e32 v41, 31, v40
	v_mfma_f32_16x16x32_bf16 v[24:27], v[108:111], v[44:47], v[24:27]
	ds_read2_b32 v[42:43], v36 offset1:1
	ds_read2_b32 v[44:45], v37 offset1:1
	ds_read2_b32 v[46:47], v38 offset1:1
	ds_read_b128 v[36:39], v96 offset:6976
	s_waitcnt lgkmcnt(3)
	v_add_f32_e32 v22, v22, v42
	v_mfma_f32_16x16x32_bf16 v[4:7], v[28:31], v[4:7], v[12:15]
	v_add_u32_e32 v42, v88, v86
	s_nop 1
	v_add_f32_e32 v13, v23, v43
	s_waitcnt lgkmcnt(0)
	v_mfma_f32_16x16x32_bf16 v[4:7], v[36:39], v[8:11], v[4:7]
	v_cndmask_b32_e64 v12, v234, v22, s[40:41]
	v_cndmask_b32_e64 v13, v234, v13, s[42:43]
	v_exp_f32_e32 v10, v12
	v_exp_f32_e32 v11, v13
	s_nop 3
	v_add_f32_e32 v4, v4, v44
	v_add_f32_e32 v5, v5, v45
	v_add_f32_e32 v6, v6, v46
	v_add_f32_e32 v7, v7, v47
	v_cndmask_b32_e64 v4, v234, v4, s[44:45]
	v_cndmask_b32_e64 v5, v234, v5, s[46:47]
	v_cndmask_b32_e64 v6, v234, v6, s[48:49]
	v_cndmask_b32_e64 v7, v234, v7, s[50:51]
	v_exp_f32_e32 v8, v20
	v_exp_f32_e32 v4, v4
	v_exp_f32_e32 v9, v21
	v_exp_f32_e32 v5, v5
	v_exp_f32_e32 v14, v6
	v_exp_f32_e32 v15, v7
	v_cvt_pk_bf16_f32 v7, v10, v11
	ds_read_b64_tr_b16 v[12:13], v97 offset:2304
	ds_read_b64_tr_b16 v[10:11], v97
	v_cvt_pk_bf16_f32 v6, v8, v9
	v_cvt_pk_bf16_f32 v8, v4, v5
	v_cvt_pk_bf16_f32 v9, v14, v15
	v_lshl_add_u64 v[4:5], s[30:31], 0, v[72:73]
	v_lshlrev_b64 v[36:37], 7, v[40:41]
	s_waitcnt lgkmcnt(0)
	v_mfma_f32_16x16x32_bf16 v[10:13], v[10:13], v[6:9], v[32:35]
	s_nop 2
	v_lshl_add_u64 v[32:33], v[4:5], 0, s[0:1]
	v_or_b32_e32 v4, s54, v82
	v_ashrrev_i32_e32 v5, 31, v4
	v_mfma_f32_16x16x32_bf16 v[14:17], v[16:19], v[6:9], v[52:55]
	v_lshlrev_b64 v[34:35], 7, v[4:5]
	ds_read_b64_tr_b16 v[18:19], v97 offset:2336
	s_nop 5
	ds_read_b64_tr_b16 v[16:17], v97 offset:32
	ds_read_b64_tr_b16 v[20:21], v97 offset:64
	ds_read_b64_tr_b16 v[28:29], v97 offset:96
	ds_read_b64_tr_b16 v[22:23], v97 offset:2368
	ds_read_b64_tr_b16 v[30:31], v97 offset:2400
	v_lshl_add_u64 v[34:35], v[32:33], 0, v[34:35]
	v_lshl_add_u64 v[36:37], v[32:33], 0, v[36:37]
	global_load_dwordx4 v[32:35], v[34:35], off
	s_nop 0
	global_load_dwordx4 v[36:39], v[36:37], off
	s_waitcnt vmcnt(1)
	ds_write_b128 v42, v[32:35] offset:9216
	s_waitcnt vmcnt(0)
	ds_write_b128 v98, v[36:39] offset:9216
	v_div_scale_f32 v32, s[0:1], v14, v14, 1.0
	v_rcp_f32_e32 v33, v32
	v_add_u32_e32 v15, v87, v68
	v_add_u32_e32 v38, 0x2000, v15
	s_waitcnt lgkmcnt(6)
	v_mfma_f32_16x16x32_bf16 v[16:19], v[16:19], v[6:9], v[48:51]
	v_fma_f32 v15, -v32, v33, 1.0
	v_fmac_f32_e32 v33, v15, v33
	v_div_scale_f32 v15, vcc, 1.0, v14, 1.0
	v_mul_f32_e32 v34, v15, v33
	s_waitcnt lgkmcnt(3)
	v_mfma_f32_16x16x32_bf16 v[20:23], v[20:23], v[6:9], v[56:59]
	v_fma_f32 v35, -v32, v34, v15
	v_fmac_f32_e32 v34, v35, v33
	v_fma_f32 v15, -v32, v34, v15
	s_waitcnt lgkmcnt(2)
	v_mfma_f32_16x16x32_bf16 v[6:9], v[28:31], v[6:9], v[24:27]
	s_nop 2
	ds_read2_b64 v[24:27], v38 offset0:128 offset1:132
	ds_read2_b64 v[28:31], v38 offset0:136 offset1:140
	v_div_fmas_f32 v15, v15, v33, v34
	v_div_fixup_f32 v14, v15, v14, 1.0
	v_pk_mul_f32 v[12:13], v[12:13], v[14:15] op_sel_hi:[1,0]
	s_waitcnt lgkmcnt(1)
; #define LAS __attribute__((address_space(3)))
; DI unsigned pk2(float lo, float hi) { f32x2_t v = {lo, hi}; bf16x2_t b = __builtin_convertvector(v, bf16x2_t); return __builtin_bit_cast(unsigned, b); }
; DI float silu_f(float x) { return x * __builtin_amdgcn_rcpf(1.f + __expf(-x)); }
; DI void mixerD2_unit(int u, const bf16* PROJ, bf16* YC, float rmax, const float* kmax_l, LAS char* vt, int wave, int lane) {
;     ...
; #pragma unroll
;     for (int c = 0; c < 4; ++c) { const f32x4 ov = o[c] * inv;
;         u32x2 w; w.x = pk2(ov[0] * silu_f(bflo(gv[c].x)), ov[1] * silu_f(bfhi(gv[c].x))); w.y = pk2(ov[2] * silu_f(bflo(gv[c].y)), ov[3] * silu_f(bfhi(gv[c].y)));
;         *(LAS u32x2*)(sc + r * VT_PITCH + (16 * c + 4 * g) * 2) = w; }
;     rows16_store(sc, YC + (size_t)b * T * 1024 + 768 + h * 64, 1024, tok0, 1, lane);
	v_lshlrev_b32_e32 v32, 16, v24
	v_and_b32_e32 v33, 0xffff0000, v24
	v_mul_f32_e32 v15, 0xbfb8aa3b, v32
	v_exp_f32_e32 v15, v15
	v_mul_f32_e32 v24, 0xbfb8aa3b, v33
	v_exp_f32_e32 v34, v24
	v_and_b32_e32 v35, 0xffff0000, v25
	v_pk_mul_f32 v[10:11], v[10:11], v[14:15] op_sel_hi:[1,0]
	v_add_f32_e32 v15, 1.0, v15
	v_rcp_f32_e32 v24, v15
	v_add_f32_e32 v15, 1.0, v34
	v_lshlrev_b32_e32 v34, 16, v25
	v_mul_f32_e32 v25, 0xbfb8aa3b, v34
	v_exp_f32_e32 v36, v25
	v_mul_f32_e32 v25, 0xbfb8aa3b, v35
	v_exp_f32_e32 v37, v25
	v_rcp_f32_e32 v25, v15
	v_add_f32_e32 v15, 1.0, v36
	v_rcp_f32_e32 v36, v15
	v_add_f32_e32 v15, 1.0, v37
	v_rcp_f32_e32 v37, v15
	v_pk_mul_f32 v[24:25], v[24:25], v[32:33]
	s_lshl_b64 s[0:1], s[26:27], 22
	v_pk_mul_f32 v[10:11], v[10:11], v[24:25]
	v_pk_mul_f32 v[24:25], v[36:37], v[34:35]
	v_cvt_pk_bf16_f32 v10, v10, v11
	v_pk_mul_f32 v[12:13], v[12:13], v[24:25]
	s_add_u32 s0, s8, s0
	v_cvt_pk_bf16_f32 v11, v12, v13
	v_pk_mul_f32 v[12:13], v[14:15], v[18:19] op_sel_hi:[0,1]
	v_lshlrev_b32_e32 v18, 16, v26
	v_and_b32_e32 v19, 0xffff0000, v26
	v_mul_f32_e32 v15, 0xbfb8aa3b, v18
	v_exp_f32_e32 v15, v15
	v_mul_f32_e32 v24, 0xbfb8aa3b, v19
	v_exp_f32_e32 v25, v24
	v_lshlrev_b32_e32 v26, 16, v27
	v_pk_mul_f32 v[16:17], v[14:15], v[16:17] op_sel_hi:[0,1]
	v_add_f32_e32 v15, 1.0, v15
	v_rcp_f32_e32 v24, v15
	v_add_f32_e32 v15, 1.0, v25
	v_and_b32_e32 v27, 0xffff0000, v27
	v_mul_f32_e32 v25, 0xbfb8aa3b, v26
	v_exp_f32_e32 v32, v25
	v_mul_f32_e32 v25, 0xbfb8aa3b, v27
	v_exp_f32_e32 v33, v25
	v_rcp_f32_e32 v25, v15
	v_add_f32_e32 v15, 1.0, v32
	v_rcp_f32_e32 v32, v15
	v_add_f32_e32 v15, 1.0, v33
	v_rcp_f32_e32 v33, v15
	v_pk_mul_f32 v[18:19], v[24:25], v[18:19]
	s_addc_u32 s1, s9, s1
	v_pk_mul_f32 v[16:17], v[16:17], v[18:19]
	v_pk_mul_f32 v[18:19], v[32:33], v[26:27]
	v_cvt_pk_bf16_f32 v16, v16, v17
	v_pk_mul_f32 v[12:13], v[12:13], v[18:19]
	s_lshl_b32 s26, s53, 7
	v_cvt_pk_bf16_f32 v17, v12, v13
	s_waitcnt lgkmcnt(0)
	v_lshlrev_b32_e32 v12, 16, v28
	ds_write2_b64 v38, v[10:11], v[16:17] offset0:128 offset1:132
	v_pk_mul_f32 v[10:11], v[14:15], v[22:23] op_sel_hi:[0,1]
	v_and_b32_e32 v13, 0xffff0000, v28
	v_mul_f32_e32 v15, 0xbfb8aa3b, v12
	v_exp_f32_e32 v15, v15
	v_mul_f32_e32 v16, 0xbfb8aa3b, v13
	v_exp_f32_e32 v19, v16
	s_add_u32 s0, s0, s26
	v_pk_mul_f32 v[16:17], v[14:15], v[20:21] op_sel_hi:[0,1]
	v_add_f32_e32 v15, 1.0, v15
	v_lshlrev_b32_e32 v20, 16, v29
	v_rcp_f32_e32 v18, v15
	v_add_f32_e32 v15, 1.0, v19
	v_and_b32_e32 v21, 0xffff0000, v29
	v_mul_f32_e32 v19, 0xbfb8aa3b, v20
	v_exp_f32_e32 v22, v19
	v_mul_f32_e32 v19, 0xbfb8aa3b, v21
	v_exp_f32_e32 v23, v19
	v_rcp_f32_e32 v19, v15
	v_add_f32_e32 v15, 1.0, v22
	v_rcp_f32_e32 v22, v15
	v_add_f32_e32 v15, 1.0, v23
	v_rcp_f32_e32 v23, v15
	v_pk_mul_f32 v[12:13], v[18:19], v[12:13]
	v_pk_mul_f32 v[8:9], v[14:15], v[8:9] op_sel_hi:[0,1]
	v_pk_mul_f32 v[12:13], v[16:17], v[12:13]
	v_pk_mul_f32 v[16:17], v[22:23], v[20:21]
	v_cvt_pk_bf16_f32 v12, v12, v13
	v_pk_mul_f32 v[10:11], v[10:11], v[16:17]
	v_and_b32_e32 v17, 0xffff0000, v31
	v_cvt_pk_bf16_f32 v13, v10, v11
	v_lshlrev_b32_e32 v10, 16, v30
	v_and_b32_e32 v11, 0xffff0000, v30
	v_mul_f32_e32 v15, 0xbfb8aa3b, v10
	v_mul_f32_e32 v16, 0xbfb8aa3b, v11
	v_exp_f32_e32 v15, v15
	v_exp_f32_e32 v16, v16
	v_mul_f32_e32 v19, 0xbfb8aa3b, v17
	v_exp_f32_e32 v19, v19
	v_pk_mul_f32 v[6:7], v[14:15], v[6:7] op_sel_hi:[0,1]
	v_add_f32_e32 v14, 1.0, v15
	v_add_f32_e32 v15, 1.0, v16
	v_lshlrev_b32_e32 v16, 16, v31
	v_mul_f32_e32 v18, 0xbfb8aa3b, v16
	v_exp_f32_e32 v18, v18
	v_rcp_f32_e32 v14, v14
	v_rcp_f32_e32 v15, v15
	v_add_f32_e32 v19, 1.0, v19
	v_add_f32_e32 v18, 1.0, v18
	v_rcp_f32_e32 v18, v18
	v_rcp_f32_e32 v19, v19
	v_pk_mul_f32 v[10:11], v[14:15], v[10:11]
	s_addc_u32 s1, s1, 0
	v_pk_mul_f32 v[6:7], v[6:7], v[10:11]
	v_pk_mul_f32 v[10:11], v[18:19], v[16:17]
	v_cvt_pk_bf16_f32 v6, v6, v7
	v_pk_mul_f32 v[8:9], v[8:9], v[10:11]
	v_lshl_add_u64 v[14:15], s[0:1], 0, v[72:73]
	v_cvt_pk_bf16_f32 v7, v8, v9
	ds_write2_b64 v38, v[12:13], v[6:7] offset0:136 offset1:140
	ds_read_b128 v[6:9], v42 offset:9216
	ds_read_b128 v[10:13], v98 offset:9216
	v_lshlrev_b64 v[4:5], 11, v[4:5]
	v_lshl_add_u64 v[4:5], v[14:15], 0, v[4:5]
	s_add_i32 s52, s52, s88
	s_waitcnt lgkmcnt(1)
	global_store_dwordx4 v[4:5], v[6:9], off offset:1536 sc1
	v_lshlrev_b64 v[4:5], 11, v[40:41]
	v_lshl_add_u64 v[4:5], v[14:15], 0, v[4:5]
	s_cmpk_lt_i32 s52, 0x200
	s_waitcnt lgkmcnt(0)
	global_store_dwordx4 v[4:5], v[10:13], off offset:1536 sc1
	s_cbranch_scc0 .LBB0_368

; DI void ssd_scan(float* STATES, const float* TOT, int gtid, int gthreads) {
;     for (int it = gtid; it < 8 * 4 * 2 * 64 * 32; it += gthreads) {
;         const int n4 = it & 31, p = (it >> 5) & 63, dir = (it >> 11) & 1, h = (it >> 12) & 3, b = it >> 14;
;         f32x4 v[16]; float e[16];
; #pragma unroll
;         for (int st = 0; st < 16; ++st) { const int c = dir ? 15 - st : st; const int hd = ((b * 16 + c) * 4 + h) * 2 + dir;
;             v[st] = *(const f32x4*)(STATES + ((size_t)hd * 64 + p) * 128 + n4 * 4); e[st] = __expf(TOT[hd]); }
.LBB0_418:
	v_and_b32_e32 v6, 0x1f80, v5
	v_lshlrev_b32_e32 v188, 2, v6
	v_and_b32_e32 v10, 0x7c, v5
	v_lshrrev_b32_e32 v8, 11, v4
	v_lshl_add_u64 v[6:7], s[12:13], 0, v[188:189]
	v_lshlrev_b32_e32 v188, 2, v10
	v_bfe_i32 v9, v4, 11, 1
	v_lshl_add_u64 v[66:67], v[6:7], 0, v[188:189]
	v_ashrrev_i32_e32 v7, 7, v4
	v_and_b32_e32 v8, 6, v8
	s_movk_i32 s2, 0xff80
	v_bfe_u32 v73, v4, 11, 1
	v_and_b32_e32 v6, 0x78, v9
	v_and_or_b32 v77, v7, s2, v8
	v_or3_b32 v10, v73, v6, v77
	v_ashrrev_i32_e32 v11, 31, v10
	v_lshlrev_b64 v[6:7], 15, v[10:11]
	v_lshl_add_u64 v[68:69], v[66:67], 0, v[6:7]
	v_lshl_add_u64 v[10:11], v[10:11], 2, s[70:71]
	global_load_dwordx4 v[6:9], v[68:69], off
	v_cmp_eq_u32_e32 vcc, 0, v73
	global_load_dword v10, v[10:11], off
	v_lshlrev_b32_e32 v40, 3, v73
	v_add_u32_e32 v4, s56, v4
	s_mov_b32 s2, 0x1ffff
	v_add_u32_e32 v5, s75, v5
	s_waitcnt vmcnt(0)
	v_mul_f32_e32 v10, 0x3fb8aa3b, v10
	v_exp_f32_e32 v81, v10
	v_cndmask_b32_e64 v10, v235, 8, vcc
	v_or3_b32 v14, v73, v10, v77
	v_ashrrev_i32_e32 v15, 31, v14
	v_lshlrev_b64 v[10:11], 15, v[14:15]
	v_lshl_add_u64 v[70:71], v[66:67], 0, v[10:11]
	v_lshl_add_u64 v[14:15], v[14:15], 2, s[70:71]
	global_load_dwordx4 v[10:13], v[70:71], off
	s_nop 0
	global_load_dword v14, v[14:15], off
	s_waitcnt vmcnt(0)
	v_mul_f32_e32 v14, 0x3fb8aa3b, v14
	v_exp_f32_e32 v72, v14
	v_cndmask_b32_e64 v14, v236, 16, vcc
	v_or3_b32 v18, v73, v14, v77
	v_ashrrev_i32_e32 v19, 31, v18
	v_lshlrev_b64 v[14:15], 15, v[18:19]
	v_lshl_add_u64 v[74:75], v[66:67], 0, v[14:15]
	v_lshl_add_u64 v[18:19], v[18:19], 2, s[70:71]
	global_load_dwordx4 v[14:17], v[74:75], off
	s_nop 0
	global_load_dword v18, v[18:19], off
	s_waitcnt vmcnt(0)
	v_mul_f32_e32 v18, 0x3fb8aa3b, v18
	v_exp_f32_e32 v76, v18
	v_cndmask_b32_e64 v18, v237, 24, vcc
	v_or3_b32 v22, v73, v18, v77
	v_ashrrev_i32_e32 v23, 31, v22
	v_lshlrev_b64 v[18:19], 15, v[22:23]
	v_lshl_add_u64 v[78:79], v[66:67], 0, v[18:19]
	v_lshl_add_u64 v[22:23], v[22:23], 2, s[70:71]
	global_load_dwordx4 v[18:21], v[78:79], off
	s_nop 0
	global_load_dword v22, v[22:23], off
	s_waitcnt vmcnt(0)
	v_mul_f32_e32 v22, 0x3fb8aa3b, v22
	v_exp_f32_e32 v80, v22
	v_cndmask_b32_e64 v22, v238, 32, vcc
	v_or3_b32 v26, v73, v22, v77
	v_ashrrev_i32_e32 v27, 31, v26
	v_lshlrev_b64 v[22:23], 15, v[26:27]
	v_lshl_add_u64 v[82:83], v[66:67], 0, v[22:23]
	v_lshl_add_u64 v[26:27], v[26:27], 2, s[70:71]
	global_load_dwordx4 v[22:25], v[82:83], off
	s_nop 0
	global_load_dword v26, v[26:27], off
	s_waitcnt vmcnt(0)
	v_mul_f32_e32 v26, 0x3fb8aa3b, v26
	v_exp_f32_e32 v84, v26
	v_cndmask_b32_e64 v26, v239, 40, vcc
	v_or3_b32 v30, v73, v26, v77
	v_ashrrev_i32_e32 v31, 31, v30
	v_lshlrev_b64 v[26:27], 15, v[30:31]
	v_lshl_add_u64 v[86:87], v[66:67], 0, v[26:27]
	v_lshl_add_u64 v[30:31], v[30:31], 2, s[70:71]
	global_load_dwordx4 v[26:29], v[86:87], off
	s_nop 0
	global_load_dword v30, v[30:31], off
	s_waitcnt vmcnt(0)
	v_mul_f32_e32 v30, 0x3fb8aa3b, v30
	v_exp_f32_e32 v88, v30
	v_cndmask_b32_e64 v30, v240, 48, vcc
	v_or3_b32 v34, v73, v30, v77
	v_ashrrev_i32_e32 v35, 31, v34
	v_lshlrev_b64 v[30:31], 15, v[34:35]
	v_lshl_add_u64 v[90:91], v[66:67], 0, v[30:31]
	v_lshl_add_u64 v[34:35], v[34:35], 2, s[70:71]
	global_load_dwordx4 v[30:33], v[90:91], off
	s_nop 0
	global_load_dword v34, v[34:35], off
	s_waitcnt vmcnt(0)
	v_mul_f32_e32 v34, 0x3fb8aa3b, v34
	v_exp_f32_e32 v92, v34
	v_or3_b32 v34, v40, v77, v73
	v_add_u32_e32 v38, 56, v34
	v_ashrrev_i32_e32 v39, 31, v38
	v_lshlrev_b64 v[34:35], 15, v[38:39]
	v_lshl_add_u64 v[94:95], v[66:67], 0, v[34:35]
	v_lshl_add_u64 v[38:39], v[38:39], 2, s[70:71]
	global_load_dwordx4 v[34:37], v[94:95], off
	s_nop 0
	global_load_dword v38, v[38:39], off
	s_waitcnt vmcnt(0)
	v_mul_f32_e32 v38, 0x3fb8aa3b, v38
	v_exp_f32_e32 v96, v38
	v_or_b32_e32 v38, 64, v73
	v_sub_u32_e32 v38, v38, v40
	v_or_b32_e32 v42, v38, v77
	v_ashrrev_i32_e32 v43, 31, v42
	v_lshlrev_b64 v[38:39], 15, v[42:43]
	v_lshl_add_u64 v[98:99], v[66:67], 0, v[38:39]
	v_lshl_add_u64 v[42:43], v[42:43], 2, s[70:71]
	global_load_dwordx4 v[38:41], v[98:99], off
	s_nop 0
	global_load_dword v42, v[42:43], off
	s_waitcnt vmcnt(0)
	v_mul_f32_e32 v42, 0x3fb8aa3b, v42
	v_exp_f32_e32 v100, v42
	v_cndmask_b32_e32 v42, 48, v240, vcc
	v_or3_b32 v46, v73, v42, v77
	v_ashrrev_i32_e32 v47, 31, v46
	v_lshlrev_b64 v[42:43], 15, v[46:47]
	v_lshl_add_u64 v[102:103], v[66:67], 0, v[42:43]
	v_lshl_add_u64 v[46:47], v[46:47], 2, s[70:71]
	global_load_dwordx4 v[42:45], v[102:103], off
	s_nop 0
	global_load_dword v46, v[46:47], off
	s_waitcnt vmcnt(0)
	v_mul_f32_e32 v46, 0x3fb8aa3b, v46
	v_exp_f32_e32 v104, v46
	v_cndmask_b32_e32 v46, 40, v239, vcc
	v_or3_b32 v50, v73, v46, v77
	v_ashrrev_i32_e32 v51, 31, v50
	v_lshlrev_b64 v[46:47], 15, v[50:51]
	v_lshl_add_u64 v[106:107], v[66:67], 0, v[46:47]
	v_lshl_add_u64 v[50:51], v[50:51], 2, s[70:71]
	global_load_dwordx4 v[46:49], v[106:107], off
	s_nop 0
	global_load_dword v50, v[50:51], off
	s_waitcnt vmcnt(0)
; DI void ssd_scan(float* STATES, const float* TOT, int gtid, int gthreads) {
;     ...
;         for (int st = 0; st < 16; ++st) { const int c = dir ? 15 - st : st; const int hd = ((b * 16 + c) * 4 + h) * 2 + dir;
;             v[st] = *(const f32x4*)(STATES + ((size_t)hd * 64 + p) * 128 + n4 * 4); e[st] = __expf(TOT[hd]); }
;         f32x4 carry = (f32x4){0.f, 0.f, 0.f, 0.f};
; #pragma unroll
;         for (int st = 0; st < 16; ++st) { const int c = dir ? 15 - st : st; const int hd = ((b * 16 + c) * 4 + h) * 2 + dir;
;             *(f32x4*)(STATES + ((size_t)hd * 64 + p) * 128 + n4 * 4) = carry; carry = carry * e[st] + v[st]; }
;     }
	v_mul_f32_e32 v50, 0x3fb8aa3b, v50
	v_exp_f32_e32 v108, v50
	v_cndmask_b32_e32 v50, 32, v238, vcc
	v_or3_b32 v54, v73, v50, v77
	v_ashrrev_i32_e32 v55, 31, v54
	v_lshlrev_b64 v[50:51], 15, v[54:55]
	v_lshl_add_u64 v[110:111], v[66:67], 0, v[50:51]
	v_lshl_add_u64 v[54:55], v[54:55], 2, s[70:71]
	global_load_dwordx4 v[50:53], v[110:111], off
	s_nop 0
	global_load_dword v54, v[54:55], off
	s_waitcnt vmcnt(0)
	v_mul_f32_e32 v54, 0x3fb8aa3b, v54
	v_exp_f32_e32 v112, v54
	v_cndmask_b32_e32 v54, 24, v237, vcc
	v_or3_b32 v58, v73, v54, v77
	v_ashrrev_i32_e32 v59, 31, v58
	v_lshlrev_b64 v[54:55], 15, v[58:59]
	v_lshl_add_u64 v[114:115], v[66:67], 0, v[54:55]
	v_lshl_add_u64 v[58:59], v[58:59], 2, s[70:71]
	global_load_dwordx4 v[54:57], v[114:115], off
	s_nop 0
	global_load_dword v58, v[58:59], off
	s_waitcnt vmcnt(0)
	v_mul_f32_e32 v58, 0x3fb8aa3b, v58
	v_exp_f32_e32 v116, v58
	v_cndmask_b32_e32 v58, 16, v236, vcc
	v_or3_b32 v62, v73, v58, v77
	v_ashrrev_i32_e32 v63, 31, v62
	v_lshlrev_b64 v[58:59], 15, v[62:63]
	v_lshl_add_u64 v[118:119], v[66:67], 0, v[58:59]
	v_lshl_add_u64 v[62:63], v[62:63], 2, s[70:71]
	global_load_dwordx4 v[58:61], v[118:119], off
	s_nop 0
	global_load_dword v62, v[62:63], off
	s_waitcnt vmcnt(0)
	v_mul_f32_e32 v62, 0x3fb8aa3b, v62
	v_exp_f32_e32 v120, v62
	v_cndmask_b32_e32 v62, 8, v235, vcc
	v_or3_b32 v122, v73, v62, v77
	v_ashrrev_i32_e32 v123, 31, v122
	v_lshlrev_b64 v[62:63], 15, v[122:123]
	v_lshl_add_u64 v[124:125], v[66:67], 0, v[62:63]
	v_lshl_add_u64 v[122:123], v[122:123], 2, s[70:71]
	global_load_dwordx4 v[62:65], v[124:125], off
	global_load_dword v85, v[122:123], off
	s_waitcnt vmcnt(0)
	v_mul_f32_e32 v85, 0x3fb8aa3b, v85
	global_store_dwordx4 v[68:69], v[0:3], off sc1
	v_mul_f32_e32 v68, 0, v81
	v_pk_add_f32 v[8:9], v[8:9], v[68:69] op_sel_hi:[1,0]
	v_pk_add_f32 v[6:7], v[6:7], v[68:69] op_sel_hi:[1,0]
	global_store_dwordx4 v[70:71], v[6:9], off sc1
	v_exp_f32_e32 v122, v85
	v_cndmask_b32_e32 v85, 0, v241, vcc
	v_pk_fma_f32 v[8:9], v[8:9], v[72:73], v[12:13] op_sel_hi:[1,0,1]
	v_pk_fma_f32 v[6:7], v[6:7], v[72:73], v[10:11] op_sel_hi:[1,0,1]
	global_store_dwordx4 v[74:75], v[6:9], off sc1
	v_or3_b32 v126, v73, v85, v77
	v_ashrrev_i32_e32 v127, 31, v126
	v_pk_fma_f32 v[8:9], v[8:9], v[76:77], v[16:17] op_sel_hi:[1,0,1]
	v_pk_fma_f32 v[6:7], v[6:7], v[76:77], v[14:15] op_sel_hi:[1,0,1]
	global_store_dwordx4 v[78:79], v[6:9], off sc1
	v_lshlrev_b64 v[10:11], 15, v[126:127]
	v_cmp_lt_i32_e32 vcc, s2, v4
	v_pk_fma_f32 v[8:9], v[8:9], v[80:81], v[20:21] op_sel_hi:[1,0,1]
	v_pk_fma_f32 v[6:7], v[6:7], v[80:81], v[18:19] op_sel_hi:[1,0,1]
	global_store_dwordx4 v[82:83], v[6:9], off sc1
	v_lshl_add_u64 v[10:11], v[66:67], 0, v[10:11]
	s_or_b64 s[20:21], vcc, s[20:21]
	v_pk_fma_f32 v[8:9], v[8:9], v[84:85], v[24:25] op_sel_hi:[1,0,1]
	v_pk_fma_f32 v[6:7], v[6:7], v[84:85], v[22:23] op_sel_hi:[1,0,1]
	global_store_dwordx4 v[86:87], v[6:9], off sc1
	s_nop 1
	v_pk_fma_f32 v[8:9], v[8:9], v[88:89], v[28:29] op_sel_hi:[1,0,1]
	v_pk_fma_f32 v[6:7], v[6:7], v[88:89], v[26:27] op_sel_hi:[1,0,1]
	global_store_dwordx4 v[90:91], v[6:9], off sc1
	s_nop 1
	v_pk_fma_f32 v[8:9], v[8:9], v[92:93], v[32:33] op_sel_hi:[1,0,1]
	v_pk_fma_f32 v[6:7], v[6:7], v[92:93], v[30:31] op_sel_hi:[1,0,1]
	global_store_dwordx4 v[94:95], v[6:9], off sc1
	s_nop 1
	v_pk_fma_f32 v[8:9], v[8:9], v[96:97], v[36:37] op_sel_hi:[1,0,1]
	v_pk_fma_f32 v[6:7], v[6:7], v[96:97], v[34:35] op_sel_hi:[1,0,1]
	global_store_dwordx4 v[98:99], v[6:9], off sc1
	s_nop 1
	v_pk_fma_f32 v[8:9], v[8:9], v[100:101], v[40:41] op_sel_hi:[1,0,1]
	v_pk_fma_f32 v[6:7], v[6:7], v[100:101], v[38:39] op_sel_hi:[1,0,1]
	global_store_dwordx4 v[102:103], v[6:9], off sc1
	s_nop 1
	v_pk_fma_f32 v[8:9], v[8:9], v[104:105], v[44:45] op_sel_hi:[1,0,1]
	v_pk_fma_f32 v[6:7], v[6:7], v[104:105], v[42:43] op_sel_hi:[1,0,1]
	global_store_dwordx4 v[106:107], v[6:9], off sc1
	s_nop 1
	v_pk_fma_f32 v[8:9], v[8:9], v[108:109], v[48:49] op_sel_hi:[1,0,1]
	v_pk_fma_f32 v[6:7], v[6:7], v[108:109], v[46:47] op_sel_hi:[1,0,1]
	global_store_dwordx4 v[110:111], v[6:9], off sc1
	s_nop 1
	v_pk_fma_f32 v[8:9], v[8:9], v[112:113], v[52:53] op_sel_hi:[1,0,1]
	v_pk_fma_f32 v[6:7], v[6:7], v[112:113], v[50:51] op_sel_hi:[1,0,1]
	global_store_dwordx4 v[114:115], v[6:9], off sc1
	s_nop 1
	v_pk_fma_f32 v[8:9], v[8:9], v[116:117], v[56:57] op_sel_hi:[1,0,1]
	v_pk_fma_f32 v[6:7], v[6:7], v[116:117], v[54:55] op_sel_hi:[1,0,1]
	global_store_dwordx4 v[118:119], v[6:9], off sc1
	s_nop 1
	v_pk_fma_f32 v[8:9], v[8:9], v[120:121], v[60:61] op_sel_hi:[1,0,1]
	v_pk_fma_f32 v[6:7], v[6:7], v[120:121], v[58:59] op_sel_hi:[1,0,1]
	global_store_dwordx4 v[124:125], v[6:9], off sc1
	s_nop 1
	v_pk_fma_f32 v[8:9], v[8:9], v[122:123], v[64:65] op_sel_hi:[1,0,1]
	v_pk_fma_f32 v[6:7], v[6:7], v[122:123], v[62:63] op_sel_hi:[1,0,1]
	global_store_dwordx4 v[10:11], v[6:9], off sc1
	s_andn2_b64 exec, exec, s[20:21]
	s_cbranch_execnz .LBB0_418

; DI float ex2(float x) { return __builtin_amdgcn_exp2f(x); }
; DI float q_norm2(const bf16x8 (&qf)[2]) { float a = sumsq8(qf[0]) + sumsq8(qf[1]); a += __shfl_xor(a, 16); a += __shfl_xor(a, 32); return a; }
; #define A_LOAD(R, t_) do { int tb_, sd_, md_; a_desc((t_), a0, rho, tb_, sd_, md_); tile_load(R, kb, vb, tb_, sd_, lane); } while (0)
; DI float a_bound(const bf16x8 (&qf)[2], const float* kmax_l, int b, int h) { return sqrtf(q_norm2(qf) * (kmax_l[b * 128 + 8 + 2 * h] + kmax_l[b * 128 + 9 + 2 * h])) * 1.01f + 0.05f; }
; DI void mixerA2_unit(int u, const bf16* PROJ, bf16* YC, const float* LPA, const float* kmax_l, LAS char* vt, int wave, int lane) {
;     const int b = u >> 6, h = (u >> 4) & 3, rho = u & 15, a0 = 16 * wave, r = lane & 15, g = lane >> 4;
;     const bf16* kb = slab(PROJ, C_AK + h * 64, b); const bf16* vb = slab(PROJ, C_AV + h * 64, b);
;     const int tq = 16 * (a0 + r) + rho;
;     bf16x8 qf[2];
; #pragma unroll
;     for (int ks = 0; ks < 2; ++ks) qf[ks] = *(const bf16x8*)(slab(PROJ, C_AQ + h * 64, b) + (size_t)tq * 64 + 32 * ks + 8 * g);
;     const float nslope2 = -ex2(-(float)(2 * h + 1)) * LOG2E;
;     const float bound = a_bound(qf, kmax_l, b, h);
;     const f32x4 cinit = {-bound, -bound, -bound, -bound};
;     f32x4 o[4], ol = {0.f, 0.f, 0.f, 0.f};
; #pragma unroll
;     for (int c = 0; c < 4; ++c) o[c] = ol;
;     TileRegs R0, R1, R2;
;     ...
;     A_LOAD(R0, 0); A_LOAD(R1, 1); A_LOAD(R2, 2);
.LBB0_421:
	s_ashr_i32 s94, s69, 6
	s_bfe_u32 s2, s69, 0x20004
	s_and_b32 s5, s69, 15
	s_ashr_i32 s95, s94, 31
	s_lshl_b32 s0, s2, 21
	s_add_u32 s4, s10, s0
	s_addc_u32 s16, s11, 0
	s_lshl_b64 s[0:1], s[94:95], 18
	v_or_b32_e32 v154, s5, v149
	s_add_u32 s30, s4, s0
	v_ashrrev_i32_e32 v155, 31, v154
	s_addc_u32 s31, s16, s1
	v_lshlrev_b64 v[4:5], 7, v[154:155]
	v_lshl_add_u64 v[4:5], s[30:31], 0, v[4:5]
	v_lshlrev_b32_e32 v188, 1, v148
	v_lshl_add_u64 v[4:5], v[4:5], 0, v[188:189]
	global_load_dwordx4 v[8:11], v[4:5], off
	s_nop 0
	global_load_dwordx4 v[4:7], v[4:5], off offset:64
	s_lshl_b32 s0, s2, 1
	s_or_b32 s1, s0, 1
	v_cvt_f32_ubyte0_e32 v12, s1
	v_exp_f32_e64 v18, -v12
	s_lshl_b32 s1, s94, 7
	s_or_b32 s0, s0, s1
	s_ashr_i32 s1, s0, 31
	s_lshl_b64 s[0:1], s[0:1], 2
	s_add_u32 s0, s60, s0
	s_addc_u32 s1, s61, s1
	v_mov_b32_e32 v151, v189
	v_mul_f32_e32 v153, 0xbfb8aa3b, v18
	s_or_b32 s4, s5, 0x600
	s_or_b32 s33, s5, s64
	s_lshl_b32 s34, s2, 2
	s_waitcnt vmcnt(0)
	v_and_b32_e32 v14, 0xffff0000, v8
	v_and_b32_e32 v15, 0xffff0000, v4
	v_lshlrev_b32_e32 v13, 16, v4
	v_lshlrev_b32_e32 v12, 16, v8
	v_pk_mul_f32 v[14:15], v[14:15], v[14:15]
	v_and_b32_e32 v17, 0xffff0000, v5
	v_and_b32_e32 v16, 0xffff0000, v9
	v_pk_fma_f32 v[12:13], v[12:13], v[12:13], v[14:15]
	v_lshlrev_b32_e32 v15, 16, v5
	v_lshlrev_b32_e32 v14, 16, v9
	v_pk_mul_f32 v[16:17], v[16:17], v[16:17]
	s_nop 0
	v_pk_fma_f32 v[14:15], v[14:15], v[14:15], v[16:17]
	v_and_b32_e32 v17, 0xffff0000, v6
	v_and_b32_e32 v16, 0xffff0000, v10
	v_pk_add_f32 v[12:13], v[12:13], v[14:15]
	v_lshlrev_b32_e32 v15, 16, v6
	v_lshlrev_b32_e32 v14, 16, v10
	v_pk_mul_f32 v[16:17], v[16:17], v[16:17]
	s_nop 0
	v_pk_fma_f32 v[14:15], v[14:15], v[14:15], v[16:17]
	v_and_b32_e32 v17, 0xffff0000, v7
	v_and_b32_e32 v16, 0xffff0000, v11
	v_pk_add_f32 v[12:13], v[14:15], v[12:13]
	v_lshlrev_b32_e32 v15, 16, v7
	v_lshlrev_b32_e32 v14, 16, v11
	v_pk_mul_f32 v[16:17], v[16:17], v[16:17]
	s_nop 0
	v_pk_fma_f32 v[14:15], v[14:15], v[14:15], v[16:17]
	global_load_dwordx2 v[16:17], v189, s[0:1] offset:32
	v_pk_add_f32 v[12:13], v[14:15], v[12:13]
	s_waitcnt vmcnt(0)
	v_mov_b32_e32 v14, v17
	v_add_f32_e32 v12, v12, v13
	ds_bpermute_b32 v13, v160, v12
	s_waitcnt lgkmcnt(0)
	v_add_f32_e32 v13, v12, v13
	ds_bpermute_b32 v15, v161, v13
	v_mov_b32_e32 v12, v16
	v_lshl_add_u64 v[16:17], s[30:31], 0, v[150:151]
	v_add_u32_e32 v151, v169, v168
	s_waitcnt lgkmcnt(0)
	v_pk_add_f32 v[12:13], v[12:13], v[14:15]
	s_nop 0
	v_mul_f32_e32 v12, v12, v13
	v_cmp_gt_f32_e32 vcc, s92, v12
	v_mul_f32_e32 v13, 0x4f800000, v12
	s_nop 0
	v_cndmask_b32_e32 v12, v12, v13, vcc
	v_sqrt_f32_e32 v13, v12
	s_nop 0
	v_add_u32_e32 v14, -1, v13
	v_fma_f32 v15, -v14, v13, v12
	v_cmp_ge_f32_e64 s[0:1], 0, v15
	v_add_u32_e32 v15, 1, v13
	s_nop 0
	v_cndmask_b32_e64 v14, v13, v14, s[0:1]
	v_fma_f32 v13, -v15, v13, v12
	v_cmp_lt_f32_e64 s[0:1], 0, v13
	s_nop 1
	v_cndmask_b32_e64 v13, v14, v15, s[0:1]
	s_mov_b64 s[0:1], 0x800000
	v_lshl_add_u64 v[156:157], v[16:17], 0, s[0:1]
	s_mov_b64 s[0:1], 0x1000000
	v_lshl_add_u64 v[158:159], v[16:17], 0, s[0:1]
	v_or_b32_e32 v16, s5, v162
	v_lshlrev_b32_e32 v188, 7, v16
	v_lshl_add_u64 v[16:17], v[156:157], 0, v[188:189]
	global_load_dwordx4 v[52:55], v[16:17], off
	v_lshl_add_u64 v[16:17], v[158:159], 0, v[188:189]
	global_load_dwordx4 v[56:59], v[16:17], off
	v_or_b32_e32 v16, s5, v163
	v_lshlrev_b32_e32 v188, 7, v16
	v_lshl_add_u64 v[16:17], v[156:157], 0, v[188:189]
	global_load_dwordx4 v[60:63], v[16:17], off
	v_lshl_add_u64 v[16:17], v[158:159], 0, v[188:189]
	global_load_dwordx4 v[64:67], v[16:17], off
	v_or_b32_e32 v16, s5, v164
	v_lshlrev_b32_e32 v188, 7, v16
	v_lshl_add_u64 v[16:17], v[156:157], 0, v[188:189]
	global_load_dwordx4 v[68:71], v[16:17], off
	v_lshl_add_u64 v[16:17], v[158:159], 0, v[188:189]
	global_load_dwordx4 v[72:75], v[16:17], off
	v_or_b32_e32 v16, s5, v165
	v_lshlrev_b32_e32 v188, 7, v16
	v_lshl_add_u64 v[16:17], v[156:157], 0, v[188:189]
	global_load_dwordx4 v[76:79], v[16:17], off
	v_lshl_add_u64 v[16:17], v[158:159], 0, v[188:189]
	global_load_dwordx4 v[80:83], v[16:17], off
	s_or_b32 s0, s5, 0x200
	v_or_b32_e32 v16, s0, v162
	v_lshlrev_b32_e32 v188, 7, v16
	v_lshl_add_u64 v[16:17], v[156:157], 0, v[188:189]
	v_lshl_add_u64 v[20:21], v[158:159], 0, v[188:189]
	global_load_dwordx4 v[16:19], v[16:17], off
	s_or_b32 s1, s5, 0x400
	global_load_dwordx4 v[84:87], v[20:21], off
	v_or_b32_e32 v20, s0, v163
	v_lshlrev_b32_e32 v188, 7, v20
	v_lshl_add_u64 v[20:21], v[156:157], 0, v[188:189]
	global_load_dwordx4 v[88:91], v[20:21], off
	v_lshl_add_u64 v[20:21], v[158:159], 0, v[188:189]
	global_load_dwordx4 v[92:95], v[20:21], off
	v_or_b32_e32 v20, s0, v164
	v_lshlrev_b32_e32 v188, 7, v20
	v_lshl_add_u64 v[20:21], v[156:157], 0, v[188:189]
	global_load_dwordx4 v[96:99], v[20:21], off
	v_lshl_add_u64 v[20:21], v[158:159], 0, v[188:189]
	global_load_dwordx4 v[100:103], v[20:21], off
	v_or_b32_e32 v20, s0, v165
	v_lshlrev_b32_e32 v188, 7, v20
	v_lshl_add_u64 v[20:21], v[156:157], 0, v[188:189]
	global_load_dwordx4 v[104:107], v[20:21], off
	v_lshl_add_u64 v[20:21], v[158:159], 0, v[188:189]
	global_load_dwordx4 v[108:111], v[20:21], off
	v_or_b32_e32 v20, s1, v162
	v_lshlrev_b32_e32 v188, 7, v20
	v_or_b32_e32 v28, s1, v163
	v_lshl_add_u64 v[20:21], v[156:157], 0, v[188:189]
	v_lshl_add_u64 v[24:25], v[158:159], 0, v[188:189]
	v_lshlrev_b32_e32 v188, 7, v28
	v_or_b32_e32 v36, s1, v164
	v_lshl_add_u64 v[28:29], v[156:157], 0, v[188:189]
	v_lshl_add_u64 v[32:33], v[158:159], 0, v[188:189]
	v_lshlrev_b32_e32 v188, 7, v36
	v_or_b32_e32 v44, s1, v165
	v_lshl_add_u64 v[36:37], v[156:157], 0, v[188:189]
	v_lshl_add_u64 v[40:41], v[158:159], 0, v[188:189]
	v_lshlrev_b32_e32 v188, 7, v44
	v_lshl_add_u64 v[44:45], v[156:157], 0, v[188:189]
	v_lshl_add_u64 v[48:49], v[158:159], 0, v[188:189]
	global_load_dwordx4 v[20:23], v[20:21], off
	v_mul_f32_e32 v14, 0x37800000, v13
	global_load_dwordx4 v[24:27], v[24:25], off
	v_cndmask_b32_e32 v13, v13, v14, vcc
	global_load_dwordx4 v[28:31], v[28:29], off
	v_cmp_class_f32_e32 vcc, v12, v226
	global_load_dwordx4 v[32:35], v[32:33], off
	s_nop 0
	global_load_dwordx4 v[36:39], v[36:37], off
	v_cndmask_b32_e32 v12, v13, v12, vcc
	global_load_dwordx4 v[40:43], v[40:41], off
	v_fmamk_f32 v12, v12, 0x3f8147ae, v227
	global_load_dwordx4 v[44:47], v[44:45], off
	v_xor_b32_e32 v12, 0x80000000, v12
	global_load_dwordx4 v[48:51], v[48:49], off
	s_waitcnt vmcnt(22)
; #define LAS __attribute__((address_space(3)))
; #define MFMA16(a, b, c) __builtin_amdgcn_mfma_f32_16x16x32_bf16((a), (b), (c), 0, 0, 0)
; #define A_LOAD(R, t_) do { int tb_, sd_, md_; a_desc((t_), a0, rho, tb_, sd_, md_); tile_load(R, kb, vb, tb_, sd_, lane); } while (0)
; #define A_STAGE(S, R, t_) do { int tb_, sd_, md_; a_desc((t_), a0, rho, tb_, sd_, md_); a_stage(S, R, vt, (t_) & 1, qf, cinit, tb_, sd_, md_, tq, nslope2, lane); } while (0)
; template <bool EDGE>
; DI void a_scores(f32x4 (&st)[2], const LAS char* kt, const bf16x8 (&qf)[2], const f32x4 cinit, int tokbase, int stride, int maxd, int tq, float nslope2, int lane) {
;     const int g = lane >> 4;
;     const int base0 = tokbase + stride * 4 * g - tq;
; #pragma unroll
;     for (int t = 0; t < 2; ++t) {
;         st[t] = MFMA16(k_frag_at(kt, t, 0, lane), qf[0], cinit); st[t] = MFMA16(k_frag_at(kt, t, 1, lane), qf[1], st[t]);
; #pragma unroll
;         for (int i = 0; i < 4; ++i) { const int d = base0 + stride * (16 * t + i);
;             bool ok = (unsigned)(d + maxd) <= (unsigned)(2 * maxd);
;             if (EDGE) ok = ok && ((unsigned)(d + tq) < (unsigned)T);
;             const float v = __builtin_fmaf(__builtin_fabsf((float)d), nslope2, st[t][i]);
;             st[t][i] = ok ? v : -1e30f; }
;     }
; }
; DI void a_stage(f32x4 (&st)[2], const TileRegs& R, LAS char* vt, int vpar, const bf16x8 (&qf)[2], const f32x4 cinit, int tokbase, int stride, int maxd, int tq, float nslope2, int lane) {
; #pragma unroll
;     for (int it = 0; it < 4; ++it) { const int n = lane + 64 * it, row = n >> 3, ch = n & 7;
;         *(LAS u32x4*)(vt + vpar * A_V1 + row * VT_PITCH + ch * 16) = R.v[it]; *(LAS u32x4*)(vt + A_K + row * VT_PITCH + ch * 16) = R.k[it]; }
;     a_scores<true>(st, vt + A_K, qf, cinit, tokbase, stride, maxd, tq, nslope2, lane);
; }
; DI void mixerA2_unit(int u, const bf16* PROJ, bf16* YC, const float* LPA, const float* kmax_l, LAS char* vt, int wave, int lane) {
;     ...
;     f32x4 sA[2], sB[2];
;     ...
;     A_STAGE(sA, R0, 0); A_LOAD(R0, 3);
;     A_STAGE(sB, R1, 1); A_LOAD(R1, 4);
;     fb_update(o, ol, sA[0], sA[1], vt, lane);
;     A_STAGE(sA, R2, 2); A_LOAD(R2, 5);
	ds_write_b128 v183, v[56:59]
	ds_write_b128 v183, v[52:55] offset:9216
	s_waitcnt vmcnt(20)
	ds_write_b128 v183, v[64:67] offset:1152
	ds_write_b128 v183, v[60:63] offset:10368
	s_waitcnt vmcnt(18)
	ds_write_b128 v183, v[72:75] offset:2304
	ds_write_b128 v183, v[68:71] offset:11520
	s_waitcnt vmcnt(16)
	ds_write_b128 v183, v[80:83] offset:3456
	ds_write_b128 v183, v[76:79] offset:12672
	ds_read_b128 v[52:55], v151 offset:9216
	ds_read_b128 v[56:59], v151 offset:9280
	v_mov_b32_e32 v13, v12
	v_mov_b32_e32 v14, v12
	v_mov_b32_e32 v15, v12
	v_or_b32_e32 v60, s4, v163
	v_or_b32_e32 v68, s4, v164
	s_waitcnt lgkmcnt(1)
	v_mfma_f32_16x16x32_bf16 v[52:55], v[52:55], v[8:11], v[12:15]
	v_or_b32_e32 v76, s4, v165
	s_waitcnt lgkmcnt(0)
	v_mfma_f32_16x16x32_bf16 v[52:55], v[56:59], v[4:7], v[52:55]
	ds_read_b128 v[56:59], v151 offset:11584
	s_nop 6
	v_fma_f32 v52, |v170|, v153, v52
	v_cndmask_b32_e64 v116, v234, v52, s[36:37]
	v_fma_f32 v52, |v171|, v153, v53
	v_cndmask_b32_e64 v117, v234, v52, s[38:39]
	v_fma_f32 v52, |v172|, v153, v54
	v_cndmask_b32_e64 v118, v234, v52, s[40:41]
	v_fma_f32 v52, |v173|, v153, v55
	v_cndmask_b32_e64 v119, v234, v52, s[42:43]
	ds_read_b128 v[52:55], v151 offset:11520
	s_waitcnt lgkmcnt(0)
	v_mfma_f32_16x16x32_bf16 v[52:55], v[52:55], v[8:11], v[12:15]
	v_mfma_f32_16x16x32_bf16 v[52:55], v[56:59], v[4:7], v[52:55]
	s_nop 7
	v_fma_f32 v52, |v174|, v153, v52
	v_cndmask_b32_e64 v120, v234, v52, s[44:45]
	v_fma_f32 v52, |v175|, v153, v53
	v_cndmask_b32_e64 v121, v234, v52, s[46:47]
	v_fma_f32 v52, |v176|, v153, v54
	v_cndmask_b32_e64 v122, v234, v52, s[48:49]
	v_fma_f32 v52, |v177|, v153, v55
	v_cndmask_b32_e64 v123, v234, v52, s[50:51]
	v_or_b32_e32 v52, s4, v162
	v_lshlrev_b32_e32 v188, 7, v52
	v_lshl_add_u64 v[52:53], v[156:157], 0, v[188:189]
	v_lshl_add_u64 v[56:57], v[158:159], 0, v[188:189]
	v_lshlrev_b32_e32 v188, 7, v60
	v_lshl_add_u64 v[60:61], v[156:157], 0, v[188:189]
	v_lshl_add_u64 v[64:65], v[158:159], 0, v[188:189]
	v_lshlrev_b32_e32 v188, 7, v68
	v_lshl_add_u64 v[68:69], v[156:157], 0, v[188:189]
	v_lshl_add_u64 v[72:73], v[158:159], 0, v[188:189]
	v_lshlrev_b32_e32 v188, 7, v76
	v_lshl_add_u64 v[76:77], v[156:157], 0, v[188:189]
	v_lshl_add_u64 v[80:81], v[158:159], 0, v[188:189]
	global_load_dwordx4 v[52:55], v[52:53], off
	s_nop 0
	global_load_dwordx4 v[56:59], v[56:57], off
	s_nop 0
	global_load_dwordx4 v[60:63], v[60:61], off
	s_nop 0
	global_load_dwordx4 v[64:67], v[64:65], off
	s_nop 0
	global_load_dwordx4 v[68:71], v[68:69], off
	s_nop 0
	global_load_dwordx4 v[72:75], v[72:73], off
	s_nop 0
	global_load_dwordx4 v[76:79], v[76:77], off
	s_nop 0
	global_load_dwordx4 v[80:83], v[80:81], off
	s_waitcnt vmcnt(22)
	ds_write_b128 v183, v[84:87] offset:4608
	ds_write_b128 v183, v[16:19] offset:9216
	s_waitcnt vmcnt(20)
	ds_write_b128 v183, v[92:95] offset:5760
	ds_write_b128 v183, v[88:91] offset:10368
	s_waitcnt vmcnt(18)
	ds_write_b128 v183, v[100:103] offset:6912
	ds_write_b128 v183, v[96:99] offset:11520
	s_waitcnt vmcnt(16)
	ds_write_b128 v183, v[108:111] offset:8064
	ds_write_b128 v183, v[104:107] offset:12672
	v_or_b32_e32 v16, s0, v167
	v_sub_u32_e32 v88, v16, v154
	ds_read_b128 v[16:19], v151 offset:9216
	ds_read_b128 v[84:87], v151 offset:9280
	s_waitcnt lgkmcnt(1)
	v_mfma_f32_16x16x32_bf16 v[16:19], v[16:19], v[8:11], v[12:15]
	s_or_b32 s0, s5, s63
	s_waitcnt lgkmcnt(0)
	v_mfma_f32_16x16x32_bf16 v[16:19], v[84:87], v[4:7], v[16:19]
	v_add_u32_e32 v84, 0x400, v88
	v_cmp_gt_u32_e32 vcc, s14, v84
	v_cvt_f32_i32_e32 v84, v88
	s_nop 4
	v_fma_f32 v16, |v84|, v153, v16
	v_cndmask_b32_e32 v128, v234, v16, vcc
	v_add_u32_e32 v16, 16, v88
	v_cvt_f32_i32_e32 v16, v16
	v_add_u32_e32 v84, 0x410, v88
	v_cmp_gt_u32_e32 vcc, s14, v84
	ds_read_b128 v[84:87], v151 offset:11584
	v_fma_f32 v16, |v16|, v153, v17
	v_cndmask_b32_e32 v129, v234, v16, vcc
	v_add_u32_e32 v16, 32, v88
	v_cvt_f32_i32_e32 v16, v16
	v_add_u32_e32 v17, 0x420, v88
	v_cmp_gt_u32_e32 vcc, s14, v17
	v_add_u32_e32 v17, 0x430, v88
	v_fma_f32 v16, |v16|, v153, v18
	v_cndmask_b32_e32 v130, v234, v16, vcc
	v_add_u32_e32 v16, 48, v88
	v_cvt_f32_i32_e32 v16, v16
	v_cmp_gt_u32_e32 vcc, s14, v17
	v_exp_f32_e32 v128, v128
	v_exp_f32_e32 v129, v129
	v_fma_f32 v16, |v16|, v153, v19
	v_cndmask_b32_e32 v131, v234, v16, vcc
	ds_read_b128 v[16:19], v151 offset:11520
	s_waitcnt lgkmcnt(0)
; #define LAS __attribute__((address_space(3)))
; #define MFMA16(a, b, c) __builtin_amdgcn_mfma_f32_16x16x32_bf16((a), (b), (c), 0, 0, 0)
; DI float ex2(float x) { return __builtin_amdgcn_exp2f(x); }
; DI s16x4 vtr(const LAS char* p) { return __builtin_bit_cast(s16x4, __builtin_amdgcn_ds_read_tr16_b64_v4i16((LAS s16x4*)p)); }
; DI bf16x8 cat8(s16x4 lo, s16x4 hi) { return __builtin_shufflevector(lo, hi, 0, 1, 2, 3, 4, 5, 6, 7); }
; DI bf16x8 pack8(f32x4 a, f32x4 b) { u32x4 w; w.x = pk2(a[0], a[1]); w.y = pk2(a[2], a[3]); w.z = pk2(b[0], b[1]); w.w = pk2(b[2], b[3]); return __builtin_bit_cast(bf16x8, w); }
; DI void fb_update(f32x4 (&o)[4], f32x4& ol, const f32x4 st0, const f32x4 st1, const LAS char* vt, int lane) {
;     f32x4 p0, p1;
; #pragma unroll
;     for (int i = 0; i < 4; ++i) { p0[i] = ex2(st0[i]); p1[i] = ex2(st1[i]); }
;     const bf16x8 pf = pack8(p0, p1);
;     const bf16x8 ones = {0x3F80, 0x3F80, 0x3F80, 0x3F80, 0x3F80, 0x3F80, 0x3F80, 0x3F80};
;     ol = MFMA16(ones, pf, ol);
;     const int g = lane >> 4, q = (lane & 15) >> 2, p = lane & 3;
;     const LAS char* v0 = vt + (4 * g + q) * VT_PITCH + 8 * p;
;     const LAS char* v1 = v0 + 16 * VT_PITCH;
; #pragma unroll
;     for (int c = 0; c < 4; ++c) { const bf16x8 vf = cat8(vtr(v0 + 32 * c), vtr(v1 + 32 * c)); o[c] = MFMA16(vf, pf, o[c]); }
; }
; DI void mixerA2_unit(int u, const bf16* PROJ, bf16* YC, const float* LPA, const float* kmax_l, LAS char* vt, int wave, int lane) {
;     ...
;     A_STAGE(sA, R0, 0); A_LOAD(R0, 3);
;     A_STAGE(sB, R1, 1); A_LOAD(R1, 4);
;     fb_update(o, ol, sA[0], sA[1], vt, lane);
;     A_STAGE(sA, R2, 2); A_LOAD(R2, 5);
;     fb_update(o, ol, sB[0], sB[1], vt + A_V1, lane);
;     A_STAGE(sB, R0, 3); A_LOAD(R0, 6);
;     fb_update(o, ol, sA[0], sA[1], vt, lane);
;     A_STAGE(sA, R1, 4); A_LOAD(R1, 7);
;     fb_update(o, ol, sB[0], sB[1], vt + A_V1, lane);
;     A_STAGE(sB, R2, 5); A_LOAD(R2, 8);
;     fb_update(o, ol, sA[0], sA[1], vt, lane);
;     A_STAGE(sA, R0, 6); A_LOAD(R0, 9);
;     fb_update(o, ol, sB[0], sB[1], vt + A_V1, lane);
;     A_STAGE(sB, R1, 7);
;     fb_update(o, ol, sA[0], sA[1], vt, lane);
;     A_STAGE(sA, R2, 8);
;     fb_update(o, ol, sB[0], sB[1], vt + A_V1, lane);
;     A_STAGE(sB, R0, 9);
;     fb_update(o, ol, sA[0], sA[1], vt, lane);
;     fb_update(o, ol, sB[0], sB[1], vt + A_V1, lane);
	v_mfma_f32_16x16x32_bf16 v[16:19], v[16:19], v[8:11], v[12:15]
	v_exp_f32_e32 v130, v130
	v_exp_f32_e32 v131, v131
	v_cvt_pk_bf16_f32 v198, v128, v129
	v_mfma_f32_16x16x32_bf16 v[16:19], v[84:87], v[4:7], v[16:19]
	v_add_u32_e32 v84, 0x100, v88
	v_cvt_f32_i32_e32 v84, v84
	v_add_u32_e32 v85, 0x500, v88
	v_cmp_gt_u32_e32 vcc, s14, v85
	v_cvt_pk_bf16_f32 v199, v130, v131
	s_nop 2
	v_fma_f32 v16, |v84|, v153, v16
	v_cndmask_b32_e32 v136, v234, v16, vcc
	v_add_u32_e32 v16, 0x110, v88
	v_cvt_f32_i32_e32 v16, v16
	v_add_u32_e32 v84, 0x510, v88
	v_cmp_gt_u32_e32 vcc, s14, v84
	v_exp_f32_e32 v136, v136
	v_fma_f32 v16, |v16|, v153, v17
	v_cndmask_b32_e32 v137, v234, v16, vcc
	v_add_u32_e32 v16, 0x120, v88
	v_cvt_f32_i32_e32 v16, v16
	v_add_u32_e32 v17, 0x520, v88
	v_cmp_gt_u32_e32 vcc, s14, v17
	v_add_u32_e32 v17, 0x530, v88
	v_fma_f32 v16, |v16|, v153, v18
	v_cndmask_b32_e32 v138, v234, v16, vcc
	v_add_u32_e32 v16, 0x130, v88
	v_cvt_f32_i32_e32 v16, v16
	v_cmp_gt_u32_e32 vcc, s14, v17
	v_exp_f32_e32 v18, v117
	v_exp_f32_e32 v117, v122
	v_fma_f32 v16, |v16|, v153, v19
	v_cndmask_b32_e32 v139, v234, v16, vcc
	v_add_u32_e32 v16, s0, v178
	v_med3_i32 v16, v16, 0, v233
	v_lshlrev_b32_e32 v188, 7, v16
	v_lshl_add_u64 v[16:17], v[156:157], 0, v[188:189]
	global_load_dwordx4 v[84:87], v[16:17], off
	v_lshl_add_u64 v[16:17], v[158:159], 0, v[188:189]
	global_load_dwordx4 v[88:91], v[16:17], off
	v_add_u32_e32 v16, s0, v179
	v_med3_i32 v16, v16, 0, v233
	v_lshlrev_b32_e32 v188, 7, v16
	v_lshl_add_u64 v[16:17], v[156:157], 0, v[188:189]
	global_load_dwordx4 v[92:95], v[16:17], off
	v_lshl_add_u64 v[16:17], v[158:159], 0, v[188:189]
	global_load_dwordx4 v[96:99], v[16:17], off
	v_add_u32_e32 v16, s0, v180
	v_med3_i32 v16, v16, 0, v233
	v_lshlrev_b32_e32 v188, 7, v16
	v_lshl_add_u64 v[16:17], v[156:157], 0, v[188:189]
	global_load_dwordx4 v[100:103], v[16:17], off
	v_lshl_add_u64 v[16:17], v[158:159], 0, v[188:189]
	global_load_dwordx4 v[104:107], v[16:17], off
	v_add_u32_e32 v16, s0, v181
	v_med3_i32 v16, v16, 0, v233
	v_lshlrev_b32_e32 v188, 7, v16
	v_lshl_add_u64 v[16:17], v[156:157], 0, v[188:189]
	global_load_dwordx4 v[108:111], v[16:17], off
	v_lshl_add_u64 v[16:17], v[158:159], 0, v[188:189]
	global_load_dwordx4 v[112:115], v[16:17], off
	v_exp_f32_e32 v16, v116
	v_exp_f32_e32 v17, v120
	v_exp_f32_e32 v19, v121
	v_exp_f32_e32 v116, v118
	v_exp_f32_e32 v118, v119
	v_exp_f32_e32 v119, v123
	ds_read_b64_tr_b16 v[122:123], v184 offset:2304
	ds_read_b64_tr_b16 v[120:121], v184
	ds_read_b64_tr_b16 v[124:125], v184 offset:32
	ds_read_b64_tr_b16 v[126:127], v184 offset:2336
	ds_read_b64_tr_b16 v[132:133], v184 offset:64
	ds_read_b64_tr_b16 v[134:135], v184 offset:2368
	ds_read_b64_tr_b16 v[144:145], v184 offset:96
	ds_read_b64_tr_b16 v[146:147], v184 offset:2400
	s_waitcnt vmcnt(22)
	ds_write_b128 v183, v[24:27]
	ds_write_b128 v183, v[20:23] offset:9216
	s_waitcnt vmcnt(20)
	ds_write_b128 v183, v[32:35] offset:1152
	ds_write_b128 v183, v[28:31] offset:10368
	s_waitcnt vmcnt(18)
	ds_write_b128 v183, v[40:43] offset:2304
	ds_write_b128 v183, v[36:39] offset:11520
	s_waitcnt vmcnt(16)
	ds_write_b128 v183, v[48:51] offset:3456
	ds_write_b128 v183, v[44:47] offset:12672
	v_or_b32_e32 v20, s1, v167
	v_sub_u32_e32 v28, v20, v154
	ds_read_b128 v[20:23], v151 offset:9216
	ds_read_b128 v[24:27], v151 offset:9280
	s_waitcnt lgkmcnt(1)
	v_mfma_f32_16x16x32_bf16 v[20:23], v[20:23], v[8:11], v[12:15]
	v_cvt_pk_bf16_f32 v140, v16, v18
	v_cvt_pk_bf16_f32 v142, v17, v19
	v_mov_b64_e32 v[16:17], s[84:85]
	s_waitcnt lgkmcnt(0)
	v_mfma_f32_16x16x32_bf16 v[20:23], v[24:27], v[4:7], v[20:23]
	v_add_u32_e32 v24, 0x400, v28
	v_mov_b64_e32 v[18:19], s[86:87]
	v_cmp_gt_u32_e32 vcc, s14, v24
	v_cvt_f32_i32_e32 v24, v28
	v_cvt_pk_bf16_f32 v141, v116, v118
	v_cvt_pk_bf16_f32 v143, v117, v119
	v_add_u32_e32 v36, s33, v180
	s_nop 0
	v_fma_f32 v20, |v24|, v153, v20
	v_mfma_f32_16x16x32_bf16 v[116:119], v[16:19], v[140:143], 0
	v_add_u32_e32 v24, 0x410, v28
	v_med3_i32 v36, v36, 0, v233
	v_add_u32_e32 v44, s33, v181
	v_mfma_f32_16x16x32_bf16 v[120:123], v[120:123], v[140:143], 0
	v_exp_f32_e32 v137, v137
	v_exp_f32_e32 v138, v138
	v_exp_f32_e32 v139, v139
	v_mfma_f32_16x16x32_bf16 v[124:127], v[124:127], v[140:143], 0
	v_med3_i32 v44, v44, 0, v233
	v_cvt_pk_bf16_f32 v200, v136, v137
	v_cvt_pk_bf16_f32 v201, v138, v139
	v_mfma_f32_16x16x32_bf16 v[132:135], v[132:135], v[140:143], 0
	v_mfma_f32_16x16x32_bf16 v[140:143], v[144:147], v[140:143], 0
	v_cndmask_b32_e32 v144, v234, v20, vcc
	v_add_u32_e32 v20, 16, v28
	v_cvt_f32_i32_e32 v20, v20
	v_cmp_gt_u32_e32 vcc, s14, v24
	ds_read_b128 v[24:27], v151 offset:11584
	v_mfma_f32_16x16x32_bf16 v[116:119], v[16:19], v[198:201], v[116:119]
	v_fma_f32 v20, |v20|, v153, v21
	v_cndmask_b32_e32 v145, v234, v20, vcc
	v_add_u32_e32 v20, 32, v28
	v_cvt_f32_i32_e32 v20, v20
	v_add_u32_e32 v21, 0x420, v28
	v_cmp_gt_u32_e32 vcc, s14, v21
	v_add_u32_e32 v21, 0x430, v28
	v_fma_f32 v20, |v20|, v153, v22
	v_cndmask_b32_e32 v146, v234, v20, vcc
	v_add_u32_e32 v20, 48, v28
	v_cvt_f32_i32_e32 v20, v20
	v_cmp_gt_u32_e32 vcc, s14, v21
	v_fma_f32 v20, |v20|, v153, v23
	s_nop 0
	v_cndmask_b32_e32 v147, v234, v20, vcc
	ds_read_b128 v[20:23], v151 offset:11520
	s_waitcnt lgkmcnt(0)
; #define LAS __attribute__((address_space(3)))
; #define MFMA16(a, b, c) __builtin_amdgcn_mfma_f32_16x16x32_bf16((a), (b), (c), 0, 0, 0)
; DI float ex2(float x) { return __builtin_amdgcn_exp2f(x); }
; DI s16x4 vtr(const LAS char* p) { return __builtin_bit_cast(s16x4, __builtin_amdgcn_ds_read_tr16_b64_v4i16((LAS s16x4*)p)); }
; DI bf16x8 cat8(s16x4 lo, s16x4 hi) { return __builtin_shufflevector(lo, hi, 0, 1, 2, 3, 4, 5, 6, 7); }
; DI bf16x8 pack8(f32x4 a, f32x4 b) { u32x4 w; w.x = pk2(a[0], a[1]); w.y = pk2(a[2], a[3]); w.z = pk2(b[0], b[1]); w.w = pk2(b[2], b[3]); return __builtin_bit_cast(bf16x8, w); }
; DI void fb_update(f32x4 (&o)[4], f32x4& ol, const f32x4 st0, const f32x4 st1, const LAS char* vt, int lane) {
;     f32x4 p0, p1;
; #pragma unroll
;     for (int i = 0; i < 4; ++i) { p0[i] = ex2(st0[i]); p1[i] = ex2(st1[i]); }
;     const bf16x8 pf = pack8(p0, p1);
;     const bf16x8 ones = {0x3F80, 0x3F80, 0x3F80, 0x3F80, 0x3F80, 0x3F80, 0x3F80, 0x3F80};
;     ol = MFMA16(ones, pf, ol);
;     const int g = lane >> 4, q = (lane & 15) >> 2, p = lane & 3;
;     const LAS char* v0 = vt + (4 * g + q) * VT_PITCH + 8 * p;
;     const LAS char* v1 = v0 + 16 * VT_PITCH;
; #pragma unroll
;     for (int c = 0; c < 4; ++c) { const bf16x8 vf = cat8(vtr(v0 + 32 * c), vtr(v1 + 32 * c)); o[c] = MFMA16(vf, pf, o[c]); }
; }
; DI void mixerA2_unit(int u, const bf16* PROJ, bf16* YC, const float* LPA, const float* kmax_l, LAS char* vt, int wave, int lane) {
;     ...
;     A_STAGE(sA, R0, 0); A_LOAD(R0, 3);
;     A_STAGE(sB, R1, 1); A_LOAD(R1, 4);
;     fb_update(o, ol, sA[0], sA[1], vt, lane);
;     A_STAGE(sA, R2, 2); A_LOAD(R2, 5);
;     fb_update(o, ol, sB[0], sB[1], vt + A_V1, lane);
;     A_STAGE(sB, R0, 3); A_LOAD(R0, 6);
;     fb_update(o, ol, sA[0], sA[1], vt, lane);
;     A_STAGE(sA, R1, 4); A_LOAD(R1, 7);
;     fb_update(o, ol, sB[0], sB[1], vt + A_V1, lane);
;     A_STAGE(sB, R2, 5); A_LOAD(R2, 8);
;     fb_update(o, ol, sA[0], sA[1], vt, lane);
;     A_STAGE(sA, R0, 6); A_LOAD(R0, 9);
;     fb_update(o, ol, sB[0], sB[1], vt + A_V1, lane);
;     A_STAGE(sB, R1, 7);
;     fb_update(o, ol, sA[0], sA[1], vt, lane);
;     A_STAGE(sA, R2, 8);
;     fb_update(o, ol, sB[0], sB[1], vt + A_V1, lane);
;     A_STAGE(sB, R0, 9);
;     fb_update(o, ol, sA[0], sA[1], vt, lane);
;     fb_update(o, ol, sB[0], sB[1], vt + A_V1, lane);
	v_mfma_f32_16x16x32_bf16 v[20:23], v[20:23], v[8:11], v[12:15]
	v_mfma_f32_16x16x32_bf16 v[20:23], v[24:27], v[4:7], v[20:23]
	v_add_u32_e32 v24, 0x100, v28
	v_cvt_f32_i32_e32 v24, v24
	v_add_u32_e32 v25, 0x500, v28
	v_cmp_gt_u32_e32 vcc, s14, v25
	s_nop 3
	v_fma_f32 v20, |v24|, v153, v20
	v_cndmask_b32_e32 v155, v234, v20, vcc
	v_add_u32_e32 v20, 0x110, v28
	v_cvt_f32_i32_e32 v20, v20
	v_add_u32_e32 v24, 0x510, v28
	v_cmp_gt_u32_e32 vcc, s14, v24
	v_fma_f32 v20, |v20|, v153, v21
	s_nop 0
	v_cndmask_b32_e32 v186, v234, v20, vcc
	v_add_u32_e32 v20, 0x120, v28
	v_cvt_f32_i32_e32 v20, v20
	v_add_u32_e32 v21, 0x520, v28
	v_cmp_gt_u32_e32 vcc, s14, v21
	v_add_u32_e32 v21, 0x530, v28
	v_fma_f32 v20, |v20|, v153, v22
	v_cndmask_b32_e32 v187, v234, v20, vcc
	v_add_u32_e32 v20, 0x130, v28
	v_cvt_f32_i32_e32 v20, v20
	v_cmp_gt_u32_e32 vcc, s14, v21
	v_add_u32_e32 v28, s33, v179
	v_med3_i32 v28, v28, 0, v233
	v_fma_f32 v20, |v20|, v153, v23
	v_cndmask_b32_e32 v191, v234, v20, vcc
	v_add_u32_e32 v20, s33, v178
	v_med3_i32 v20, v20, 0, v233
	v_lshlrev_b32_e32 v188, 7, v20
	v_lshl_add_u64 v[20:21], v[156:157], 0, v[188:189]
	v_lshl_add_u64 v[24:25], v[158:159], 0, v[188:189]
	v_lshlrev_b32_e32 v188, 7, v28
	v_lshl_add_u64 v[28:29], v[156:157], 0, v[188:189]
	v_lshl_add_u64 v[32:33], v[158:159], 0, v[188:189]
	v_lshlrev_b32_e32 v188, 7, v36
	v_lshl_add_u64 v[36:37], v[156:157], 0, v[188:189]
	v_lshl_add_u64 v[40:41], v[158:159], 0, v[188:189]
	v_lshlrev_b32_e32 v188, 7, v44
	v_lshl_add_u64 v[44:45], v[156:157], 0, v[188:189]
	v_lshl_add_u64 v[48:49], v[158:159], 0, v[188:189]
	global_load_dwordx4 v[20:23], v[20:21], off
	s_nop 0
	global_load_dwordx4 v[24:27], v[24:25], off
	s_nop 0
	global_load_dwordx4 v[28:31], v[28:29], off
	s_nop 0
	global_load_dwordx4 v[32:35], v[32:33], off
	s_nop 0
	global_load_dwordx4 v[36:39], v[36:37], off
	s_nop 0
	global_load_dwordx4 v[40:43], v[40:41], off
	s_nop 0
	global_load_dwordx4 v[44:47], v[44:45], off
	s_nop 0
	global_load_dwordx4 v[48:51], v[48:49], off
	ds_read_b64_tr_b16 v[130:131], v184 offset:6912
	ds_read_b64_tr_b16 v[128:129], v184 offset:4608
	ds_read_b64_tr_b16 v[136:137], v184 offset:4640
	ds_read_b64_tr_b16 v[138:139], v184 offset:6944
	s_waitcnt lgkmcnt(2)
	v_mfma_f32_16x16x32_bf16 v[120:123], v[128:131], v[198:201], v[120:123]
	s_waitcnt lgkmcnt(0)
	v_mfma_f32_16x16x32_bf16 v[128:131], v[136:139], v[198:201], v[124:127]
	s_nop 2
	ds_read_b64_tr_b16 v[124:125], v184 offset:4672
	ds_read_b64_tr_b16 v[126:127], v184 offset:6976
	s_waitcnt lgkmcnt(0)
	v_mfma_f32_16x16x32_bf16 v[136:139], v[124:127], v[198:201], v[132:135]
	ds_read_b64_tr_b16 v[124:125], v184 offset:4704
	ds_read_b64_tr_b16 v[126:127], v184 offset:7008
	s_waitcnt vmcnt(22)
	ds_write_b128 v183, v[56:59] offset:4608
	ds_write_b128 v183, v[52:55] offset:9216
	s_waitcnt vmcnt(20)
	ds_write_b128 v183, v[64:67] offset:5760
	ds_write_b128 v183, v[60:63] offset:10368
	s_waitcnt vmcnt(18)
	ds_write_b128 v183, v[72:75] offset:6912
	ds_write_b128 v183, v[68:71] offset:11520
	s_waitcnt vmcnt(16)
	ds_write_b128 v183, v[80:83] offset:8064
	ds_write_b128 v183, v[76:79] offset:12672
	v_or_b32_e32 v52, s4, v167
	v_sub_u32_e32 v60, v52, v154
	ds_read_b128 v[52:55], v151 offset:9216
	ds_read_b128 v[56:59], v151 offset:9280
	s_waitcnt lgkmcnt(1)
	v_mfma_f32_16x16x32_bf16 v[52:55], v[52:55], v[8:11], v[12:15]
	s_or_b32 s4, s5, s62
	v_add_u32_e32 v68, s4, v180
	v_exp_f32_e32 v132, v146
	s_waitcnt lgkmcnt(0)
	v_mfma_f32_16x16x32_bf16 v[52:55], v[56:59], v[4:7], v[52:55]
	v_add_u32_e32 v56, 0x400, v60
	v_cmp_gt_u32_e32 vcc, s14, v56
	v_cvt_f32_i32_e32 v56, v60
	v_mfma_f32_16x16x32_bf16 v[140:143], v[124:127], v[198:201], v[140:143]
	v_exp_f32_e32 v124, v144
	v_exp_f32_e32 v125, v155
	s_nop 1
	v_fma_f32 v52, |v56|, v153, v52
	v_cndmask_b32_e32 v193, v234, v52, vcc
	v_add_u32_e32 v52, 16, v60
	v_cvt_f32_i32_e32 v52, v52
	v_add_u32_e32 v56, 0x410, v60
	v_cmp_gt_u32_e32 vcc, s14, v56
	ds_read_b128 v[56:59], v151 offset:11584
	v_fma_f32 v52, |v52|, v153, v53
	v_cndmask_b32_e32 v198, v234, v52, vcc
	v_add_u32_e32 v52, 32, v60
	v_cvt_f32_i32_e32 v52, v52
	v_add_u32_e32 v53, 0x420, v60
	v_cmp_gt_u32_e32 vcc, s14, v53
	v_add_u32_e32 v53, 0x430, v60
	v_fma_f32 v52, |v52|, v153, v54
	v_cndmask_b32_e32 v199, v234, v52, vcc
	v_add_u32_e32 v52, 48, v60
	v_cvt_f32_i32_e32 v52, v52
	v_cmp_gt_u32_e32 vcc, s14, v53
	v_exp_f32_e32 v126, v145
	v_exp_f32_e32 v127, v186
	v_fma_f32 v52, |v52|, v153, v55
	v_cndmask_b32_e32 v200, v234, v52, vcc
	ds_read_b128 v[52:55], v151 offset:11520
	s_waitcnt lgkmcnt(0)
; #define LAS __attribute__((address_space(3)))
; #define MFMA16(a, b, c) __builtin_amdgcn_mfma_f32_16x16x32_bf16((a), (b), (c), 0, 0, 0)
; #define A_LOAD(R, t_) do { int tb_, sd_, md_; a_desc((t_), a0, rho, tb_, sd_, md_); tile_load(R, kb, vb, tb_, sd_, lane); } while (0)
; #define A_STAGE(S, R, t_) do { int tb_, sd_, md_; a_desc((t_), a0, rho, tb_, sd_, md_); a_stage(S, R, vt, (t_) & 1, qf, cinit, tb_, sd_, md_, tq, nslope2, lane); } while (0)
; template <bool EDGE>
; DI void a_scores(f32x4 (&st)[2], const LAS char* kt, const bf16x8 (&qf)[2], const f32x4 cinit, int tokbase, int stride, int maxd, int tq, float nslope2, int lane) {
;     const int g = lane >> 4;
;     const int base0 = tokbase + stride * 4 * g - tq;
; #pragma unroll
;     for (int t = 0; t < 2; ++t) {
;         st[t] = MFMA16(k_frag_at(kt, t, 0, lane), qf[0], cinit); st[t] = MFMA16(k_frag_at(kt, t, 1, lane), qf[1], st[t]);
; #pragma unroll
;         for (int i = 0; i < 4; ++i) { const int d = base0 + stride * (16 * t + i);
;             bool ok = (unsigned)(d + maxd) <= (unsigned)(2 * maxd);
;             if (EDGE) ok = ok && ((unsigned)(d + tq) < (unsigned)T);
;             const float v = __builtin_fmaf(__builtin_fabsf((float)d), nslope2, st[t][i]);
;             st[t][i] = ok ? v : -1e30f; }
;     }
; }
; DI void mixerA2_unit(int u, const bf16* PROJ, bf16* YC, const float* LPA, const float* kmax_l, LAS char* vt, int wave, int lane) {
;     ...
;     A_STAGE(sA, R0, 0); A_LOAD(R0, 3);
;     A_STAGE(sB, R1, 1); A_LOAD(R1, 4);
;     fb_update(o, ol, sA[0], sA[1], vt, lane);
;     A_STAGE(sA, R2, 2); A_LOAD(R2, 5);
;     fb_update(o, ol, sB[0], sB[1], vt + A_V1, lane);
;     A_STAGE(sB, R0, 3); A_LOAD(R0, 6);
;     fb_update(o, ol, sA[0], sA[1], vt, lane);
;     A_STAGE(sA, R1, 4); A_LOAD(R1, 7);
;     fb_update(o, ol, sB[0], sB[1], vt + A_V1, lane);
;     A_STAGE(sB, R2, 5); A_LOAD(R2, 8);
;     fb_update(o, ol, sA[0], sA[1], vt, lane);
;     A_STAGE(sA, R0, 6); A_LOAD(R0, 9);
;     fb_update(o, ol, sB[0], sB[1], vt + A_V1, lane);
;     A_STAGE(sB, R1, 7);
;     fb_update(o, ol, sA[0], sA[1], vt, lane);
;     A_STAGE(sA, R2, 8);
;     fb_update(o, ol, sB[0], sB[1], vt + A_V1, lane);
;     A_STAGE(sB, R0, 9);
;     fb_update(o, ol, sA[0], sA[1], vt, lane);
;     fb_update(o, ol, sB[0], sB[1], vt + A_V1, lane);
	v_mfma_f32_16x16x32_bf16 v[52:55], v[52:55], v[8:11], v[12:15]
	v_exp_f32_e32 v133, v187
	v_exp_f32_e32 v134, v147
	v_exp_f32_e32 v135, v191
	v_mfma_f32_16x16x32_bf16 v[52:55], v[56:59], v[4:7], v[52:55]
	v_add_u32_e32 v56, 0x100, v60
	v_cvt_f32_i32_e32 v56, v56
	v_add_u32_e32 v57, 0x500, v60
	v_cmp_gt_u32_e32 vcc, s14, v57
	v_med3_i32 v68, v68, 0, v233
	s_nop 2
	v_fma_f32 v52, |v56|, v153, v52
	v_cndmask_b32_e32 v201, v234, v52, vcc
	v_add_u32_e32 v52, 0x110, v60
	v_cvt_f32_i32_e32 v52, v52
	v_add_u32_e32 v56, 0x510, v60
	v_cmp_gt_u32_e32 vcc, s14, v56
	v_add_u32_e32 v76, s4, v181
	v_fma_f32 v52, |v52|, v153, v53
	v_cndmask_b32_e32 v202, v234, v52, vcc
	v_add_u32_e32 v52, 0x120, v60
	v_cvt_f32_i32_e32 v52, v52
	v_add_u32_e32 v53, 0x520, v60
	v_cmp_gt_u32_e32 vcc, s14, v53
	v_add_u32_e32 v53, 0x530, v60
	v_fma_f32 v52, |v52|, v153, v54
	v_cndmask_b32_e32 v203, v234, v52, vcc
	v_add_u32_e32 v52, 0x130, v60
	v_cvt_f32_i32_e32 v52, v52
	v_cmp_gt_u32_e32 vcc, s14, v53
	v_add_u32_e32 v60, s4, v179
	v_med3_i32 v60, v60, 0, v233
	v_fma_f32 v52, |v52|, v153, v55
	v_cndmask_b32_e32 v204, v234, v52, vcc
	v_add_u32_e32 v52, s4, v178
	v_med3_i32 v52, v52, 0, v233
	v_lshlrev_b32_e32 v188, 7, v52
	v_lshl_add_u64 v[52:53], v[156:157], 0, v[188:189]
	v_lshl_add_u64 v[56:57], v[158:159], 0, v[188:189]
	v_lshlrev_b32_e32 v188, 7, v60
	v_lshl_add_u64 v[60:61], v[156:157], 0, v[188:189]
	v_lshl_add_u64 v[64:65], v[158:159], 0, v[188:189]
	v_lshlrev_b32_e32 v188, 7, v68
	v_med3_i32 v76, v76, 0, v233
	v_lshl_add_u64 v[68:69], v[156:157], 0, v[188:189]
	v_lshl_add_u64 v[72:73], v[158:159], 0, v[188:189]
	v_lshlrev_b32_e32 v188, 7, v76
	v_lshl_add_u64 v[76:77], v[156:157], 0, v[188:189]
	v_lshl_add_u64 v[80:81], v[158:159], 0, v[188:189]
	v_cvt_pk_bf16_f32 v144, v124, v126
	v_cvt_pk_bf16_f32 v145, v132, v134
	v_cvt_pk_bf16_f32 v146, v125, v127
	v_cvt_pk_bf16_f32 v147, v133, v135
	global_load_dwordx4 v[52:55], v[52:53], off
	s_or_b32 s16, s4, 0x80
	global_load_dwordx4 v[56:59], v[56:57], off
	v_mfma_f32_16x16x32_bf16 v[132:135], v[16:19], v[144:147], v[116:119]
	global_load_dwordx4 v[60:63], v[60:61], off
	s_nop 0
	global_load_dwordx4 v[64:67], v[64:65], off
	s_nop 0
	global_load_dwordx4 v[68:71], v[68:69], off
	s_nop 0
	global_load_dwordx4 v[72:75], v[72:73], off
	s_nop 0
	global_load_dwordx4 v[76:79], v[76:77], off
	s_nop 0
	global_load_dwordx4 v[80:83], v[80:81], off
	ds_read_b64_tr_b16 v[118:119], v184 offset:2304
	ds_read_b64_tr_b16 v[116:117], v184
	ds_read_b64_tr_b16 v[206:207], v184 offset:32
	s_waitcnt lgkmcnt(1)
	v_mfma_f32_16x16x32_bf16 v[124:127], v[116:119], v[144:147], v[120:123]
	ds_read_b64_tr_b16 v[208:209], v184 offset:2336
	ds_read_b64_tr_b16 v[116:117], v184 offset:64
	ds_read_b64_tr_b16 v[118:119], v184 offset:2368
	s_waitcnt lgkmcnt(0)
	v_mfma_f32_16x16x32_bf16 v[120:123], v[116:119], v[144:147], v[136:139]
	ds_read_b64_tr_b16 v[116:117], v184 offset:96
	ds_read_b64_tr_b16 v[118:119], v184 offset:2400
	s_waitcnt vmcnt(22)
	ds_write_b128 v183, v[88:91]
	ds_write_b128 v183, v[84:87] offset:9216
	s_waitcnt vmcnt(20)
	ds_write_b128 v183, v[96:99] offset:1152
	ds_write_b128 v183, v[92:95] offset:10368
	s_waitcnt vmcnt(18)
	ds_write_b128 v183, v[104:107] offset:2304
	ds_write_b128 v183, v[100:103] offset:11520
	s_waitcnt vmcnt(16)
	ds_write_b128 v183, v[112:115] offset:3456
	ds_write_b128 v183, v[108:111] offset:12672
	ds_read_b128 v[84:87], v151 offset:9216
	ds_read_b128 v[88:91], v151 offset:9280
	s_waitcnt lgkmcnt(1)
	v_mfma_f32_16x16x32_bf16 v[84:87], v[84:87], v[8:11], v[12:15]
	v_or_b32_e32 v92, s0, v168
	v_sub_u32_e32 v93, v92, v154
	v_cmp_gt_u32_e64 s[0:1], s67, v92
	s_waitcnt lgkmcnt(0)
	v_mfma_f32_16x16x32_bf16 v[84:87], v[88:91], v[4:7], v[84:87]
	v_add_u32_e32 v88, 0x100, v93
	v_cmp_gt_u32_e32 vcc, s22, v88
	v_cvt_f32_i32_e32 v88, v93
	s_and_b64 vcc, s[54:55], vcc
	v_mfma_f32_16x16x32_bf16 v[128:131], v[206:209], v[144:147], v[128:131]
	v_exp_f32_e32 v136, v193
	s_nop 1
	v_fma_f32 v84, |v88|, v153, v84
	v_add_u32_e32 v88, 0x104, v93
	v_mfma_f32_16x16x32_bf16 v[116:119], v[116:119], v[144:147], v[140:143]
	v_cndmask_b32_e32 v144, v234, v84, vcc
	v_add_u32_e32 v84, 4, v93
	v_cvt_f32_i32_e32 v84, v84
	v_cmp_gt_u32_e32 vcc, s22, v88
	s_and_b64 vcc, vcc, s[0:1]
	v_cmp_gt_u32_e64 s[0:1], s23, v92
	v_fma_f32 v84, |v84|, v153, v85
	v_cndmask_b32_e32 v145, v234, v84, vcc
	v_add_u32_e32 v84, 8, v93
	v_cvt_f32_i32_e32 v84, v84
	v_add_u32_e32 v85, 0x108, v93
	v_cmp_gt_u32_e32 vcc, s22, v85
	s_and_b64 vcc, vcc, s[0:1]
	v_fma_f32 v84, |v84|, v153, v86
	v_cndmask_b32_e32 v146, v234, v84, vcc
	v_add_u32_e32 v84, 12, v93
	v_cvt_f32_i32_e32 v84, v84
	v_add_u32_e32 v85, 0x10c, v93
	v_cmp_gt_u32_e32 vcc, s22, v85
	v_cmp_gt_u32_e64 s[0:1], s17, v92
	s_and_b64 vcc, vcc, s[0:1]
	v_fma_f32 v84, |v84|, v153, v87
	v_cndmask_b32_e32 v147, v234, v84, vcc
	ds_read_b128 v[84:87], v151 offset:11520
	ds_read_b128 v[88:91], v151 offset:11584
	s_waitcnt lgkmcnt(1)
	v_mfma_f32_16x16x32_bf16 v[84:87], v[84:87], v[8:11], v[12:15]
	v_cmp_gt_u32_e64 s[0:1], s58, v92
	v_exp_f32_e32 v138, v201
	v_exp_f32_e32 v137, v198
	s_waitcnt lgkmcnt(0)
; #define LAS __attribute__((address_space(3)))
; #define MFMA16(a, b, c) __builtin_amdgcn_mfma_f32_16x16x32_bf16((a), (b), (c), 0, 0, 0)
; #define A_LOAD(R, t_) do { int tb_, sd_, md_; a_desc((t_), a0, rho, tb_, sd_, md_); tile_load(R, kb, vb, tb_, sd_, lane); } while (0)
; #define A_STAGE(S, R, t_) do { int tb_, sd_, md_; a_desc((t_), a0, rho, tb_, sd_, md_); a_stage(S, R, vt, (t_) & 1, qf, cinit, tb_, sd_, md_, tq, nslope2, lane); } while (0)
; template <bool EDGE>
; DI void a_scores(f32x4 (&st)[2], const LAS char* kt, const bf16x8 (&qf)[2], const f32x4 cinit, int tokbase, int stride, int maxd, int tq, float nslope2, int lane) {
;     const int g = lane >> 4;
;     const int base0 = tokbase + stride * 4 * g - tq;
; #pragma unroll
;     for (int t = 0; t < 2; ++t) {
;         st[t] = MFMA16(k_frag_at(kt, t, 0, lane), qf[0], cinit); st[t] = MFMA16(k_frag_at(kt, t, 1, lane), qf[1], st[t]);
; #pragma unroll
;         for (int i = 0; i < 4; ++i) { const int d = base0 + stride * (16 * t + i);
;             bool ok = (unsigned)(d + maxd) <= (unsigned)(2 * maxd);
;             if (EDGE) ok = ok && ((unsigned)(d + tq) < (unsigned)T);
;             const float v = __builtin_fmaf(__builtin_fabsf((float)d), nslope2, st[t][i]);
;             st[t][i] = ok ? v : -1e30f; }
;     }
; }
; DI void mixerA2_unit(int u, const bf16* PROJ, bf16* YC, const float* LPA, const float* kmax_l, LAS char* vt, int wave, int lane) {
;     ...
;     A_STAGE(sB, R0, 3); A_LOAD(R0, 6);
;     fb_update(o, ol, sA[0], sA[1], vt, lane);
;     A_STAGE(sA, R1, 4); A_LOAD(R1, 7);
;     fb_update(o, ol, sB[0], sB[1], vt + A_V1, lane);
;     A_STAGE(sB, R2, 5); A_LOAD(R2, 8);
;     fb_update(o, ol, sA[0], sA[1], vt, lane);
;     A_STAGE(sA, R0, 6); A_LOAD(R0, 9);
;     fb_update(o, ol, sB[0], sB[1], vt + A_V1, lane);
;     A_STAGE(sB, R1, 7);
;     fb_update(o, ol, sA[0], sA[1], vt, lane);
;     A_STAGE(sA, R2, 8);
;     fb_update(o, ol, sB[0], sB[1], vt + A_V1, lane);
	v_mfma_f32_16x16x32_bf16 v[84:87], v[88:91], v[4:7], v[84:87]
	v_add_u32_e32 v88, 64, v93
	v_cvt_f32_i32_e32 v88, v88
	v_add_u32_e32 v89, 0x140, v93
	v_cmp_gt_u32_e32 vcc, s22, v89
	s_and_b64 vcc, s[54:55], vcc
	s_nop 2
	v_fma_f32 v84, |v88|, v153, v84
	v_cndmask_b32_e32 v155, v234, v84, vcc
	v_add_u32_e32 v84, 0x44, v93
	v_cvt_f32_i32_e32 v84, v84
	v_add_u32_e32 v88, 0x144, v93
	v_cmp_gt_u32_e32 vcc, s22, v88
	s_and_b64 vcc, vcc, s[0:1]
	v_fma_f32 v84, |v84|, v153, v85
	v_cndmask_b32_e32 v186, v234, v84, vcc
	v_add_u32_e32 v84, 0x48, v93
	v_cvt_f32_i32_e32 v84, v84
	v_add_u32_e32 v85, 0x148, v93
	v_cmp_gt_u32_e32 vcc, s22, v85
	v_cmp_gt_u32_e64 s[0:1], s59, v92
	s_and_b64 vcc, vcc, s[0:1]
	v_fma_f32 v84, |v84|, v153, v86
	v_cndmask_b32_e32 v187, v234, v84, vcc
	v_add_u32_e32 v84, 0x4c, v93
	v_cvt_f32_i32_e32 v84, v84
	v_add_u32_e32 v85, 0x14c, v93
	v_cmp_gt_u32_e32 vcc, s22, v85
	v_cmp_gt_u32_e64 s[0:1], s52, v92
	s_and_b64 vcc, vcc, s[0:1]
	v_fma_f32 v84, |v84|, v153, v87
	v_cndmask_b32_e32 v191, v234, v84, vcc
	v_add_u32_e32 v84, s16, v178
	v_med3_i32 v84, v84, 0, v233
	v_lshlrev_b32_e32 v188, 7, v84
	v_lshl_add_u64 v[84:85], v[156:157], 0, v[188:189]
	global_load_dwordx4 v[108:111], v[84:85], off
	v_lshl_add_u64 v[84:85], v[158:159], 0, v[188:189]
	global_load_dwordx4 v[112:115], v[84:85], off
	v_add_u32_e32 v84, s16, v179
	v_med3_i32 v84, v84, 0, v233
	v_lshlrev_b32_e32 v188, 7, v84
	v_lshl_add_u64 v[84:85], v[156:157], 0, v[188:189]
	global_load_dwordx4 v[100:103], v[84:85], off
	v_lshl_add_u64 v[84:85], v[158:159], 0, v[188:189]
	global_load_dwordx4 v[104:107], v[84:85], off
	v_add_u32_e32 v84, s16, v180
	v_med3_i32 v84, v84, 0, v233
	v_lshlrev_b32_e32 v188, 7, v84
	v_lshl_add_u64 v[84:85], v[156:157], 0, v[188:189]
	global_load_dwordx4 v[92:95], v[84:85], off
	v_lshl_add_u64 v[84:85], v[158:159], 0, v[188:189]
	global_load_dwordx4 v[96:99], v[84:85], off
	v_add_u32_e32 v84, s16, v181
	v_exp_f32_e32 v139, v202
	v_exp_f32_e32 v140, v199
	v_exp_f32_e32 v141, v203
	v_exp_f32_e32 v142, v200
	v_exp_f32_e32 v143, v204
	v_med3_i32 v84, v84, 0, v233
	v_lshlrev_b32_e32 v188, 7, v84
	v_lshl_add_u64 v[84:85], v[156:157], 0, v[188:189]
	v_lshl_add_u64 v[88:89], v[158:159], 0, v[188:189]
	global_load_dwordx4 v[84:87], v[84:85], off
	v_cvt_pk_bf16_f32 v136, v136, v137
	global_load_dwordx4 v[88:91], v[88:89], off
	v_cvt_pk_bf16_f32 v137, v140, v142
	v_cvt_pk_bf16_f32 v138, v138, v139
	v_cvt_pk_bf16_f32 v139, v141, v143
	ds_read_b64_tr_b16 v[142:143], v184 offset:6912
	ds_read_b64_tr_b16 v[140:141], v184 offset:4608
	ds_read_b64_tr_b16 v[198:199], v184 offset:4640
	s_waitcnt lgkmcnt(1)
	v_mfma_f32_16x16x32_bf16 v[124:127], v[140:143], v[136:139], v[124:127]
	ds_read_b64_tr_b16 v[200:201], v184 offset:6944
	ds_read_b64_tr_b16 v[140:141], v184 offset:4672
	ds_read_b64_tr_b16 v[142:143], v184 offset:6976
	s_waitcnt lgkmcnt(0)
	v_mfma_f32_16x16x32_bf16 v[140:143], v[140:143], v[136:139], v[120:123]
	s_nop 2
	ds_read_b64_tr_b16 v[120:121], v184 offset:4704
	ds_read_b64_tr_b16 v[122:123], v184 offset:7008
	s_waitcnt vmcnt(22)
	ds_write_b128 v183, v[24:27] offset:4608
	ds_write_b128 v183, v[20:23] offset:9216
	s_waitcnt vmcnt(20)
	ds_write_b128 v183, v[32:35] offset:5760
	ds_write_b128 v183, v[28:31] offset:10368
	s_waitcnt vmcnt(18)
	ds_write_b128 v183, v[40:43] offset:6912
	ds_write_b128 v183, v[36:39] offset:11520
	s_waitcnt vmcnt(16)
	ds_write_b128 v183, v[48:51] offset:8064
	ds_write_b128 v183, v[44:47] offset:12672
	ds_read_b128 v[20:23], v151 offset:9216
	ds_read_b128 v[24:27], v151 offset:9280
	s_waitcnt lgkmcnt(1)
	v_mfma_f32_16x16x32_bf16 v[20:23], v[20:23], v[8:11], v[12:15]
	v_or_b32_e32 v28, s33, v168
	v_sub_u32_e32 v29, v28, v154
	v_cmp_gt_u32_e64 s[0:1], s67, v28
	s_waitcnt lgkmcnt(0)
	v_mfma_f32_16x16x32_bf16 v[20:23], v[24:27], v[4:7], v[20:23]
	v_add_u32_e32 v24, 0x100, v29
	v_cmp_gt_u32_e32 vcc, s22, v24
	v_cvt_f32_i32_e32 v24, v29
	s_and_b64 vcc, s[90:91], vcc
	v_mfma_f32_16x16x32_bf16 v[128:131], v[198:201], v[136:139], v[128:131]
	s_or_b32 s33, s5, s65
	s_nop 1
	v_fma_f32 v20, |v24|, v153, v20
	v_cndmask_b32_e32 v193, v234, v20, vcc
	v_add_u32_e32 v20, 4, v29
	v_cvt_f32_i32_e32 v20, v20
	v_add_u32_e32 v24, 0x104, v29
	v_cmp_gt_u32_e32 vcc, s22, v24
	s_and_b64 vcc, vcc, s[0:1]
	v_fma_f32 v20, |v20|, v153, v21
	v_cndmask_b32_e32 v198, v234, v20, vcc
	v_add_u32_e32 v20, 8, v29
	v_cvt_f32_i32_e32 v20, v20
	v_add_u32_e32 v21, 0x108, v29
	v_cmp_gt_u32_e32 vcc, s22, v21
	v_cmp_gt_u32_e64 s[0:1], s23, v28
	s_and_b64 vcc, vcc, s[0:1]
	v_fma_f32 v20, |v20|, v153, v22
	v_cndmask_b32_e32 v199, v234, v20, vcc
	v_add_u32_e32 v20, 12, v29
	v_cvt_f32_i32_e32 v20, v20
	v_add_u32_e32 v21, 0x10c, v29
	v_cmp_gt_u32_e32 vcc, s22, v21
	v_cmp_gt_u32_e64 s[0:1], s17, v28
	s_and_b64 vcc, vcc, s[0:1]
	v_fma_f32 v20, |v20|, v153, v23
	v_cndmask_b32_e32 v200, v234, v20, vcc
	ds_read_b128 v[20:23], v151 offset:11520
	ds_read_b128 v[24:27], v151 offset:11584
	s_waitcnt lgkmcnt(1)
	v_mfma_f32_16x16x32_bf16 v[20:23], v[20:23], v[8:11], v[12:15]
	v_add_u32_e32 v32, s33, v181
	v_med3_i32 v32, v32, 0, v233
	s_or_b32 s5, s5, s68
	s_waitcnt lgkmcnt(0)
; #define LAS __attribute__((address_space(3)))
; #define MFMA16(a, b, c) __builtin_amdgcn_mfma_f32_16x16x32_bf16((a), (b), (c), 0, 0, 0)
; DI float ex2(float x) { return __builtin_amdgcn_exp2f(x); }
; DI s16x4 vtr(const LAS char* p) { return __builtin_bit_cast(s16x4, __builtin_amdgcn_ds_read_tr16_b64_v4i16((LAS s16x4*)p)); }
; DI bf16x8 cat8(s16x4 lo, s16x4 hi) { return __builtin_shufflevector(lo, hi, 0, 1, 2, 3, 4, 5, 6, 7); }
; DI bf16x8 pack8(f32x4 a, f32x4 b) { u32x4 w; w.x = pk2(a[0], a[1]); w.y = pk2(a[2], a[3]); w.z = pk2(b[0], b[1]); w.w = pk2(b[2], b[3]); return __builtin_bit_cast(bf16x8, w); }
; #define A_LOAD(R, t_) do { int tb_, sd_, md_; a_desc((t_), a0, rho, tb_, sd_, md_); tile_load(R, kb, vb, tb_, sd_, lane); } while (0)
; #define A_STAGE(S, R, t_) do { int tb_, sd_, md_; a_desc((t_), a0, rho, tb_, sd_, md_); a_stage(S, R, vt, (t_) & 1, qf, cinit, tb_, sd_, md_, tq, nslope2, lane); } while (0)
; DI void fb_update(f32x4 (&o)[4], f32x4& ol, const f32x4 st0, const f32x4 st1, const LAS char* vt, int lane) {
;     f32x4 p0, p1;
; #pragma unroll
;     for (int i = 0; i < 4; ++i) { p0[i] = ex2(st0[i]); p1[i] = ex2(st1[i]); }
;     const bf16x8 pf = pack8(p0, p1);
;     const bf16x8 ones = {0x3F80, 0x3F80, 0x3F80, 0x3F80, 0x3F80, 0x3F80, 0x3F80, 0x3F80};
;     ol = MFMA16(ones, pf, ol);
;     const int g = lane >> 4, q = (lane & 15) >> 2, p = lane & 3;
;     const LAS char* v0 = vt + (4 * g + q) * VT_PITCH + 8 * p;
;     const LAS char* v1 = v0 + 16 * VT_PITCH;
; #pragma unroll
;     for (int c = 0; c < 4; ++c) { const bf16x8 vf = cat8(vtr(v0 + 32 * c), vtr(v1 + 32 * c)); o[c] = MFMA16(vf, pf, o[c]); }
; }
; DI void mixerA2_unit(int u, const bf16* PROJ, bf16* YC, const float* LPA, const float* kmax_l, LAS char* vt, int wave, int lane) {
;     ...
;     A_STAGE(sA, R1, 4); A_LOAD(R1, 7);
;     fb_update(o, ol, sB[0], sB[1], vt + A_V1, lane);
;     A_STAGE(sB, R2, 5); A_LOAD(R2, 8);
;     fb_update(o, ol, sA[0], sA[1], vt, lane);
;     A_STAGE(sA, R0, 6); A_LOAD(R0, 9);
;     fb_update(o, ol, sB[0], sB[1], vt + A_V1, lane);
;     A_STAGE(sB, R1, 7);
;     fb_update(o, ol, sA[0], sA[1], vt, lane);
;     A_STAGE(sA, R2, 8);
;     fb_update(o, ol, sB[0], sB[1], vt + A_V1, lane);
;     A_STAGE(sB, R0, 9);
	v_mfma_f32_16x16x32_bf16 v[20:23], v[24:27], v[4:7], v[20:23]
	v_add_u32_e32 v24, 64, v29
	v_cvt_f32_i32_e32 v24, v24
	v_add_u32_e32 v25, 0x140, v29
	v_cmp_gt_u32_e32 vcc, s22, v25
	s_and_b64 vcc, s[90:91], vcc
	s_nop 2
	v_fma_f32 v20, |v24|, v153, v20
	v_cndmask_b32_e32 v201, v234, v20, vcc
	v_add_u32_e32 v20, 0x44, v29
	v_cvt_f32_i32_e32 v20, v20
	v_add_u32_e32 v24, 0x144, v29
	v_cmp_gt_u32_e32 vcc, s22, v24
	v_add_u32_e32 v24, 0x44, v28
	v_cmp_gt_u32_e64 s[0:1], s24, v24
	s_and_b64 vcc, vcc, s[0:1]
	v_fma_f32 v20, |v20|, v153, v21
	v_cndmask_b32_e32 v202, v234, v20, vcc
	v_add_u32_e32 v20, 0x48, v29
	v_cvt_f32_i32_e32 v20, v20
	v_add_u32_e32 v21, 0x148, v29
	v_cmp_gt_u32_e32 vcc, s22, v21
	v_add_u32_e32 v21, 0x48, v28
	v_cmp_gt_u32_e64 s[0:1], s24, v21
	s_and_b64 vcc, vcc, s[0:1]
	v_fma_f32 v20, |v20|, v153, v22
	v_cndmask_b32_e32 v203, v234, v20, vcc
	v_add_u32_e32 v20, 0x4c, v29
	v_cvt_f32_i32_e32 v20, v20
	v_add_u32_e32 v21, 0x14c, v29
	v_cmp_gt_u32_e32 vcc, s22, v21
	v_add_u32_e32 v21, 0x4c, v28
	v_cmp_gt_u32_e64 s[0:1], s24, v21
	s_and_b64 vcc, vcc, s[0:1]
	v_fma_f32 v20, |v20|, v153, v23
	v_cndmask_b32_e32 v204, v234, v20, vcc
	v_add_u32_e32 v20, s33, v178
	v_med3_i32 v20, v20, 0, v233
	v_lshlrev_b32_e32 v188, 7, v20
	v_lshl_add_u64 v[20:21], v[156:157], 0, v[188:189]
	global_load_dwordx4 v[44:47], v[20:21], off
	v_lshl_add_u64 v[20:21], v[158:159], 0, v[188:189]
	global_load_dwordx4 v[48:51], v[20:21], off
	v_add_u32_e32 v20, s33, v179
	v_med3_i32 v20, v20, 0, v233
	v_lshlrev_b32_e32 v188, 7, v20
	v_lshl_add_u64 v[20:21], v[156:157], 0, v[188:189]
	v_lshl_add_u64 v[24:25], v[158:159], 0, v[188:189]
	v_mfma_f32_16x16x32_bf16 v[132:135], v[16:19], v[136:139], v[132:135]
	global_load_dwordx4 v[20:23], v[20:21], off
	s_nop 0
	global_load_dwordx4 v[36:39], v[24:25], off
	v_mfma_f32_16x16x32_bf16 v[116:119], v[120:123], v[136:139], v[116:119]
	v_add_u32_e32 v24, s33, v180
	v_exp_f32_e32 v120, v144
	v_exp_f32_e32 v121, v155
	v_exp_f32_e32 v122, v145
	v_exp_f32_e32 v123, v186
	v_exp_f32_e32 v136, v146
	v_exp_f32_e32 v137, v187
	v_exp_f32_e32 v138, v147
	v_exp_f32_e32 v139, v191
	v_med3_i32 v24, v24, 0, v233
	v_lshlrev_b32_e32 v188, 7, v24
	v_lshl_add_u64 v[24:25], v[156:157], 0, v[188:189]
	v_lshl_add_u64 v[28:29], v[158:159], 0, v[188:189]
	v_lshlrev_b32_e32 v188, 7, v32
	v_lshl_add_u64 v[32:33], v[156:157], 0, v[188:189]
	v_lshl_add_u64 v[40:41], v[158:159], 0, v[188:189]
	v_cvt_pk_bf16_f32 v144, v120, v122
	v_cvt_pk_bf16_f32 v145, v136, v138
	v_cvt_pk_bf16_f32 v146, v121, v123
	v_cvt_pk_bf16_f32 v147, v137, v139
	global_load_dwordx4 v[24:27], v[24:25], off
	s_nop 0
	global_load_dwordx4 v[28:31], v[28:29], off
	v_mfma_f32_16x16x32_bf16 v[136:139], v[16:19], v[144:147], v[132:135]
	global_load_dwordx4 v[32:35], v[32:33], off
	s_nop 0
	global_load_dwordx4 v[40:43], v[40:41], off
	ds_read_b64_tr_b16 v[122:123], v184 offset:2304
	ds_read_b64_tr_b16 v[120:121], v184
	ds_read_b64_tr_b16 v[132:133], v184 offset:32
	ds_read_b64_tr_b16 v[134:135], v184 offset:2336
	s_waitcnt lgkmcnt(2)
	v_mfma_f32_16x16x32_bf16 v[120:123], v[120:123], v[144:147], v[124:127]
	s_waitcnt lgkmcnt(0)
	v_mfma_f32_16x16x32_bf16 v[124:127], v[132:135], v[144:147], v[128:131]
	s_nop 2
	ds_read_b64_tr_b16 v[128:129], v184 offset:64
	ds_read_b64_tr_b16 v[130:131], v184 offset:2368
	ds_read_b64_tr_b16 v[132:133], v184 offset:96
	ds_read_b64_tr_b16 v[134:135], v184 offset:2400
	s_waitcnt vmcnt(22)
	ds_write_b128 v183, v[56:59]
	ds_write_b128 v183, v[52:55] offset:9216
	s_waitcnt vmcnt(20)
	ds_write_b128 v183, v[64:67] offset:1152
	ds_write_b128 v183, v[60:63] offset:10368
	s_waitcnt vmcnt(18)
	ds_write_b128 v183, v[72:75] offset:2304
	ds_write_b128 v183, v[68:71] offset:11520
	s_waitcnt vmcnt(16)
	ds_write_b128 v183, v[80:83] offset:3456
	ds_write_b128 v183, v[76:79] offset:12672
	ds_read_b128 v[52:55], v151 offset:9216
	ds_read_b128 v[56:59], v151 offset:9280
	s_waitcnt lgkmcnt(1)
	v_mfma_f32_16x16x32_bf16 v[52:55], v[52:55], v[8:11], v[12:15]
	v_or_b32_e32 v60, s4, v168
	v_sub_u32_e32 v61, v60, v154
	v_cmp_gt_u32_e64 s[0:1], s67, v60
	s_waitcnt lgkmcnt(0)
	v_mfma_f32_16x16x32_bf16 v[52:55], v[56:59], v[4:7], v[52:55]
	v_add_u32_e32 v56, 0x100, v61
	v_cmp_gt_u32_e32 vcc, s22, v56
	v_cvt_f32_i32_e32 v56, v61
	s_and_b64 vcc, s[20:21], vcc
	v_mfma_f32_16x16x32_bf16 v[128:131], v[128:131], v[144:147], v[140:143]
	v_add_u32_e32 v68, s5, v180
	s_nop 1
	v_fma_f32 v52, |v56|, v153, v52
	v_add_u32_e32 v56, 0x104, v61
	v_mfma_f32_16x16x32_bf16 v[132:135], v[132:135], v[144:147], v[116:119]
	v_cndmask_b32_e32 v144, v234, v52, vcc
	v_add_u32_e32 v52, 4, v61
	v_cvt_f32_i32_e32 v52, v52
	v_cmp_gt_u32_e32 vcc, s22, v56
	s_and_b64 vcc, vcc, s[0:1]
	v_cmp_gt_u32_e64 s[0:1], s23, v60
	v_fma_f32 v52, |v52|, v153, v53
	v_cndmask_b32_e32 v145, v234, v52, vcc
	v_add_u32_e32 v52, 8, v61
	v_cvt_f32_i32_e32 v52, v52
	v_add_u32_e32 v53, 0x108, v61
	v_cmp_gt_u32_e32 vcc, s22, v53
	s_and_b64 vcc, vcc, s[0:1]
	v_fma_f32 v52, |v52|, v153, v54
	v_cndmask_b32_e32 v146, v234, v52, vcc
	v_add_u32_e32 v52, 12, v61
	v_cvt_f32_i32_e32 v52, v52
	v_add_u32_e32 v53, 0x10c, v61
	v_cmp_gt_u32_e32 vcc, s22, v53
	v_cmp_gt_u32_e64 s[0:1], s17, v60
	s_and_b64 vcc, vcc, s[0:1]
	v_fma_f32 v52, |v52|, v153, v55
	v_cndmask_b32_e32 v147, v234, v52, vcc
	ds_read_b128 v[52:55], v151 offset:11520
	ds_read_b128 v[56:59], v151 offset:11584
	s_waitcnt lgkmcnt(1)
	v_mfma_f32_16x16x32_bf16 v[52:55], v[52:55], v[8:11], v[12:15]
	v_cmp_gt_u32_e64 s[0:1], s58, v60
	v_med3_i32 v68, v68, 0, v233
	v_add_u32_e32 v76, s5, v181
	s_waitcnt lgkmcnt(0)
; #define LAS __attribute__((address_space(3)))
; #define MFMA16(a, b, c) __builtin_amdgcn_mfma_f32_16x16x32_bf16((a), (b), (c), 0, 0, 0)
; DI float ex2(float x) { return __builtin_amdgcn_exp2f(x); }
; DI s16x4 vtr(const LAS char* p) { return __builtin_bit_cast(s16x4, __builtin_amdgcn_ds_read_tr16_b64_v4i16((LAS s16x4*)p)); }
; DI bf16x8 cat8(s16x4 lo, s16x4 hi) { return __builtin_shufflevector(lo, hi, 0, 1, 2, 3, 4, 5, 6, 7); }
; DI bf16x8 pack8(f32x4 a, f32x4 b) { u32x4 w; w.x = pk2(a[0], a[1]); w.y = pk2(a[2], a[3]); w.z = pk2(b[0], b[1]); w.w = pk2(b[2], b[3]); return __builtin_bit_cast(bf16x8, w); }
; #define A_LOAD(R, t_) do { int tb_, sd_, md_; a_desc((t_), a0, rho, tb_, sd_, md_); tile_load(R, kb, vb, tb_, sd_, lane); } while (0)
; #define A_STAGE(S, R, t_) do { int tb_, sd_, md_; a_desc((t_), a0, rho, tb_, sd_, md_); a_stage(S, R, vt, (t_) & 1, qf, cinit, tb_, sd_, md_, tq, nslope2, lane); } while (0)
; DI void fb_update(f32x4 (&o)[4], f32x4& ol, const f32x4 st0, const f32x4 st1, const LAS char* vt, int lane) {
;     f32x4 p0, p1;
; #pragma unroll
;     for (int i = 0; i < 4; ++i) { p0[i] = ex2(st0[i]); p1[i] = ex2(st1[i]); }
;     const bf16x8 pf = pack8(p0, p1);
;     const bf16x8 ones = {0x3F80, 0x3F80, 0x3F80, 0x3F80, 0x3F80, 0x3F80, 0x3F80, 0x3F80};
;     ol = MFMA16(ones, pf, ol);
;     const int g = lane >> 4, q = (lane & 15) >> 2, p = lane & 3;
;     const LAS char* v0 = vt + (4 * g + q) * VT_PITCH + 8 * p;
;     const LAS char* v1 = v0 + 16 * VT_PITCH;
; #pragma unroll
;     for (int c = 0; c < 4; ++c) { const bf16x8 vf = cat8(vtr(v0 + 32 * c), vtr(v1 + 32 * c)); o[c] = MFMA16(vf, pf, o[c]); }
; }
; DI void mixerA2_unit(int u, const bf16* PROJ, bf16* YC, const float* LPA, const float* kmax_l, LAS char* vt, int wave, int lane) {
;     ...
;     A_STAGE(sB, R2, 5); A_LOAD(R2, 8);
;     fb_update(o, ol, sA[0], sA[1], vt, lane);
;     A_STAGE(sA, R0, 6); A_LOAD(R0, 9);
;     fb_update(o, ol, sB[0], sB[1], vt + A_V1, lane);
;     A_STAGE(sB, R1, 7);
;     fb_update(o, ol, sA[0], sA[1], vt, lane);
;     A_STAGE(sA, R2, 8);
;     fb_update(o, ol, sB[0], sB[1], vt + A_V1, lane);
;     A_STAGE(sB, R0, 9);
;     fb_update(o, ol, sA[0], sA[1], vt, lane);
	v_mfma_f32_16x16x32_bf16 v[52:55], v[56:59], v[4:7], v[52:55]
	v_add_u32_e32 v56, 64, v61
	v_cvt_f32_i32_e32 v56, v56
	v_add_u32_e32 v57, 0x140, v61
	v_cmp_gt_u32_e32 vcc, s22, v57
	s_and_b64 vcc, s[20:21], vcc
	s_nop 2
	v_fma_f32 v52, |v56|, v153, v52
	v_cndmask_b32_e32 v155, v234, v52, vcc
	v_add_u32_e32 v52, 0x44, v61
	v_cvt_f32_i32_e32 v52, v52
	v_add_u32_e32 v56, 0x144, v61
	v_cmp_gt_u32_e32 vcc, s22, v56
	s_and_b64 vcc, vcc, s[0:1]
	v_fma_f32 v52, |v52|, v153, v53
	v_cndmask_b32_e32 v186, v234, v52, vcc
	v_add_u32_e32 v52, 0x48, v61
	v_cvt_f32_i32_e32 v52, v52
	v_add_u32_e32 v53, 0x148, v61
	v_cmp_gt_u32_e32 vcc, s22, v53
	v_cmp_gt_u32_e64 s[0:1], s59, v60
	s_and_b64 vcc, vcc, s[0:1]
	v_fma_f32 v52, |v52|, v153, v54
	v_cndmask_b32_e32 v187, v234, v52, vcc
	v_add_u32_e32 v52, 0x4c, v61
	v_cvt_f32_i32_e32 v52, v52
	v_add_u32_e32 v53, 0x14c, v61
	v_cmp_gt_u32_e32 vcc, s22, v53
	v_cmp_gt_u32_e64 s[0:1], s52, v60
	s_and_b64 vcc, vcc, s[0:1]
	v_fma_f32 v52, |v52|, v153, v55
	v_cndmask_b32_e32 v191, v234, v52, vcc
	v_add_u32_e32 v52, s5, v178
	v_med3_i32 v52, v52, 0, v233
	v_add_u32_e32 v60, s5, v179
	v_lshlrev_b32_e32 v188, 7, v52
	v_med3_i32 v60, v60, 0, v233
	v_lshl_add_u64 v[52:53], v[156:157], 0, v[188:189]
	v_lshl_add_u64 v[56:57], v[158:159], 0, v[188:189]
	v_lshlrev_b32_e32 v188, 7, v60
	v_lshl_add_u64 v[60:61], v[156:157], 0, v[188:189]
	v_lshl_add_u64 v[64:65], v[158:159], 0, v[188:189]
	v_lshlrev_b32_e32 v188, 7, v68
	v_med3_i32 v76, v76, 0, v233
	v_lshl_add_u64 v[68:69], v[156:157], 0, v[188:189]
	v_lshl_add_u64 v[72:73], v[158:159], 0, v[188:189]
	v_lshlrev_b32_e32 v188, 7, v76
	v_lshl_add_u64 v[76:77], v[156:157], 0, v[188:189]
	v_exp_f32_e32 v116, v193
	v_exp_f32_e32 v117, v201
	v_exp_f32_e32 v118, v198
	v_exp_f32_e32 v119, v202
	v_exp_f32_e32 v141, v199
	v_exp_f32_e32 v143, v203
	v_exp_f32_e32 v142, v200
	v_exp_f32_e32 v156, v204
	v_lshl_add_u64 v[80:81], v[158:159], 0, v[188:189]
	v_cvt_pk_bf16_f32 v140, v116, v118
	v_cvt_pk_bf16_f32 v141, v141, v142
	v_cvt_pk_bf16_f32 v142, v117, v119
	v_cvt_pk_bf16_f32 v143, v143, v156
	global_load_dwordx4 v[52:55], v[52:53], off
	s_nop 0
	global_load_dwordx4 v[56:59], v[56:57], off
	v_mfma_f32_16x16x32_bf16 v[116:119], v[16:19], v[140:143], v[136:139]
	global_load_dwordx4 v[60:63], v[60:61], off
	s_nop 0
	global_load_dwordx4 v[64:67], v[64:65], off
	s_nop 0
	global_load_dwordx4 v[68:71], v[68:69], off
	s_nop 0
	global_load_dwordx4 v[72:75], v[72:73], off
	s_nop 0
	global_load_dwordx4 v[76:79], v[76:77], off
	s_nop 0
	global_load_dwordx4 v[80:83], v[80:81], off
	ds_read_b64_tr_b16 v[138:139], v184 offset:6912
	ds_read_b64_tr_b16 v[136:137], v184 offset:4608
	ds_read_b64_tr_b16 v[156:157], v184 offset:4640
	ds_read_b64_tr_b16 v[158:159], v184 offset:6944
	s_waitcnt lgkmcnt(2)
	v_mfma_f32_16x16x32_bf16 v[136:139], v[136:139], v[140:143], v[120:123]
	s_waitcnt lgkmcnt(0)
	v_mfma_f32_16x16x32_bf16 v[120:123], v[156:159], v[140:143], v[124:127]
	s_nop 2
	ds_read_b64_tr_b16 v[124:125], v184 offset:4672
	ds_read_b64_tr_b16 v[126:127], v184 offset:6976
	s_waitcnt lgkmcnt(0)
	v_mfma_f32_16x16x32_bf16 v[124:127], v[124:127], v[140:143], v[128:131]
	s_nop 2
	ds_read_b64_tr_b16 v[128:129], v184 offset:4704
	ds_read_b64_tr_b16 v[130:131], v184 offset:7008
	s_waitcnt vmcnt(22)
	ds_write_b128 v183, v[112:115] offset:4608
	ds_write_b128 v183, v[108:111] offset:9216
	s_waitcnt vmcnt(20)
	ds_write_b128 v183, v[104:107] offset:5760
	ds_write_b128 v183, v[100:103] offset:10368
	s_waitcnt vmcnt(18)
	ds_write_b128 v183, v[96:99] offset:6912
	ds_write_b128 v183, v[92:95] offset:11520
	s_waitcnt vmcnt(16)
	ds_write_b128 v183, v[88:91] offset:8064
	ds_write_b128 v183, v[84:87] offset:12672
	ds_read_b128 v[84:87], v151 offset:9216
	ds_read_b128 v[88:91], v151 offset:9280
	s_waitcnt lgkmcnt(1)
	v_mfma_f32_16x16x32_bf16 v[84:87], v[84:87], v[8:11], v[12:15]
	v_or_b32_e32 v99, s16, v168
	v_sub_u32_e32 v100, v99, v154
	v_cmp_gt_u32_e64 s[0:1], s67, v99
	s_waitcnt lgkmcnt(0)
	v_mfma_f32_16x16x32_bf16 v[84:87], v[88:91], v[4:7], v[84:87]
	v_add_u32_e32 v88, 0x100, v100
	v_cmp_gt_u32_e32 vcc, s22, v88
	v_cvt_f32_i32_e32 v88, v100
	s_and_b64 vcc, s[20:21], vcc
	v_mfma_f32_16x16x32_bf16 v[128:131], v[128:131], v[140:143], v[132:135]
	s_nop 2
	v_fma_f32 v84, |v88|, v153, v84
	v_cndmask_b32_e32 v92, v234, v84, vcc
	v_add_u32_e32 v84, 4, v100
	v_cvt_f32_i32_e32 v84, v84
	v_add_u32_e32 v88, 0x104, v100
	v_cmp_gt_u32_e32 vcc, s22, v88
	s_and_b64 vcc, vcc, s[0:1]
	v_fma_f32 v84, |v84|, v153, v85
	v_cndmask_b32_e32 v93, v234, v84, vcc
	v_add_u32_e32 v84, 8, v100
	v_cvt_f32_i32_e32 v84, v84
	v_add_u32_e32 v85, 0x108, v100
	v_cmp_gt_u32_e32 vcc, s22, v85
	v_cmp_gt_u32_e64 s[0:1], s23, v99
	s_and_b64 vcc, vcc, s[0:1]
	v_fma_f32 v84, |v84|, v153, v86
	v_cndmask_b32_e32 v94, v234, v84, vcc
	v_add_u32_e32 v84, 12, v100
	v_cvt_f32_i32_e32 v84, v84
	v_add_u32_e32 v85, 0x10c, v100
	v_cmp_gt_u32_e32 vcc, s22, v85
	v_cmp_gt_u32_e64 s[0:1], s17, v99
	s_and_b64 vcc, vcc, s[0:1]
	v_fma_f32 v84, |v84|, v153, v87
	v_cndmask_b32_e32 v95, v234, v84, vcc
	ds_read_b128 v[84:87], v151 offset:11520
	ds_read_b128 v[88:91], v151 offset:11584
	s_waitcnt lgkmcnt(1)
	v_mfma_f32_16x16x32_bf16 v[84:87], v[84:87], v[8:11], v[12:15]
	s_waitcnt lgkmcnt(0)
; #define LAS __attribute__((address_space(3)))
; #define MFMA16(a, b, c) __builtin_amdgcn_mfma_f32_16x16x32_bf16((a), (b), (c), 0, 0, 0)
; DI float ex2(float x) { return __builtin_amdgcn_exp2f(x); }
; DI s16x4 vtr(const LAS char* p) { return __builtin_bit_cast(s16x4, __builtin_amdgcn_ds_read_tr16_b64_v4i16((LAS s16x4*)p)); }
; DI bf16x8 cat8(s16x4 lo, s16x4 hi) { return __builtin_shufflevector(lo, hi, 0, 1, 2, 3, 4, 5, 6, 7); }
; DI bf16x8 pack8(f32x4 a, f32x4 b) { u32x4 w; w.x = pk2(a[0], a[1]); w.y = pk2(a[2], a[3]); w.z = pk2(b[0], b[1]); w.w = pk2(b[2], b[3]); return __builtin_bit_cast(bf16x8, w); }
; #define A_LOAD(R, t_) do { int tb_, sd_, md_; a_desc((t_), a0, rho, tb_, sd_, md_); tile_load(R, kb, vb, tb_, sd_, lane); } while (0)
; #define A_STAGE(S, R, t_) do { int tb_, sd_, md_; a_desc((t_), a0, rho, tb_, sd_, md_); a_stage(S, R, vt, (t_) & 1, qf, cinit, tb_, sd_, md_, tq, nslope2, lane); } while (0)
; DI void fb_update(f32x4 (&o)[4], f32x4& ol, const f32x4 st0, const f32x4 st1, const LAS char* vt, int lane) {
;     f32x4 p0, p1;
; #pragma unroll
;     for (int i = 0; i < 4; ++i) { p0[i] = ex2(st0[i]); p1[i] = ex2(st1[i]); }
;     const bf16x8 pf = pack8(p0, p1);
;     const bf16x8 ones = {0x3F80, 0x3F80, 0x3F80, 0x3F80, 0x3F80, 0x3F80, 0x3F80, 0x3F80};
;     ol = MFMA16(ones, pf, ol);
;     const int g = lane >> 4, q = (lane & 15) >> 2, p = lane & 3;
;     const LAS char* v0 = vt + (4 * g + q) * VT_PITCH + 8 * p;
;     const LAS char* v1 = v0 + 16 * VT_PITCH;
; #pragma unroll
;     for (int c = 0; c < 4; ++c) { const bf16x8 vf = cat8(vtr(v0 + 32 * c), vtr(v1 + 32 * c)); o[c] = MFMA16(vf, pf, o[c]); }
; }
; DI void mixerA2_unit(int u, const bf16* PROJ, bf16* YC, const float* LPA, const float* kmax_l, LAS char* vt, int wave, int lane) {
;     ...
;     A_STAGE(sA, R0, 6); A_LOAD(R0, 9);
;     fb_update(o, ol, sB[0], sB[1], vt + A_V1, lane);
;     A_STAGE(sB, R1, 7);
;     fb_update(o, ol, sA[0], sA[1], vt, lane);
;     A_STAGE(sA, R2, 8);
;     fb_update(o, ol, sB[0], sB[1], vt + A_V1, lane);
;     A_STAGE(sB, R0, 9);
;     fb_update(o, ol, sA[0], sA[1], vt, lane);
;     fb_update(o, ol, sB[0], sB[1], vt + A_V1, lane);
	v_mfma_f32_16x16x32_bf16 v[84:87], v[88:91], v[4:7], v[84:87]
	v_add_u32_e32 v88, 64, v100
	v_cvt_f32_i32_e32 v88, v88
	v_add_u32_e32 v89, 0x140, v100
	v_cmp_gt_u32_e32 vcc, s22, v89
	s_and_b64 vcc, s[20:21], vcc
	s_nop 2
	v_fma_f32 v84, |v88|, v153, v84
	v_cndmask_b32_e32 v96, v234, v84, vcc
	v_add_u32_e32 v84, 0x44, v100
	v_cvt_f32_i32_e32 v84, v84
	v_add_u32_e32 v88, 0x144, v100
	v_cmp_gt_u32_e32 vcc, s22, v88
	v_add_u32_e32 v88, 0x44, v99
	v_cmp_gt_u32_e64 s[0:1], s24, v88
	s_and_b64 vcc, vcc, s[0:1]
	v_fma_f32 v84, |v84|, v153, v85
	v_cndmask_b32_e32 v97, v234, v84, vcc
	v_add_u32_e32 v84, 0x48, v100
	v_cvt_f32_i32_e32 v84, v84
	v_add_u32_e32 v85, 0x148, v100
	v_cmp_gt_u32_e32 vcc, s22, v85
	v_add_u32_e32 v85, 0x48, v99
	v_cmp_gt_u32_e64 s[0:1], s24, v85
	s_and_b64 vcc, vcc, s[0:1]
	v_fma_f32 v84, |v84|, v153, v86
	v_cndmask_b32_e32 v98, v234, v84, vcc
	v_add_u32_e32 v84, 0x4c, v100
	v_add_u32_e32 v85, 0x14c, v100
	v_exp_f32_e32 v91, v187
	v_exp_f32_e32 v100, v191
	v_cvt_f32_i32_e32 v84, v84
	v_cmp_gt_u32_e32 vcc, s22, v85
	v_add_u32_e32 v85, 0x4c, v99
	v_cvt_pk_bf16_f32 v91, v91, v100
	ds_read_b64_tr_b16 v[102:103], v184 offset:2304
	ds_read_b64_tr_b16 v[100:101], v184
	ds_read_b64_tr_b16 v[104:105], v184 offset:32
	ds_read_b64_tr_b16 v[106:107], v184 offset:2336
	ds_read_b64_tr_b16 v[108:109], v184 offset:64
	ds_read_b64_tr_b16 v[110:111], v184 offset:2368
	ds_read_b64_tr_b16 v[112:113], v184 offset:96
	ds_read_b64_tr_b16 v[114:115], v184 offset:2400
	s_waitcnt vmcnt(14)
	ds_write_b128 v183, v[48:51]
	ds_write_b128 v183, v[44:47] offset:9216
	s_waitcnt vmcnt(12)
	ds_write_b128 v183, v[36:39] offset:1152
	ds_write_b128 v183, v[20:23] offset:10368
	s_waitcnt vmcnt(10)
	ds_write_b128 v183, v[28:31] offset:2304
	ds_write_b128 v183, v[24:27] offset:11520
	s_waitcnt vmcnt(8)
	ds_write_b128 v183, v[40:43] offset:3456
	ds_write_b128 v183, v[32:35] offset:12672
	ds_read_b128 v[20:23], v151 offset:9216
	ds_read_b128 v[24:27], v151 offset:9280
	s_waitcnt lgkmcnt(1)
	v_mfma_f32_16x16x32_bf16 v[20:23], v[20:23], v[8:11], v[12:15]
	v_or_b32_e32 v28, s33, v168
	v_cmp_gt_u32_e64 s[0:1], s24, v85
	v_sub_u32_e32 v29, v28, v154
	s_and_b64 vcc, vcc, s[0:1]
	v_fma_f32 v84, |v84|, v153, v87
	s_waitcnt lgkmcnt(0)
	v_mfma_f32_16x16x32_bf16 v[20:23], v[24:27], v[4:7], v[20:23]
	v_add_u32_e32 v24, 0x100, v29
	v_cndmask_b32_e32 v99, v234, v84, vcc
	v_cmp_gt_u32_e32 vcc, s22, v24
	v_cvt_f32_i32_e32 v24, v29
	s_and_b64 vcc, s[96:97], vcc
	v_cmp_gt_u32_e64 s[0:1], s67, v28
	v_exp_f32_e32 v84, v144
	s_nop 0
	v_fma_f32 v20, |v24|, v153, v20
	v_cndmask_b32_e32 v48, v234, v20, vcc
	v_add_u32_e32 v20, 4, v29
	v_cvt_f32_i32_e32 v20, v20
	v_add_u32_e32 v24, 0x104, v29
	v_cmp_gt_u32_e32 vcc, s22, v24
	s_and_b64 vcc, vcc, s[0:1]
	v_fma_f32 v20, |v20|, v153, v21
	v_cndmask_b32_e32 v49, v234, v20, vcc
	v_add_u32_e32 v20, 8, v29
	v_cvt_f32_i32_e32 v20, v20
	v_add_u32_e32 v21, 0x108, v29
	v_cmp_gt_u32_e32 vcc, s22, v21
	v_cmp_gt_u32_e64 s[0:1], s23, v28
	s_and_b64 vcc, vcc, s[0:1]
	v_fma_f32 v20, |v20|, v153, v22
	v_cndmask_b32_e32 v50, v234, v20, vcc
	v_add_u32_e32 v20, 12, v29
	v_cvt_f32_i32_e32 v20, v20
	v_add_u32_e32 v21, 0x10c, v29
	v_cmp_gt_u32_e32 vcc, s22, v21
	v_cmp_gt_u32_e64 s[0:1], s17, v28
	s_and_b64 vcc, vcc, s[0:1]
	v_fma_f32 v20, |v20|, v153, v23
	v_cndmask_b32_e32 v51, v234, v20, vcc
	ds_read_b128 v[20:23], v151 offset:11520
	ds_read_b128 v[24:27], v151 offset:11584
	s_waitcnt lgkmcnt(1)
	v_mfma_f32_16x16x32_bf16 v[20:23], v[20:23], v[8:11], v[12:15]
	v_exp_f32_e32 v85, v155
	v_exp_f32_e32 v86, v145
	v_exp_f32_e32 v87, v186
	s_waitcnt lgkmcnt(0)
	v_mfma_f32_16x16x32_bf16 v[20:23], v[24:27], v[4:7], v[20:23]
	v_add_u32_e32 v24, 64, v29
	v_exp_f32_e32 v89, v146
	v_exp_f32_e32 v90, v147
	v_cvt_f32_i32_e32 v24, v24
	v_add_u32_e32 v25, 0x140, v29
	v_cmp_gt_u32_e32 vcc, s22, v25
	v_cvt_pk_bf16_f32 v88, v84, v86
	v_cvt_pk_bf16_f32 v89, v89, v90
	v_cvt_pk_bf16_f32 v90, v85, v87
	s_and_b64 vcc, s[96:97], vcc
	v_fma_f32 v20, |v24|, v153, v20
	v_mfma_f32_16x16x32_bf16 v[84:87], v[16:19], v[88:91], v[116:119]
	v_add_u32_e32 v24, 0x144, v29
	v_cmp_gt_u32_e64 s[0:1], s58, v28
	v_exp_f32_e32 v25, v98
	v_mfma_f32_16x16x32_bf16 v[100:103], v[100:103], v[88:91], v[136:139]
	v_exp_f32_e32 v26, v95
	v_exp_f32_e32 v27, v99
	v_mfma_f32_16x16x32_bf16 v[104:107], v[104:107], v[88:91], v[120:123]
	v_mfma_f32_16x16x32_bf16 v[108:111], v[108:111], v[88:91], v[124:127]
	v_mfma_f32_16x16x32_bf16 v[88:91], v[112:115], v[88:91], v[128:131]
	v_cndmask_b32_e32 v112, v234, v20, vcc
	v_add_u32_e32 v20, 0x44, v29
	v_cvt_f32_i32_e32 v20, v20
	v_cmp_gt_u32_e32 vcc, s22, v24
	s_and_b64 vcc, vcc, s[0:1]
	v_cmp_gt_u32_e64 s[0:1], s59, v28
	v_fma_f32 v20, |v20|, v153, v21
	v_cndmask_b32_e32 v113, v234, v20, vcc
	v_add_u32_e32 v20, 0x48, v29
	v_cvt_f32_i32_e32 v20, v20
	v_add_u32_e32 v21, 0x148, v29
	v_cmp_gt_u32_e32 vcc, s22, v21
	s_and_b64 vcc, vcc, s[0:1]
	v_fma_f32 v20, |v20|, v153, v22
	v_cndmask_b32_e32 v114, v234, v20, vcc
	v_add_u32_e32 v20, 0x4c, v29
	v_cvt_f32_i32_e32 v20, v20
	v_add_u32_e32 v21, 0x14c, v29
	v_cmp_gt_u32_e64 s[0:1], s52, v28
	ds_read_b64_tr_b16 v[30:31], v184 offset:6912
	ds_read_b64_tr_b16 v[28:29], v184 offset:4608
	ds_read_b64_tr_b16 v[32:33], v184 offset:4640
	ds_read_b64_tr_b16 v[34:35], v184 offset:6944
	v_cmp_gt_u32_e32 vcc, s22, v21
	s_and_b64 vcc, vcc, s[0:1]
	v_fma_f32 v20, |v20|, v153, v23
	v_cndmask_b32_e32 v115, v234, v20, vcc
	v_exp_f32_e32 v20, v92
	v_exp_f32_e32 v22, v96
	v_exp_f32_e32 v21, v93
	v_exp_f32_e32 v23, v97
	v_exp_f32_e32 v24, v94
	ds_read_b64_tr_b16 v[36:37], v184 offset:4672
	ds_read_b64_tr_b16 v[38:39], v184 offset:6976
	ds_read_b64_tr_b16 v[40:41], v184 offset:4704
	ds_read_b64_tr_b16 v[42:43], v184 offset:7008
	v_cvt_pk_bf16_f32 v20, v20, v21
	v_cvt_pk_bf16_f32 v21, v24, v26
	v_cvt_pk_bf16_f32 v22, v22, v23
	v_cvt_pk_bf16_f32 v23, v25, v27
	s_waitcnt vmcnt(6)
; DI void fb_update(f32x4 (&o)[4], f32x4& ol, const f32x4 st0, const f32x4 st1, const LAS char* vt, int lane) {
;     f32x4 p0, p1;
; #pragma unroll
;     for (int i = 0; i < 4; ++i) { p0[i] = ex2(st0[i]); p1[i] = ex2(st1[i]); }
;     const bf16x8 pf = pack8(p0, p1);
;     const bf16x8 ones = {0x3F80, 0x3F80, 0x3F80, 0x3F80, 0x3F80, 0x3F80, 0x3F80, 0x3F80};
;     ol = MFMA16(ones, pf, ol);
;     const int g = lane >> 4, q = (lane & 15) >> 2, p = lane & 3;
;     const LAS char* v0 = vt + (4 * g + q) * VT_PITCH + 8 * p;
;     const LAS char* v1 = v0 + 16 * VT_PITCH;
; #pragma unroll
;     for (int c = 0; c < 4; ++c) { const bf16x8 vf = cat8(vtr(v0 + 32 * c), vtr(v1 + 32 * c)); o[c] = MFMA16(vf, pf, o[c]); }
; }
; DI float q_norm2(const bf16x8 (&qf)[2]) { float a = sumsq8(qf[0]) + sumsq8(qf[1]); a += __shfl_xor(a, 16); a += __shfl_xor(a, 32); return a; }
; DI void a_desc(int ti, int a0, int rho, int& tokbase, int& stride, int& maxd) {
;     if (ti < 4) { stride = 16; tokbase = rho + 512 * ti; maxd = 1024; }
;     else if (ti < 10) { stride = 4; const int m0 = 4 * a0 + (rho >> 2) - 64 + 32 * (ti - 4); tokbase = 4 * m0 + (rho & 3); maxd = 256; }
;     else { stride = 1; tokbase = 16 * a0 + rho - 64 + 32 * (ti - 10); maxd = 64; }
; }
; template <bool EDGE>
; DI void a_scores(f32x4 (&st)[2], const LAS char* kt, const bf16x8 (&qf)[2], const f32x4 cinit, int tokbase, int stride, int maxd, int tq, float nslope2, int lane) {
;     const int g = lane >> 4;
;     const int base0 = tokbase + stride * 4 * g - tq;
; #pragma unroll
;     for (int t = 0; t < 2; ++t) {
;         st[t] = MFMA16(k_frag_at(kt, t, 0, lane), qf[0], cinit); st[t] = MFMA16(k_frag_at(kt, t, 1, lane), qf[1], st[t]);
; #pragma unroll
;         for (int i = 0; i < 4; ++i) { const int d = base0 + stride * (16 * t + i);
;             bool ok = (unsigned)(d + maxd) <= (unsigned)(2 * maxd);
;             if (EDGE) ok = ok && ((unsigned)(d + tq) < (unsigned)T);
;             const float v = __builtin_fmaf(__builtin_fabsf((float)d), nslope2, st[t][i]);
;             st[t][i] = ok ? v : -1e30f; }
;     }
; }
; DI void a_stage(f32x4 (&st)[2], const TileRegs& R, LAS char* vt, int vpar, const bf16x8 (&qf)[2], const f32x4 cinit, int tokbase, int stride, int maxd, int tq, float nslope2, int lane) {
; #pragma unroll
;     for (int it = 0; it < 4; ++it) { const int n = lane + 64 * it, row = n >> 3, ch = n & 7;
	ds_write_b128 v183, v[56:59] offset:4608
	ds_write_b128 v183, v[52:55] offset:9216
	s_waitcnt vmcnt(4)
	ds_write_b128 v183, v[64:67] offset:5760
	ds_write_b128 v183, v[60:63] offset:10368
	s_waitcnt vmcnt(2)
	ds_write_b128 v183, v[72:75] offset:6912
	ds_write_b128 v183, v[68:71] offset:11520
	s_waitcnt vmcnt(0)
	ds_write_b128 v183, v[80:83] offset:8064
	ds_write_b128 v183, v[76:79] offset:12672
	v_mfma_f32_16x16x32_bf16 v[24:27], v[16:19], v[20:23], v[84:87]
	ds_read_b128 v[44:47], v151 offset:9280
	v_or_b32_e32 v52, s5, v168
	v_sub_u32_e32 v53, v52, v154
	s_waitcnt lgkmcnt(14)
	v_mfma_f32_16x16x32_bf16 v[28:31], v[28:31], v[20:23], v[100:103]
	v_cmp_gt_u32_e64 s[0:1], s67, v52
	s_waitcnt lgkmcnt(13)
	v_mfma_f32_16x16x32_bf16 v[32:35], v[32:35], v[20:23], v[104:107]
	s_waitcnt lgkmcnt(11)
	v_mfma_f32_16x16x32_bf16 v[36:39], v[36:39], v[20:23], v[108:111]
	s_waitcnt lgkmcnt(9)
	v_mfma_f32_16x16x32_bf16 v[20:23], v[40:43], v[20:23], v[88:91]
	ds_read_b128 v[40:43], v151 offset:9216
	s_waitcnt lgkmcnt(0)
	v_mfma_f32_16x16x32_bf16 v[40:43], v[40:43], v[8:11], v[12:15]
	v_mfma_f32_16x16x32_bf16 v[40:43], v[44:47], v[4:7], v[40:43]
	v_add_u32_e32 v44, 0x100, v53
	v_cmp_gt_u32_e32 vcc, s22, v44
	v_cvt_f32_i32_e32 v44, v53
	s_and_b64 vcc, s[26:27], vcc
	v_add_u32_e32 v45, 0x104, v53
	s_nop 2
	v_fma_f32 v40, |v44|, v153, v40
	v_cndmask_b32_e32 v44, v234, v40, vcc
	v_add_u32_e32 v40, 4, v53
	v_cvt_f32_i32_e32 v40, v40
	v_cmp_gt_u32_e32 vcc, s22, v45
	s_and_b64 vcc, vcc, s[0:1]
	v_cmp_gt_u32_e64 s[0:1], s23, v52
	v_fma_f32 v40, |v40|, v153, v41
	v_cndmask_b32_e32 v45, v234, v40, vcc
	v_add_u32_e32 v40, 8, v53
	v_cvt_f32_i32_e32 v40, v40
	v_add_u32_e32 v41, 0x108, v53
	v_cmp_gt_u32_e32 vcc, s22, v41
	s_and_b64 vcc, vcc, s[0:1]
	v_fma_f32 v40, |v40|, v153, v42
	v_cndmask_b32_e32 v46, v234, v40, vcc
	v_add_u32_e32 v40, 12, v53
	v_cvt_f32_i32_e32 v40, v40
	v_add_u32_e32 v41, 0x10c, v53
	v_cmp_gt_u32_e32 vcc, s22, v41
	v_cmp_gt_u32_e64 s[0:1], s17, v52
	s_and_b64 vcc, vcc, s[0:1]
	v_fma_f32 v40, |v40|, v153, v43
	v_cndmask_b32_e32 v47, v234, v40, vcc
	ds_read_b128 v[40:43], v151 offset:11520
	s_waitcnt lgkmcnt(0)
	v_mfma_f32_16x16x32_bf16 v[8:11], v[40:43], v[8:11], v[12:15]
	s_nop 2
	ds_read_b128 v[12:15], v151 offset:11584
	s_waitcnt lgkmcnt(0)
	v_mfma_f32_16x16x32_bf16 v[4:7], v[12:15], v[4:7], v[8:11]
	s_nop 2
	v_add_u32_e32 v8, 64, v53
	v_cvt_f32_i32_e32 v8, v8
	v_add_u32_e32 v9, 0x140, v53
	v_cmp_gt_u32_e32 vcc, s22, v9
	s_and_b64 vcc, s[26:27], vcc
	v_fma_f32 v4, |v8|, v153, v4
	v_cndmask_b32_e32 v40, v234, v4, vcc
	v_add_u32_e32 v4, 0x44, v53
	v_cvt_f32_i32_e32 v4, v4
	v_add_u32_e32 v8, 0x144, v53
	v_cmp_gt_u32_e32 vcc, s22, v8
	v_add_u32_e32 v8, 0x44, v52
	v_cmp_gt_u32_e64 s[0:1], s24, v8
	s_and_b64 vcc, vcc, s[0:1]
	v_fma_f32 v4, |v4|, v153, v5
	v_cndmask_b32_e32 v41, v234, v4, vcc
	v_add_u32_e32 v4, 0x48, v53
	v_cvt_f32_i32_e32 v4, v4
	v_add_u32_e32 v5, 0x148, v53
	v_cmp_gt_u32_e32 vcc, s22, v5
	v_add_u32_e32 v5, 0x48, v52
	v_cmp_gt_u32_e64 s[0:1], s24, v5
	s_and_b64 vcc, vcc, s[0:1]
	v_fma_f32 v4, |v4|, v153, v6
	v_cndmask_b32_e32 v42, v234, v4, vcc
	v_add_u32_e32 v4, 0x4c, v53
	v_cvt_f32_i32_e32 v4, v4
	v_add_u32_e32 v5, 0x14c, v53
	v_cmp_gt_u32_e32 vcc, s22, v5
	v_add_u32_e32 v5, 0x4c, v52
	v_cmp_gt_u32_e64 s[0:1], s24, v5
	s_and_b64 vcc, vcc, s[0:1]
	v_fma_f32 v4, |v4|, v153, v7
	v_cndmask_b32_e32 v43, v234, v4, vcc
	v_exp_f32_e32 v4, v48
	v_exp_f32_e32 v6, v112
	v_exp_f32_e32 v5, v49
	v_exp_f32_e32 v7, v113
	v_exp_f32_e32 v8, v50
	v_exp_f32_e32 v9, v114
	v_exp_f32_e32 v10, v51
	v_exp_f32_e32 v11, v115
	v_cvt_pk_bf16_f32 v4, v4, v5
	v_cvt_pk_bf16_f32 v6, v6, v7
	v_cvt_pk_bf16_f32 v5, v8, v10
	v_cvt_pk_bf16_f32 v7, v9, v11
	s_lshl_b64 s[0:1], s[94:95], 22
	s_add_u32 s0, s8, s0
	v_mfma_f32_16x16x32_bf16 v[8:11], v[16:19], v[4:7], v[24:27]
	ds_read_b64_tr_b16 v[14:15], v184 offset:2304
	ds_read_b64_tr_b16 v[12:13], v184
	s_nop 0
	ds_read_b64_tr_b16 v[24:25], v184 offset:32
	ds_read_b64_tr_b16 v[26:27], v184 offset:2336
	s_addc_u32 s1, s9, s1
	s_waitcnt lgkmcnt(2)
	v_mfma_f32_16x16x32_bf16 v[12:15], v[12:15], v[4:7], v[28:31]
	s_nop 2
	ds_read_b64_tr_b16 v[28:29], v184 offset:64
	ds_read_b64_tr_b16 v[30:31], v184 offset:2368
	s_lshl_b32 s2, s2, 7
	s_add_u32 s0, s0, s2
	s_waitcnt lgkmcnt(2)
	v_mfma_f32_16x16x32_bf16 v[24:27], v[24:27], v[4:7], v[32:35]
	s_nop 2
	ds_read_b64_tr_b16 v[32:33], v184 offset:96
	ds_read_b64_tr_b16 v[34:35], v184 offset:2400
	s_addc_u32 s1, s1, 0
	v_mov_b32_e32 v153, v189
	s_waitcnt lgkmcnt(2)
	v_mfma_f32_16x16x32_bf16 v[28:31], v[28:31], v[4:7], v[36:39]
	s_add_i32 s69, s69, s88
	s_cmpk_lt_i32 s69, 0x200
	s_waitcnt lgkmcnt(0)
	v_mfma_f32_16x16x32_bf16 v[4:7], v[32:35], v[4:7], v[20:23]
	v_exp_f32_e32 v32, v46
	v_exp_f32_e32 v33, v42
	v_exp_f32_e32 v34, v47
	v_exp_f32_e32 v20, v44
	v_exp_f32_e32 v22, v40
	v_exp_f32_e32 v21, v45
	v_exp_f32_e32 v23, v41
	v_exp_f32_e32 v35, v43
	v_or_b32_e32 v40, s4, v163
	v_cvt_pk_bf16_f32 v20, v20, v21
	v_cvt_pk_bf16_f32 v21, v32, v34
	v_cvt_pk_bf16_f32 v22, v22, v23
	v_cvt_pk_bf16_f32 v23, v33, v35
	v_ashrrev_i32_e32 v41, 31, v40
	s_nop 0
	v_mfma_f32_16x16x32_bf16 v[32:35], v[16:19], v[20:23], v[8:11]
	s_nop 2
	ds_read_b64_tr_b16 v[8:9], v184 offset:4608
	ds_read_b64_tr_b16 v[10:11], v184 offset:6912
	s_nop 2
	v_add_u32_e32 v34, v169, v148
	s_waitcnt lgkmcnt(0)
	v_mfma_f32_16x16x32_bf16 v[16:19], v[8:11], v[20:23], v[12:15]
	ds_read_b64_tr_b16 v[8:9], v184 offset:4640
	ds_read_b64_tr_b16 v[10:11], v184 offset:6944
	s_waitcnt lgkmcnt(0)
	v_mfma_f32_16x16x32_bf16 v[12:15], v[8:11], v[20:23], v[24:27]
	ds_read_b64_tr_b16 v[8:9], v184 offset:4672
	ds_read_b64_tr_b16 v[10:11], v184 offset:6976
	s_nop 0
	ds_read_b64_tr_b16 v[24:25], v184 offset:4704
	ds_read_b64_tr_b16 v[26:27], v184 offset:7008
	s_waitcnt lgkmcnt(2)
; #define LAS __attribute__((address_space(3)))
; DI void rows16_load(LAS char* t, const bf16* base, int pitch, int tok0, int tstride, int lane) {
; #pragma unroll
;     for (int it = 0; it < 2; ++it) { const int n = lane + 64 * it, row = n >> 3, ch = n & 7;
;         *(LAS u32x4*)(t + row * VT_PITCH + ch * 16) = *(const u32x4*)(base + (size_t)(tok0 + tstride * row) * pitch + ch * 8); }
; }
; DI void mixerA2_unit(int u, const bf16* PROJ, bf16* YC, const float* LPA, const float* kmax_l, LAS char* vt, int wave, int lane) {
;     ...
;     const float inv = 1.f / (ol[0] + LPA[(size_t)(b * T + tq) * 4 + h]);
;     LAS char* sc = vt + SC_OFF; const int tok0 = 16 * a0 + rho;
;     bf16* ybase = YC + (size_t)b * T * 1024 + h * 64;
;     u32x2 pv[4], gv[4];
;     rows16_load(sc, ybase, 1024, tok0, 16, lane);
; #pragma unroll
;     for (int c = 0; c < 4; ++c) pv[c] = *(const LAS u32x2*)(sc + r * VT_PITCH + (16 * c + 4 * g) * 2);
;     rows16_load(sc, slab(PROJ, C_AG + h * 64, b), 64, tok0, 16, lane);
; #pragma unroll
;     for (int c = 0; c < 4; ++c) gv[c] = *(const LAS u32x2*)(sc + r * VT_PITCH + (16 * c + 4 * g) * 2);
; #pragma unroll
;     for (int c = 0; c < 4; ++c) {
;         f32x4 ov = o[c]; ov[0] += bflo(pv[c].x); ov[1] += bfhi(pv[c].x); ov[2] += bflo(pv[c].y); ov[3] += bfhi(pv[c].y); ov = ov * inv;
	v_mfma_f32_16x16x32_bf16 v[8:11], v[8:11], v[20:23], v[28:31]
	s_nop 2
	v_add_u32_e32 v29, v182, v166
	s_waitcnt lgkmcnt(0)
	v_mfma_f32_16x16x32_bf16 v[4:7], v[24:27], v[20:23], v[4:7]
	v_lshl_add_u32 v20, s94, 11, v154
	v_ashrrev_i32_e32 v21, 31, v20
	v_lshl_add_u64 v[20:21], v[20:21], 4, s[56:57]
	v_lshl_add_u64 v[20:21], v[20:21], 0, s[34:35]
	global_load_dword v20, v[20:21], off
	v_lshl_add_u64 v[26:27], s[0:1], 0, v[152:153]
	s_mov_b64 s[0:1], 0x1800000
	s_waitcnt vmcnt(0)
	v_add_f32_e32 v28, v32, v20
	v_or_b32_e32 v32, s4, v162
	v_ashrrev_i32_e32 v33, 31, v32
	v_lshlrev_b64 v[20:21], 11, v[32:33]
	v_lshl_add_u64 v[20:21], v[26:27], 0, v[20:21]
	global_load_dwordx4 v[22:25], v[20:21], off
	v_lshlrev_b64 v[32:33], 7, v[32:33]
	s_waitcnt vmcnt(0)
	ds_write_b128 v29, v[22:25] offset:9216
	v_lshlrev_b64 v[22:23], 11, v[40:41]
	v_lshl_add_u64 v[22:23], v[26:27], 0, v[22:23]
	global_load_dwordx4 v[24:27], v[22:23], off
	s_waitcnt vmcnt(0)
	ds_write_b128 v185, v[24:27] offset:9216
	v_lshl_add_u64 v[24:25], s[30:31], 0, v[152:153]
	v_lshl_add_u64 v[24:25], v[24:25], 0, s[0:1]
	v_lshl_add_u64 v[32:33], v[24:25], 0, v[32:33]
	ds_read_b64 v[42:43], v34 offset:9216
	ds_read_b64 v[44:45], v34 offset:9248
	ds_read_b64 v[30:31], v34 offset:9280
	ds_read_b64 v[26:27], v34 offset:9312
	global_load_dwordx4 v[36:39], v[32:33], off
	v_lshlrev_b64 v[32:33], 7, v[40:41]
	v_lshl_add_u64 v[24:25], v[24:25], 0, v[32:33]
	v_div_scale_f32 v35, s[0:1], v28, v28, 1.0
	v_rcp_f32_e32 v40, v35
	s_waitcnt vmcnt(0)
	ds_write_b128 v29, v[36:39] offset:9216
	global_load_dwordx4 v[36:39], v[24:25], off
	v_fma_f32 v41, -v35, v40, 1.0
	v_fmac_f32_e32 v40, v41, v40
	v_div_scale_f32 v41, vcc, 1.0, v28, 1.0
	v_mul_f32_e32 v46, v41, v40
	v_fma_f32 v47, -v35, v46, v41
	v_fmac_f32_e32 v46, v47, v40
	v_fma_f32 v35, -v35, v46, v41
	v_div_fmas_f32 v35, v35, v40, v46
	s_waitcnt lgkmcnt(4)
	v_lshlrev_b32_e32 v40, 16, v42
	v_and_b32_e32 v41, 0xffff0000, v42
	v_pk_add_f32 v[16:17], v[16:17], v[40:41]
	v_lshlrev_b32_e32 v40, 16, v43
	v_and_b32_e32 v41, 0xffff0000, v43
	v_pk_add_f32 v[18:19], v[18:19], v[40:41]
	v_div_fixup_f32 v28, v35, v28, 1.0
	v_pk_mul_f32 v[16:17], v[28:29], v[16:17] op_sel_hi:[0,1]
	v_pk_mul_f32 v[18:19], v[28:29], v[18:19] op_sel_hi:[0,1]
	s_waitcnt vmcnt(0)
	ds_write_b128 v185, v[36:39] offset:9216
	ds_read_b64 v[36:37], v34 offset:9216
	ds_read_b64 v[38:39], v34 offset:9248
	ds_read_b64 v[32:33], v34 offset:9280
	ds_read_b64 v[24:25], v34 offset:9312
	s_waitcnt lgkmcnt(3)
	v_lshlrev_b32_e32 v40, 16, v36
	v_mul_f32_e32 v35, 0xbfb8aa3b, v40
	v_exp_f32_e32 v35, v35
	v_and_b32_e32 v41, 0xffff0000, v36
	v_lshlrev_b32_e32 v36, 16, v37
	v_and_b32_e32 v37, 0xffff0000, v37
	v_add_f32_e32 v35, 1.0, v35
	v_rcp_f32_e32 v42, v35
	v_mul_f32_e32 v35, 0xbfb8aa3b, v41
	v_exp_f32_e32 v35, v35
	s_nop 0
	v_add_f32_e32 v35, 1.0, v35
	v_rcp_f32_e32 v43, v35
	s_nop 0
	v_pk_mul_f32 v[40:41], v[42:43], v[40:41]
	s_nop 0
	v_pk_mul_f32 v[16:17], v[16:17], v[40:41]
	s_nop 0
	v_cvt_pk_bf16_f32 v16, v16, v17
	v_mul_f32_e32 v17, 0xbfb8aa3b, v36
	v_exp_f32_e32 v17, v17
	s_nop 0
	v_add_f32_e32 v17, 1.0, v17
	v_rcp_f32_e32 v40, v17
	v_mul_f32_e32 v17, 0xbfb8aa3b, v37
	v_exp_f32_e32 v17, v17
	s_nop 0
	v_add_f32_e32 v17, 1.0, v17
	v_rcp_f32_e32 v41, v17
	s_nop 0
	v_pk_mul_f32 v[36:37], v[40:41], v[36:37]
	s_nop 0
	v_pk_mul_f32 v[18:19], v[18:19], v[36:37]
	s_nop 0
	v_cvt_pk_bf16_f32 v17, v18, v19
	v_lshlrev_b32_e32 v18, 16, v44
	v_and_b32_e32 v19, 0xffff0000, v44
	v_pk_add_f32 v[12:13], v[12:13], v[18:19]
	v_lshlrev_b32_e32 v18, 16, v45
	v_and_b32_e32 v19, 0xffff0000, v45
	v_pk_add_f32 v[14:15], v[14:15], v[18:19]
	s_waitcnt lgkmcnt(2)
; #define LAS __attribute__((address_space(3)))
; DI unsigned pk2(float lo, float hi) { f32x2_t v = {lo, hi}; bf16x2_t b = __builtin_convertvector(v, bf16x2_t); return __builtin_bit_cast(unsigned, b); }
; DI float silu_f(float x) { return x * __builtin_amdgcn_rcpf(1.f + __expf(-x)); }
; DI void rows16_store(const LAS char* t, bf16* base, int pitch, int tok0, int tstride, int lane) {
; #pragma unroll
;     for (int it = 0; it < 2; ++it) { const int n = lane + 64 * it, row = n >> 3, ch = n & 7;
;         *(u32x4*)(base + (size_t)(tok0 + tstride * row) * pitch + ch * 8) = *(const LAS u32x4*)(t + row * VT_PITCH + ch * 16); }
; }
; DI void mixerA2_unit(int u, const bf16* PROJ, bf16* YC, const float* LPA, const float* kmax_l, LAS char* vt, int wave, int lane) {
;     ...
;     for (int c = 0; c < 4; ++c) {
;         f32x4 ov = o[c]; ov[0] += bflo(pv[c].x); ov[1] += bfhi(pv[c].x); ov[2] += bflo(pv[c].y); ov[3] += bfhi(pv[c].y); ov = ov * inv;
;         u32x2 w; w.x = pk2(ov[0] * silu_f(bflo(gv[c].x)), ov[1] * silu_f(bfhi(gv[c].x))); w.y = pk2(ov[2] * silu_f(bflo(gv[c].y)), ov[3] * silu_f(bfhi(gv[c].y)));
;         *(LAS u32x2*)(sc + r * VT_PITCH + (16 * c + 4 * g) * 2) = w; }
;     rows16_store(sc, ybase, 1024, tok0, 16, lane);
	v_lshlrev_b32_e32 v18, 16, v38
	v_mul_f32_e32 v35, 0xbfb8aa3b, v18
	v_exp_f32_e32 v35, v35
	v_and_b32_e32 v19, 0xffff0000, v38
	v_pk_mul_f32 v[12:13], v[28:29], v[12:13] op_sel_hi:[0,1]
	v_pk_mul_f32 v[14:15], v[28:29], v[14:15] op_sel_hi:[0,1]
	v_add_f32_e32 v35, 1.0, v35
	v_rcp_f32_e32 v36, v35
	v_mul_f32_e32 v35, 0xbfb8aa3b, v19
	v_exp_f32_e32 v35, v35
	s_nop 0
	v_add_f32_e32 v35, 1.0, v35
	v_rcp_f32_e32 v37, v35
	s_nop 0
	v_pk_mul_f32 v[18:19], v[36:37], v[18:19]
	s_nop 0
	v_pk_mul_f32 v[12:13], v[12:13], v[18:19]
	v_lshlrev_b32_e32 v18, 16, v39
	v_cvt_pk_bf16_f32 v12, v12, v13
	v_mul_f32_e32 v13, 0xbfb8aa3b, v18
	v_exp_f32_e32 v13, v13
	v_and_b32_e32 v19, 0xffff0000, v39
	v_add_f32_e32 v13, 1.0, v13
	v_rcp_f32_e32 v36, v13
	v_mul_f32_e32 v13, 0xbfb8aa3b, v19
	v_exp_f32_e32 v13, v13
	s_nop 0
	v_add_f32_e32 v13, 1.0, v13
	v_rcp_f32_e32 v37, v13
	s_nop 0
	v_pk_mul_f32 v[18:19], v[36:37], v[18:19]
	s_nop 0
	v_pk_mul_f32 v[14:15], v[14:15], v[18:19]
	s_nop 0
	v_cvt_pk_bf16_f32 v13, v14, v15
	v_add_u32_e32 v14, 0x2000, v34
	ds_write2_b64 v14, v[16:17], v[12:13] offset0:128 offset1:132
	v_lshlrev_b32_e32 v12, 16, v30
	v_and_b32_e32 v13, 0xffff0000, v30
	v_pk_add_f32 v[8:9], v[8:9], v[12:13]
	v_lshlrev_b32_e32 v12, 16, v31
	v_and_b32_e32 v13, 0xffff0000, v31
	v_pk_add_f32 v[10:11], v[10:11], v[12:13]
	s_waitcnt lgkmcnt(2)
	v_lshlrev_b32_e32 v12, 16, v32
	v_mul_f32_e32 v15, 0xbfb8aa3b, v12
	v_exp_f32_e32 v15, v15
	v_and_b32_e32 v13, 0xffff0000, v32
	v_pk_mul_f32 v[8:9], v[28:29], v[8:9] op_sel_hi:[0,1]
	v_pk_mul_f32 v[10:11], v[28:29], v[10:11] op_sel_hi:[0,1]
	v_add_f32_e32 v15, 1.0, v15
	v_rcp_f32_e32 v16, v15
	v_mul_f32_e32 v15, 0xbfb8aa3b, v13
	v_exp_f32_e32 v15, v15
	s_nop 0
	v_add_f32_e32 v15, 1.0, v15
	v_rcp_f32_e32 v17, v15
	s_nop 0
	v_pk_mul_f32 v[12:13], v[16:17], v[12:13]
	s_nop 0
	v_pk_mul_f32 v[8:9], v[8:9], v[12:13]
	v_lshlrev_b32_e32 v12, 16, v33
	v_cvt_pk_bf16_f32 v8, v8, v9
	v_mul_f32_e32 v9, 0xbfb8aa3b, v12
	v_exp_f32_e32 v9, v9
	v_and_b32_e32 v13, 0xffff0000, v33
	v_add_f32_e32 v9, 1.0, v9
	v_rcp_f32_e32 v16, v9
	v_mul_f32_e32 v9, 0xbfb8aa3b, v13
	v_exp_f32_e32 v9, v9
	s_nop 0
	v_add_f32_e32 v9, 1.0, v9
	v_rcp_f32_e32 v17, v9
	s_nop 0
	v_pk_mul_f32 v[12:13], v[16:17], v[12:13]
	s_nop 0
	v_pk_mul_f32 v[10:11], v[10:11], v[12:13]
	s_nop 0
	v_cvt_pk_bf16_f32 v9, v10, v11
	v_lshlrev_b32_e32 v10, 16, v26
	v_and_b32_e32 v11, 0xffff0000, v26
	v_pk_add_f32 v[10:11], v[4:5], v[10:11]
	v_lshlrev_b32_e32 v4, 16, v27
	v_and_b32_e32 v5, 0xffff0000, v27
	v_pk_add_f32 v[4:5], v[6:7], v[4:5]
	v_pk_mul_f32 v[6:7], v[28:29], v[10:11] op_sel_hi:[0,1]
	s_waitcnt lgkmcnt(1)
	v_lshlrev_b32_e32 v10, 16, v24
	v_and_b32_e32 v11, 0xffff0000, v24
	v_mul_f32_e32 v12, 0xbfb8aa3b, v10
	v_mul_f32_e32 v13, 0xbfb8aa3b, v11
	v_exp_f32_e32 v12, v12
	v_exp_f32_e32 v13, v13
	v_pk_mul_f32 v[4:5], v[28:29], v[4:5] op_sel_hi:[0,1]
	v_add_f32_e32 v12, 1.0, v12
	v_add_f32_e32 v13, 1.0, v13
	v_rcp_f32_e32 v12, v12
	v_rcp_f32_e32 v13, v13
	s_nop 0
	v_pk_mul_f32 v[10:11], v[12:13], v[10:11]
	s_nop 0
	v_pk_mul_f32 v[6:7], v[6:7], v[10:11]
	v_lshlrev_b32_e32 v10, 16, v25
	v_cvt_pk_bf16_f32 v6, v6, v7
	v_mul_f32_e32 v7, 0xbfb8aa3b, v10
	v_exp_f32_e32 v7, v7
	v_and_b32_e32 v11, 0xffff0000, v25
	v_add_f32_e32 v7, 1.0, v7
	v_rcp_f32_e32 v12, v7
	v_mul_f32_e32 v7, 0xbfb8aa3b, v11
	v_exp_f32_e32 v7, v7
	s_nop 0
	v_add_f32_e32 v7, 1.0, v7
	v_rcp_f32_e32 v13, v7
	s_nop 0
	v_pk_mul_f32 v[10:11], v[12:13], v[10:11]
	s_nop 0
	v_pk_mul_f32 v[4:5], v[4:5], v[10:11]
	s_nop 0
	v_cvt_pk_bf16_f32 v7, v4, v5
	ds_write2_b64 v14, v[8:9], v[6:7] offset0:136 offset1:140
	ds_read_b128 v[4:7], v29 offset:9216
	s_waitcnt lgkmcnt(0)
	global_store_dwordx4 v[20:21], v[4:7], off sc1
	ds_read_b128 v[4:7], v185 offset:9216
	s_waitcnt lgkmcnt(0)
	global_store_dwordx4 v[22:23], v[4:7], off sc1
	s_cbranch_scc1 .LBB0_421
	v_readlane_b32 s94, v255, 33
	v_readlane_b32 s90, v255, 23
	v_readlane_b32 s58, v253, 24
	v_readlane_b32 s26, v255, 35
	v_readlane_b32 s95, v255, 34
	s_mov_b64 s[96:97], s[56:57]
	v_readlane_b32 s56, v255, 21
	v_readlane_b32 s91, v255, 24
	v_readlane_b32 s59, v253, 25
	v_readlane_b32 s27, v255, 36
	v_readlane_b32 s57, v255, 22

; #define LAS __attribute__((address_space(3)))
; DI float silu_f(float x) { return x * __builtin_amdgcn_rcpf(1.f + __expf(-x)); }
; DI void ssd_part2_unit(int u, const bf16* PROJ, const float* DT, const float* cw, const float* cb, const float* a_log_l, const float* dskip_l, const float* snw_l,
;                        const float* STATES, bf16* YC, LAS unsigned char* ldsu, int tid, int wave, int lane) {
;     ...
;     const int token = t0 + lq; float ss = 0.f;
; #pragma unroll
;     for (int hh = 0; hh < 2; ++hh) { const float dsk = dskip_l[2 * grp + hh];
; #pragma unroll
;         for (int pt = 0; pt < 4; ++pt) { const int ch = hh * 64 + 16 * pt + 4 * g;
;             const u32x2 xv = *(const LAS u32x2*)(XS + lq * IMG_PITCH + ch * 2);
;             const u32x2 zv = *(const u32x2*)(slab(PROJ, C_CZ + grp * 128 + hh * 64, b) + (size_t)token * 64 + 16 * pt + 4 * g);
;             f32x4 y = acc[hh][pt];
;             y[0] = (y[0] + dsk * bflo(xv.x)) * silu_f(bflo(zv.x)); y[1] = (y[1] + dsk * bfhi(xv.x)) * silu_f(bfhi(zv.x));
;             y[2] = (y[2] + dsk * bflo(xv.y)) * silu_f(bflo(zv.y)); y[3] = (y[3] + dsk * bfhi(xv.y)) * silu_f(bfhi(zv.y));
;             acc[hh][pt] = y; ss += (y[0] * y[0] + y[1] * y[1]) + (y[2] * y[2] + y[3] * y[3]); } }
;     ss += __shfl_xor(ss, 16); ss += __shfl_xor(ss, 32);
;     const float rstd = rsqrtf(ss * (1.f / 128.f) + EPS);
.LBB0_472:
	s_lshl_b32 s0, s57, 22
	s_lshl_b32 s1, s89, 2
	s_add_u32 s0, s10, s0
	v_add_u32_e32 v52, s75, v202
	v_mov_b32_e32 v18, s1
	s_addc_u32 s1, s11, 0
	v_ashrrev_i32_e32 v53, 31, v52
	s_add_u32 s0, s0, s62
	v_lshlrev_b64 v[16:17], 7, v[52:53]
	s_addc_u32 s1, s1, s63
	v_lshlrev_b32_e32 v188, 1, v204
	v_lshl_add_u64 v[16:17], s[0:1], 0, v[16:17]
	v_lshl_add_u64 v[56:57], v[16:17], 0, v[188:189]
	s_mov_b64 s[0:1], 0x4000000
	v_lshl_add_u64 v[16:17], v[56:57], 0, s[0:1]
	s_brev_b32 s0, 32
	global_load_dwordx2 v[54:55], v18, s[54:55]
	v_add_co_u32_e32 v18, vcc, s0, v56
	ds_read2_b64 v[24:27], v231 offset1:4
	s_nop 0
	v_addc_co_u32_e32 v19, vcc, 0, v57, vcc
	global_load_dwordx2 v[18:19], v[18:19], off
	s_mov_b64 s[0:1], 0x4200000
	s_waitcnt lgkmcnt(0)
	v_lshlrev_b32_e32 v28, 16, v24
	v_and_b32_e32 v29, 0xffff0000, v24
	v_lshlrev_b32_e32 v24, 16, v25
	v_and_b32_e32 v25, 0xffff0000, v25
	v_lshlrev_b32_e32 v30, 16, v26
	v_and_b32_e32 v31, 0xffff0000, v26
	s_add_i32 s2, s2, s88
	s_cmpk_gt_i32 s2, 0xff
	s_mov_b32 s89, 0x2aaaaaab
	s_waitcnt vmcnt(1)
	v_pk_fma_f32 v[24:25], v[54:55], v[24:25], v[50:51] op_sel_hi:[0,1,1]
	v_pk_fma_f32 v[28:29], v[54:55], v[28:29], v[48:49] op_sel_hi:[0,1,1]
	v_pk_fma_f32 v[30:31], v[54:55], v[30:31], v[44:45] op_sel_hi:[0,1,1]
	s_waitcnt vmcnt(0)
	v_lshlrev_b32_e32 v20, 16, v18
	v_and_b32_e32 v21, 0xffff0000, v18
	v_mul_f32_e32 v18, 0xbfb8aa3b, v20
	v_exp_f32_e32 v18, v18
	s_nop 0
	v_add_f32_e32 v18, 1.0, v18
	v_rcp_f32_e32 v22, v18
	v_mul_f32_e32 v18, 0xbfb8aa3b, v21
	v_exp_f32_e32 v18, v18
	s_nop 0
	v_add_f32_e32 v18, 1.0, v18
	v_rcp_f32_e32 v23, v18
	v_lshlrev_b32_e32 v18, 16, v19
	v_and_b32_e32 v19, 0xffff0000, v19
	v_pk_mul_f32 v[20:21], v[22:23], v[20:21]
	v_mul_f32_e32 v22, 0xbfb8aa3b, v18
	v_mul_f32_e32 v23, 0xbfb8aa3b, v19
	v_exp_f32_e32 v22, v22
	v_exp_f32_e32 v23, v23
	v_pk_mul_f32 v[20:21], v[28:29], v[20:21]
	v_add_f32_e32 v22, 1.0, v22
	v_add_f32_e32 v23, 1.0, v23
	v_rcp_f32_e32 v22, v22
	v_rcp_f32_e32 v23, v23
	s_nop 0
	v_pk_mul_f32 v[18:19], v[22:23], v[18:19]
	s_nop 0
	v_pk_mul_f32 v[22:23], v[24:25], v[18:19]
	global_load_dwordx2 v[18:19], v[16:17], off offset:32
	s_waitcnt vmcnt(0)
	v_lshlrev_b32_e32 v24, 16, v18
	v_and_b32_e32 v25, 0xffff0000, v18
	v_mul_f32_e32 v18, 0xbfb8aa3b, v24
	v_exp_f32_e32 v18, v18
	s_nop 0
	v_add_f32_e32 v18, 1.0, v18
	v_rcp_f32_e32 v28, v18
	v_mul_f32_e32 v18, 0xbfb8aa3b, v25
	v_exp_f32_e32 v18, v18
	s_nop 0
	v_add_f32_e32 v18, 1.0, v18
	v_rcp_f32_e32 v29, v18
	v_lshlrev_b32_e32 v18, 16, v19
	v_and_b32_e32 v19, 0xffff0000, v19
	v_mul_f32_e32 v26, 0xbfb8aa3b, v18
	v_pk_mul_f32 v[24:25], v[28:29], v[24:25]
	v_lshlrev_b32_e32 v28, 16, v27
	v_and_b32_e32 v29, 0xffff0000, v27
	v_mul_f32_e32 v27, 0xbfb8aa3b, v19
	v_exp_f32_e32 v26, v26
	v_exp_f32_e32 v27, v27
	v_pk_mul_f32 v[24:25], v[30:31], v[24:25]
	v_pk_fma_f32 v[28:29], v[54:55], v[28:29], v[46:47] op_sel_hi:[0,1,1]
	v_add_f32_e32 v26, 1.0, v26
	v_add_f32_e32 v27, 1.0, v27
	v_rcp_f32_e32 v26, v26
	v_rcp_f32_e32 v27, v27
	v_mov_b32_e32 v30, v23
	ds_read2_b64 v[46:49], v231 offset0:8 offset1:12
	v_pk_mul_f32 v[18:19], v[26:27], v[18:19]
	s_nop 0
	v_pk_mul_f32 v[26:27], v[28:29], v[18:19]
	v_mov_b32_e32 v28, v21
	v_mov_b32_e32 v29, v25
	v_mov_b32_e32 v18, v20
	v_mov_b32_e32 v19, v24
	v_pk_mul_f32 v[28:29], v[28:29], v[28:29]
	v_mov_b32_e32 v31, v27
	v_pk_fma_f32 v[18:19], v[18:19], v[18:19], v[28:29]
	v_mov_b32_e32 v28, v22
	v_mov_b32_e32 v29, v26
	v_pk_mul_f32 v[30:31], v[30:31], v[30:31]
	s_waitcnt lgkmcnt(0)
	v_lshlrev_b32_e32 v50, 16, v46
	v_pk_fma_f32 v[28:29], v[28:29], v[28:29], v[30:31]
	v_and_b32_e32 v51, 0xffff0000, v46
	v_pk_add_f32 v[18:19], v[18:19], v[28:29]
	v_pk_fma_f32 v[40:41], v[54:55], v[50:51], v[40:41] op_sel_hi:[0,1,1]
	v_pk_add_f32 v[44:45], v[18:19], v[18:19] op_sel:[0,1] op_sel_hi:[1,0]
	global_load_dwordx2 v[18:19], v[16:17], off offset:64
	v_lshlrev_b32_e32 v46, 16, v48
	global_load_dwordx2 v[16:17], v[16:17], off offset:96
	s_waitcnt vmcnt(1)
	v_lshlrev_b32_e32 v28, 16, v18
	v_and_b32_e32 v29, 0xffff0000, v18
	v_mul_f32_e32 v18, 0xbfb8aa3b, v28
	v_exp_f32_e32 v18, v18
	s_nop 0
	v_add_f32_e32 v18, 1.0, v18
	v_rcp_f32_e32 v30, v18
	v_mul_f32_e32 v18, 0xbfb8aa3b, v29
	v_exp_f32_e32 v18, v18
	s_nop 0
	v_add_f32_e32 v18, 1.0, v18
	v_rcp_f32_e32 v31, v18
	v_lshlrev_b32_e32 v18, 16, v19
	v_and_b32_e32 v19, 0xffff0000, v19
	v_pk_mul_f32 v[28:29], v[30:31], v[28:29]
	v_mul_f32_e32 v30, 0xbfb8aa3b, v18
	v_mul_f32_e32 v31, 0xbfb8aa3b, v19
	v_exp_f32_e32 v30, v30
	v_exp_f32_e32 v31, v31
	v_pk_mul_f32 v[28:29], v[40:41], v[28:29]
	v_lshlrev_b32_e32 v40, 16, v47
	v_add_f32_e32 v30, 1.0, v30
	v_add_f32_e32 v31, 1.0, v31
	v_rcp_f32_e32 v30, v30
	v_rcp_f32_e32 v31, v31
	v_and_b32_e32 v41, 0xffff0000, v47
	v_pk_fma_f32 v[40:41], v[54:55], v[40:41], v[42:43] op_sel_hi:[0,1,1]
	v_and_b32_e32 v47, 0xffff0000, v48
	v_pk_mul_f32 v[18:19], v[30:31], v[18:19]
	v_pk_fma_f32 v[36:37], v[54:55], v[46:47], v[36:37] op_sel_hi:[0,1,1]
	v_pk_mul_f32 v[30:31], v[40:41], v[18:19]
	v_mov_b32_e32 v40, v29
	v_mov_b32_e32 v41, v31
	v_mov_b32_e32 v18, v28
	v_mov_b32_e32 v19, v30
	v_pk_mul_f32 v[40:41], v[40:41], v[40:41]
	s_nop 0
	v_pk_fma_f32 v[18:19], v[18:19], v[18:19], v[40:41]
	s_nop 0
	v_pk_add_f32 v[42:43], v[18:19], v[18:19] op_sel:[0,1] op_sel_hi:[1,0]
	s_waitcnt vmcnt(0)
; #define LAS __attribute__((address_space(3)))
; DI float silu_f(float x) { return x * __builtin_amdgcn_rcpf(1.f + __expf(-x)); }
; DI void ssd_part2_unit(int u, const bf16* PROJ, const float* DT, const float* cw, const float* cb, const float* a_log_l, const float* dskip_l, const float* snw_l,
;                        const float* STATES, bf16* YC, LAS unsigned char* ldsu, int tid, int wave, int lane) {
;     ...
;     const int token = t0 + lq; float ss = 0.f;
; #pragma unroll
;     for (int hh = 0; hh < 2; ++hh) { const float dsk = dskip_l[2 * grp + hh];
; #pragma unroll
;         for (int pt = 0; pt < 4; ++pt) { const int ch = hh * 64 + 16 * pt + 4 * g;
;             const u32x2 xv = *(const LAS u32x2*)(XS + lq * IMG_PITCH + ch * 2);
;             const u32x2 zv = *(const u32x2*)(slab(PROJ, C_CZ + grp * 128 + hh * 64, b) + (size_t)token * 64 + 16 * pt + 4 * g);
;             f32x4 y = acc[hh][pt];
;             y[0] = (y[0] + dsk * bflo(xv.x)) * silu_f(bflo(zv.x)); y[1] = (y[1] + dsk * bfhi(xv.x)) * silu_f(bfhi(zv.x));
;             y[2] = (y[2] + dsk * bflo(xv.y)) * silu_f(bflo(zv.y)); y[3] = (y[3] + dsk * bfhi(xv.y)) * silu_f(bfhi(zv.y));
;             acc[hh][pt] = y; ss += (y[0] * y[0] + y[1] * y[1]) + (y[2] * y[2] + y[3] * y[3]); } }
;     ss += __shfl_xor(ss, 16); ss += __shfl_xor(ss, 32);
;     const float rstd = rsqrtf(ss * (1.f / 128.f) + EPS);
	v_lshlrev_b32_e32 v18, 16, v16
	v_and_b32_e32 v19, 0xffff0000, v16
	v_mul_f32_e32 v16, 0xbfb8aa3b, v18
	v_exp_f32_e32 v16, v16
	s_nop 0
	v_add_f32_e32 v16, 1.0, v16
	v_rcp_f32_e32 v40, v16
	v_mul_f32_e32 v16, 0xbfb8aa3b, v19
	v_exp_f32_e32 v16, v16
	s_nop 0
	v_add_f32_e32 v16, 1.0, v16
	v_rcp_f32_e32 v41, v16
	v_lshlrev_b32_e32 v16, 16, v17
	v_and_b32_e32 v17, 0xffff0000, v17
	v_pk_mul_f32 v[18:19], v[40:41], v[18:19]
	v_lshlrev_b32_e32 v40, 16, v49
	v_and_b32_e32 v41, 0xffff0000, v49
	v_pk_fma_f32 v[38:39], v[54:55], v[40:41], v[38:39] op_sel_hi:[0,1,1]
	v_lshl_add_u64 v[40:41], v[56:57], 0, s[0:1]
	s_mov_b32 s0, 0x4200000
	v_add_co_u32_e32 v50, vcc, s0, v56
	v_pk_mul_f32 v[36:37], v[36:37], v[18:19]
	s_nop 0
	v_addc_co_u32_e32 v51, vcc, 0, v57, vcc
	global_load_dwordx2 v[50:51], v[50:51], off
	v_mul_f32_e32 v18, 0xbfb8aa3b, v16
	v_mul_f32_e32 v19, 0xbfb8aa3b, v17
	v_exp_f32_e32 v18, v18
	v_exp_f32_e32 v19, v19
	v_add_f32_e32 v18, 1.0, v18
	v_add_f32_e32 v19, 1.0, v19
	v_rcp_f32_e32 v18, v18
	v_rcp_f32_e32 v19, v19
	s_waitcnt vmcnt(0)
	v_lshlrev_b32_e32 v56, 16, v50
	v_pk_mul_f32 v[16:17], v[18:19], v[16:17]
	v_and_b32_e32 v57, 0xffff0000, v50
	v_pk_mul_f32 v[38:39], v[38:39], v[16:17]
	v_mul_f32_e32 v16, v37, v37
	v_pk_fma_f32 v[46:47], v[36:37], v[36:37], v[16:17] op_sel_hi:[1,1,0]
	v_mul_f32_e32 v16, v39, v39
	v_pk_fma_f32 v[48:49], v[38:39], v[38:39], v[16:17] op_sel_hi:[1,1,0]
	ds_read2_b64 v[16:19], v231 offset0:16 offset1:20
	v_mul_f32_e32 v43, 0xbfb8aa3b, v56
	v_exp_f32_e32 v43, v43
	v_lshlrev_b32_e32 v50, 16, v51
	v_and_b32_e32 v51, 0xffff0000, v51
	s_waitcnt lgkmcnt(0)
	v_lshlrev_b32_e32 v60, 16, v16
	v_and_b32_e32 v61, 0xffff0000, v16
	v_mul_f32_e32 v16, 0xbfb8aa3b, v57
	v_exp_f32_e32 v16, v16
	v_add_f32_e32 v43, 1.0, v43
	v_rcp_f32_e32 v58, v43
	v_pk_fma_f32 v[32:33], v[54:55], v[60:61], v[32:33] op_sel:[1,0,0]
	v_add_f32_e32 v16, 1.0, v16
	v_rcp_f32_e32 v59, v16
	v_mul_f32_e32 v16, 0xbfb8aa3b, v50
	v_exp_f32_e32 v16, v16
	v_pk_mul_f32 v[56:57], v[58:59], v[56:57]
	s_nop 0
	v_pk_mul_f32 v[32:33], v[32:33], v[56:57]
	v_lshlrev_b32_e32 v56, 16, v17
	v_and_b32_e32 v57, 0xffff0000, v17
	v_mul_f32_e32 v17, 0xbfb8aa3b, v51
	v_exp_f32_e32 v17, v17
	v_add_f32_e32 v16, 1.0, v16
	v_rcp_f32_e32 v16, v16
	v_pk_fma_f32 v[34:35], v[54:55], v[56:57], v[34:35] op_sel:[1,0,0]
	v_add_f32_e32 v17, 1.0, v17
	v_rcp_f32_e32 v17, v17
	s_nop 0
	v_pk_mul_f32 v[16:17], v[16:17], v[50:51]
	s_nop 0
	v_pk_mul_f32 v[16:17], v[34:35], v[16:17]
	v_pk_mul_f32 v[34:35], v[32:33], v[32:33]
	v_pk_mul_f32 v[50:51], v[16:17], v[16:17]
	v_mov_b32_e32 v45, v34
	v_mov_b32_e32 v43, v35
	v_pk_add_f32 v[34:35], v[44:45], v[42:43]
	global_load_dwordx2 v[44:45], v[40:41], off offset:32
	v_mov_b32_e32 v47, v50
	v_mov_b32_e32 v49, v51
	v_pk_add_f32 v[42:43], v[46:47], v[48:49]
	v_lshlrev_b32_e32 v48, 16, v18
	v_pk_add_f32 v[34:35], v[34:35], v[42:43]
	v_and_b32_e32 v49, 0xffff0000, v18
	v_pk_add_f32 v[42:43], v[34:35], v[34:35] op_sel:[0,1] op_sel_hi:[1,0]
	v_pk_fma_f32 v[12:13], v[54:55], v[48:49], v[12:13] op_sel:[1,0,0]
	s_waitcnt vmcnt(0)
	v_lshlrev_b32_e32 v34, 16, v44
	v_and_b32_e32 v35, 0xffff0000, v44
	v_mul_f32_e32 v43, 0xbfb8aa3b, v34
	v_mul_f32_e32 v18, 0xbfb8aa3b, v35
	v_exp_f32_e32 v43, v43
	v_exp_f32_e32 v18, v18
	v_lshlrev_b32_e32 v44, 16, v19
	v_add_f32_e32 v43, 1.0, v43
	v_add_f32_e32 v18, 1.0, v18
	v_rcp_f32_e32 v46, v43
	v_rcp_f32_e32 v47, v18
	s_nop 0
	v_pk_mul_f32 v[34:35], v[46:47], v[34:35]
	global_load_dwordx2 v[46:47], v[40:41], off offset:64
	v_pk_mul_f32 v[34:35], v[12:13], v[34:35]
	global_load_dwordx2 v[40:41], v[40:41], off offset:96
	v_lshlrev_b32_e32 v12, 16, v45
	v_and_b32_e32 v13, 0xffff0000, v45
	v_mul_f32_e32 v18, 0xbfb8aa3b, v12
	v_and_b32_e32 v45, 0xffff0000, v19
	v_mul_f32_e32 v19, 0xbfb8aa3b, v13
	v_exp_f32_e32 v18, v18
	v_exp_f32_e32 v19, v19
	v_pk_fma_f32 v[14:15], v[54:55], v[44:45], v[14:15] op_sel:[1,0,0]
	v_add_f32_e32 v18, 1.0, v18
	v_add_f32_e32 v19, 1.0, v19
	v_rcp_f32_e32 v18, v18
	v_rcp_f32_e32 v19, v19
	s_waitcnt vmcnt(1)
	v_lshlrev_b32_e32 v48, 16, v46
	v_pk_mul_f32 v[12:13], v[18:19], v[12:13]
	v_and_b32_e32 v49, 0xffff0000, v46
	v_pk_mul_f32 v[18:19], v[14:15], v[12:13]
	v_mov_b32_e32 v14, v35
	v_mov_b32_e32 v15, v19
	v_mov_b32_e32 v12, v34
	v_mov_b32_e32 v13, v18
	v_pk_mul_f32 v[14:15], v[14:15], v[14:15]
	v_mul_f32_e32 v43, 0xbfb8aa3b, v48
	v_pk_fma_f32 v[12:13], v[12:13], v[12:13], v[14:15]
	v_exp_f32_e32 v43, v43
	v_pk_add_f32 v[44:45], v[12:13], v[12:13] op_sel:[0,1] op_sel_hi:[1,0]
	ds_read2_b64 v[12:15], v231 offset0:24 offset1:28
	v_lshlrev_b32_e32 v46, 16, v47
	v_add_f32_e32 v43, 1.0, v43
	v_rcp_f32_e32 v50, v43
	v_and_b32_e32 v47, 0xffff0000, v47
	s_waitcnt lgkmcnt(0)
	v_lshlrev_b32_e32 v56, 16, v12
	v_and_b32_e32 v57, 0xffff0000, v12
	v_mul_f32_e32 v12, 0xbfb8aa3b, v49
	v_exp_f32_e32 v12, v12
	v_pk_fma_f32 v[8:9], v[54:55], v[56:57], v[8:9] op_sel:[1,0,0]
	v_lshlrev_b32_e32 v56, 16, v14
	v_and_b32_e32 v57, 0xffff0000, v14
	v_add_f32_e32 v12, 1.0, v12
	v_rcp_f32_e32 v51, v12
	v_mul_f32_e32 v12, 0xbfb8aa3b, v46
	v_exp_f32_e32 v12, v12
	v_pk_fma_f32 v[4:5], v[54:55], v[56:57], v[4:5] op_sel:[1,0,0]
	v_pk_mul_f32 v[48:49], v[50:51], v[48:49]
	v_add_f32_e32 v12, 1.0, v12
	v_pk_mul_f32 v[8:9], v[8:9], v[48:49]
	v_lshlrev_b32_e32 v48, 16, v13
	v_and_b32_e32 v49, 0xffff0000, v13
	v_mul_f32_e32 v13, 0xbfb8aa3b, v47
	v_exp_f32_e32 v13, v13
	v_rcp_f32_e32 v12, v12
	v_pk_fma_f32 v[10:11], v[54:55], v[48:49], v[10:11] op_sel:[1,0,0]
	v_add_f32_e32 v13, 1.0, v13
	v_rcp_f32_e32 v13, v13
	s_nop 0
	v_pk_mul_f32 v[12:13], v[12:13], v[46:47]
	s_nop 0
	v_pk_mul_f32 v[10:11], v[10:11], v[12:13]
	v_mul_f32_e32 v12, v9, v9
	v_pk_fma_f32 v[46:47], v[8:9], v[8:9], v[12:13] op_sel_hi:[1,1,0]
	v_mul_f32_e32 v12, v11, v11
	v_pk_fma_f32 v[48:49], v[10:11], v[10:11], v[12:13] op_sel_hi:[1,1,0]
	s_waitcnt vmcnt(0)
; DI unsigned pk2(float lo, float hi) { f32x2_t v = {lo, hi}; bf16x2_t b = __builtin_convertvector(v, bf16x2_t); return __builtin_bit_cast(unsigned, b); }
; DI void ssd_part2_unit(int u, const bf16* PROJ, const float* DT, const float* cw, const float* cb, const float* a_log_l, const float* dskip_l, const float* snw_l,
;                        const float* STATES, bf16* YC, LAS unsigned char* ldsu, int tid, int wave, int lane) {
;     ...
;     ss += __shfl_xor(ss, 16); ss += __shfl_xor(ss, 32);
;     const float rstd = rsqrtf(ss * (1.f / 128.f) + EPS);
; #pragma unroll
;     for (int hh = 0; hh < 2; ++hh)
; #pragma unroll
;         for (int pt = 0; pt < 4; ++pt) { const int ch = grp * 128 + hh * 64 + 16 * pt + 4 * g;
;             const f32x4 nw = *(const f32x4*)(snw_l + ch); const f32x4 y = acc[hh][pt] * rstd * nw;
;             u32x2 w; w.x = pk2(y[0], y[1]); w.y = pk2(y[2], y[3]);
;             *(u32x2*)(YC + (size_t)(b * T + token) * 1024 + 512 + ch) = w; }
	v_lshlrev_b32_e32 v12, 16, v40
	v_and_b32_e32 v13, 0xffff0000, v40
	v_mul_f32_e32 v40, 0xbfb8aa3b, v12
	v_mul_f32_e32 v14, 0xbfb8aa3b, v13
	v_exp_f32_e32 v40, v40
	v_exp_f32_e32 v14, v14
	v_add_f32_e32 v40, 1.0, v40
	v_add_f32_e32 v14, 1.0, v14
	v_rcp_f32_e32 v50, v40
	v_rcp_f32_e32 v51, v14
	v_lshlrev_b32_e32 v40, 16, v15
	v_pk_mul_f32 v[12:13], v[50:51], v[12:13]
	s_nop 0
	v_pk_mul_f32 v[12:13], v[4:5], v[12:13]
	v_lshlrev_b32_e32 v4, 16, v41
	v_and_b32_e32 v5, 0xffff0000, v41
	v_mul_f32_e32 v14, 0xbfb8aa3b, v4
	v_and_b32_e32 v41, 0xffff0000, v15
	v_mul_f32_e32 v15, 0xbfb8aa3b, v5
	v_exp_f32_e32 v14, v14
	v_exp_f32_e32 v15, v15
	v_pk_fma_f32 v[6:7], v[54:55], v[40:41], v[6:7] op_sel:[1,0,0]
	v_or_b32_e32 v41, s34, v204
	v_add_f32_e32 v14, 1.0, v14
	v_add_f32_e32 v15, 1.0, v15
	v_rcp_f32_e32 v14, v14
	v_rcp_f32_e32 v15, v15
	v_lshlrev_b32_e32 v188, 1, v41
	v_pk_mul_f32 v[4:5], v[14:15], v[4:5]
	s_nop 0
	v_pk_mul_f32 v[14:15], v[6:7], v[4:5]
	v_pk_mul_f32 v[4:5], v[12:13], v[12:13]
	v_pk_mul_f32 v[6:7], v[14:15], v[14:15]
	v_mov_b32_e32 v43, v4
	v_mov_b32_e32 v45, v5
	v_mov_b32_e32 v47, v6
	v_mov_b32_e32 v49, v7
	v_pk_add_f32 v[4:5], v[42:43], v[44:45]
	v_pk_add_f32 v[6:7], v[46:47], v[48:49]
	v_lshlrev_b32_e32 v44, 2, v41
	v_pk_add_f32 v[4:5], v[4:5], v[6:7]
	s_nop 0
	v_add_f32_e32 v4, v4, v5
	ds_bpermute_b32 v5, v223, v4
	s_waitcnt lgkmcnt(0)
	v_add_f32_e32 v4, v4, v5
	ds_bpermute_b32 v5, v242, v4
	s_waitcnt lgkmcnt(0)
	v_add_f32_e32 v4, v4, v5
	v_fmamk_f32 v4, v4, 0x3c000000, v190
	v_cmp_gt_f32_e32 vcc, s15, v4
	v_mul_f32_e32 v5, 0x4b800000, v4
	s_nop 0
	v_cndmask_b32_e32 v4, v4, v5, vcc
	v_rsq_f32_e32 v4, v4
	s_nop 0
	v_mul_f32_e32 v5, 0x45800000, v4
	v_cndmask_b32_e32 v40, v4, v5, vcc
	v_lshl_add_u32 v4, s94, 11, v52
	v_ashrrev_i32_e32 v5, 31, v4
	v_lshlrev_b64 v[4:5], 11, v[4:5]
	v_lshl_add_u64 v[42:43], s[8:9], 0, v[4:5]
	global_load_dwordx4 v[4:7], v44, s[90:91]
	v_pk_mul_f32 v[20:21], v[20:21], v[40:41] op_sel_hi:[1,0]
	v_pk_mul_f32 v[22:23], v[22:23], v[40:41] op_sel_hi:[1,0]
	v_pk_mul_f32 v[16:17], v[16:17], v[40:41] op_sel_hi:[1,0]
	v_pk_mul_f32 v[18:19], v[18:19], v[40:41] op_sel_hi:[1,0]
	v_pk_mul_f32 v[8:9], v[8:9], v[40:41] op_sel_hi:[1,0]
	v_pk_mul_f32 v[10:11], v[10:11], v[40:41] op_sel_hi:[1,0]
	s_waitcnt vmcnt(0)
	v_pk_mul_f32 v[6:7], v[6:7], v[22:23]
	v_pk_mul_f32 v[4:5], v[4:5], v[20:21]
	v_lshl_add_u64 v[20:21], v[42:43], 0, v[188:189]
	v_cvt_pk_bf16_f32 v4, v4, v5
	v_cvt_pk_bf16_f32 v5, v6, v7
	global_store_dwordx2 v[20:21], v[4:5], off offset:1024 sc1
	global_load_dwordx4 v[4:7], v44, s[90:91] offset:64
	v_pk_mul_f32 v[22:23], v[24:25], v[40:41] op_sel_hi:[1,0]
	v_pk_mul_f32 v[24:25], v[26:27], v[40:41] op_sel_hi:[1,0]
	s_waitcnt vmcnt(0)
	v_pk_mul_f32 v[4:5], v[4:5], v[22:23]
	v_pk_mul_f32 v[6:7], v[6:7], v[24:25]
	v_cvt_pk_bf16_f32 v4, v4, v5
	v_cvt_pk_bf16_f32 v5, v6, v7
	global_store_dwordx2 v[20:21], v[4:5], off offset:1056 sc1
	global_load_dwordx4 v[4:7], v44, s[90:91] offset:128
	v_pk_mul_f32 v[22:23], v[28:29], v[40:41] op_sel_hi:[1,0]
	v_pk_mul_f32 v[24:25], v[30:31], v[40:41] op_sel_hi:[1,0]
	s_waitcnt vmcnt(0)
	v_pk_mul_f32 v[4:5], v[4:5], v[22:23]
	v_pk_mul_f32 v[6:7], v[6:7], v[24:25]
	v_cvt_pk_bf16_f32 v4, v4, v5
	v_cvt_pk_bf16_f32 v5, v6, v7
	global_store_dwordx2 v[20:21], v[4:5], off offset:1088 sc1
	global_load_dwordx4 v[4:7], v44, s[90:91] offset:192
	v_pk_mul_f32 v[22:23], v[36:37], v[40:41] op_sel_hi:[1,0]
	v_pk_mul_f32 v[24:25], v[38:39], v[40:41] op_sel_hi:[1,0]
	s_waitcnt vmcnt(0)
	v_pk_mul_f32 v[4:5], v[4:5], v[22:23]
	v_pk_mul_f32 v[6:7], v[6:7], v[24:25]
	v_cvt_pk_bf16_f32 v4, v4, v5
	v_cvt_pk_bf16_f32 v5, v6, v7
	global_store_dwordx2 v[20:21], v[4:5], off offset:1120 sc1
	global_load_dwordx4 v[4:7], v44, s[90:91] offset:256
	v_pk_mul_f32 v[22:23], v[32:33], v[40:41] op_sel_hi:[1,0]
	s_waitcnt vmcnt(0)
	v_pk_mul_f32 v[6:7], v[6:7], v[16:17]
	v_pk_mul_f32 v[4:5], v[4:5], v[22:23]
	v_pk_mul_f32 v[16:17], v[34:35], v[40:41] op_sel_hi:[1,0]
	v_cvt_pk_bf16_f32 v4, v4, v5
	v_cvt_pk_bf16_f32 v5, v6, v7
	global_store_dwordx2 v[20:21], v[4:5], off offset:1152 sc1
	global_load_dwordx4 v[4:7], v44, s[90:91] offset:320
	s_waitcnt vmcnt(0)
	v_pk_mul_f32 v[6:7], v[6:7], v[18:19]
	v_pk_mul_f32 v[4:5], v[4:5], v[16:17]
	s_nop 0
	v_cvt_pk_bf16_f32 v4, v4, v5
	v_cvt_pk_bf16_f32 v5, v6, v7
	global_store_dwordx2 v[20:21], v[4:5], off offset:1184 sc1
	global_load_dwordx4 v[4:7], v44, s[90:91] offset:384
	s_waitcnt vmcnt(0)
	v_pk_mul_f32 v[6:7], v[6:7], v[10:11]
	v_pk_mul_f32 v[4:5], v[4:5], v[8:9]
	v_pk_mul_f32 v[8:9], v[12:13], v[40:41] op_sel_hi:[1,0]
	v_cvt_pk_bf16_f32 v4, v4, v5
	v_cvt_pk_bf16_f32 v5, v6, v7
	global_store_dwordx2 v[20:21], v[4:5], off offset:1216 sc1
	global_load_dwordx4 v[4:7], v44, s[90:91] offset:448
	v_pk_mul_f32 v[10:11], v[14:15], v[40:41] op_sel_hi:[1,0]
	s_waitcnt vmcnt(0)
	v_pk_mul_f32 v[4:5], v[4:5], v[8:9]
	v_pk_mul_f32 v[6:7], v[6:7], v[10:11]
	v_cvt_pk_bf16_f32 v4, v4, v5
	v_cvt_pk_bf16_f32 v5, v6, v7
	global_store_dwordx2 v[20:21], v[4:5], off offset:1248 sc1
	s_cbranch_scc1 .LBB0_523

;     __device__ __forceinline__ void operator()(const f32x4 (&acc)[2][2][4][2], const Unit& u, int wr, int wc, int fr, int fq) const {
;         const int row0 = u.pm * BM + wr * 64 + fr; const int col0 = u.pn * BM + wc * 32 + 4 * fq;
;         const int b = (u.pm * BM) >> 11;
;         f32x4 gt[2][2];
; #pragma unroll
;         for (int bj = 0; bj < 2; ++bj)
; #pragma unroll
;             for (int n = 0; n < 2; ++n) gt[bj][n] = *(const f32x4*)(modf + (size_t)b * 3072 + 2048 + col0 + bj * HALF + 16 * n);
; #pragma unroll
;         for (int ai = 0; ai < 2; ++ai)
; #pragma unroll
;             for (int m = 0; m < 4; ++m) { const size_t ro = (size_t)(row0 + ai * HALF + m * 16) * 1024 + col0;
; #pragma unroll
;                 for (int bj = 0; bj < 2; ++bj)
; #pragma unroll
;                     for (int n = 0; n < 2; ++n) { const size_t o = ro + bj * HALF + 16 * n; const f32x4 xi = *(const f32x4*)(xin + o);
;                         *(f32x4*)(xout + o) = xi + gt[bj][n] * acc[ai][bj][m][n]; } }
;     }
.LBB0_589:
	s_ashr_i32 s31, s57, 3
	s_mul_hi_i32 s39, s31, 0x3000
	s_mulk_i32 s31, 0x3000
	v_lshl_add_u32 v158, s57, 8, v160
	v_lshl_or_b32 v156, s60, 8, v162
	s_add_u32 s44, s51, s31
	v_ashrrev_i32_e32 v159, 31, v158
	s_addc_u32 s45, s52, s39
	v_ashrrev_i32_e32 v157, 31, v156
	v_lshlrev_b64 v[154:155], 10, v[158:159]
	v_lshl_add_u64 v[128:129], v[156:157], 2, s[44:45]
	s_mov_b64 s[44:45], 0x2000
	s_movk_i32 s31, 0x2000
	v_lshl_add_u64 v[154:155], v[154:155], 0, v[156:157]
	v_lshl_add_u64 v[130:131], v[128:129], 0, s[44:45]
	v_add_co_u32_e32 v128, vcc, s31, v128
	v_lshlrev_b64 v[154:155], 2, v[154:155]
	s_nop 0
	v_addc_co_u32_e32 v129, vcc, 0, v129, vcc
	v_lshl_add_u64 v[168:169], s[18:19], 0, v[154:155]
	global_load_dwordx4 v[144:147], v[128:129], off
	global_load_dwordx4 v[140:143], v[130:131], off offset:64
	global_load_dwordx4 v[132:135], v[130:131], off offset:512
	s_nop 0
	global_load_dwordx4 v[128:131], v[130:131], off offset:576
	s_mov_b64 s[44:45], 0x80000
	global_load_dwordx4 v[164:167], v[168:169], off
	s_andn2_b64 vcc, exec, s[36:37]
	v_readlane_b32 s75, v255, 25
	s_waitcnt vmcnt(0)
	v_pk_fma_f32 v[138:139], v[138:139], v[146:147], v[166:167]
	v_pk_fma_f32 v[136:137], v[136:137], v[144:145], v[164:165]
	v_lshl_add_u64 v[164:165], s[78:79], 0, v[154:155]
	global_store_dwordx4 v[164:165], v[136:139], off sc1
	global_load_dwordx4 v[136:139], v[168:169], off offset:64
	s_waitcnt vmcnt(0)
	v_pk_fma_f32 v[126:127], v[126:127], v[142:143], v[138:139]
	v_pk_fma_f32 v[124:125], v[124:125], v[140:141], v[136:137]
	global_store_dwordx4 v[164:165], v[124:127], off offset:64 sc1
	global_load_dwordx4 v[124:127], v[168:169], off offset:512
	s_waitcnt vmcnt(0)
	v_pk_fma_f32 v[122:123], v[122:123], v[134:135], v[126:127]
	v_pk_fma_f32 v[120:121], v[120:121], v[132:133], v[124:125]
	global_store_dwordx4 v[164:165], v[120:123], off offset:512 sc1
	global_load_dwordx4 v[120:123], v[168:169], off offset:576
	s_waitcnt vmcnt(0)
	v_pk_fma_f32 v[118:119], v[118:119], v[130:131], v[122:123]
	v_pk_fma_f32 v[116:117], v[116:117], v[128:129], v[120:121]
	global_store_dwordx4 v[164:165], v[116:119], off offset:576 sc1
	s_nop 1
	v_or_b32_e32 v116, 16, v158
	v_ashrrev_i32_e32 v117, 31, v116
	v_lshlrev_b64 v[116:117], 10, v[116:117]
	v_lshl_add_u64 v[116:117], v[116:117], 0, v[156:157]
	v_lshlrev_b64 v[120:121], 2, v[116:117]
	v_lshl_add_u64 v[122:123], s[18:19], 0, v[120:121]
	global_load_dwordx4 v[116:119], v[122:123], off
	s_waitcnt vmcnt(0)
	v_pk_fma_f32 v[114:115], v[114:115], v[146:147], v[118:119]
	v_pk_fma_f32 v[112:113], v[112:113], v[144:145], v[116:117]
	v_lshl_add_u64 v[116:117], s[78:79], 0, v[120:121]
	global_store_dwordx4 v[116:117], v[112:115], off sc1
	global_load_dwordx4 v[112:115], v[122:123], off offset:64
	s_waitcnt vmcnt(0)
	v_pk_fma_f32 v[110:111], v[110:111], v[142:143], v[114:115]
	v_pk_fma_f32 v[108:109], v[108:109], v[140:141], v[112:113]
	global_store_dwordx4 v[116:117], v[108:111], off offset:64 sc1
	global_load_dwordx4 v[108:111], v[122:123], off offset:512
	s_waitcnt vmcnt(0)
	v_pk_fma_f32 v[106:107], v[106:107], v[134:135], v[110:111]
	v_pk_fma_f32 v[104:105], v[104:105], v[132:133], v[108:109]
	global_store_dwordx4 v[116:117], v[104:107], off offset:512 sc1
	global_load_dwordx4 v[104:107], v[122:123], off offset:576
	s_waitcnt vmcnt(0)
	v_pk_fma_f32 v[102:103], v[102:103], v[130:131], v[106:107]
	v_pk_fma_f32 v[100:101], v[100:101], v[128:129], v[104:105]
	global_store_dwordx4 v[116:117], v[100:103], off offset:576 sc1
	s_nop 1
	v_or_b32_e32 v100, 32, v158
	v_ashrrev_i32_e32 v101, 31, v100
	v_lshlrev_b64 v[100:101], 10, v[100:101]
	v_lshl_add_u64 v[100:101], v[100:101], 0, v[156:157]
	v_lshlrev_b64 v[104:105], 2, v[100:101]
	v_lshl_add_u64 v[106:107], s[18:19], 0, v[104:105]
	global_load_dwordx4 v[100:103], v[106:107], off
	s_waitcnt vmcnt(0)
	v_pk_fma_f32 v[98:99], v[98:99], v[146:147], v[102:103]
	v_pk_fma_f32 v[96:97], v[96:97], v[144:145], v[100:101]
	v_lshl_add_u64 v[100:101], s[78:79], 0, v[104:105]
	global_store_dwordx4 v[100:101], v[96:99], off sc1
	global_load_dwordx4 v[96:99], v[106:107], off offset:64
	s_waitcnt vmcnt(0)
	v_pk_fma_f32 v[94:95], v[94:95], v[142:143], v[98:99]
	v_pk_fma_f32 v[92:93], v[92:93], v[140:141], v[96:97]
	global_store_dwordx4 v[100:101], v[92:95], off offset:64 sc1
	global_load_dwordx4 v[92:95], v[106:107], off offset:512
	s_waitcnt vmcnt(0)
	v_pk_fma_f32 v[90:91], v[90:91], v[134:135], v[94:95]
	v_pk_fma_f32 v[88:89], v[88:89], v[132:133], v[92:93]
	global_store_dwordx4 v[100:101], v[88:91], off offset:512 sc1
	global_load_dwordx4 v[88:91], v[106:107], off offset:576
	s_waitcnt vmcnt(0)
	v_pk_fma_f32 v[86:87], v[86:87], v[130:131], v[90:91]
	v_pk_fma_f32 v[84:85], v[84:85], v[128:129], v[88:89]
	global_store_dwordx4 v[100:101], v[84:87], off offset:576 sc1
	s_nop 1
	v_or_b32_e32 v84, 48, v158
	v_ashrrev_i32_e32 v85, 31, v84
	v_lshlrev_b64 v[84:85], 10, v[84:85]
	v_lshl_add_u64 v[84:85], v[84:85], 0, v[156:157]
	v_lshlrev_b64 v[88:89], 2, v[84:85]
	v_lshl_add_u64 v[90:91], s[18:19], 0, v[88:89]
	global_load_dwordx4 v[84:87], v[90:91], off
	s_waitcnt vmcnt(0)
	v_pk_fma_f32 v[82:83], v[82:83], v[146:147], v[86:87]
	v_pk_fma_f32 v[80:81], v[80:81], v[144:145], v[84:85]
	v_lshl_add_u64 v[84:85], s[78:79], 0, v[88:89]
	global_store_dwordx4 v[84:85], v[80:83], off sc1
	global_load_dwordx4 v[80:83], v[90:91], off offset:64
	s_waitcnt vmcnt(0)
;     __device__ __forceinline__ void operator()(const f32x4 (&acc)[2][2][4][2], const Unit& u, int wr, int wc, int fr, int fq) const {
;     ...
;             for (int m = 0; m < 4; ++m) { const size_t ro = (size_t)(row0 + ai * HALF + m * 16) * 1024 + col0;
; #pragma unroll
;                 for (int bj = 0; bj < 2; ++bj)
; #pragma unroll
;                     for (int n = 0; n < 2; ++n) { const size_t o = ro + bj * HALF + 16 * n; const f32x4 xi = *(const f32x4*)(xin + o);
;                         *(f32x4*)(xout + o) = xi + gt[bj][n] * acc[ai][bj][m][n]; } }
;     }
	v_pk_fma_f32 v[78:79], v[78:79], v[142:143], v[82:83]
	v_pk_fma_f32 v[76:77], v[76:77], v[140:141], v[80:81]
	global_store_dwordx4 v[84:85], v[76:79], off offset:64 sc1
	global_load_dwordx4 v[76:79], v[90:91], off offset:512
	s_waitcnt vmcnt(0)
	v_pk_fma_f32 v[74:75], v[74:75], v[134:135], v[78:79]
	v_pk_fma_f32 v[72:73], v[72:73], v[132:133], v[76:77]
	global_store_dwordx4 v[84:85], v[72:75], off offset:512 sc1
	global_load_dwordx4 v[72:75], v[90:91], off offset:576
	s_waitcnt vmcnt(0)
	v_pk_fma_f32 v[70:71], v[70:71], v[130:131], v[74:75]
	v_pk_fma_f32 v[68:69], v[68:69], v[128:129], v[72:73]
	v_lshl_add_u64 v[72:73], v[154:155], 0, s[44:45]
	global_store_dwordx4 v[84:85], v[68:71], off offset:576 sc1
	v_lshl_add_u64 v[74:75], s[18:19], 0, v[72:73]
	global_load_dwordx4 v[68:71], v[74:75], off
	s_mov_b64 s[44:45], 0x90000
	s_waitcnt vmcnt(0)
	v_pk_fma_f32 v[66:67], v[66:67], v[146:147], v[70:71]
	v_pk_fma_f32 v[64:65], v[64:65], v[144:145], v[68:69]
	v_lshl_add_u64 v[68:69], s[78:79], 0, v[72:73]
	global_store_dwordx4 v[68:69], v[64:67], off sc1
	global_load_dwordx4 v[64:67], v[74:75], off offset:64
	s_waitcnt vmcnt(0)
	v_pk_fma_f32 v[62:63], v[62:63], v[142:143], v[66:67]
	v_pk_fma_f32 v[60:61], v[60:61], v[140:141], v[64:65]
	global_store_dwordx4 v[68:69], v[60:63], off offset:64 sc1
	global_load_dwordx4 v[60:63], v[74:75], off offset:512
	s_waitcnt vmcnt(0)
	v_pk_fma_f32 v[58:59], v[58:59], v[134:135], v[62:63]
	v_pk_fma_f32 v[56:57], v[56:57], v[132:133], v[60:61]
	global_store_dwordx4 v[68:69], v[56:59], off offset:512 sc1
	global_load_dwordx4 v[56:59], v[74:75], off offset:576
	s_waitcnt vmcnt(0)
	v_pk_fma_f32 v[54:55], v[54:55], v[130:131], v[58:59]
	v_pk_fma_f32 v[52:53], v[52:53], v[128:129], v[56:57]
	v_lshl_add_u64 v[56:57], v[154:155], 0, s[44:45]
	global_store_dwordx4 v[68:69], v[52:55], off offset:576 sc1
	v_lshl_add_u64 v[58:59], s[18:19], 0, v[56:57]
	global_load_dwordx4 v[52:55], v[58:59], off
	s_mov_b64 s[44:45], 0xa0000
	s_waitcnt vmcnt(0)
	v_pk_fma_f32 v[50:51], v[50:51], v[146:147], v[54:55]
	v_pk_fma_f32 v[48:49], v[48:49], v[144:145], v[52:53]
	v_lshl_add_u64 v[52:53], s[78:79], 0, v[56:57]
	global_store_dwordx4 v[52:53], v[48:51], off sc1
	global_load_dwordx4 v[48:51], v[58:59], off offset:64
	s_waitcnt vmcnt(0)
	v_pk_fma_f32 v[46:47], v[46:47], v[142:143], v[50:51]
	v_pk_fma_f32 v[44:45], v[44:45], v[140:141], v[48:49]
	global_store_dwordx4 v[52:53], v[44:47], off offset:64 sc1
	global_load_dwordx4 v[44:47], v[58:59], off offset:512
	s_waitcnt vmcnt(0)
	v_pk_fma_f32 v[42:43], v[42:43], v[134:135], v[46:47]
	v_pk_fma_f32 v[40:41], v[40:41], v[132:133], v[44:45]
	global_store_dwordx4 v[52:53], v[40:43], off offset:512 sc1
	global_load_dwordx4 v[40:43], v[58:59], off offset:576
	s_waitcnt vmcnt(0)
	v_pk_fma_f32 v[38:39], v[38:39], v[130:131], v[42:43]
	v_pk_fma_f32 v[36:37], v[36:37], v[128:129], v[40:41]
	v_lshl_add_u64 v[40:41], v[154:155], 0, s[44:45]
	global_store_dwordx4 v[52:53], v[36:39], off offset:576 sc1
	v_lshl_add_u64 v[42:43], s[18:19], 0, v[40:41]
	global_load_dwordx4 v[36:39], v[42:43], off
	s_mov_b64 s[44:45], 0xb0000
	s_waitcnt vmcnt(0)
	v_pk_fma_f32 v[34:35], v[34:35], v[146:147], v[38:39]
	v_pk_fma_f32 v[32:33], v[32:33], v[144:145], v[36:37]
	v_lshl_add_u64 v[36:37], s[78:79], 0, v[40:41]
	global_store_dwordx4 v[36:37], v[32:35], off sc1
	global_load_dwordx4 v[32:35], v[42:43], off offset:64
	s_waitcnt vmcnt(0)
	v_pk_fma_f32 v[30:31], v[30:31], v[142:143], v[34:35]
	v_pk_fma_f32 v[28:29], v[28:29], v[140:141], v[32:33]
	global_store_dwordx4 v[36:37], v[28:31], off offset:64 sc1
	global_load_dwordx4 v[28:31], v[42:43], off offset:512
	s_waitcnt vmcnt(0)
	v_pk_fma_f32 v[26:27], v[26:27], v[134:135], v[30:31]
	v_pk_fma_f32 v[24:25], v[24:25], v[132:133], v[28:29]
	global_store_dwordx4 v[36:37], v[24:27], off offset:512 sc1
	global_load_dwordx4 v[24:27], v[42:43], off offset:576
	s_waitcnt vmcnt(0)
	v_pk_fma_f32 v[22:23], v[22:23], v[130:131], v[26:27]
	v_pk_fma_f32 v[20:21], v[20:21], v[128:129], v[24:25]
	v_lshl_add_u64 v[24:25], v[154:155], 0, s[44:45]
	global_store_dwordx4 v[36:37], v[20:23], off offset:576 sc1
	v_lshl_add_u64 v[26:27], s[18:19], 0, v[24:25]
	global_load_dwordx4 v[20:23], v[26:27], off
	s_mov_b64 s[44:45], -1
	s_waitcnt vmcnt(0)
	v_pk_fma_f32 v[18:19], v[18:19], v[146:147], v[22:23]
	v_pk_fma_f32 v[16:17], v[16:17], v[144:145], v[20:21]
	v_lshl_add_u64 v[20:21], s[78:79], 0, v[24:25]
	global_store_dwordx4 v[20:21], v[16:19], off sc1
	global_load_dwordx4 v[16:19], v[26:27], off offset:64
	s_waitcnt vmcnt(0)
	v_pk_fma_f32 v[14:15], v[14:15], v[142:143], v[18:19]
	v_pk_fma_f32 v[12:13], v[12:13], v[140:141], v[16:17]
	global_store_dwordx4 v[20:21], v[12:15], off offset:64 sc1
	global_load_dwordx4 v[12:15], v[26:27], off offset:512
	s_waitcnt vmcnt(0)
	v_pk_fma_f32 v[10:11], v[10:11], v[134:135], v[14:15]
	v_pk_fma_f32 v[8:9], v[8:9], v[132:133], v[12:13]
	global_store_dwordx4 v[20:21], v[8:11], off offset:512 sc1
	global_load_dwordx4 v[8:11], v[26:27], off offset:576
	s_waitcnt vmcnt(0)
	v_pk_fma_f32 v[6:7], v[6:7], v[130:131], v[10:11]
	v_pk_fma_f32 v[4:5], v[4:5], v[128:129], v[8:9]
	global_store_dwordx4 v[20:21], v[4:7], off offset:576 sc1
	s_cbranch_vccnz .LBB0_578
	s_andn2_b64 vcc, exec, s[20:21]
	s_cbranch_vccnz .LBB0_577
	s_barrier
	s_branch .LBB0_577

; #define PG8_LAS __attribute__((address_space(3)))
;     __device__ __forceinline__ void fused(f32x4 (&acc)[2][2][4][2], const Unit& u, int wr, int wc, int fr, int fq, PG8_LAS unsigned char* lds, int wid, int lane) const {
;         const int row0 = u.pm * BM + wr * 64 + fr; const int col0 = u.pn * BM + wc * 32 + 4 * fq;
;         const int b = (u.pm * BM) >> 11;
;         PG8_LAS float* P = (PG8_LAS float*)lds; PG8_LAS float* S = P + 1024;
;         {
;         f32x4 gt[2][2];
; #pragma unroll
;         for (int bj = 0; bj < 2; ++bj)
; #pragma unroll
;             for (int n = 0; n < 2; ++n) gt[bj][n] = *(const f32x4*)(modf + (size_t)b * 3072 + 2048 + col0 + bj * HALF + 16 * n);
; #pragma unroll
;         for (int ai = 0; ai < 2; ++ai)
; #pragma unroll
;             for (int m = 0; m < 4; ++m) { const size_t ro = (size_t)(row0 + ai * HALF + m * 16) * 1024 + col0; float s = 0.f;
; #pragma unroll
;                 for (int bj = 0; bj < 2; ++bj)
; #pragma unroll
;                     for (int n = 0; n < 2; ++n) { const f32x4 xi = __builtin_nontemporal_load((const f32x4*)(xin + ro + bj * HALF + 16 * n));
;                         const f32x4 v = xi + gt[bj][n] * acc[ai][bj][m][n]; acc[ai][bj][m][n] = v;
;                         *(f32x4*)(xout + ro + bj * HALF + 16 * n) = v;
;                         s += (v[0] * v[0] + v[1] * v[1]) + (v[2] * v[2] + v[3] * v[3]); }
;                 s += __shfl_xor(s, 16); s += __shfl_xor(s, 32);
;                 if (fq == 0) P[(ai * HALF + wr * 64 + m * 16 + fr) * 4 + wc] = s; }
.LBB0_615:
	s_lshl_b32 s30, s20, 8
	s_lshl_b32 s27, s21, 5
	s_add_i32 s36, s30, s5
	s_lshl_b32 s30, s26, 8
	s_or_b32 s27, s30, s27
	v_lshrrev_b32_e32 v132, 2, v191
	v_and_or_b32 v180, v132, 12, s27
	s_ashr_i32 s27, s20, 3
	s_mul_i32 s34, s27, 0x3000
	v_readlane_b32 s30, v253, 48
	s_mul_hi_i32 s33, s27, 0x3000
	v_readlane_b32 s31, v253, 49
	s_add_u32 s30, s30, s34
	s_addc_u32 s31, s31, s33
	v_ashrrev_i32_e32 v181, 31, v180
	v_lshl_add_u64 v[132:133], v[180:181], 2, s[30:31]
	s_movk_i32 s27, 0x2000
	v_add_co_u32_e32 v134, vcc, s27, v132
	v_or_b32_e32 v182, s36, v210
	s_nop 0
	v_addc_co_u32_e32 v135, vcc, 0, v133, vcc
	v_ashrrev_i32_e32 v183, 31, v182
	s_waitcnt vmcnt(0)
	s_barrier
	global_load_dwordx4 v[140:143], v[134:135], off
	v_lshlrev_b64 v[134:135], 10, v[182:183]
	v_lshl_add_u64 v[134:135], v[134:135], 0, v[180:181]
	v_lshlrev_b64 v[154:155], 2, v[134:135]
	v_lshl_add_u64 v[156:157], s[18:19], 0, v[154:155]
	global_load_dwordx4 v[212:215], v[156:157], off nt
	global_load_dwordx4 v[216:219], v[156:157], off offset:64 nt
	global_load_dwordx4 v[220:223], v[156:157], off offset:512 nt
	global_load_dwordx4 v[242:245], v[156:157], off offset:576 nt
	s_mov_b64 s[30:31], 0x2000
	v_lshl_add_u64 v[132:133], v[132:133], 0, s[30:31]
	v_lshl_add_u64 v[158:159], s[78:79], 0, v[154:155]
	global_load_dwordx4 v[144:147], v[132:133], off offset:64
	global_load_dwordx4 v[136:139], v[132:133], off offset:512
	s_nop 0
	global_load_dwordx4 v[132:135], v[132:133], off offset:576
	s_lshl_b32 s21, s21, 2
	v_and_b32_e32 v149, 63, v191
	s_add_i32 s21, s21, 0
	v_lshl_add_u32 v148, v148, 4, s21
	s_waitcnt vmcnt(0)
	v_pk_fma_f32 v[110:111], v[110:111], v[142:143], v[214:215]
	v_pk_fma_f32 v[108:109], v[108:109], v[140:141], v[212:213]
	global_store_dwordx4 v[158:159], v[108:111], off sc1
	v_mul_f32_e32 v160, v111, v111
	v_fmac_f32_e32 v160, v110, v110
	s_waitcnt vmcnt(3)
	v_pk_fma_f32 v[122:123], v[122:123], v[146:147], v[218:219]
	v_pk_fma_f32 v[120:121], v[120:121], v[144:145], v[216:217]
	global_store_dwordx4 v[158:159], v[120:123], off offset:64 sc1
	v_mul_f32_e32 v161, v123, v123
	v_fmac_f32_e32 v161, v122, v122
	s_waitcnt vmcnt(3)
	v_pk_fma_f32 v[114:115], v[114:115], v[138:139], v[222:223]
	v_pk_fma_f32 v[112:113], v[112:113], v[136:137], v[220:221]
	global_store_dwordx4 v[158:159], v[112:115], off offset:512 sc1
	v_mul_f32_e32 v157, v109, v109
	v_fmac_f32_e32 v157, v108, v108
	v_add_f32_e32 v157, v157, v160
	v_mul_f32_e32 v160, v121, v121
	v_fmac_f32_e32 v160, v120, v120
	v_add_f32_e32 v160, v160, v161
	v_and_b32_e32 v151, 64, v224
	v_add_f32_e32 v157, v157, v160
	v_mul_f32_e32 v160, v113, v113
	v_mul_f32_e32 v161, v115, v115
	v_xor_b32_e32 v150, 16, v224
	v_add_u32_e32 v151, 64, v151
	v_fmac_f32_e32 v160, v112, v112
	v_fmac_f32_e32 v161, v114, v114
	v_cmp_lt_i32_e32 vcc, v150, v151
	v_add_f32_e32 v160, v160, v161
	v_add_f32_e32 v157, v157, v160
	v_cndmask_b32_e32 v150, v224, v150, vcc
	v_lshlrev_b32_e32 v150, 2, v150
	v_xor_b32_e32 v156, 32, v224
	v_cmp_lt_i32_e32 vcc, v156, v151
	s_waitcnt vmcnt(3)
	v_pk_fma_f32 v[130:131], v[130:131], v[134:135], v[244:245]
	v_pk_fma_f32 v[128:129], v[128:129], v[132:133], v[242:243]
	v_mul_f32_e32 v153, v131, v131
	v_mul_f32_e32 v152, v129, v129
	v_fmac_f32_e32 v152, v128, v128
	v_fmac_f32_e32 v153, v130, v130
	v_add_f32_e32 v152, v152, v153
	v_add_f32_e32 v152, v157, v152
	ds_bpermute_b32 v153, v150, v152
	v_cndmask_b32_e32 v151, v224, v156, vcc
	v_lshlrev_b32_e32 v151, 2, v151
	v_cmp_gt_u32_e32 vcc, 16, v149
	global_store_dwordx4 v[158:159], v[128:131], off offset:576 sc1
	s_waitcnt lgkmcnt(0)
	v_add_f32_e32 v152, v152, v153
	ds_bpermute_b32 v153, v151, v152
	s_and_saveexec_b64 s[30:31], vcc
	s_cbranch_execz .LBB0_617
	s_waitcnt lgkmcnt(0)
	v_add_f32_e32 v152, v152, v153
	ds_write_b32 v148, v152
.LBB0_617:
	s_or_b64 exec, exec, s[30:31]
	v_or_b32_e32 v184, 16, v182
	v_ashrrev_i32_e32 v185, 31, v184
	s_waitcnt lgkmcnt(0)
	v_lshlrev_b64 v[152:153], 10, v[184:185]
	v_lshl_add_u64 v[152:153], v[152:153], 0, v[180:181]
	v_lshlrev_b64 v[156:157], 2, v[152:153]
	v_lshl_add_u64 v[158:159], s[18:19], 0, v[156:157]
	global_load_dwordx4 v[212:215], v[158:159], off nt
	global_load_dwordx4 v[216:219], v[158:159], off offset:64 nt
	global_load_dwordx4 v[220:223], v[158:159], off offset:512 nt
	global_load_dwordx4 v[242:245], v[158:159], off offset:576 nt
	v_lshl_add_u64 v[156:157], s[78:79], 0, v[156:157]
	s_waitcnt vmcnt(3)
	v_pk_fma_f32 v[126:127], v[126:127], v[142:143], v[214:215]
	v_pk_fma_f32 v[124:125], v[124:125], v[140:141], v[212:213]
	global_store_dwordx4 v[156:157], v[124:127], off sc1
	s_waitcnt vmcnt(3)
	v_pk_fma_f32 v[118:119], v[118:119], v[146:147], v[218:219]
	v_pk_fma_f32 v[116:117], v[116:117], v[144:145], v[216:217]
	global_store_dwordx4 v[156:157], v[116:119], off offset:64 sc1
	v_mul_f32_e32 v160, v119, v119
	v_fmac_f32_e32 v160, v118, v118
	s_waitcnt vmcnt(3)
	v_pk_fma_f32 v[106:107], v[106:107], v[138:139], v[222:223]
	v_pk_fma_f32 v[104:105], v[104:105], v[136:137], v[220:221]
	global_store_dwordx4 v[156:157], v[104:107], off offset:512 sc1
	v_mul_f32_e32 v158, v125, v125
	v_mul_f32_e32 v159, v127, v127
	v_fmac_f32_e32 v158, v124, v124
	v_fmac_f32_e32 v159, v126, v126
	v_add_f32_e32 v158, v158, v159
	v_mul_f32_e32 v159, v117, v117
	v_fmac_f32_e32 v159, v116, v116
	v_add_f32_e32 v159, v159, v160
	v_add_f32_e32 v158, v158, v159
	v_mul_f32_e32 v159, v105, v105
	v_mul_f32_e32 v160, v107, v107
	v_fmac_f32_e32 v159, v104, v104
	v_fmac_f32_e32 v160, v106, v106
	v_add_f32_e32 v159, v159, v160
	v_add_f32_e32 v158, v158, v159
	s_waitcnt vmcnt(3)
	v_pk_fma_f32 v[102:103], v[102:103], v[134:135], v[244:245]
	v_pk_fma_f32 v[100:101], v[100:101], v[132:133], v[242:243]
	v_mul_f32_e32 v153, v103, v103
	v_mul_f32_e32 v152, v101, v101
	v_fmac_f32_e32 v152, v100, v100
	v_fmac_f32_e32 v153, v102, v102
	v_add_f32_e32 v152, v152, v153
	v_add_f32_e32 v152, v158, v152
	ds_bpermute_b32 v153, v150, v152
	global_store_dwordx4 v[156:157], v[100:103], off offset:576 sc1
	s_waitcnt lgkmcnt(0)
	v_add_f32_e32 v152, v152, v153
	ds_bpermute_b32 v153, v151, v152
	s_and_saveexec_b64 s[30:31], vcc
	s_cbranch_execz .LBB0_619
	s_waitcnt lgkmcnt(0)
	v_add_f32_e32 v152, v152, v153
	ds_write_b32 v148, v152 offset:256
;     __device__ __forceinline__ void fused(f32x4 (&acc)[2][2][4][2], const Unit& u, int wr, int wc, int fr, int fq, PG8_LAS unsigned char* lds, int wid, int lane) const {
;     ...
;         for (int ai = 0; ai < 2; ++ai)
; #pragma unroll
;             for (int m = 0; m < 4; ++m) { const size_t ro = (size_t)(row0 + ai * HALF + m * 16) * 1024 + col0; float s = 0.f;
; #pragma unroll
;                 for (int bj = 0; bj < 2; ++bj)
; #pragma unroll
;                     for (int n = 0; n < 2; ++n) { const f32x4 xi = __builtin_nontemporal_load((const f32x4*)(xin + ro + bj * HALF + 16 * n));
;                         const f32x4 v = xi + gt[bj][n] * acc[ai][bj][m][n]; acc[ai][bj][m][n] = v;
;                         *(f32x4*)(xout + ro + bj * HALF + 16 * n) = v;
;                         s += (v[0] * v[0] + v[1] * v[1]) + (v[2] * v[2] + v[3] * v[3]); }
;                 s += __shfl_xor(s, 16); s += __shfl_xor(s, 32);
;                 if (fq == 0) P[(ai * HALF + wr * 64 + m * 16 + fr) * 4 + wc] = s; }
.LBB0_619:
	s_or_b64 exec, exec, s[30:31]
	v_or_b32_e32 v186, 32, v182
	v_ashrrev_i32_e32 v187, 31, v186
	s_waitcnt lgkmcnt(0)
	v_lshlrev_b64 v[152:153], 10, v[186:187]
	v_lshl_add_u64 v[152:153], v[152:153], 0, v[180:181]
	v_lshlrev_b64 v[156:157], 2, v[152:153]
	v_lshl_add_u64 v[158:159], s[18:19], 0, v[156:157]
	global_load_dwordx4 v[212:215], v[158:159], off nt
	global_load_dwordx4 v[216:219], v[158:159], off offset:64 nt
	global_load_dwordx4 v[220:223], v[158:159], off offset:512 nt
	global_load_dwordx4 v[242:245], v[158:159], off offset:576 nt
	v_lshl_add_u64 v[156:157], s[78:79], 0, v[156:157]
	s_waitcnt vmcnt(3)
	v_pk_fma_f32 v[98:99], v[98:99], v[142:143], v[214:215]
	v_pk_fma_f32 v[96:97], v[96:97], v[140:141], v[212:213]
	global_store_dwordx4 v[156:157], v[96:99], off sc1
	s_waitcnt vmcnt(3)
	v_pk_fma_f32 v[94:95], v[94:95], v[146:147], v[218:219]
	v_pk_fma_f32 v[92:93], v[92:93], v[144:145], v[216:217]
	global_store_dwordx4 v[156:157], v[92:95], off offset:64 sc1
	v_mul_f32_e32 v160, v95, v95
	v_fmac_f32_e32 v160, v94, v94
	s_waitcnt vmcnt(3)
	v_pk_fma_f32 v[90:91], v[90:91], v[138:139], v[222:223]
	v_pk_fma_f32 v[88:89], v[88:89], v[136:137], v[220:221]
	global_store_dwordx4 v[156:157], v[88:91], off offset:512 sc1
	v_mul_f32_e32 v158, v97, v97
	v_mul_f32_e32 v159, v99, v99
	v_fmac_f32_e32 v158, v96, v96
	v_fmac_f32_e32 v159, v98, v98
	v_add_f32_e32 v158, v158, v159
	v_mul_f32_e32 v159, v93, v93
	v_fmac_f32_e32 v159, v92, v92
	v_add_f32_e32 v159, v159, v160
	v_add_f32_e32 v158, v158, v159
	v_mul_f32_e32 v159, v89, v89
	v_mul_f32_e32 v160, v91, v91
	v_fmac_f32_e32 v159, v88, v88
	v_fmac_f32_e32 v160, v90, v90
	v_add_f32_e32 v159, v159, v160
	v_add_f32_e32 v158, v158, v159
	s_waitcnt vmcnt(3)
	v_pk_fma_f32 v[86:87], v[86:87], v[134:135], v[244:245]
	v_pk_fma_f32 v[84:85], v[84:85], v[132:133], v[242:243]
	v_mul_f32_e32 v153, v87, v87
	v_mul_f32_e32 v152, v85, v85
	v_fmac_f32_e32 v152, v84, v84
	v_fmac_f32_e32 v153, v86, v86
	v_add_f32_e32 v152, v152, v153
	v_add_f32_e32 v152, v158, v152
	ds_bpermute_b32 v153, v150, v152
	global_store_dwordx4 v[156:157], v[84:87], off offset:576 sc1
	s_waitcnt lgkmcnt(0)
	v_add_f32_e32 v152, v152, v153
	ds_bpermute_b32 v153, v151, v152
	s_and_saveexec_b64 s[30:31], vcc
	s_cbranch_execz .LBB0_621
	s_waitcnt lgkmcnt(0)
	v_add_f32_e32 v152, v152, v153
	ds_write_b32 v148, v152 offset:512
.LBB0_621:
	s_or_b64 exec, exec, s[30:31]
	v_or_b32_e32 v198, 48, v182
	v_ashrrev_i32_e32 v199, 31, v198
	s_waitcnt lgkmcnt(0)
	v_lshlrev_b64 v[152:153], 10, v[198:199]
	v_lshl_add_u64 v[152:153], v[152:153], 0, v[180:181]
	v_lshlrev_b64 v[156:157], 2, v[152:153]
	v_lshl_add_u64 v[158:159], s[18:19], 0, v[156:157]
	global_load_dwordx4 v[212:215], v[158:159], off nt
	global_load_dwordx4 v[216:219], v[158:159], off offset:64 nt
	global_load_dwordx4 v[220:223], v[158:159], off offset:512 nt
	global_load_dwordx4 v[242:245], v[158:159], off offset:576 nt
	v_lshl_add_u64 v[156:157], s[78:79], 0, v[156:157]
	s_waitcnt vmcnt(3)
	v_pk_fma_f32 v[82:83], v[82:83], v[142:143], v[214:215]
	v_pk_fma_f32 v[80:81], v[80:81], v[140:141], v[212:213]
	global_store_dwordx4 v[156:157], v[80:83], off sc1
	s_waitcnt vmcnt(3)
	v_pk_fma_f32 v[78:79], v[78:79], v[146:147], v[218:219]
	v_pk_fma_f32 v[76:77], v[76:77], v[144:145], v[216:217]
	global_store_dwordx4 v[156:157], v[76:79], off offset:64 sc1
	v_mul_f32_e32 v160, v79, v79
	v_fmac_f32_e32 v160, v78, v78
	s_waitcnt vmcnt(3)
	v_pk_fma_f32 v[74:75], v[74:75], v[138:139], v[222:223]
	v_pk_fma_f32 v[72:73], v[72:73], v[136:137], v[220:221]
	global_store_dwordx4 v[156:157], v[72:75], off offset:512 sc1
	v_mul_f32_e32 v158, v81, v81
	v_mul_f32_e32 v159, v83, v83
	v_fmac_f32_e32 v158, v80, v80
	v_fmac_f32_e32 v159, v82, v82
	v_add_f32_e32 v158, v158, v159
	v_mul_f32_e32 v159, v77, v77
	v_fmac_f32_e32 v159, v76, v76
	v_add_f32_e32 v159, v159, v160
	v_add_f32_e32 v158, v158, v159
	v_mul_f32_e32 v159, v73, v73
	v_mul_f32_e32 v160, v75, v75
	v_fmac_f32_e32 v159, v72, v72
	v_fmac_f32_e32 v160, v74, v74
	v_add_f32_e32 v159, v159, v160
	v_add_f32_e32 v158, v158, v159
	s_waitcnt vmcnt(3)
	v_pk_fma_f32 v[70:71], v[70:71], v[134:135], v[244:245]
	v_pk_fma_f32 v[68:69], v[68:69], v[132:133], v[242:243]
	v_mul_f32_e32 v153, v71, v71
	v_mul_f32_e32 v152, v69, v69
	v_fmac_f32_e32 v152, v68, v68
	v_fmac_f32_e32 v153, v70, v70
	v_add_f32_e32 v152, v152, v153
	v_add_f32_e32 v152, v158, v152
	ds_bpermute_b32 v153, v150, v152
	global_store_dwordx4 v[156:157], v[68:71], off offset:576 sc1
	s_waitcnt lgkmcnt(0)
	v_add_f32_e32 v152, v152, v153
	ds_bpermute_b32 v153, v151, v152
	s_and_saveexec_b64 s[30:31], vcc
	s_cbranch_execz .LBB0_623
	s_waitcnt lgkmcnt(0)
	v_add_f32_e32 v152, v152, v153
	ds_write_b32 v148, v152 offset:768
;     __device__ __forceinline__ void fused(f32x4 (&acc)[2][2][4][2], const Unit& u, int wr, int wc, int fr, int fq, PG8_LAS unsigned char* lds, int wid, int lane) const {
;     ...
;         for (int ai = 0; ai < 2; ++ai)
; #pragma unroll
;             for (int m = 0; m < 4; ++m) { const size_t ro = (size_t)(row0 + ai * HALF + m * 16) * 1024 + col0; float s = 0.f;
; #pragma unroll
;                 for (int bj = 0; bj < 2; ++bj)
; #pragma unroll
;                     for (int n = 0; n < 2; ++n) { const f32x4 xi = __builtin_nontemporal_load((const f32x4*)(xin + ro + bj * HALF + 16 * n));
;                         const f32x4 v = xi + gt[bj][n] * acc[ai][bj][m][n]; acc[ai][bj][m][n] = v;
;                         *(f32x4*)(xout + ro + bj * HALF + 16 * n) = v;
;                         s += (v[0] * v[0] + v[1] * v[1]) + (v[2] * v[2] + v[3] * v[3]); }
;                 s += __shfl_xor(s, 16); s += __shfl_xor(s, 32);
;                 if (fq == 0) P[(ai * HALF + wr * 64 + m * 16 + fr) * 4 + wc] = s; }
.LBB0_623:
	s_or_b64 exec, exec, s[30:31]
	v_add_u32_e32 v200, 0x80, v182
	v_ashrrev_i32_e32 v201, 31, v200
	s_waitcnt lgkmcnt(0)
	v_lshlrev_b64 v[152:153], 10, v[200:201]
	v_lshl_add_u64 v[152:153], v[152:153], 0, v[180:181]
	v_lshlrev_b64 v[156:157], 2, v[152:153]
	v_lshl_add_u64 v[158:159], s[18:19], 0, v[156:157]
	global_load_dwordx4 v[212:215], v[158:159], off nt
	global_load_dwordx4 v[216:219], v[158:159], off offset:64 nt
	global_load_dwordx4 v[220:223], v[158:159], off offset:512 nt
	global_load_dwordx4 v[242:245], v[158:159], off offset:576 nt
	v_lshl_add_u64 v[156:157], s[78:79], 0, v[156:157]
	s_waitcnt vmcnt(3)
	v_pk_fma_f32 v[66:67], v[66:67], v[142:143], v[214:215]
	v_pk_fma_f32 v[64:65], v[64:65], v[140:141], v[212:213]
	global_store_dwordx4 v[156:157], v[64:67], off sc1
	s_waitcnt vmcnt(3)
	v_pk_fma_f32 v[62:63], v[62:63], v[146:147], v[218:219]
	v_pk_fma_f32 v[60:61], v[60:61], v[144:145], v[216:217]
	global_store_dwordx4 v[156:157], v[60:63], off offset:64 sc1
	v_mul_f32_e32 v160, v63, v63
	v_fmac_f32_e32 v160, v62, v62
	s_waitcnt vmcnt(3)
	v_pk_fma_f32 v[58:59], v[58:59], v[138:139], v[222:223]
	v_pk_fma_f32 v[56:57], v[56:57], v[136:137], v[220:221]
	global_store_dwordx4 v[156:157], v[56:59], off offset:512 sc1
	v_mul_f32_e32 v158, v65, v65
	v_mul_f32_e32 v159, v67, v67
	v_fmac_f32_e32 v158, v64, v64
	v_fmac_f32_e32 v159, v66, v66
	v_add_f32_e32 v158, v158, v159
	v_mul_f32_e32 v159, v61, v61
	v_fmac_f32_e32 v159, v60, v60
	v_add_f32_e32 v159, v159, v160
	v_add_f32_e32 v158, v158, v159
	v_mul_f32_e32 v159, v57, v57
	v_mul_f32_e32 v160, v59, v59
	v_fmac_f32_e32 v159, v56, v56
	v_fmac_f32_e32 v160, v58, v58
	v_add_f32_e32 v159, v159, v160
	v_add_f32_e32 v158, v158, v159
	s_waitcnt vmcnt(3)
	v_pk_fma_f32 v[54:55], v[54:55], v[134:135], v[244:245]
	v_pk_fma_f32 v[52:53], v[52:53], v[132:133], v[242:243]
	v_mul_f32_e32 v153, v55, v55
	v_mul_f32_e32 v152, v53, v53
	v_fmac_f32_e32 v152, v52, v52
	v_fmac_f32_e32 v153, v54, v54
	v_add_f32_e32 v152, v152, v153
	v_add_f32_e32 v152, v158, v152
	ds_bpermute_b32 v153, v150, v152
	global_store_dwordx4 v[156:157], v[52:55], off offset:576 sc1
	s_waitcnt lgkmcnt(0)
	v_add_f32_e32 v152, v152, v153
	ds_bpermute_b32 v153, v151, v152
	s_and_saveexec_b64 s[30:31], vcc
	s_cbranch_execz .LBB0_625
	s_waitcnt lgkmcnt(0)
	v_add_f32_e32 v152, v152, v153
	ds_write_b32 v148, v152 offset:2048
.LBB0_625:
	s_or_b64 exec, exec, s[30:31]
	v_add_u32_e32 v202, 0x90, v182
	v_ashrrev_i32_e32 v203, 31, v202
	s_waitcnt lgkmcnt(0)
	v_lshlrev_b64 v[152:153], 10, v[202:203]
	v_lshl_add_u64 v[152:153], v[152:153], 0, v[180:181]
	v_lshlrev_b64 v[156:157], 2, v[152:153]
	v_lshl_add_u64 v[158:159], s[18:19], 0, v[156:157]
	global_load_dwordx4 v[212:215], v[158:159], off nt
	global_load_dwordx4 v[216:219], v[158:159], off offset:64 nt
	global_load_dwordx4 v[220:223], v[158:159], off offset:512 nt
	global_load_dwordx4 v[242:245], v[158:159], off offset:576 nt
	v_lshl_add_u64 v[156:157], s[78:79], 0, v[156:157]
	s_waitcnt vmcnt(3)
	v_pk_fma_f32 v[50:51], v[50:51], v[142:143], v[214:215]
	v_pk_fma_f32 v[48:49], v[48:49], v[140:141], v[212:213]
	global_store_dwordx4 v[156:157], v[48:51], off sc1
	s_waitcnt vmcnt(3)
	v_pk_fma_f32 v[46:47], v[46:47], v[146:147], v[218:219]
	v_pk_fma_f32 v[44:45], v[44:45], v[144:145], v[216:217]
	global_store_dwordx4 v[156:157], v[44:47], off offset:64 sc1
	v_mul_f32_e32 v160, v47, v47
	v_fmac_f32_e32 v160, v46, v46
	s_waitcnt vmcnt(3)
	v_pk_fma_f32 v[42:43], v[42:43], v[138:139], v[222:223]
	v_pk_fma_f32 v[40:41], v[40:41], v[136:137], v[220:221]
	global_store_dwordx4 v[156:157], v[40:43], off offset:512 sc1
	v_mul_f32_e32 v158, v49, v49
	v_mul_f32_e32 v159, v51, v51
	v_fmac_f32_e32 v158, v48, v48
	v_fmac_f32_e32 v159, v50, v50
	v_add_f32_e32 v158, v158, v159
	v_mul_f32_e32 v159, v45, v45
	v_fmac_f32_e32 v159, v44, v44
	v_add_f32_e32 v159, v159, v160
	v_add_f32_e32 v158, v158, v159
	v_mul_f32_e32 v159, v41, v41
	v_mul_f32_e32 v160, v43, v43
	v_fmac_f32_e32 v159, v40, v40
	v_fmac_f32_e32 v160, v42, v42
	v_add_f32_e32 v159, v159, v160
	v_add_f32_e32 v158, v158, v159
	s_waitcnt vmcnt(3)
	v_pk_fma_f32 v[38:39], v[38:39], v[134:135], v[244:245]
	v_pk_fma_f32 v[36:37], v[36:37], v[132:133], v[242:243]
	v_mul_f32_e32 v153, v39, v39
	v_mul_f32_e32 v152, v37, v37
	v_fmac_f32_e32 v152, v36, v36
	v_fmac_f32_e32 v153, v38, v38
	v_add_f32_e32 v152, v152, v153
	v_add_f32_e32 v152, v158, v152
	ds_bpermute_b32 v153, v150, v152
	global_store_dwordx4 v[156:157], v[36:39], off offset:576 sc1
	s_waitcnt lgkmcnt(0)
	v_add_f32_e32 v152, v152, v153
	ds_bpermute_b32 v153, v151, v152
	s_and_saveexec_b64 s[30:31], vcc
	s_cbranch_execz .LBB0_627
	s_waitcnt lgkmcnt(0)
	v_add_f32_e32 v152, v152, v153
	ds_write_b32 v148, v152 offset:2304
;     __device__ __forceinline__ void fused(f32x4 (&acc)[2][2][4][2], const Unit& u, int wr, int wc, int fr, int fq, PG8_LAS unsigned char* lds, int wid, int lane) const {
;     ...
;         for (int ai = 0; ai < 2; ++ai)
; #pragma unroll
;             for (int m = 0; m < 4; ++m) { const size_t ro = (size_t)(row0 + ai * HALF + m * 16) * 1024 + col0; float s = 0.f;
; #pragma unroll
;                 for (int bj = 0; bj < 2; ++bj)
; #pragma unroll
;                     for (int n = 0; n < 2; ++n) { const f32x4 xi = __builtin_nontemporal_load((const f32x4*)(xin + ro + bj * HALF + 16 * n));
;                         const f32x4 v = xi + gt[bj][n] * acc[ai][bj][m][n]; acc[ai][bj][m][n] = v;
;                         *(f32x4*)(xout + ro + bj * HALF + 16 * n) = v;
;                         s += (v[0] * v[0] + v[1] * v[1]) + (v[2] * v[2] + v[3] * v[3]); }
;                 s += __shfl_xor(s, 16); s += __shfl_xor(s, 32);
;                 if (fq == 0) P[(ai * HALF + wr * 64 + m * 16 + fr) * 4 + wc] = s; }
.LBB0_627:
	s_or_b64 exec, exec, s[30:31]
	v_add_u32_e32 v204, 0xa0, v182
	v_ashrrev_i32_e32 v205, 31, v204
	s_waitcnt lgkmcnt(0)
	v_lshlrev_b64 v[152:153], 10, v[204:205]
	v_lshl_add_u64 v[152:153], v[152:153], 0, v[180:181]
	v_lshlrev_b64 v[156:157], 2, v[152:153]
	v_lshl_add_u64 v[158:159], s[18:19], 0, v[156:157]
	global_load_dwordx4 v[212:215], v[158:159], off nt
	global_load_dwordx4 v[216:219], v[158:159], off offset:64 nt
	global_load_dwordx4 v[220:223], v[158:159], off offset:512 nt
	global_load_dwordx4 v[242:245], v[158:159], off offset:576 nt
	v_lshl_add_u64 v[156:157], s[78:79], 0, v[156:157]
	s_waitcnt vmcnt(3)
	v_pk_fma_f32 v[34:35], v[34:35], v[142:143], v[214:215]
	v_pk_fma_f32 v[32:33], v[32:33], v[140:141], v[212:213]
	global_store_dwordx4 v[156:157], v[32:35], off sc1
	s_waitcnt vmcnt(3)
	v_pk_fma_f32 v[30:31], v[30:31], v[146:147], v[218:219]
	v_pk_fma_f32 v[28:29], v[28:29], v[144:145], v[216:217]
	global_store_dwordx4 v[156:157], v[28:31], off offset:64 sc1
	v_mul_f32_e32 v160, v31, v31
	v_fmac_f32_e32 v160, v30, v30
	s_waitcnt vmcnt(3)
	v_pk_fma_f32 v[26:27], v[26:27], v[138:139], v[222:223]
	v_pk_fma_f32 v[24:25], v[24:25], v[136:137], v[220:221]
	global_store_dwordx4 v[156:157], v[24:27], off offset:512 sc1
	v_mul_f32_e32 v158, v33, v33
	v_mul_f32_e32 v159, v35, v35
	v_fmac_f32_e32 v158, v32, v32
	v_fmac_f32_e32 v159, v34, v34
	v_add_f32_e32 v158, v158, v159
	v_mul_f32_e32 v159, v29, v29
	v_fmac_f32_e32 v159, v28, v28
	v_add_f32_e32 v159, v159, v160
	v_add_f32_e32 v158, v158, v159
	v_mul_f32_e32 v159, v25, v25
	v_mul_f32_e32 v160, v27, v27
	v_fmac_f32_e32 v159, v24, v24
	v_fmac_f32_e32 v160, v26, v26
	v_add_f32_e32 v159, v159, v160
	v_add_f32_e32 v158, v158, v159
	s_waitcnt vmcnt(3)
	v_pk_fma_f32 v[22:23], v[22:23], v[134:135], v[244:245]
	v_pk_fma_f32 v[20:21], v[20:21], v[132:133], v[242:243]
	v_mul_f32_e32 v153, v23, v23
	v_mul_f32_e32 v152, v21, v21
	v_fmac_f32_e32 v152, v20, v20
	v_fmac_f32_e32 v153, v22, v22
	v_add_f32_e32 v152, v152, v153
	v_add_f32_e32 v152, v158, v152
	ds_bpermute_b32 v153, v150, v152
	global_store_dwordx4 v[156:157], v[20:23], off offset:576 sc1
	s_waitcnt lgkmcnt(0)
	v_add_f32_e32 v152, v152, v153
	ds_bpermute_b32 v153, v151, v152
	s_and_saveexec_b64 s[30:31], vcc
	s_cbranch_execz .LBB0_629
	s_waitcnt lgkmcnt(0)
	v_add_f32_e32 v152, v152, v153
	ds_write_b32 v148, v152 offset:2560
.LBB0_629:
	s_or_b64 exec, exec, s[30:31]
	v_add_u32_e32 v206, 0xb0, v182
	v_ashrrev_i32_e32 v207, 31, v206
	s_waitcnt lgkmcnt(0)
	v_lshlrev_b64 v[152:153], 10, v[206:207]
	v_lshl_add_u64 v[152:153], v[152:153], 0, v[180:181]
	v_lshlrev_b64 v[156:157], 2, v[152:153]
	v_lshl_add_u64 v[158:159], s[18:19], 0, v[156:157]
	global_load_dwordx4 v[212:215], v[158:159], off nt
	global_load_dwordx4 v[216:219], v[158:159], off offset:64 nt
	global_load_dwordx4 v[220:223], v[158:159], off offset:512 nt
	global_load_dwordx4 v[242:245], v[158:159], off offset:576 nt
	v_lshl_add_u64 v[156:157], s[78:79], 0, v[156:157]
	s_waitcnt vmcnt(3)
	v_pk_fma_f32 v[18:19], v[18:19], v[142:143], v[214:215]
	v_pk_fma_f32 v[16:17], v[16:17], v[140:141], v[212:213]
	global_store_dwordx4 v[156:157], v[16:19], off sc1
	s_waitcnt vmcnt(3)
	v_pk_fma_f32 v[14:15], v[14:15], v[146:147], v[218:219]
	v_pk_fma_f32 v[12:13], v[12:13], v[144:145], v[216:217]
	global_store_dwordx4 v[156:157], v[12:15], off offset:64 sc1
	s_waitcnt vmcnt(3)
	v_pk_fma_f32 v[10:11], v[10:11], v[138:139], v[222:223]
	v_pk_fma_f32 v[8:9], v[8:9], v[136:137], v[220:221]
	global_store_dwordx4 v[156:157], v[8:11], off offset:512 sc1
	v_mul_f32_e32 v140, v17, v17
	v_mul_f32_e32 v141, v19, v19
	v_fmac_f32_e32 v140, v16, v16
	v_fmac_f32_e32 v141, v18, v18
	v_add_f32_e32 v140, v140, v141
	v_mul_f32_e32 v141, v13, v13
	v_mul_f32_e32 v142, v15, v15
	v_fmac_f32_e32 v141, v12, v12
	v_fmac_f32_e32 v142, v14, v14
	v_add_f32_e32 v141, v141, v142
	v_add_f32_e32 v140, v140, v141
	v_mul_f32_e32 v141, v9, v9
	v_mul_f32_e32 v142, v11, v11
	v_fmac_f32_e32 v141, v8, v8
	v_fmac_f32_e32 v142, v10, v10
	v_add_f32_e32 v141, v141, v142
	v_add_f32_e32 v140, v140, v141
	s_waitcnt vmcnt(3)
	v_pk_fma_f32 v[6:7], v[6:7], v[134:135], v[244:245]
	v_pk_fma_f32 v[4:5], v[4:5], v[132:133], v[242:243]
	v_mul_f32_e32 v133, v7, v7
	v_mul_f32_e32 v132, v5, v5
	v_fmac_f32_e32 v132, v4, v4
	v_fmac_f32_e32 v133, v6, v6
	v_add_f32_e32 v132, v132, v133
	v_add_f32_e32 v132, v140, v132
	ds_bpermute_b32 v133, v150, v132
	global_store_dwordx4 v[156:157], v[4:7], off offset:576 sc1
	s_waitcnt lgkmcnt(0)
	v_add_f32_e32 v132, v132, v133
	ds_bpermute_b32 v133, v151, v132
	s_and_saveexec_b64 s[30:31], vcc
	s_cbranch_execz .LBB0_631
	s_waitcnt lgkmcnt(0)
	v_add_f32_e32 v132, v132, v133
	ds_write_b32 v148, v132 offset:2816

; __device__ __forceinline__ unsigned cvt_pk_bf16(float lo, float hi) { unsigned r; asm volatile("v_cvt_pk_bf16_f32 %0, %1, %2" : "=v"(r) : "v"(lo), "v"(hi)); return r; }
;     __device__ __forceinline__ void fused(f32x4 (&acc)[2][2][4][2], const Unit& u, int wr, int wc, int fr, int fq, PG8_LAS unsigned char* lds, int wid, int lane) const {
;     ...
;         f32x4 mul[2][2], add[2][2];
; #pragma unroll
;         for (int bj = 0; bj < 2; ++bj)
; #pragma unroll
;             for (int n = 0; n < 2; ++n) { const int c = col0 + bj * HALF + 16 * n;
;                 mul[bj][n] = *(const f32x4*)(nw + c) * (*(const f32x4*)(modf2 + (size_t)b * 3072 + 1024 + c) + 1.f); add[bj][n] = *(const f32x4*)(modf2 + (size_t)b * 3072 + c); }
;         __syncthreads();
;         if (t < 256) { float tot = 0.f;
; #pragma unroll
;             for (int pn2 = 0; pn2 < 4; ++pn2) tot += __hip_atomic_load(xch + ((size_t)u.pm * 256 + t) * 4 + pn2, __ATOMIC_RELAXED, __HIP_MEMORY_SCOPE_AGENT);
;             S[t] = rsqrtf(tot * (1.f / 1024.f) + 1e-6f); }
;         __syncthreads();
; #pragma unroll
;         for (int ai = 0; ai < 2; ++ai)
; #pragma unroll
;             for (int m = 0; m < 4; ++m) { const float rstd = S[ai * HALF + wr * 64 + m * 16 + fr]; bf16_t* hp = Hn + (size_t)(row0 + ai * HALF + m * 16) * 1024 + col0;
; #pragma unroll
;                 for (int bj = 0; bj < 2; ++bj) { const f32x4 h0 = acc[ai][bj][m][0] * rstd * mul[bj][0] + add[bj][0], h1 = acc[ai][bj][m][1] * rstd * mul[bj][1] + add[bj][1];
;                     typedef unsigned u32x2e __attribute__((ext_vector_type(2)));
;                     u32x2e w0, w1; w0.x = cvt_pk_bf16(h0[0], h0[1]); w0.y = cvt_pk_bf16(h0[2], h0[3]); w1.x = cvt_pk_bf16(h1[0], h1[1]); w1.y = cvt_pk_bf16(h1[2], h1[3]);
;                     *(u32x2e*)(hp + bj * HALF) = w0; *(u32x2e*)(hp + bj * HALF + 16) = w1; } }
.LBB0_646:
	s_or_b64 exec, exec, s[26:27]
	s_lshl_b32 s5, s5, 2
	s_waitcnt vmcnt(10)
	v_pk_add_f32 v[154:155], v[154:155], 1.0 op_sel_hi:[1,0]
	s_add_i32 s5, s5, 0
	v_pk_mul_f32 v[150:151], v[150:151], v[154:155]
	v_lshl_add_u32 v155, v210, 2, s5
	s_waitcnt lgkmcnt(0)
	s_barrier
	ds_read_b32 v154, v155 offset:4096
	v_pk_add_f32 v[152:153], v[152:153], 1.0 op_sel_hi:[1,0]
	v_readlane_b32 s20, v254, 52
	s_waitcnt vmcnt(8)
	v_pk_add_f32 v[162:163], v[162:163], 1.0 op_sel_hi:[1,0]
	v_pk_add_f32 v[160:161], v[160:161], 1.0 op_sel_hi:[1,0]
	v_pk_mul_f32 v[148:149], v[148:149], v[152:153]
	v_lshlrev_b64 v[152:153], 11, v[182:183]
	v_readlane_b32 s21, v254, 53
	s_waitcnt lgkmcnt(0)
	v_pk_mul_f32 v[110:111], v[110:111], v[154:155] op_sel_hi:[1,0]
	v_pk_mul_f32 v[108:109], v[108:109], v[154:155] op_sel_hi:[1,0]
	s_waitcnt vmcnt(7)
	v_pk_mul_f32 v[158:159], v[158:159], v[162:163]
	v_pk_mul_f32 v[156:157], v[156:157], v[160:161]
	v_lshl_add_u64 v[160:161], s[20:21], 0, v[152:153]
	v_lshlrev_b64 v[152:153], 1, v[180:181]
	v_pk_fma_f32 v[110:111], v[150:151], v[110:111], v[142:143]
	v_pk_fma_f32 v[108:109], v[148:149], v[108:109], v[140:141]
	v_pk_mul_f32 v[122:123], v[122:123], v[154:155] op_sel_hi:[1,0]
	v_pk_mul_f32 v[120:121], v[120:121], v[154:155] op_sel_hi:[1,0]
	s_waitcnt vmcnt(5)
	v_pk_add_f32 v[168:169], v[168:169], 1.0 op_sel_hi:[1,0]
	v_lshl_add_u64 v[160:161], v[160:161], 0, v[152:153]
	s_waitcnt vmcnt(4)
	v_pk_fma_f32 v[122:123], v[158:159], v[122:123], v[146:147]
	v_pk_fma_f32 v[120:121], v[156:157], v[120:121], v[144:145]
	v_cvt_pk_bf16_f32 v108, v108, v109
	v_cvt_pk_bf16_f32 v109, v110, v111
	v_pk_add_f32 v[170:171], v[170:171], 1.0 op_sel_hi:[1,0]
	v_cvt_pk_bf16_f32 v110, v120, v121
	v_cvt_pk_bf16_f32 v111, v122, v123
	v_pk_mul_f32 v[164:165], v[164:165], v[168:169]
	global_store_dwordx2 v[160:161], v[108:109], off sc1
	global_store_dwordx2 v[160:161], v[110:111], off offset:32 sc1
	v_pk_mul_f32 v[110:111], v[112:113], v[154:155] op_sel_hi:[1,0]
	s_waitcnt vmcnt(3)
	v_pk_add_f32 v[178:179], v[178:179], 1.0 op_sel_hi:[1,0]
	v_pk_add_f32 v[176:177], v[176:177], 1.0 op_sel_hi:[1,0]
	v_pk_mul_f32 v[166:167], v[166:167], v[170:171]
	v_pk_mul_f32 v[108:109], v[114:115], v[154:155] op_sel_hi:[1,0]
	v_pk_fma_f32 v[110:111], v[164:165], v[110:111], v[132:133]
	v_pk_mul_f32 v[174:175], v[174:175], v[178:179]
	v_pk_mul_f32 v[172:173], v[172:173], v[176:177]
	v_pk_fma_f32 v[108:109], v[166:167], v[108:109], v[134:135]
	v_pk_mul_f32 v[112:113], v[130:131], v[154:155] op_sel_hi:[1,0]
	v_pk_mul_f32 v[114:115], v[128:129], v[154:155] op_sel_hi:[1,0]
	v_cvt_pk_bf16_f32 v110, v110, v111
	s_waitcnt vmcnt(2)
	v_pk_fma_f32 v[112:113], v[174:175], v[112:113], v[138:139]
	v_pk_fma_f32 v[114:115], v[172:173], v[114:115], v[136:137]
	v_cvt_pk_bf16_f32 v111, v108, v109
	s_nop 0
	v_cvt_pk_bf16_f32 v108, v114, v115
	v_cvt_pk_bf16_f32 v109, v112, v113
	global_store_dwordx2 v[160:161], v[110:111], off offset:256 sc1
	ds_read_b32 v110, v155 offset:4160
	global_store_dwordx2 v[160:161], v[108:109], off offset:288 sc1
	v_lshlrev_b64 v[108:109], 11, v[184:185]
	v_lshl_add_u64 v[108:109], s[20:21], 0, v[108:109]
	v_lshl_add_u64 v[108:109], v[108:109], 0, v[152:153]
	s_waitcnt lgkmcnt(0)
	v_pk_mul_f32 v[114:115], v[124:125], v[110:111] op_sel_hi:[1,0]
	v_pk_mul_f32 v[112:113], v[126:127], v[110:111] op_sel_hi:[1,0]
	v_pk_fma_f32 v[114:115], v[148:149], v[114:115], v[140:141]
	v_pk_mul_f32 v[104:105], v[104:105], v[110:111] op_sel_hi:[1,0]
	v_pk_mul_f32 v[102:103], v[102:103], v[110:111] op_sel_hi:[1,0]
	v_pk_mul_f32 v[100:101], v[100:101], v[110:111] op_sel_hi:[1,0]
	v_pk_fma_f32 v[112:113], v[150:151], v[112:113], v[142:143]
	v_pk_mul_f32 v[118:119], v[118:119], v[110:111] op_sel_hi:[1,0]
	v_pk_mul_f32 v[116:117], v[116:117], v[110:111] op_sel_hi:[1,0]
	v_cvt_pk_bf16_f32 v114, v114, v115
	v_cvt_pk_bf16_f32 v115, v112, v113
	v_pk_mul_f32 v[106:107], v[106:107], v[110:111] op_sel_hi:[1,0]
	v_pk_fma_f32 v[104:105], v[164:165], v[104:105], v[132:133]
	v_pk_fma_f32 v[102:103], v[174:175], v[102:103], v[138:139]
	v_pk_fma_f32 v[100:101], v[172:173], v[100:101], v[136:137]
	v_pk_fma_f32 v[118:119], v[158:159], v[118:119], v[146:147]
	v_pk_fma_f32 v[116:117], v[156:157], v[116:117], v[144:145]
	v_pk_fma_f32 v[106:107], v[166:167], v[106:107], v[134:135]
	v_cvt_pk_bf16_f32 v112, v116, v117
	v_cvt_pk_bf16_f32 v113, v118, v119
	global_store_dwordx2 v[108:109], v[114:115], off sc1
	global_store_dwordx2 v[108:109], v[112:113], off offset:32 sc1
	v_cvt_pk_bf16_f32 v104, v104, v105
	v_cvt_pk_bf16_f32 v105, v106, v107
	v_cvt_pk_bf16_f32 v100, v100, v101
	v_cvt_pk_bf16_f32 v101, v102, v103
	ds_read_b32 v102, v155 offset:4224
	global_store_dwordx2 v[108:109], v[100:101], off offset:288 sc1
	v_lshlrev_b64 v[100:101], 11, v[186:187]
	v_lshl_add_u64 v[100:101], s[20:21], 0, v[100:101]
	global_store_dwordx2 v[108:109], v[104:105], off offset:256 sc1
	s_waitcnt lgkmcnt(0)
; __device__ __forceinline__ unsigned cvt_pk_bf16(float lo, float hi) { unsigned r; asm volatile("v_cvt_pk_bf16_f32 %0, %1, %2" : "=v"(r) : "v"(lo), "v"(hi)); return r; }
;     __device__ __forceinline__ void fused(f32x4 (&acc)[2][2][4][2], const Unit& u, int wr, int wc, int fr, int fq, PG8_LAS unsigned char* lds, int wid, int lane) const {
;     ...
; #pragma unroll
;         for (int ai = 0; ai < 2; ++ai)
; #pragma unroll
;             for (int m = 0; m < 4; ++m) { const float rstd = S[ai * HALF + wr * 64 + m * 16 + fr]; bf16_t* hp = Hn + (size_t)(row0 + ai * HALF + m * 16) * 1024 + col0;
; #pragma unroll
;                 for (int bj = 0; bj < 2; ++bj) { const f32x4 h0 = acc[ai][bj][m][0] * rstd * mul[bj][0] + add[bj][0], h1 = acc[ai][bj][m][1] * rstd * mul[bj][1] + add[bj][1];
;                     typedef unsigned u32x2e __attribute__((ext_vector_type(2)));
;                     u32x2e w0, w1; w0.x = cvt_pk_bf16(h0[0], h0[1]); w0.y = cvt_pk_bf16(h0[2], h0[3]); w1.x = cvt_pk_bf16(h1[0], h1[1]); w1.y = cvt_pk_bf16(h1[2], h1[3]);
;                     *(u32x2e*)(hp + bj * HALF) = w0; *(u32x2e*)(hp + bj * HALF + 16) = w1; } }
	v_pk_mul_f32 v[96:97], v[96:97], v[102:103] op_sel_hi:[1,0]
	v_pk_mul_f32 v[98:99], v[98:99], v[102:103] op_sel_hi:[1,0]
	v_pk_fma_f32 v[96:97], v[148:149], v[96:97], v[140:141]
	v_pk_mul_f32 v[92:93], v[92:93], v[102:103] op_sel_hi:[1,0]
	v_pk_mul_f32 v[88:89], v[88:89], v[102:103] op_sel_hi:[1,0]
	v_pk_mul_f32 v[86:87], v[86:87], v[102:103] op_sel_hi:[1,0]
	v_pk_mul_f32 v[84:85], v[84:85], v[102:103] op_sel_hi:[1,0]
	v_lshl_add_u64 v[100:101], v[100:101], 0, v[152:153]
	v_pk_fma_f32 v[98:99], v[150:151], v[98:99], v[142:143]
	v_pk_mul_f32 v[94:95], v[94:95], v[102:103] op_sel_hi:[1,0]
	v_pk_fma_f32 v[92:93], v[156:157], v[92:93], v[144:145]
	v_cvt_pk_bf16_f32 v96, v96, v97
	v_cvt_pk_bf16_f32 v97, v98, v99
	v_pk_mul_f32 v[90:91], v[90:91], v[102:103] op_sel_hi:[1,0]
	v_pk_fma_f32 v[88:89], v[164:165], v[88:89], v[132:133]
	v_pk_fma_f32 v[86:87], v[174:175], v[86:87], v[138:139]
	v_pk_fma_f32 v[84:85], v[172:173], v[84:85], v[136:137]
	v_pk_fma_f32 v[94:95], v[158:159], v[94:95], v[146:147]
	v_cvt_pk_bf16_f32 v92, v92, v93
	v_pk_fma_f32 v[90:91], v[166:167], v[90:91], v[134:135]
	v_cvt_pk_bf16_f32 v93, v94, v95
	global_store_dwordx2 v[100:101], v[96:97], off sc1
	global_store_dwordx2 v[100:101], v[92:93], off offset:32 sc1
	v_cvt_pk_bf16_f32 v88, v88, v89
	v_cvt_pk_bf16_f32 v89, v90, v91
	v_cvt_pk_bf16_f32 v84, v84, v85
	v_cvt_pk_bf16_f32 v85, v86, v87
	ds_read_b32 v86, v155 offset:4288
	global_store_dwordx2 v[100:101], v[84:85], off offset:288 sc1
	v_lshlrev_b64 v[84:85], 11, v[198:199]
	v_lshl_add_u64 v[84:85], s[20:21], 0, v[84:85]
	global_store_dwordx2 v[100:101], v[88:89], off offset:256 sc1
	s_waitcnt lgkmcnt(0)
	v_pk_mul_f32 v[80:81], v[80:81], v[86:87] op_sel_hi:[1,0]
	v_pk_mul_f32 v[82:83], v[82:83], v[86:87] op_sel_hi:[1,0]
	v_pk_fma_f32 v[80:81], v[148:149], v[80:81], v[140:141]
	v_pk_mul_f32 v[76:77], v[76:77], v[86:87] op_sel_hi:[1,0]
	v_pk_mul_f32 v[72:73], v[72:73], v[86:87] op_sel_hi:[1,0]
	v_pk_mul_f32 v[70:71], v[70:71], v[86:87] op_sel_hi:[1,0]
	v_pk_mul_f32 v[68:69], v[68:69], v[86:87] op_sel_hi:[1,0]
	v_lshl_add_u64 v[84:85], v[84:85], 0, v[152:153]
	v_pk_fma_f32 v[82:83], v[150:151], v[82:83], v[142:143]
	v_pk_mul_f32 v[78:79], v[78:79], v[86:87] op_sel_hi:[1,0]
	v_pk_fma_f32 v[76:77], v[156:157], v[76:77], v[144:145]
	v_cvt_pk_bf16_f32 v80, v80, v81
	v_cvt_pk_bf16_f32 v81, v82, v83
	v_pk_mul_f32 v[74:75], v[74:75], v[86:87] op_sel_hi:[1,0]
	v_pk_fma_f32 v[72:73], v[164:165], v[72:73], v[132:133]
	v_pk_fma_f32 v[70:71], v[174:175], v[70:71], v[138:139]
	v_pk_fma_f32 v[68:69], v[172:173], v[68:69], v[136:137]
	v_pk_fma_f32 v[78:79], v[158:159], v[78:79], v[146:147]
	v_cvt_pk_bf16_f32 v76, v76, v77
	v_pk_fma_f32 v[74:75], v[166:167], v[74:75], v[134:135]
	v_cvt_pk_bf16_f32 v77, v78, v79
	global_store_dwordx2 v[84:85], v[80:81], off sc1
	global_store_dwordx2 v[84:85], v[76:77], off offset:32 sc1
	v_cvt_pk_bf16_f32 v72, v72, v73
	v_cvt_pk_bf16_f32 v73, v74, v75
	v_cvt_pk_bf16_f32 v68, v68, v69
	v_cvt_pk_bf16_f32 v69, v70, v71
	ds_read_b32 v70, v155 offset:4608
	global_store_dwordx2 v[84:85], v[68:69], off offset:288 sc1
	v_lshlrev_b64 v[68:69], 11, v[200:201]
	v_lshl_add_u64 v[68:69], s[20:21], 0, v[68:69]
	global_store_dwordx2 v[84:85], v[72:73], off offset:256 sc1
	s_waitcnt lgkmcnt(0)
	v_pk_mul_f32 v[64:65], v[64:65], v[70:71] op_sel_hi:[1,0]
	v_pk_mul_f32 v[66:67], v[66:67], v[70:71] op_sel_hi:[1,0]
	v_pk_fma_f32 v[64:65], v[148:149], v[64:65], v[140:141]
	v_pk_mul_f32 v[60:61], v[60:61], v[70:71] op_sel_hi:[1,0]
	v_pk_mul_f32 v[56:57], v[56:57], v[70:71] op_sel_hi:[1,0]
	v_pk_mul_f32 v[54:55], v[54:55], v[70:71] op_sel_hi:[1,0]
	v_pk_mul_f32 v[52:53], v[52:53], v[70:71] op_sel_hi:[1,0]
	v_lshl_add_u64 v[68:69], v[68:69], 0, v[152:153]
	v_pk_fma_f32 v[66:67], v[150:151], v[66:67], v[142:143]
	v_pk_mul_f32 v[62:63], v[62:63], v[70:71] op_sel_hi:[1,0]
	v_pk_fma_f32 v[60:61], v[156:157], v[60:61], v[144:145]
	v_cvt_pk_bf16_f32 v64, v64, v65
	v_cvt_pk_bf16_f32 v65, v66, v67
	v_pk_mul_f32 v[58:59], v[58:59], v[70:71] op_sel_hi:[1,0]
	v_pk_fma_f32 v[56:57], v[164:165], v[56:57], v[132:133]
	v_pk_fma_f32 v[54:55], v[174:175], v[54:55], v[138:139]
	v_pk_fma_f32 v[52:53], v[172:173], v[52:53], v[136:137]
	v_pk_fma_f32 v[62:63], v[158:159], v[62:63], v[146:147]
	v_cvt_pk_bf16_f32 v60, v60, v61
	v_pk_fma_f32 v[58:59], v[166:167], v[58:59], v[134:135]
	v_cvt_pk_bf16_f32 v61, v62, v63
	global_store_dwordx2 v[68:69], v[64:65], off sc1
	global_store_dwordx2 v[68:69], v[60:61], off offset:32 sc1
	v_cvt_pk_bf16_f32 v56, v56, v57
	v_cvt_pk_bf16_f32 v57, v58, v59
	v_cvt_pk_bf16_f32 v52, v52, v53
	v_cvt_pk_bf16_f32 v53, v54, v55
	ds_read_b32 v54, v155 offset:4672
	global_store_dwordx2 v[68:69], v[52:53], off offset:288 sc1
	v_lshlrev_b64 v[52:53], 11, v[202:203]
	v_lshl_add_u64 v[52:53], s[20:21], 0, v[52:53]
	global_store_dwordx2 v[68:69], v[56:57], off offset:256 sc1
	s_waitcnt lgkmcnt(0)
; __device__ __forceinline__ unsigned cvt_pk_bf16(float lo, float hi) { unsigned r; asm volatile("v_cvt_pk_bf16_f32 %0, %1, %2" : "=v"(r) : "v"(lo), "v"(hi)); return r; }
;     __device__ __forceinline__ void fused(f32x4 (&acc)[2][2][4][2], const Unit& u, int wr, int wc, int fr, int fq, PG8_LAS unsigned char* lds, int wid, int lane) const {
;     ...
; #pragma unroll
;         for (int ai = 0; ai < 2; ++ai)
; #pragma unroll
;             for (int m = 0; m < 4; ++m) { const float rstd = S[ai * HALF + wr * 64 + m * 16 + fr]; bf16_t* hp = Hn + (size_t)(row0 + ai * HALF + m * 16) * 1024 + col0;
; #pragma unroll
;                 for (int bj = 0; bj < 2; ++bj) { const f32x4 h0 = acc[ai][bj][m][0] * rstd * mul[bj][0] + add[bj][0], h1 = acc[ai][bj][m][1] * rstd * mul[bj][1] + add[bj][1];
;                     typedef unsigned u32x2e __attribute__((ext_vector_type(2)));
;                     u32x2e w0, w1; w0.x = cvt_pk_bf16(h0[0], h0[1]); w0.y = cvt_pk_bf16(h0[2], h0[3]); w1.x = cvt_pk_bf16(h1[0], h1[1]); w1.y = cvt_pk_bf16(h1[2], h1[3]);
;                     *(u32x2e*)(hp + bj * HALF) = w0; *(u32x2e*)(hp + bj * HALF + 16) = w1; } }
;         __syncthreads();
	v_pk_mul_f32 v[48:49], v[48:49], v[54:55] op_sel_hi:[1,0]
	v_pk_mul_f32 v[50:51], v[50:51], v[54:55] op_sel_hi:[1,0]
	v_pk_fma_f32 v[48:49], v[148:149], v[48:49], v[140:141]
	v_pk_mul_f32 v[44:45], v[44:45], v[54:55] op_sel_hi:[1,0]
	v_pk_mul_f32 v[40:41], v[40:41], v[54:55] op_sel_hi:[1,0]
	v_pk_mul_f32 v[38:39], v[38:39], v[54:55] op_sel_hi:[1,0]
	v_pk_mul_f32 v[36:37], v[36:37], v[54:55] op_sel_hi:[1,0]
	v_lshl_add_u64 v[52:53], v[52:53], 0, v[152:153]
	v_pk_fma_f32 v[50:51], v[150:151], v[50:51], v[142:143]
	v_pk_mul_f32 v[46:47], v[46:47], v[54:55] op_sel_hi:[1,0]
	v_pk_fma_f32 v[44:45], v[156:157], v[44:45], v[144:145]
	v_cvt_pk_bf16_f32 v48, v48, v49
	v_cvt_pk_bf16_f32 v49, v50, v51
	v_pk_mul_f32 v[42:43], v[42:43], v[54:55] op_sel_hi:[1,0]
	v_pk_fma_f32 v[40:41], v[164:165], v[40:41], v[132:133]
	v_pk_fma_f32 v[38:39], v[174:175], v[38:39], v[138:139]
	v_pk_fma_f32 v[36:37], v[172:173], v[36:37], v[136:137]
	v_pk_fma_f32 v[46:47], v[158:159], v[46:47], v[146:147]
	v_cvt_pk_bf16_f32 v44, v44, v45
	v_pk_fma_f32 v[42:43], v[166:167], v[42:43], v[134:135]
	v_cvt_pk_bf16_f32 v45, v46, v47
	global_store_dwordx2 v[52:53], v[48:49], off sc1
	global_store_dwordx2 v[52:53], v[44:45], off offset:32 sc1
	v_cvt_pk_bf16_f32 v40, v40, v41
	v_cvt_pk_bf16_f32 v41, v42, v43
	v_cvt_pk_bf16_f32 v36, v36, v37
	v_cvt_pk_bf16_f32 v37, v38, v39
	ds_read_b32 v38, v155 offset:4736
	global_store_dwordx2 v[52:53], v[36:37], off offset:288 sc1
	v_lshlrev_b64 v[36:37], 11, v[204:205]
	v_lshl_add_u64 v[36:37], s[20:21], 0, v[36:37]
	global_store_dwordx2 v[52:53], v[40:41], off offset:256 sc1
	s_waitcnt lgkmcnt(0)
	v_pk_mul_f32 v[32:33], v[32:33], v[38:39] op_sel_hi:[1,0]
	v_pk_mul_f32 v[34:35], v[34:35], v[38:39] op_sel_hi:[1,0]
	v_pk_fma_f32 v[32:33], v[148:149], v[32:33], v[140:141]
	v_pk_mul_f32 v[28:29], v[28:29], v[38:39] op_sel_hi:[1,0]
	v_pk_mul_f32 v[24:25], v[24:25], v[38:39] op_sel_hi:[1,0]
	v_pk_mul_f32 v[22:23], v[22:23], v[38:39] op_sel_hi:[1,0]
	v_pk_mul_f32 v[20:21], v[20:21], v[38:39] op_sel_hi:[1,0]
	v_lshl_add_u64 v[36:37], v[36:37], 0, v[152:153]
	v_pk_fma_f32 v[34:35], v[150:151], v[34:35], v[142:143]
	v_pk_mul_f32 v[30:31], v[30:31], v[38:39] op_sel_hi:[1,0]
	v_pk_fma_f32 v[28:29], v[156:157], v[28:29], v[144:145]
	v_cvt_pk_bf16_f32 v32, v32, v33
	v_cvt_pk_bf16_f32 v33, v34, v35
	v_pk_mul_f32 v[26:27], v[26:27], v[38:39] op_sel_hi:[1,0]
	v_pk_fma_f32 v[24:25], v[164:165], v[24:25], v[132:133]
	v_pk_fma_f32 v[22:23], v[174:175], v[22:23], v[138:139]
	v_pk_fma_f32 v[20:21], v[172:173], v[20:21], v[136:137]
	v_pk_fma_f32 v[30:31], v[158:159], v[30:31], v[146:147]
	v_cvt_pk_bf16_f32 v28, v28, v29
	v_pk_fma_f32 v[26:27], v[166:167], v[26:27], v[134:135]
	v_cvt_pk_bf16_f32 v29, v30, v31
	global_store_dwordx2 v[36:37], v[32:33], off sc1
	global_store_dwordx2 v[36:37], v[28:29], off offset:32 sc1
	v_cvt_pk_bf16_f32 v24, v24, v25
	v_cvt_pk_bf16_f32 v25, v26, v27
	v_cvt_pk_bf16_f32 v20, v20, v21
	v_cvt_pk_bf16_f32 v21, v22, v23
	ds_read_b32 v22, v155 offset:4800
	global_store_dwordx2 v[36:37], v[20:21], off offset:288 sc1
	v_lshlrev_b64 v[20:21], 11, v[206:207]
	v_lshl_add_u64 v[20:21], s[20:21], 0, v[20:21]
	global_store_dwordx2 v[36:37], v[24:25], off offset:256 sc1
	s_waitcnt lgkmcnt(0)
	v_pk_mul_f32 v[16:17], v[16:17], v[22:23] op_sel_hi:[1,0]
	v_pk_mul_f32 v[18:19], v[18:19], v[22:23] op_sel_hi:[1,0]
	v_pk_fma_f32 v[16:17], v[148:149], v[16:17], v[140:141]
	v_pk_mul_f32 v[12:13], v[12:13], v[22:23] op_sel_hi:[1,0]
	v_pk_mul_f32 v[8:9], v[8:9], v[22:23] op_sel_hi:[1,0]
	v_lshl_add_u64 v[20:21], v[20:21], 0, v[152:153]
	v_pk_fma_f32 v[18:19], v[150:151], v[18:19], v[142:143]
	v_pk_mul_f32 v[14:15], v[14:15], v[22:23] op_sel_hi:[1,0]
	v_pk_fma_f32 v[12:13], v[156:157], v[12:13], v[144:145]
	v_cvt_pk_bf16_f32 v16, v16, v17
	v_cvt_pk_bf16_f32 v17, v18, v19
	v_pk_mul_f32 v[10:11], v[10:11], v[22:23] op_sel_hi:[1,0]
	v_pk_fma_f32 v[8:9], v[164:165], v[8:9], v[132:133]
	v_pk_mul_f32 v[4:5], v[4:5], v[22:23] op_sel_hi:[1,0]
	v_pk_fma_f32 v[14:15], v[158:159], v[14:15], v[146:147]
	v_cvt_pk_bf16_f32 v12, v12, v13
	v_pk_fma_f32 v[10:11], v[166:167], v[10:11], v[134:135]
	v_cvt_pk_bf16_f32 v13, v14, v15
	global_store_dwordx2 v[20:21], v[16:17], off sc1
	global_store_dwordx2 v[20:21], v[12:13], off offset:32 sc1
	v_pk_mul_f32 v[6:7], v[6:7], v[22:23] op_sel_hi:[1,0]
	v_pk_fma_f32 v[4:5], v[172:173], v[4:5], v[136:137]
	v_cvt_pk_bf16_f32 v8, v8, v9
	v_cvt_pk_bf16_f32 v9, v10, v11
	v_pk_fma_f32 v[6:7], v[174:175], v[6:7], v[138:139]
	v_cvt_pk_bf16_f32 v4, v4, v5
	s_nop 0
	v_cvt_pk_bf16_f32 v5, v6, v7
	global_store_dwordx2 v[20:21], v[8:9], off offset:256 sc1
	global_store_dwordx2 v[20:21], v[4:5], off offset:288 sc1
	s_barrier

;     __device__ __forceinline__ void fused(f32x4 (&acc)[2][2][4][2], const Unit& u, int wr, int wc, int fr, int fq, PG8_LAS unsigned char* lds, int wid, int lane) const {
;     ...
;         __syncthreads();
;         f32x4 fwv[2][2];
; #pragma unroll
;         for (int bj = 0; bj < 2; ++bj)
; #pragma unroll
;             for (int n = 0; n < 2; ++n) fwv[bj][n] = *(const f32x4*)(fw + col0 + bj * HALF + 16 * n);
; #pragma unroll
;         for (int ai = 0; ai < 2; ++ai)
; #pragma unroll
;             for (int m = 0; m < 4; ++m) { const float rstd = S[ai * HALF + wr * 64 + m * 16 + fr]; const size_t ro = (size_t)(row0 + ai * HALF + m * 16) * 1024 + col0;
; #pragma unroll
;                 for (int bj = 0; bj < 2; ++bj)
; #pragma unroll
;                     for (int n = 0; n < 2; ++n) *(f32x4*)(xout + ro + bj * HALF + 16 * n) = acc[ai][bj][m][n] * rstd * fwv[bj][n]; }
;         __syncthreads();
.LBB0_700:
	s_or_b64 exec, exec, s[18:19]
	v_lshl_add_u64 v[4:5], s[76:77], 0, v[148:149]
	s_waitcnt lgkmcnt(0)
	s_barrier
	global_load_dwordx4 v[16:19], v[4:5], off
	global_load_dwordx4 v[12:15], v[4:5], off offset:64
	global_load_dwordx4 v[8:11], v[4:5], off offset:512
	s_nop 0
	global_load_dwordx4 v[4:7], v[4:5], off offset:576
	s_lshl_b32 s2, s5, 2
	s_add_i32 s2, s2, 0
	v_lshl_add_u32 v160, v168, 2, s2
	v_add_u32_e32 v160, 0x1000, v160
	ds_read2_b32 v[168:169], v160 offset1:16
	v_lshl_add_u64 v[150:151], s[78:79], 0, v[150:151]
	v_lshl_add_u64 v[150:151], v[150:151], 0, v[148:149]
	v_lshl_add_u64 v[96:97], s[78:79], 0, v[96:97]
	v_lshl_add_u64 v[96:97], v[96:97], 0, v[148:149]
	s_waitcnt lgkmcnt(0)
	v_pk_mul_f32 v[134:135], v[134:135], v[168:169] op_sel_hi:[1,0]
	v_pk_mul_f32 v[132:133], v[132:133], v[168:169] op_sel_hi:[1,0]
	v_pk_mul_f32 v[146:147], v[146:147], v[168:169] op_sel_hi:[1,0]
	v_pk_mul_f32 v[144:145], v[144:145], v[168:169] op_sel_hi:[1,0]
	v_pk_mul_f32 v[142:143], v[142:143], v[168:169] op_sel_hi:[1,0]
	v_pk_mul_f32 v[140:141], v[140:141], v[168:169] op_sel_hi:[1,0]
	v_pk_mul_f32 v[138:139], v[138:139], v[168:169] op_sel_hi:[1,0]
	v_pk_mul_f32 v[136:137], v[136:137], v[168:169] op_sel_hi:[1,0]
	s_waitcnt vmcnt(3)
	v_pk_mul_f32 v[146:147], v[18:19], v[146:147]
	v_pk_mul_f32 v[144:145], v[16:17], v[144:145]
	s_waitcnt vmcnt(2)
	v_pk_mul_f32 v[142:143], v[14:15], v[142:143]
	s_waitcnt vmcnt(0)
	v_pk_mul_f32 v[134:135], v[6:7], v[134:135]
	v_pk_mul_f32 v[132:133], v[4:5], v[132:133]
	global_store_dwordx4 v[150:151], v[132:135], off offset:576 sc1
	v_pk_mul_f32 v[140:141], v[12:13], v[140:141]
	v_pk_mul_f32 v[138:139], v[10:11], v[138:139]
	v_mov_b32_e32 v132, v169
	v_lshl_add_u64 v[134:135], s[78:79], 0, v[152:153]
	v_pk_mul_f32 v[122:123], v[122:123], v[132:133] op_sel_hi:[1,0]
	v_pk_mul_f32 v[120:121], v[120:121], v[132:133] op_sel_hi:[1,0]
	v_lshl_add_u64 v[134:135], v[134:135], 0, v[148:149]
	v_pk_mul_f32 v[122:123], v[10:11], v[122:123]
	v_pk_mul_f32 v[120:121], v[8:9], v[120:121]
	global_store_dwordx4 v[134:135], v[120:123], off offset:512 sc1
	v_pk_mul_f32 v[118:119], v[118:119], v[132:133] op_sel_hi:[1,0]
	v_pk_mul_f32 v[130:131], v[130:131], v[132:133] op_sel_hi:[1,0]
	v_pk_mul_f32 v[122:123], v[154:155], v[132:133] op_sel_hi:[1,0]
	v_pk_mul_f32 v[120:121], v[6:7], v[118:119]
	v_pk_mul_f32 v[118:119], v[4:5], v[122:123]
	global_store_dwordx4 v[134:135], v[118:121], off offset:576 sc1
	ds_read2_b32 v[118:119], v160 offset0:32 offset1:48
	v_pk_mul_f32 v[128:129], v[128:129], v[132:133] op_sel_hi:[1,0]
	v_pk_mul_f32 v[130:131], v[18:19], v[130:131]
	v_pk_mul_f32 v[128:129], v[16:17], v[128:129]
	v_pk_mul_f32 v[126:127], v[126:127], v[132:133] op_sel_hi:[1,0]
	s_waitcnt lgkmcnt(0)
	v_pk_mul_f32 v[114:115], v[114:115], v[118:119] op_sel_hi:[1,0]
	v_pk_mul_f32 v[106:107], v[106:107], v[118:119] op_sel_hi:[1,0]
	v_pk_mul_f32 v[122:123], v[18:19], v[114:115]
	v_lshl_add_u64 v[114:115], s[78:79], 0, v[116:117]
	v_pk_mul_f32 v[104:105], v[104:105], v[118:119] op_sel_hi:[1,0]
	v_lshl_add_u64 v[114:115], v[114:115], 0, v[148:149]
	v_pk_mul_f32 v[106:107], v[10:11], v[106:107]
	v_pk_mul_f32 v[104:105], v[8:9], v[104:105]
	v_pk_mul_f32 v[98:99], v[98:99], v[118:119] op_sel_hi:[1,0]
	global_store_dwordx4 v[114:115], v[104:107], off offset:512 sc1
	v_pk_mul_f32 v[120:121], v[156:157], v[118:119] op_sel_hi:[1,0]
	v_pk_mul_f32 v[124:125], v[124:125], v[132:133] op_sel_hi:[1,0]
	v_pk_mul_f32 v[106:107], v[6:7], v[98:99]
	v_mov_b32_e32 v98, v119
	v_pk_mul_f32 v[70:71], v[70:71], v[98:99] op_sel_hi:[1,0]
	v_pk_mul_f32 v[68:69], v[68:69], v[98:99] op_sel_hi:[1,0]
	v_pk_mul_f32 v[70:71], v[6:7], v[70:71]
	v_pk_mul_f32 v[68:69], v[4:5], v[68:69]
	global_store_dwordx4 v[96:97], v[68:71], off offset:576 sc1
	ds_read2_b32 v[68:69], v160 offset0:128 offset1:144
	v_pk_mul_f32 v[90:91], v[90:91], v[98:99] op_sel_hi:[1,0]
	v_lshl_add_u64 v[70:71], s[78:79], 0, v[158:159]
	v_lshl_add_u64 v[70:71], v[70:71], 0, v[148:149]
	v_pk_mul_f32 v[88:89], v[88:89], v[98:99] op_sel_hi:[1,0]
	s_waitcnt lgkmcnt(0)
	v_pk_mul_f32 v[54:55], v[54:55], v[68:69] op_sel_hi:[1,0]
	v_pk_mul_f32 v[52:53], v[52:53], v[68:69] op_sel_hi:[1,0]
	v_pk_mul_f32 v[54:55], v[6:7], v[54:55]
	v_pk_mul_f32 v[52:53], v[4:5], v[52:53]
	global_store_dwordx4 v[70:71], v[52:55], off offset:576 sc1
	v_pk_mul_f32 v[66:67], v[66:67], v[68:69] op_sel_hi:[1,0]
	v_pk_mul_f32 v[90:91], v[18:19], v[90:91]
	v_mov_b32_e32 v52, v69
	v_lshl_add_u64 v[54:55], s[78:79], 0, v[162:163]
	v_pk_mul_f32 v[38:39], v[38:39], v[52:53] op_sel_hi:[1,0]
	v_pk_mul_f32 v[36:37], v[36:37], v[52:53] op_sel_hi:[1,0]
	v_lshl_add_u64 v[54:55], v[54:55], 0, v[148:149]
	v_pk_mul_f32 v[38:39], v[6:7], v[38:39]
	v_pk_mul_f32 v[36:37], v[4:5], v[36:37]
	global_store_dwordx4 v[54:55], v[36:39], off offset:576 sc1
	ds_read2_b32 v[36:37], v160 offset0:160 offset1:176
	v_pk_mul_f32 v[50:51], v[50:51], v[52:53] op_sel_hi:[1,0]
	v_lshl_add_u64 v[38:39], s[78:79], 0, v[164:165]
	v_lshl_add_u64 v[38:39], v[38:39], 0, v[148:149]
	v_pk_mul_f32 v[64:65], v[64:65], v[68:69] op_sel_hi:[1,0]
	s_waitcnt lgkmcnt(0)
;     __device__ __forceinline__ void fused(f32x4 (&acc)[2][2][4][2], const Unit& u, int wr, int wc, int fr, int fq, PG8_LAS unsigned char* lds, int wid, int lane) const {
;     ...
; #pragma unroll
;         for (int ai = 0; ai < 2; ++ai)
; #pragma unroll
;             for (int m = 0; m < 4; ++m) { const float rstd = S[ai * HALF + wr * 64 + m * 16 + fr]; const size_t ro = (size_t)(row0 + ai * HALF + m * 16) * 1024 + col0;
; #pragma unroll
;                 for (int bj = 0; bj < 2; ++bj)
; #pragma unroll
;                     for (int n = 0; n < 2; ++n) *(f32x4*)(xout + ro + bj * HALF + 16 * n) = acc[ai][bj][m][n] * rstd * fwv[bj][n]; }
;         __syncthreads();
	v_pk_mul_f32 v[22:23], v[22:23], v[36:37] op_sel_hi:[1,0]
	v_pk_mul_f32 v[20:21], v[20:21], v[36:37] op_sel_hi:[1,0]
	v_pk_mul_f32 v[22:23], v[6:7], v[22:23]
	v_pk_mul_f32 v[20:21], v[4:5], v[20:21]
	v_pk_mul_f32 v[26:27], v[26:27], v[36:37] op_sel_hi:[1,0]
	v_pk_mul_f32 v[24:25], v[24:25], v[36:37] op_sel_hi:[1,0]
	global_store_dwordx4 v[38:39], v[20:23], off offset:576 sc1
	v_pk_mul_f32 v[34:35], v[34:35], v[36:37] op_sel_hi:[1,0]
	v_pk_mul_f32 v[26:27], v[10:11], v[26:27]
	v_mov_b32_e32 v20, v37
	v_pk_mul_f32 v[24:25], v[8:9], v[24:25]
	v_pk_mul_f32 v[22:23], v[102:103], v[20:21] op_sel_hi:[1,0]
	v_pk_mul_f32 v[66:67], v[18:19], v[66:67]
	v_pk_mul_f32 v[48:49], v[48:49], v[52:53] op_sel_hi:[1,0]
	v_pk_mul_f32 v[50:51], v[18:19], v[50:51]
	v_pk_mul_f32 v[32:33], v[32:33], v[36:37] op_sel_hi:[1,0]
	v_pk_mul_f32 v[34:35], v[18:19], v[34:35]
	global_store_dwordx4 v[38:39], v[24:27], off offset:512 sc1
	v_pk_mul_f32 v[18:19], v[18:19], v[22:23]
	v_lshl_add_u64 v[22:23], s[78:79], 0, v[166:167]
	v_pk_mul_f32 v[24:25], v[100:101], v[20:21] op_sel_hi:[1,0]
	v_pk_mul_f32 v[120:121], v[16:17], v[120:121]
	v_pk_mul_f32 v[88:89], v[16:17], v[88:89]
	v_pk_mul_f32 v[64:65], v[16:17], v[64:65]
	v_pk_mul_f32 v[48:49], v[16:17], v[48:49]
	v_pk_mul_f32 v[32:33], v[16:17], v[32:33]
	v_pk_mul_f32 v[16:17], v[16:17], v[24:25]
	v_lshl_add_u64 v[22:23], v[22:23], 0, v[148:149]
	v_pk_mul_f32 v[110:111], v[110:111], v[118:119] op_sel_hi:[1,0]
	v_pk_mul_f32 v[108:109], v[108:109], v[118:119] op_sel_hi:[1,0]
	v_pk_mul_f32 v[82:83], v[82:83], v[98:99] op_sel_hi:[1,0]
	v_pk_mul_f32 v[80:81], v[80:81], v[98:99] op_sel_hi:[1,0]
	v_pk_mul_f32 v[62:63], v[62:63], v[68:69] op_sel_hi:[1,0]
	v_pk_mul_f32 v[60:61], v[60:61], v[68:69] op_sel_hi:[1,0]
	v_pk_mul_f32 v[46:47], v[46:47], v[52:53] op_sel_hi:[1,0]
	v_pk_mul_f32 v[44:45], v[44:45], v[52:53] op_sel_hi:[1,0]
	v_pk_mul_f32 v[30:31], v[30:31], v[36:37] op_sel_hi:[1,0]
	v_pk_mul_f32 v[28:29], v[28:29], v[36:37] op_sel_hi:[1,0]
	global_store_dwordx4 v[22:23], v[16:19], off sc1
	v_pk_mul_f32 v[126:127], v[14:15], v[126:127]
	v_pk_mul_f32 v[124:125], v[12:13], v[124:125]
	v_pk_mul_f32 v[16:17], v[94:95], v[20:21] op_sel_hi:[1,0]
	v_pk_mul_f32 v[18:19], v[92:93], v[20:21] op_sel_hi:[1,0]
	v_pk_mul_f32 v[110:111], v[14:15], v[110:111]
	v_pk_mul_f32 v[108:109], v[12:13], v[108:109]
	v_pk_mul_f32 v[82:83], v[14:15], v[82:83]
	v_pk_mul_f32 v[80:81], v[12:13], v[80:81]
	v_pk_mul_f32 v[62:63], v[14:15], v[62:63]
	v_pk_mul_f32 v[60:61], v[12:13], v[60:61]
	v_pk_mul_f32 v[46:47], v[14:15], v[46:47]
	v_pk_mul_f32 v[44:45], v[12:13], v[44:45]
	v_pk_mul_f32 v[30:31], v[14:15], v[30:31]
	v_pk_mul_f32 v[28:29], v[12:13], v[28:29]
	v_pk_mul_f32 v[14:15], v[14:15], v[16:17]
	v_pk_mul_f32 v[12:13], v[12:13], v[18:19]
	v_pk_mul_f32 v[74:75], v[74:75], v[98:99] op_sel_hi:[1,0]
	v_pk_mul_f32 v[72:73], v[72:73], v[98:99] op_sel_hi:[1,0]
	v_pk_mul_f32 v[58:59], v[58:59], v[68:69] op_sel_hi:[1,0]
	v_pk_mul_f32 v[56:57], v[56:57], v[68:69] op_sel_hi:[1,0]
	v_pk_mul_f32 v[42:43], v[42:43], v[52:53] op_sel_hi:[1,0]
	v_pk_mul_f32 v[40:41], v[40:41], v[52:53] op_sel_hi:[1,0]
	global_store_dwordx4 v[22:23], v[12:15], off offset:64 sc1
	v_pk_mul_f32 v[136:137], v[8:9], v[136:137]
	v_pk_mul_f32 v[74:75], v[10:11], v[74:75]
	v_pk_mul_f32 v[12:13], v[86:87], v[20:21] op_sel_hi:[1,0]
	v_pk_mul_f32 v[14:15], v[84:85], v[20:21] op_sel_hi:[1,0]
	v_pk_mul_f32 v[72:73], v[8:9], v[72:73]
	v_pk_mul_f32 v[58:59], v[10:11], v[58:59]
	v_pk_mul_f32 v[56:57], v[8:9], v[56:57]
	v_pk_mul_f32 v[42:43], v[10:11], v[42:43]
	v_pk_mul_f32 v[40:41], v[8:9], v[40:41]
	v_pk_mul_f32 v[10:11], v[10:11], v[12:13]
	v_pk_mul_f32 v[8:9], v[8:9], v[14:15]
	v_pk_mul_f32 v[104:105], v[112:113], v[118:119] op_sel_hi:[1,0]
	global_store_dwordx4 v[22:23], v[8:11], off offset:512 sc1
	v_pk_mul_f32 v[104:105], v[4:5], v[104:105]
	global_store_dwordx4 v[150:151], v[144:147], off sc1
	v_pk_mul_f32 v[8:9], v[78:79], v[20:21] op_sel_hi:[1,0]
	v_pk_mul_f32 v[10:11], v[76:77], v[20:21] op_sel_hi:[1,0]
	v_pk_mul_f32 v[6:7], v[6:7], v[8:9]
	v_pk_mul_f32 v[4:5], v[4:5], v[10:11]
	global_store_dwordx4 v[150:151], v[140:143], off offset:64 sc1
	global_store_dwordx4 v[150:151], v[136:139], off offset:512 sc1
	global_store_dwordx4 v[134:135], v[128:131], off sc1
	global_store_dwordx4 v[134:135], v[124:127], off offset:64 sc1
	global_store_dwordx4 v[114:115], v[120:123], off sc1
	global_store_dwordx4 v[114:115], v[108:111], off offset:64 sc1
	global_store_dwordx4 v[114:115], v[104:107], off offset:576 sc1
	global_store_dwordx4 v[96:97], v[88:91], off sc1
	global_store_dwordx4 v[96:97], v[80:83], off offset:64 sc1
	global_store_dwordx4 v[96:97], v[72:75], off offset:512 sc1
	global_store_dwordx4 v[70:71], v[64:67], off sc1
	global_store_dwordx4 v[70:71], v[60:63], off offset:64 sc1
	global_store_dwordx4 v[70:71], v[56:59], off offset:512 sc1
	global_store_dwordx4 v[54:55], v[48:51], off sc1
	global_store_dwordx4 v[54:55], v[44:47], off offset:64 sc1
	global_store_dwordx4 v[54:55], v[40:43], off offset:512 sc1
	global_store_dwordx4 v[38:39], v[32:35], off sc1
	global_store_dwordx4 v[38:39], v[28:31], off offset:64 sc1
	global_store_dwordx4 v[22:23], v[4:7], off offset:576 sc1
	s_barrier
